# top-k phase: both heads' key images resident in LDS (one fill + one barrier per phase, loads issued first thing), no per-unit barriers
# baseline (speedup 1.0000x reference)
.LBB0_485:
	s_cmp_lt_i32 s56, 7
	s_cselect_b64 s[0:1], -1, 0
	s_and_b64 s[44:45], s[0:1], s[4:5]
	s_andn2_b64 vcc, exec, s[44:45]
	s_cbranch_vccnz .LBB0_540
	v_mbcnt_lo_u32_b32 v246, -1, 0
	v_mbcnt_hi_u32_b32 v246, -1, v246
	v_readlane_b32 s21, v248, 0
	s_andn2_b32 s26, s21, 63
	v_add_u32_e32 v242, s26, v246
	s_lshr_b32 s21, s21, 6
	s_mov_b32 s4, 0
	s_mov_b32 s5, -1
	s_mov_b32 s6, 0xffffff80
	s_mov_b32 s7, 0xffffffc0
	v_lshrrev_b32_e32 v245, 5, v246
	v_and_b32_e32 v247, 31, v246
	v_lshlrev_b32_e32 v239, 12, v247
	v_lshl_or_b32 v239, v245, 4, v239
	v_lshlrev_b32_e32 v241, 9, v247
	v_lshl_or_b32 v241, v245, 5, v241
	v_lshlrev_b32_e32 v240, 4, v247
	s_lshl_b32 s26, s21, 10
	s_add_i32 s26, s26, 0x20100
	v_add_u32_e32 v240, s26, v240
	v_and_b32_e32 v215, 15, v246
	v_xor_b32_e32 v215, v215, v245
	v_lshlrev_b32_e32 v215, 4, v215
	v_lshl_or_b32 v215, v247, 8, v215
	v_xor_b32_e32 v232, 32, v215
	v_xor_b32_e32 v233, 64, v215
	v_xor_b32_e32 v234, 0x60, v215
	v_xor_b32_e32 v235, 0x80, v215
	v_xor_b32_e32 v236, 0xa0, v215
	v_xor_b32_e32 v237, 0xc0, v215
	v_xor_b32_e32 v238, 0xe0, v215
	v_lshlrev_b32_e32 v247, 2, v245
	v_xor_b32_e32 v211, 4, v247
	v_lshrrev_b32_e32 v243, 4, v242
	v_xor_b32_e32 v247, v243, v242
	v_lshlrev_b32_e32 v242, 4, v242
	v_and_b32_e32 v247, 15, v247
	v_lshlrev_b32_e32 v247, 4, v247
	v_lshl_or_b32 v243, v243, 8, v247
	s_lshr_b32 s26, s2, 6
	s_lshl_b32 s26, s26, 16
	s_add_i32 s26, s26, 0x300000
	s_add_u32 s18, s54, s26
	s_addc_u32 s19, s55, 0
	global_load_dwordx4 v[0:3], v242, s[18:19]
	v_add_u32_e32 v247, 0x2000, v242
	global_load_dwordx4 v[4:7], v247, s[18:19]
	v_add_u32_e32 v247, 0x4000, v242
	global_load_dwordx4 v[8:11], v247, s[18:19]
	v_add_u32_e32 v247, 0x6000, v242
	global_load_dwordx4 v[12:15], v247, s[18:19]
	v_add_u32_e32 v247, 0x8000, v242
	global_load_dwordx4 v[16:19], v247, s[18:19]
	v_add_u32_e32 v247, 0xa000, v242
	global_load_dwordx4 v[20:23], v247, s[18:19]
	v_add_u32_e32 v247, 0xc000, v242
	global_load_dwordx4 v[24:27], v247, s[18:19]
	v_add_u32_e32 v247, 0xe000, v242
	global_load_dwordx4 v[28:31], v247, s[18:19]
	v_add_u32_e32 v247, 0x40000, v242
	global_load_dwordx4 v[32:35], v247, s[18:19]
	v_add_u32_e32 v247, 0x42000, v242
	global_load_dwordx4 v[36:39], v247, s[18:19]
	v_add_u32_e32 v247, 0x44000, v242
	global_load_dwordx4 v[40:43], v247, s[18:19]
	v_add_u32_e32 v247, 0x46000, v242
	global_load_dwordx4 v[44:47], v247, s[18:19]
	v_add_u32_e32 v247, 0x48000, v242
	global_load_dwordx4 v[48:51], v247, s[18:19]
	v_add_u32_e32 v247, 0x4a000, v242
	global_load_dwordx4 v[52:55], v247, s[18:19]
	v_add_u32_e32 v247, 0x4c000, v242
	global_load_dwordx4 v[56:59], v247, s[18:19]
	v_add_u32_e32 v247, 0x4e000, v242
	global_load_dwordx4 v[60:63], v247, s[18:19]
	v_mov_b32_e32 v244, 0xff800000
	v_mov_b32_e32 v247, 0x22100
	v_mov_b32_e32 v128, 0x20021001
	ds_write_b32 v247, v128 offset:0
	v_mov_b32_e32 v128, 0x40043003
	ds_write_b32 v247, v128 offset:4
	v_mov_b32_e32 v128, 0x60065005
	ds_write_b32 v247, v128 offset:8
	v_mov_b32_e32 v128, 0x80087007
	ds_write_b32 v247, v128 offset:12
	v_mov_b32_e32 v128, 0xa00a9009
	ds_write_b32 v247, v128 offset:16
	v_mov_b32_e32 v128, 0xc00cb00b
	ds_write_b32 v247, v128 offset:20
	v_mov_b32_e32 v128, 0xe00ed00d
	ds_write_b32 v247, v128 offset:24
	v_mov_b32_e32 v128, 0x2112f00f
	ds_write_b32 v247, v128 offset:28
	v_mov_b32_e32 v128, 0x41143113
	ds_write_b32 v247, v128 offset:32
	v_mov_b32_e32 v128, 0x61165115
	ds_write_b32 v247, v128 offset:36
	v_mov_b32_e32 v128, 0x32237117
	ds_write_b32 v247, v128 offset:40
	v_mov_b32_e32 v128, 0x4224
	ds_write_b32 v247, v128 offset:44
	v_mov_b32_e32 v128, 0x22221111
	ds_write_b32 v247, v128 offset:48
	v_mov_b32_e32 v128, 0x3333
	ds_write_b32 v247, v128 offset:52
	v_mov_b32_e32 v128, 0
	ds_write_b32 v247, v128 offset:56
	v_mov_b32_e32 v128, 0
	ds_write_b32 v247, v128 offset:60
	s_and_b32 s25, s2, 7
	s_lshl_b32 s25, s25, 3
	s_bfe_u32 s26, s2, 0x30003
	s_add_i32 s25, s25, s26
	s_lshl_b32 s23, s25, 8
	s_lshl_b32 s26, s21, 5
	s_add_i32 s23, s23, s26
	v_lshlrev_b32_e32 v212, 4, v246
	v_lshlrev_b32_e32 v213, 1, v246
	v_mov_b32_e32 v214, 0
	s_lshl_b32 s14, s2, 3
	s_add_i32 s14, s14, s21
	s_and_b32 s15, s14, 1
	s_lshr_b32 s14, s14, 1
	v_readlane_b32 s8, v248, 12
	v_readlane_b32 s9, v248, 13
	s_lshl_b32 s26, s14, 13
	s_lshl_b32 s25, s15, 12
	s_add_i32 s26, s26, s25
	s_add_u32 s8, s8, s26
	s_addc_u32 s9, s9, 0
	v_readlane_b32 s12, v248, 14
	v_readlane_b32 s13, v248, 15
	s_add_u32 s12, s12, s25
	s_addc_u32 s13, s13, 0
	global_load_dwordx4 v[176:179], v212, s[12:13] offset:0
	global_load_dwordx4 v[180:183], v212, s[12:13] offset:1024
	global_load_dwordx4 v[184:187], v212, s[12:13] offset:2048
	global_load_dwordx4 v[188:191], v212, s[12:13] offset:3072
	s_lshl_b32 s26, s15, 23
	s_lshl_b32 s25, s14, 7
	s_add_i32 s26, s26, s25
	s_add_i32 s26, s26, 0x8000000
	s_add_u32 s10, s54, s26
	s_addc_u32 s11, s55, 0
	s_lshl_b32 s26, s14, 3
	s_lshl_b32 s25, s15, 2
	s_add_i32 s26, s26, s25
	s_add_i32 s26, s26, 0x80000
	s_add_u32 s12, s54, s26
	s_addc_u32 s13, s55, 0
	global_load_dwordx4 v[160:163], v212, s[8:9] offset:0 nt
	global_load_dwordx4 v[164:167], v212, s[8:9] offset:1024 nt
	global_load_dwordx4 v[168:171], v212, s[8:9] offset:2048 nt
	global_load_dwordx4 v[172:175], v212, s[8:9] offset:3072 nt
	s_add_u32 s8, s8, 0x800000
	s_addc_u32 s9, s9, 0
	v_mov_b32_e32 v246, 0x22100
	s_lshr_b32 s24, s2, 6
	s_mov_b32 s22, 0
	v_add_u32_e32 v247, 0x10000, v243
	s_waitcnt vmcnt(23)
	ds_write_b128 v243, v[0:3] offset:0
	s_waitcnt vmcnt(22)
	ds_write_b128 v243, v[4:7] offset:8192
	s_waitcnt vmcnt(21)
	ds_write_b128 v243, v[8:11] offset:16384
	s_waitcnt vmcnt(20)
	ds_write_b128 v243, v[12:15] offset:24576
	s_waitcnt vmcnt(19)
	ds_write_b128 v243, v[16:19] offset:32768
	s_waitcnt vmcnt(18)
	ds_write_b128 v243, v[20:23] offset:40960
	s_waitcnt vmcnt(17)
	ds_write_b128 v243, v[24:27] offset:49152
	s_waitcnt vmcnt(16)
	ds_write_b128 v243, v[28:31] offset:57344
	s_waitcnt vmcnt(15)
	ds_write_b128 v247, v[32:35] offset:0
	s_waitcnt vmcnt(14)
	ds_write_b128 v247, v[36:39] offset:8192
	s_waitcnt vmcnt(13)
	ds_write_b128 v247, v[40:43] offset:16384
	s_waitcnt vmcnt(12)
	ds_write_b128 v247, v[44:47] offset:24576
	s_waitcnt vmcnt(11)
	ds_write_b128 v247, v[48:51] offset:32768
	s_waitcnt vmcnt(10)
	ds_write_b128 v247, v[52:55] offset:40960
	s_waitcnt vmcnt(9)
	ds_write_b128 v247, v[56:59] offset:49152
	s_waitcnt vmcnt(8)
	ds_write_b128 v247, v[60:63] offset:57344
	s_waitcnt lgkmcnt(0)
	s_barrier
.Ltk0_unit:
	s_lshl_b32 s26, s24, 9
	s_lshl_b32 s20, s23, 12
	s_add_i32 s26, s26, s20
	s_add_i32 s26, s26, 0x1c000000
	s_add_u32 s16, s54, s26
	s_addc_u32 s17, s55, 0
	s_lshl_b32 s26, s24, 16
	s_add_i32 s26, s26, 0x300000
	s_add_u32 s18, s54, s26
	s_addc_u32 s19, s55, 0
	s_lshl_b32 s20, s23, 9
	s_lshl_b32 s26, s24, 6
	s_add_i32 s20, s20, s26
	s_add_i32 s26, s20, 0x28000000
	s_add_u32 s28, s54, s26
	s_addc_u32 s29, s55, 0
	s_add_i32 s26, s20, 0x28800000
	s_add_u32 s30, s54, s26
	s_addc_u32 s31, s55, 0
	global_load_dwordx4 v[64:67], v239, s[16:17] offset:0
	global_load_dwordx4 v[68:71], v239, s[16:17] offset:32
	global_load_dwordx4 v[72:75], v239, s[16:17] offset:64
	global_load_dwordx4 v[76:79], v239, s[16:17] offset:96
	global_load_dwordx4 v[80:83], v239, s[16:17] offset:128
	global_load_dwordx4 v[84:87], v239, s[16:17] offset:160
	global_load_dwordx4 v[88:91], v239, s[16:17] offset:192
	global_load_dwordx4 v[92:95], v239, s[16:17] offset:224
	ds_read_b128 v[96:99], v215 offset:0
	ds_read_b128 v[100:103], v232 offset:0
	ds_read_b128 v[104:107], v233 offset:0
	ds_read_b128 v[108:111], v234 offset:0
	ds_read_b128 v[112:115], v235 offset:0
	ds_read_b128 v[116:119], v236 offset:0
	ds_read_b128 v[120:123], v237 offset:0
	ds_read_b128 v[124:127], v238 offset:0
	s_waitcnt vmcnt(0)
	s_waitcnt lgkmcnt(4)
	v_mfma_f32_32x32x16_bf16 v[0:15], v[96:99], v[64:67], 0
	v_mfma_f32_32x32x16_bf16 v[0:15], v[100:103], v[68:71], v[0:15]
	v_mfma_f32_32x32x16_bf16 v[0:15], v[104:107], v[72:75], v[0:15]
	v_mfma_f32_32x32x16_bf16 v[0:15], v[108:111], v[76:79], v[0:15]
	ds_read_b128 v[96:99], v215 offset:8192
	ds_read_b128 v[100:103], v232 offset:8192
	ds_read_b128 v[104:107], v233 offset:8192
	ds_read_b128 v[108:111], v234 offset:8192
	s_waitcnt lgkmcnt(4)
	v_mfma_f32_32x32x16_bf16 v[0:15], v[112:115], v[80:83], v[0:15]
	v_mfma_f32_32x32x16_bf16 v[0:15], v[116:119], v[84:87], v[0:15]
	v_mfma_f32_32x32x16_bf16 v[0:15], v[120:123], v[88:91], v[0:15]
	v_mfma_f32_32x32x16_bf16 v[0:15], v[124:127], v[92:95], v[0:15]
	ds_read_b128 v[112:115], v235 offset:8192
	ds_read_b128 v[116:119], v236 offset:8192
	ds_read_b128 v[120:123], v237 offset:8192
	ds_read_b128 v[124:127], v238 offset:8192
	s_waitcnt lgkmcnt(4)
	v_mfma_f32_32x32x16_bf16 v[16:31], v[96:99], v[64:67], 0
	v_mfma_f32_32x32x16_bf16 v[16:31], v[100:103], v[68:71], v[16:31]
	v_mfma_f32_32x32x16_bf16 v[16:31], v[104:107], v[72:75], v[16:31]
	v_mfma_f32_32x32x16_bf16 v[16:31], v[108:111], v[76:79], v[16:31]
	ds_read_b128 v[96:99], v215 offset:16384
	ds_read_b128 v[100:103], v232 offset:16384
	ds_read_b128 v[104:107], v233 offset:16384
	ds_read_b128 v[108:111], v234 offset:16384
	s_waitcnt lgkmcnt(4)
	v_mfma_f32_32x32x16_bf16 v[16:31], v[112:115], v[80:83], v[16:31]
	v_mfma_f32_32x32x16_bf16 v[16:31], v[116:119], v[84:87], v[16:31]
	v_mfma_f32_32x32x16_bf16 v[16:31], v[120:123], v[88:91], v[16:31]
	v_mfma_f32_32x32x16_bf16 v[16:31], v[124:127], v[92:95], v[16:31]
	ds_read_b128 v[112:115], v235 offset:16384
	ds_read_b128 v[116:119], v236 offset:16384
	ds_read_b128 v[120:123], v237 offset:16384
	ds_read_b128 v[124:127], v238 offset:16384
	s_waitcnt lgkmcnt(4)
	v_mfma_f32_32x32x16_bf16 v[32:47], v[96:99], v[64:67], 0
	v_mfma_f32_32x32x16_bf16 v[32:47], v[100:103], v[68:71], v[32:47]
	v_mfma_f32_32x32x16_bf16 v[32:47], v[104:107], v[72:75], v[32:47]
	v_mfma_f32_32x32x16_bf16 v[32:47], v[108:111], v[76:79], v[32:47]
	ds_read_b128 v[96:99], v215 offset:24576
	ds_read_b128 v[100:103], v232 offset:24576
	ds_read_b128 v[104:107], v233 offset:24576
	ds_read_b128 v[108:111], v234 offset:24576
	s_waitcnt lgkmcnt(4)
	v_mfma_f32_32x32x16_bf16 v[32:47], v[112:115], v[80:83], v[32:47]
	v_mfma_f32_32x32x16_bf16 v[32:47], v[116:119], v[84:87], v[32:47]
	v_mfma_f32_32x32x16_bf16 v[32:47], v[120:123], v[88:91], v[32:47]
	v_mfma_f32_32x32x16_bf16 v[32:47], v[124:127], v[92:95], v[32:47]
	ds_read_b128 v[112:115], v235 offset:24576
	ds_read_b128 v[116:119], v236 offset:24576
	ds_read_b128 v[120:123], v237 offset:24576
	ds_read_b128 v[124:127], v238 offset:24576
	s_waitcnt lgkmcnt(4)
	v_mfma_f32_32x32x16_bf16 v[48:63], v[96:99], v[64:67], 0
	v_mfma_f32_32x32x16_bf16 v[48:63], v[100:103], v[68:71], v[48:63]
	v_mfma_f32_32x32x16_bf16 v[48:63], v[104:107], v[72:75], v[48:63]
	v_mfma_f32_32x32x16_bf16 v[48:63], v[108:111], v[76:79], v[48:63]
	s_waitcnt lgkmcnt(0)
	v_mfma_f32_32x32x16_bf16 v[48:63], v[112:115], v[80:83], v[48:63]
	v_mfma_f32_32x32x16_bf16 v[48:63], v[116:119], v[84:87], v[48:63]
	v_mfma_f32_32x32x16_bf16 v[48:63], v[120:123], v[88:91], v[48:63]
	v_mfma_f32_32x32x16_bf16 v[48:63], v[124:127], v[92:95], v[48:63]
	global_load_dwordx4 v[64:67], v239, s[16:17] offset:256
	global_load_dwordx4 v[68:71], v239, s[16:17] offset:288
	global_load_dwordx4 v[72:75], v239, s[16:17] offset:320
	global_load_dwordx4 v[76:79], v239, s[16:17] offset:352
	global_load_dwordx4 v[80:83], v239, s[16:17] offset:384
	global_load_dwordx4 v[84:87], v239, s[16:17] offset:416
	global_load_dwordx4 v[88:91], v239, s[16:17] offset:448
	global_load_dwordx4 v[92:95], v239, s[16:17] offset:480
	s_nop 11
	v_and_or_b32 v0, v0, s6, v211
	v_or_b32_e32 v0, 0x7b, v0
	v_and_or_b32 v1, v1, s6, v211
	v_or_b32_e32 v1, 0x7a, v1
	v_and_or_b32 v2, v2, s6, v211
	v_or_b32_e32 v2, 0x79, v2
	v_and_or_b32 v3, v3, s6, v211
	v_or_b32_e32 v3, 0x78, v3
	v_and_or_b32 v4, v4, s6, v211
	v_or_b32_e32 v4, 0x73, v4
	v_and_or_b32 v5, v5, s6, v211
	v_or_b32_e32 v5, 0x72, v5
	v_and_or_b32 v6, v6, s6, v211
	v_or_b32_e32 v6, 0x71, v6
	v_and_or_b32 v7, v7, s6, v211
	v_or_b32_e32 v7, 0x70, v7
	v_and_or_b32 v8, v8, s6, v211
	v_or_b32_e32 v8, 0x6b, v8
	v_and_or_b32 v9, v9, s6, v211
	v_or_b32_e32 v9, 0x6a, v9
	v_and_or_b32 v10, v10, s6, v211
	v_or_b32_e32 v10, 0x69, v10
	v_and_or_b32 v11, v11, s6, v211
	v_or_b32_e32 v11, 0x68, v11
	v_and_or_b32 v12, v12, s6, v211
	v_or_b32_e32 v12, 0x63, v12
	v_and_or_b32 v13, v13, s6, v211
	v_or_b32_e32 v13, 0x62, v13
	v_and_or_b32 v14, v14, s6, v211
	v_or_b32_e32 v14, 0x61, v14
	v_and_or_b32 v15, v15, s6, v211
	v_or_b32_e32 v15, 0x60, v15
	v_and_or_b32 v16, v16, s6, v211
	v_or_b32_e32 v16, 0x5b, v16
	v_and_or_b32 v17, v17, s6, v211
	v_or_b32_e32 v17, 0x5a, v17
	v_and_or_b32 v18, v18, s6, v211
	v_or_b32_e32 v18, 0x59, v18
	v_and_or_b32 v19, v19, s6, v211
	v_or_b32_e32 v19, 0x58, v19
	v_and_or_b32 v20, v20, s6, v211
	v_or_b32_e32 v20, 0x53, v20
	v_and_or_b32 v21, v21, s6, v211
	v_or_b32_e32 v21, 0x52, v21
	v_and_or_b32 v22, v22, s6, v211
	v_or_b32_e32 v22, 0x51, v22
	v_and_or_b32 v23, v23, s6, v211
	v_or_b32_e32 v23, 0x50, v23
	v_and_or_b32 v24, v24, s6, v211
	v_or_b32_e32 v24, 0x4b, v24
	v_and_or_b32 v25, v25, s6, v211
	v_or_b32_e32 v25, 0x4a, v25
	v_and_or_b32 v26, v26, s6, v211
	v_or_b32_e32 v26, 0x49, v26
	v_and_or_b32 v27, v27, s6, v211
	v_or_b32_e32 v27, 0x48, v27
	v_and_or_b32 v28, v28, s6, v211
	v_or_b32_e32 v28, 0x43, v28
	v_and_or_b32 v29, v29, s6, v211
	v_or_b32_e32 v29, 0x42, v29
	v_and_or_b32 v30, v30, s6, v211
	v_or_b32_e32 v30, 0x41, v30
	v_and_or_b32 v31, v31, s6, v211
	v_or_b32_e32 v31, 64, v31
	v_and_or_b32 v32, v32, s6, v211
	v_or_b32_e32 v32, 59, v32
	v_and_or_b32 v33, v33, s6, v211
	v_or_b32_e32 v33, 58, v33
	v_and_or_b32 v34, v34, s6, v211
	v_or_b32_e32 v34, 57, v34
	v_and_or_b32 v35, v35, s6, v211
	v_or_b32_e32 v35, 56, v35
	v_and_or_b32 v36, v36, s6, v211
	v_or_b32_e32 v36, 51, v36
	v_and_or_b32 v37, v37, s6, v211
	v_or_b32_e32 v37, 50, v37
	v_and_or_b32 v38, v38, s6, v211
	v_or_b32_e32 v38, 49, v38
	v_and_or_b32 v39, v39, s6, v211
	v_or_b32_e32 v39, 48, v39
	v_and_or_b32 v40, v40, s6, v211
	v_or_b32_e32 v40, 43, v40
	v_and_or_b32 v41, v41, s6, v211
	v_or_b32_e32 v41, 42, v41
	v_and_or_b32 v42, v42, s6, v211
	v_or_b32_e32 v42, 41, v42
	v_and_or_b32 v43, v43, s6, v211
	v_or_b32_e32 v43, 40, v43
	v_and_or_b32 v44, v44, s6, v211
	v_or_b32_e32 v44, 35, v44
	v_and_or_b32 v45, v45, s6, v211
	v_or_b32_e32 v45, 34, v45
	v_and_or_b32 v46, v46, s6, v211
	v_or_b32_e32 v46, 33, v46
	v_and_or_b32 v47, v47, s6, v211
	v_or_b32_e32 v47, 32, v47
	v_and_or_b32 v48, v48, s6, v211
	v_or_b32_e32 v48, 27, v48
	v_and_or_b32 v49, v49, s6, v211
	v_or_b32_e32 v49, 26, v49
	v_and_or_b32 v50, v50, s6, v211
	v_or_b32_e32 v50, 25, v50
	v_and_or_b32 v51, v51, s6, v211
	v_or_b32_e32 v51, 24, v51
	v_and_or_b32 v52, v52, s6, v211
	v_or_b32_e32 v52, 19, v52
	v_and_or_b32 v53, v53, s6, v211
	v_or_b32_e32 v53, 18, v53
	v_and_or_b32 v54, v54, s6, v211
	v_or_b32_e32 v54, 17, v54
	v_and_or_b32 v55, v55, s6, v211
	v_or_b32_e32 v55, 16, v55
	v_and_or_b32 v56, v56, s6, v211
	v_or_b32_e32 v56, 11, v56
	v_and_or_b32 v57, v57, s6, v211
	v_or_b32_e32 v57, 10, v57
	v_and_or_b32 v58, v58, s6, v211
	v_or_b32_e32 v58, 9, v58
	v_and_or_b32 v59, v59, s6, v211
	v_or_b32_e32 v59, 8, v59
	v_and_or_b32 v60, v60, s6, v211
	v_or_b32_e32 v60, 3, v60
	v_and_or_b32 v61, v61, s6, v211
	v_or_b32_e32 v61, 2, v61
	v_and_or_b32 v62, v62, s6, v211
	v_or_b32_e32 v62, 1, v62
	v_and_or_b32 v63, v63, s6, v211
	v_or_b32_e32 v63, 0, v63
	v_max_f32_e32 v144, v0, v13
	v_min_f32_e32 v13, v0, v13
	v_max_f32_e32 v145, v1, v12
	v_min_f32_e32 v12, v1, v12
	v_max_f32_e32 v146, v2, v15
	v_min_f32_e32 v15, v2, v15
	v_max_f32_e32 v147, v3, v14
	v_min_f32_e32 v14, v3, v14
	v_max_f32_e32 v148, v4, v8
	v_min_f32_e32 v8, v4, v8
	v_max_f32_e32 v149, v5, v6
	v_min_f32_e32 v6, v5, v6
	v_max_f32_e32 v150, v7, v11
	v_min_f32_e32 v11, v7, v11
	v_max_f32_e32 v151, v9, v10
	v_min_f32_e32 v10, v9, v10
	v_max_f32_e32 v249, v144, v149
	v_min_f32_e32 v149, v144, v149
	v_max_f32_e32 v250, v145, v150
	v_min_f32_e32 v150, v145, v150
	v_max_f32_e32 v251, v146, v151
	v_min_f32_e32 v151, v146, v151
	v_max_f32_e32 v252, v147, v148
	v_min_f32_e32 v148, v147, v148
	v_max_f32_e32 v253, v6, v13
	v_min_f32_e32 v13, v6, v13
	v_max_f32_e32 v254, v8, v14
	v_min_f32_e32 v14, v8, v14
	v_max_f32_e32 v255, v10, v15
	v_min_f32_e32 v15, v10, v15
	v_max_f32_e32 v96, v11, v12
	v_min_f32_e32 v12, v11, v12
	v_max_f32_e32 v97, v249, v250
	v_min_f32_e32 v250, v249, v250
	v_max_f32_e32 v98, v251, v252
	v_min_f32_e32 v252, v251, v252
	v_max_f32_e32 v99, v148, v149
	v_min_f32_e32 v149, v148, v149
	v_max_f32_e32 v100, v253, v254
	v_min_f32_e32 v254, v253, v254
	v_max_f32_e32 v101, v150, v151
	v_min_f32_e32 v151, v150, v151
	v_max_f32_e32 v102, v255, v96
	v_min_f32_e32 v96, v255, v96
	v_max_f32_e32 v103, v12, v13
	v_min_f32_e32 v13, v12, v13
	v_max_f32_e32 v104, v14, v15
	v_min_f32_e32 v15, v14, v15
	v_max_f32_e32 v105, v97, v98
	v_min_f32_e32 v98, v97, v98
	v_max_f32_e32 v106, v250, v252
	v_min_f32_e32 v252, v250, v252
	v_max_f32_e32 v107, v99, v102
	v_min_f32_e32 v102, v99, v102
	v_max_f32_e32 v108, v149, v96
	v_min_f32_e32 v96, v149, v96
	v_max_f32_e32 v109, v100, v101
	v_min_f32_e32 v101, v100, v101
	v_max_f32_e32 v110, v254, v151
	v_min_f32_e32 v151, v254, v151
	v_max_f32_e32 v111, v103, v104
	v_min_f32_e32 v104, v103, v104
	v_max_f32_e32 v112, v13, v15
	v_min_f32_e32 v15, v13, v15
	v_max_f32_e32 v113, v106, v98
	v_min_f32_e32 v98, v106, v98
	v_max_f32_e32 v114, v252, v111
	v_min_f32_e32 v111, v252, v111
	v_max_f32_e32 v115, v107, v109
	v_min_f32_e32 v109, v107, v109
	v_max_f32_e32 v116, v108, v101
	v_min_f32_e32 v101, v108, v101
	v_max_f32_e32 v117, v110, v102
	v_min_f32_e32 v102, v110, v102
	v_max_f32_e32 v118, v151, v96
	v_min_f32_e32 v96, v151, v96
	v_max_f32_e32 v119, v112, v104
	v_min_f32_e32 v104, v112, v104
	v_max_f32_e32 v120, v113, v115
	v_min_f32_e32 v115, v113, v115
	v_max_f32_e32 v121, v98, v109
	v_min_f32_e32 v109, v98, v109
	v_max_f32_e32 v122, v116, v117
	v_min_f32_e32 v117, v116, v117
	v_max_f32_e32 v123, v101, v102
	v_min_f32_e32 v102, v101, v102
	v_max_f32_e32 v124, v118, v119
	v_min_f32_e32 v119, v118, v119
	v_max_f32_e32 v125, v96, v104
	v_min_f32_e32 v104, v96, v104
	v_max_f32_e32 v126, v121, v115
	v_min_f32_e32 v115, v121, v115
	v_max_f32_e32 v127, v114, v109
	v_min_f32_e32 v109, v114, v109
	v_max_f32_e32 v0, v124, v111
	v_min_f32_e32 v111, v124, v111
	v_max_f32_e32 v1, v125, v119
	v_min_f32_e32 v119, v125, v119
	v_max_f32_e32 v2, v127, v122
	v_min_f32_e32 v122, v127, v122
	v_max_f32_e32 v3, v109, v117
	v_min_f32_e32 v117, v109, v117
	v_max_f32_e32 v4, v123, v0
	v_min_f32_e32 v0, v123, v0
	v_max_f32_e32 v5, v102, v111
	v_min_f32_e32 v111, v102, v111
	v_max_f32_e32 v7, v2, v115
	v_min_f32_e32 v115, v2, v115
	v_max_f32_e32 v9, v122, v3
	v_min_f32_e32 v3, v122, v3
	v_max_f32_e32 v144, v4, v117
	v_min_f32_e32 v117, v4, v117
	v_max_f32_e32 v145, v0, v5
	v_min_f32_e32 v5, v0, v5
	v_max_f32_e32 v146, v1, v111
	v_min_f32_e32 v111, v1, v111
	v_max_f32_e32 v147, v3, v144
	v_min_f32_e32 v144, v3, v144
	v_max_f32_e32 v6, v117, v145
	v_min_f32_e32 v145, v117, v145
	v_max_f32_e32 v8, v16, v29
	v_min_f32_e32 v29, v16, v29
	v_max_f32_e32 v10, v17, v28
	v_min_f32_e32 v28, v17, v28
	v_max_f32_e32 v11, v18, v31
	v_min_f32_e32 v31, v18, v31
	v_max_f32_e32 v249, v19, v30
	v_min_f32_e32 v30, v19, v30
	v_max_f32_e32 v251, v20, v24
	v_min_f32_e32 v24, v20, v24
	v_max_f32_e32 v148, v21, v22
	v_min_f32_e32 v22, v21, v22
	v_max_f32_e32 v253, v23, v27
	v_min_f32_e32 v27, v23, v27
	v_max_f32_e32 v150, v25, v26
	v_min_f32_e32 v26, v25, v26
	v_max_f32_e32 v255, v8, v148
	v_min_f32_e32 v148, v8, v148
	v_max_f32_e32 v12, v10, v253
	v_min_f32_e32 v253, v10, v253
	v_max_f32_e32 v14, v11, v150
	v_min_f32_e32 v150, v11, v150
	v_max_f32_e32 v97, v249, v251
	v_min_f32_e32 v251, v249, v251
	v_max_f32_e32 v250, v22, v29
	v_min_f32_e32 v29, v22, v29
	v_max_f32_e32 v99, v24, v30
	v_min_f32_e32 v30, v24, v30
	v_max_f32_e32 v149, v26, v31
	v_min_f32_e32 v31, v26, v31
	v_max_f32_e32 v100, v27, v28
	v_min_f32_e32 v28, v27, v28
	v_max_f32_e32 v254, v255, v12
	v_min_f32_e32 v12, v255, v12
	v_max_f32_e32 v103, v14, v97
	v_min_f32_e32 v97, v14, v97
	v_max_f32_e32 v13, v251, v148
	v_min_f32_e32 v148, v251, v148
	v_max_f32_e32 v106, v250, v99
	v_min_f32_e32 v99, v250, v99
	v_max_f32_e32 v252, v253, v150
	v_min_f32_e32 v150, v253, v150
	v_max_f32_e32 v107, v149, v100
	v_min_f32_e32 v100, v149, v100
	v_max_f32_e32 v108, v28, v29
	v_min_f32_e32 v29, v28, v29
	v_max_f32_e32 v110, v30, v31
	v_min_f32_e32 v31, v30, v31
	v_max_f32_e32 v151, v254, v103
	v_min_f32_e32 v103, v254, v103
	v_max_f32_e32 v112, v12, v97
	v_min_f32_e32 v97, v12, v97
	v_max_f32_e32 v113, v13, v107
	v_min_f32_e32 v107, v13, v107
	v_max_f32_e32 v98, v148, v100
	v_min_f32_e32 v100, v148, v100
	v_max_f32_e32 v116, v106, v252
	v_min_f32_e32 v252, v106, v252
	v_max_f32_e32 v101, v99, v150
	v_min_f32_e32 v150, v99, v150
	v_max_f32_e32 v118, v108, v110
	v_min_f32_e32 v110, v108, v110
	v_max_f32_e32 v96, v29, v31
	v_min_f32_e32 v31, v29, v31
	v_max_f32_e32 v121, v112, v103
	v_min_f32_e32 v103, v112, v103
	v_max_f32_e32 v114, v97, v118
	v_min_f32_e32 v118, v97, v118
	v_max_f32_e32 v124, v113, v116
	v_min_f32_e32 v116, v113, v116
	v_max_f32_e32 v125, v98, v252
	v_min_f32_e32 v252, v98, v252
	v_max_f32_e32 v127, v101, v107
	v_min_f32_e32 v107, v101, v107
	v_max_f32_e32 v109, v150, v100
	v_min_f32_e32 v100, v150, v100
	v_max_f32_e32 v123, v96, v110
	v_min_f32_e32 v110, v96, v110
	v_max_f32_e32 v102, v121, v124
	v_min_f32_e32 v124, v121, v124
	v_max_f32_e32 v2, v103, v116
	v_min_f32_e32 v116, v103, v116
	v_max_f32_e32 v122, v125, v127
	v_min_f32_e32 v127, v125, v127
	v_max_f32_e32 v4, v252, v107
	v_min_f32_e32 v107, v252, v107
	v_max_f32_e32 v0, v109, v123
	v_min_f32_e32 v123, v109, v123
	v_max_f32_e32 v1, v100, v110
	v_min_f32_e32 v110, v100, v110
	v_max_f32_e32 v3, v2, v124
	v_min_f32_e32 v124, v2, v124
	v_max_f32_e32 v117, v114, v116
	v_min_f32_e32 v116, v114, v116
	v_max_f32_e32 v16, v0, v118
	v_min_f32_e32 v118, v0, v118
	v_max_f32_e32 v17, v1, v123
	v_min_f32_e32 v123, v1, v123
	v_max_f32_e32 v18, v117, v122
	v_min_f32_e32 v122, v117, v122
	v_max_f32_e32 v19, v116, v127
	v_min_f32_e32 v127, v116, v127
	v_max_f32_e32 v20, v4, v16
	v_min_f32_e32 v16, v4, v16
	v_max_f32_e32 v21, v107, v118
	v_min_f32_e32 v118, v107, v118
	v_max_f32_e32 v23, v18, v124
	v_min_f32_e32 v124, v18, v124
	v_max_f32_e32 v25, v122, v19
	v_min_f32_e32 v19, v122, v19
	v_max_f32_e32 v8, v20, v127
	v_min_f32_e32 v127, v20, v127
	v_max_f32_e32 v10, v16, v21
	v_min_f32_e32 v21, v16, v21
	v_max_f32_e32 v11, v17, v118
	v_min_f32_e32 v118, v17, v118
	v_max_f32_e32 v249, v19, v8
	v_min_f32_e32 v8, v19, v8
	v_max_f32_e32 v22, v127, v10
	v_min_f32_e32 v10, v127, v10
	s_waitcnt vmcnt(16)
	v_pk_mul_f32 v[160:161], v[160:161], v[176:177]
	v_pk_mul_f32 v[162:163], v[162:163], v[178:179]
	v_pk_mul_f32 v[164:165], v[164:165], v[180:181]
	v_pk_mul_f32 v[166:167], v[166:167], v[182:183]
	v_pk_mul_f32 v[168:169], v[168:169], v[184:185]
	v_pk_mul_f32 v[170:171], v[170:171], v[186:187]
	v_pk_mul_f32 v[172:173], v[172:173], v[188:189]
	v_pk_mul_f32 v[174:175], v[174:175], v[190:191]
	v_max3_f32 v192, |v160|, |v161|, |v162|
	v_max3_f32 v192, |v163|, |v164|, v192
	v_max3_f32 v192, |v165|, |v166|, v192
	v_max3_f32 v192, |v167|, |v168|, v192
	v_max3_f32 v192, |v169|, |v170|, v192
	v_max3_f32 v192, |v171|, |v172|, v192
	v_max3_f32 v192, |v173|, |v174|, v192
	v_max_f32_e64 v192, |v175|, v192
	s_nop 1
	v_mov_b32_dpp v193, v192 quad_perm:[1,0,3,2] row_mask:0xf bank_mask:0xf bound_ctrl:1
	v_max_f32_e32 v192, v192, v193
	s_nop 1
	v_mov_b32_dpp v193, v192 quad_perm:[2,3,0,1] row_mask:0xf bank_mask:0xf bound_ctrl:1
	v_max_f32_e32 v192, v192, v193
	s_nop 1
	v_mov_b32_dpp v193, v192 row_half_mirror row_mask:0xf bank_mask:0xf bound_ctrl:1
	v_max_f32_e32 v192, v192, v193
	s_nop 1
	v_mov_b32_dpp v193, v192 row_mirror row_mask:0xf bank_mask:0xf bound_ctrl:1
	v_max_f32_e32 v192, v192, v193
	v_mov_b32_e32 v193, v192
	s_nop 1
	v_permlane16_swap_b32_e32 v192, v193
	s_nop 1
	v_max_f32_e32 v192, v192, v193
	v_mov_b32_e32 v193, v192
	s_nop 1
	v_permlane32_swap_b32_e32 v192, v193
	s_nop 1
	v_max_f32_e32 v192, v192, v193
	v_max_f32_e32 v192, 0xda24260, v192
	v_mul_f32_e32 v194, 0x3e2aaaab, v192
	global_store_dword v214, v194, s[12:13]
	v_div_scale_f32 v195, s[26:27], v194, v194, 1.0
	v_rcp_f32_e32 v196, v195
	v_div_scale_f32 v204, vcc, 1.0, v194, 1.0
	v_fma_f32 v205, -v195, v196, 1.0
	v_fmac_f32_e32 v196, v205, v196
	v_mul_f32_e32 v205, v204, v196
	v_fma_f32 v206, -v195, v205, v204
	v_fmac_f32_e32 v205, v206, v196
	v_fma_f32 v195, -v195, v205, v204
	s_nop 0
	v_div_fmas_f32 v195, v195, v196, v205
	v_div_fixup_f32 v207, v195, v194, 1.0
	v_mul_f32_e32 v160, v207, v160
	v_mul_f32_e32 v161, v207, v161
	v_mul_f32_e32 v162, v207, v162
	v_mul_f32_e32 v163, v207, v163
	v_mul_f32_e32 v164, v207, v164
	v_mul_f32_e32 v165, v207, v165
	v_mul_f32_e32 v166, v207, v166
	v_mul_f32_e32 v167, v207, v167
	v_mul_f32_e32 v168, v207, v168
	v_mul_f32_e32 v169, v207, v169
	v_mul_f32_e32 v170, v207, v170
	v_mul_f32_e32 v171, v207, v171
	v_mul_f32_e32 v172, v207, v172
	v_mul_f32_e32 v173, v207, v173
	v_mul_f32_e32 v174, v207, v174
	v_mul_f32_e32 v175, v207, v175
	v_mov_b32_e32 v208, 0
	v_mov_b32_e32 v209, 0
	v_mov_b32_e32 v210, 0
	v_mov_b32_e32 v193, 0
	v_cvt_scalef32_pk_fp4_f32 v208, v160, v161, 1.0
	v_cvt_scalef32_pk_fp4_f32 v209, v164, v165, 1.0
	v_cvt_scalef32_pk_fp4_f32 v210, v168, v169, 1.0
	v_cvt_scalef32_pk_fp4_f32 v193, v172, v173, 1.0
	v_cvt_scalef32_pk_fp4_f32 v208, v162, v163, 1.0 op_sel:[0,0,1,0]
	v_cvt_scalef32_pk_fp4_f32 v209, v166, v167, 1.0 op_sel:[0,0,1,0]
	v_cvt_scalef32_pk_fp4_f32 v210, v170, v171, 1.0 op_sel:[0,0,1,0]
	v_cvt_scalef32_pk_fp4_f32 v193, v174, v175, 1.0 op_sel:[0,0,1,0]
	global_store_short v213, v208, s[10:11] nt
	s_add_u32 s14, s10, 0x200000
	s_addc_u32 s15, s11, 0
	global_store_short v213, v209, s[14:15] nt
	s_add_u32 s14, s10, 0x400000
	s_addc_u32 s15, s11, 0
	global_store_short v213, v210, s[14:15] nt
	s_add_u32 s14, s10, 0x600000
	s_addc_u32 s15, s11, 0
	global_store_short v213, v193, s[14:15] nt
	s_add_u32 s10, s10, 0x20000
	s_addc_u32 s11, s11, 0
	s_add_u32 s12, s12, 0x2000
	s_addc_u32 s13, s13, 0
	global_load_dwordx4 v[160:163], v212, s[8:9] offset:0 nt
	global_load_dwordx4 v[164:167], v212, s[8:9] offset:1024 nt
	global_load_dwordx4 v[168:171], v212, s[8:9] offset:2048 nt
	global_load_dwordx4 v[172:175], v212, s[8:9] offset:3072 nt
	s_add_u32 s8, s8, 0x800000
	s_addc_u32 s9, s9, 0
	v_max_f32_e32 v24, v32, v45
	v_min_f32_e32 v45, v32, v45
	v_max_f32_e32 v26, v33, v44
	v_min_f32_e32 v44, v33, v44
	v_max_f32_e32 v27, v34, v47
	v_min_f32_e32 v47, v34, v47
	v_max_f32_e32 v255, v35, v46
	v_min_f32_e32 v46, v35, v46
	v_max_f32_e32 v14, v36, v40
	v_min_f32_e32 v40, v36, v40
	v_max_f32_e32 v251, v37, v38
	v_min_f32_e32 v38, v37, v38
	v_max_f32_e32 v250, v39, v43
	v_min_f32_e32 v43, v39, v43
	v_max_f32_e32 v253, v41, v42
	v_min_f32_e32 v42, v41, v42
	v_max_f32_e32 v149, v24, v251
	v_min_f32_e32 v251, v24, v251
	v_max_f32_e32 v28, v26, v250
	v_min_f32_e32 v250, v26, v250
	v_max_f32_e32 v30, v27, v253
	v_min_f32_e32 v253, v27, v253
	v_max_f32_e32 v254, v255, v14
	v_min_f32_e32 v14, v255, v14
	v_max_f32_e32 v12, v38, v45
	v_min_f32_e32 v45, v38, v45
	v_max_f32_e32 v13, v40, v46
	v_min_f32_e32 v46, v40, v46
	v_max_f32_e32 v148, v42, v47
	v_min_f32_e32 v47, v42, v47
	v_max_f32_e32 v106, v43, v44
	v_min_f32_e32 v44, v43, v44
	v_max_f32_e32 v99, v149, v28
	v_min_f32_e32 v28, v149, v28
	v_max_f32_e32 v108, v30, v254
	v_min_f32_e32 v254, v30, v254
	v_max_f32_e32 v29, v14, v251
	v_min_f32_e32 v251, v14, v251
	v_max_f32_e32 v112, v12, v13
	v_min_f32_e32 v13, v12, v13
	v_max_f32_e32 v97, v250, v253
	v_min_f32_e32 v253, v250, v253
	v_max_f32_e32 v113, v148, v106
	v_min_f32_e32 v106, v148, v106
	v_max_f32_e32 v98, v44, v45
	v_min_f32_e32 v45, v44, v45
	v_max_f32_e32 v101, v46, v47
	v_min_f32_e32 v47, v46, v47
	v_max_f32_e32 v150, v99, v108
	v_min_f32_e32 v108, v99, v108
	v_max_f32_e32 v96, v28, v254
	v_min_f32_e32 v254, v28, v254
	v_max_f32_e32 v121, v29, v113
	v_min_f32_e32 v113, v29, v113
	v_max_f32_e32 v103, v251, v106
	v_min_f32_e32 v106, v251, v106
	v_max_f32_e32 v125, v112, v97
	v_min_f32_e32 v97, v112, v97
	v_max_f32_e32 v252, v13, v253
	v_min_f32_e32 v253, v13, v253
	v_max_f32_e32 v109, v98, v101
	v_min_f32_e32 v101, v98, v101
	v_max_f32_e32 v100, v45, v47
	v_min_f32_e32 v47, v45, v47
	v_max_f32_e32 v2, v96, v108
	v_min_f32_e32 v108, v96, v108
	v_max_f32_e32 v114, v254, v109
	v_min_f32_e32 v109, v254, v109
	v_max_f32_e32 v0, v121, v125
	v_min_f32_e32 v125, v121, v125
	v_max_f32_e32 v1, v103, v97
	v_min_f32_e32 v97, v103, v97
	v_max_f32_e32 v117, v252, v113
	v_min_f32_e32 v113, v252, v113
	v_max_f32_e32 v116, v253, v106
	v_min_f32_e32 v106, v253, v106
	v_max_f32_e32 v4, v100, v101
	v_min_f32_e32 v101, v100, v101
	v_max_f32_e32 v107, v2, v0
	v_min_f32_e32 v0, v2, v0
	v_max_f32_e32 v18, v108, v125
	v_min_f32_e32 v125, v108, v125
	v_max_f32_e32 v122, v1, v117
	v_min_f32_e32 v117, v1, v117
	v_max_f32_e32 v20, v97, v113
	v_min_f32_e32 v113, v97, v113
	v_max_f32_e32 v16, v116, v4
	v_min_f32_e32 v4, v116, v4
	v_max_f32_e32 v17, v106, v101
	v_min_f32_e32 v101, v106, v101
	v_max_f32_e32 v19, v18, v0
	v_min_f32_e32 v0, v18, v0
	v_max_f32_e32 v127, v114, v125
	v_min_f32_e32 v125, v114, v125
	v_max_f32_e32 v32, v16, v109
	v_min_f32_e32 v109, v16, v109
	v_max_f32_e32 v33, v17, v4
	v_min_f32_e32 v4, v17, v4
	v_max_f32_e32 v34, v127, v122
	v_min_f32_e32 v122, v127, v122
	v_max_f32_e32 v35, v125, v117
	v_min_f32_e32 v117, v125, v117
	v_max_f32_e32 v36, v20, v32
	v_min_f32_e32 v32, v20, v32
	v_max_f32_e32 v37, v113, v109
	v_min_f32_e32 v109, v113, v109
	v_max_f32_e32 v39, v34, v0
	v_min_f32_e32 v0, v34, v0
	v_max_f32_e32 v41, v122, v35
	v_min_f32_e32 v35, v122, v35
	v_max_f32_e32 v24, v36, v117
	v_min_f32_e32 v117, v36, v117
	v_max_f32_e32 v26, v32, v37
	v_min_f32_e32 v37, v32, v37
	v_max_f32_e32 v27, v33, v109
	v_min_f32_e32 v109, v33, v109
	v_max_f32_e32 v255, v35, v24
	v_min_f32_e32 v24, v35, v24
	v_max_f32_e32 v38, v117, v26
	v_min_f32_e32 v26, v117, v26
	v_max_f32_e32 v40, v48, v61
	v_min_f32_e32 v61, v48, v61
	v_max_f32_e32 v42, v49, v60
	v_min_f32_e32 v60, v49, v60
	v_max_f32_e32 v43, v50, v63
	v_min_f32_e32 v63, v50, v63
	v_max_f32_e32 v149, v51, v62
	v_min_f32_e32 v62, v51, v62
	v_max_f32_e32 v30, v52, v56
	v_min_f32_e32 v56, v52, v56
	v_max_f32_e32 v14, v53, v54
	v_min_f32_e32 v54, v53, v54
	v_max_f32_e32 v12, v55, v59
	v_min_f32_e32 v59, v55, v59
	v_max_f32_e32 v250, v57, v58
	v_min_f32_e32 v58, v57, v58
	v_max_f32_e32 v148, v40, v14
	v_min_f32_e32 v14, v40, v14
	v_max_f32_e32 v44, v42, v12
	v_min_f32_e32 v12, v42, v12
	v_max_f32_e32 v46, v43, v250
	v_min_f32_e32 v250, v43, v250
	v_max_f32_e32 v99, v149, v30
	v_min_f32_e32 v30, v149, v30
	v_max_f32_e32 v28, v54, v61
	v_min_f32_e32 v61, v54, v61
	v_max_f32_e32 v29, v56, v62
	v_min_f32_e32 v62, v56, v62
	v_max_f32_e32 v251, v58, v63
	v_min_f32_e32 v63, v58, v63
	v_max_f32_e32 v112, v59, v60
	v_min_f32_e32 v60, v59, v60
	v_max_f32_e32 v13, v148, v44
	v_min_f32_e32 v44, v148, v44
	v_max_f32_e32 v98, v46, v99
	v_min_f32_e32 v99, v46, v99
	v_max_f32_e32 v45, v30, v14
	v_min_f32_e32 v14, v30, v14
	v_max_f32_e32 v96, v28, v29
	v_min_f32_e32 v29, v28, v29
	v_max_f32_e32 v254, v12, v250
	v_min_f32_e32 v250, v12, v250
	v_max_f32_e32 v121, v251, v112
	v_min_f32_e32 v112, v251, v112
	v_max_f32_e32 v103, v60, v61
	v_min_f32_e32 v61, v60, v61
	v_max_f32_e32 v252, v62, v63
	v_min_f32_e32 v63, v62, v63
	v_max_f32_e32 v253, v13, v98
	v_min_f32_e32 v98, v13, v98
	v_max_f32_e32 v100, v44, v99
	v_min_f32_e32 v99, v44, v99
	v_max_f32_e32 v2, v45, v121
	v_min_f32_e32 v121, v45, v121
	v_max_f32_e32 v108, v14, v112
	v_min_f32_e32 v112, v14, v112
	v_max_f32_e32 v1, v96, v254
	v_min_f32_e32 v254, v96, v254
	v_max_f32_e32 v97, v29, v250
	v_min_f32_e32 v250, v29, v250
	v_max_f32_e32 v116, v103, v252
	v_min_f32_e32 v252, v103, v252
	v_max_f32_e32 v106, v61, v63
	v_min_f32_e32 v63, v61, v63
	v_max_f32_e32 v18, v100, v98
	v_min_f32_e32 v98, v100, v98
	v_max_f32_e32 v114, v99, v116
	v_min_f32_e32 v116, v99, v116
	v_max_f32_e32 v16, v2, v1
	v_min_f32_e32 v1, v2, v1
	v_max_f32_e32 v17, v108, v254
	v_min_f32_e32 v254, v108, v254
	v_max_f32_e32 v127, v97, v121
	v_min_f32_e32 v121, v97, v121
	v_max_f32_e32 v125, v250, v112
	v_min_f32_e32 v112, v250, v112
	v_max_f32_e32 v20, v106, v252
	v_min_f32_e32 v252, v106, v252
	v_max_f32_e32 v113, v18, v16
	v_min_f32_e32 v16, v18, v16
	v_max_f32_e32 v34, v98, v1
	v_min_f32_e32 v1, v98, v1
	v_max_f32_e32 v122, v17, v127
	v_min_f32_e32 v127, v17, v127
	v_max_f32_e32 v36, v254, v121
	v_min_f32_e32 v121, v254, v121
	v_max_f32_e32 v32, v125, v20
	v_min_f32_e32 v20, v125, v20
	v_max_f32_e32 v33, v112, v252
	v_min_f32_e32 v252, v112, v252
	v_max_f32_e32 v35, v34, v16
	v_min_f32_e32 v16, v34, v16
	v_max_f32_e32 v117, v114, v1
	v_min_f32_e32 v1, v114, v1
	v_max_f32_e32 v48, v32, v116
	v_min_f32_e32 v116, v32, v116
	v_max_f32_e32 v49, v33, v20
	v_min_f32_e32 v20, v33, v20
	v_max_f32_e32 v50, v117, v122
	v_min_f32_e32 v122, v117, v122
	v_max_f32_e32 v51, v1, v127
	v_min_f32_e32 v127, v1, v127
	v_max_f32_e32 v52, v36, v48
	v_min_f32_e32 v48, v36, v48
	v_max_f32_e32 v53, v121, v116
	v_min_f32_e32 v116, v121, v116
	v_max_f32_e32 v55, v50, v16
	v_min_f32_e32 v16, v50, v16
	v_max_f32_e32 v57, v122, v51
	v_min_f32_e32 v51, v122, v51
	v_max_f32_e32 v40, v52, v127
	v_min_f32_e32 v127, v52, v127
	v_max_f32_e32 v42, v48, v53
	v_min_f32_e32 v53, v48, v53
	v_max_f32_e32 v43, v49, v116
	v_min_f32_e32 v116, v49, v116
	v_max_f32_e32 v149, v51, v40
	v_min_f32_e32 v40, v51, v40
	v_max_f32_e32 v54, v127, v42
	v_min_f32_e32 v42, v127, v42
	s_waitcnt vmcnt(0)
	v_pk_mul_f32 v[160:161], v[160:161], v[176:177]
	v_pk_mul_f32 v[162:163], v[162:163], v[178:179]
	v_pk_mul_f32 v[164:165], v[164:165], v[180:181]
	v_pk_mul_f32 v[166:167], v[166:167], v[182:183]
	v_pk_mul_f32 v[168:169], v[168:169], v[184:185]
	v_pk_mul_f32 v[170:171], v[170:171], v[186:187]
	v_pk_mul_f32 v[172:173], v[172:173], v[188:189]
	v_pk_mul_f32 v[174:175], v[174:175], v[190:191]
	v_max3_f32 v192, |v160|, |v161|, |v162|
	v_max3_f32 v192, |v163|, |v164|, v192
	v_max3_f32 v192, |v165|, |v166|, v192
	v_max3_f32 v192, |v167|, |v168|, v192
	v_max3_f32 v192, |v169|, |v170|, v192
	v_max3_f32 v192, |v171|, |v172|, v192
	v_max3_f32 v192, |v173|, |v174|, v192
	v_max_f32_e64 v192, |v175|, v192
	s_nop 1
	v_mov_b32_dpp v193, v192 quad_perm:[1,0,3,2] row_mask:0xf bank_mask:0xf bound_ctrl:1
	v_max_f32_e32 v192, v192, v193
	s_nop 1
	v_mov_b32_dpp v193, v192 quad_perm:[2,3,0,1] row_mask:0xf bank_mask:0xf bound_ctrl:1
	v_max_f32_e32 v192, v192, v193
	s_nop 1
	v_mov_b32_dpp v193, v192 row_half_mirror row_mask:0xf bank_mask:0xf bound_ctrl:1
	v_max_f32_e32 v192, v192, v193
	s_nop 1
	v_mov_b32_dpp v193, v192 row_mirror row_mask:0xf bank_mask:0xf bound_ctrl:1
	v_max_f32_e32 v192, v192, v193
	v_mov_b32_e32 v193, v192
	s_nop 1
	v_permlane16_swap_b32_e32 v192, v193
	s_nop 1
	v_max_f32_e32 v192, v192, v193
	v_mov_b32_e32 v193, v192
	s_nop 1
	v_permlane32_swap_b32_e32 v192, v193
	s_nop 1
	v_max_f32_e32 v192, v192, v193
	v_max_f32_e32 v192, 0xda24260, v192
	v_mul_f32_e32 v194, 0x3e2aaaab, v192
	global_store_dword v214, v194, s[12:13]
	v_div_scale_f32 v195, s[26:27], v194, v194, 1.0
	v_rcp_f32_e32 v196, v195
	v_div_scale_f32 v204, vcc, 1.0, v194, 1.0
	v_fma_f32 v205, -v195, v196, 1.0
	v_fmac_f32_e32 v196, v205, v196
	v_mul_f32_e32 v205, v204, v196
	v_fma_f32 v206, -v195, v205, v204
	v_fmac_f32_e32 v205, v206, v196
	v_fma_f32 v195, -v195, v205, v204
	s_nop 0
	v_div_fmas_f32 v195, v195, v196, v205
	v_div_fixup_f32 v207, v195, v194, 1.0
	v_mul_f32_e32 v160, v207, v160
	v_mul_f32_e32 v161, v207, v161
	v_mul_f32_e32 v162, v207, v162
	v_mul_f32_e32 v163, v207, v163
	v_mul_f32_e32 v164, v207, v164
	v_mul_f32_e32 v165, v207, v165
	v_mul_f32_e32 v166, v207, v166
	v_mul_f32_e32 v167, v207, v167
	v_mul_f32_e32 v168, v207, v168
	v_mul_f32_e32 v169, v207, v169
	v_mul_f32_e32 v170, v207, v170
	v_mul_f32_e32 v171, v207, v171
	v_mul_f32_e32 v172, v207, v172
	v_mul_f32_e32 v173, v207, v173
	v_mul_f32_e32 v174, v207, v174
	v_mul_f32_e32 v175, v207, v175
	v_mov_b32_e32 v208, 0
	v_mov_b32_e32 v209, 0
	v_mov_b32_e32 v210, 0
	v_mov_b32_e32 v193, 0
	v_cvt_scalef32_pk_fp4_f32 v208, v160, v161, 1.0
	v_cvt_scalef32_pk_fp4_f32 v209, v164, v165, 1.0
	v_cvt_scalef32_pk_fp4_f32 v210, v168, v169, 1.0
	v_cvt_scalef32_pk_fp4_f32 v193, v172, v173, 1.0
	v_cvt_scalef32_pk_fp4_f32 v208, v162, v163, 1.0 op_sel:[0,0,1,0]
	v_cvt_scalef32_pk_fp4_f32 v209, v166, v167, 1.0 op_sel:[0,0,1,0]
	v_cvt_scalef32_pk_fp4_f32 v210, v170, v171, 1.0 op_sel:[0,0,1,0]
	v_cvt_scalef32_pk_fp4_f32 v193, v174, v175, 1.0 op_sel:[0,0,1,0]
	global_store_short v213, v208, s[10:11] nt
	s_add_u32 s14, s10, 0x200000
	s_addc_u32 s15, s11, 0
	global_store_short v213, v209, s[14:15] nt
	s_add_u32 s14, s10, 0x400000
	s_addc_u32 s15, s11, 0
	global_store_short v213, v210, s[14:15] nt
	s_add_u32 s14, s10, 0x600000
	s_addc_u32 s15, s11, 0
	global_store_short v213, v193, s[14:15] nt
	s_add_u32 s10, s10, 0x20000
	s_addc_u32 s11, s11, 0
	s_add_u32 s12, s12, 0x2000
	s_addc_u32 s13, s13, 0
	global_load_dwordx4 v[160:163], v212, s[8:9] offset:0 nt
	global_load_dwordx4 v[164:167], v212, s[8:9] offset:1024 nt
	global_load_dwordx4 v[168:171], v212, s[8:9] offset:2048 nt
	global_load_dwordx4 v[172:175], v212, s[8:9] offset:3072 nt
	s_add_u32 s8, s8, 0x800000
	s_addc_u32 s9, s9, 0
	v_max_f32_e32 v105, v105, v31
	v_max_f32_e32 v120, v120, v110
	v_max_f32_e32 v126, v126, v123
	v_max_f32_e32 v7, v7, v118
	v_max_f32_e32 v115, v115, v11
	v_max_f32_e32 v9, v9, v21
	v_max_f32_e32 v147, v147, v10
	v_max_f32_e32 v144, v144, v22
	v_max_f32_e32 v6, v6, v8
	v_max_f32_e32 v145, v145, v249
	v_max_f32_e32 v5, v5, v25
	v_max_f32_e32 v146, v146, v124
	v_max_f32_e32 v111, v111, v23
	v_max_f32_e32 v119, v119, v3
	v_max_f32_e32 v104, v104, v102
	v_max_f32_e32 v15, v15, v151
	v_max_f32_e32 v56, v105, v6
	v_min_f32_e32 v6, v105, v6
	v_max_f32_e32 v58, v120, v145
	v_min_f32_e32 v145, v120, v145
	v_max_f32_e32 v59, v126, v5
	v_min_f32_e32 v5, v126, v5
	v_max_f32_e32 v148, v7, v146
	v_min_f32_e32 v146, v7, v146
	v_max_f32_e32 v46, v115, v111
	v_min_f32_e32 v111, v115, v111
	v_max_f32_e32 v30, v9, v119
	v_min_f32_e32 v119, v9, v119
	v_max_f32_e32 v28, v147, v104
	v_min_f32_e32 v104, v147, v104
	v_max_f32_e32 v12, v144, v15
	v_min_f32_e32 v15, v144, v15
	v_max_f32_e32 v251, v56, v46
	v_min_f32_e32 v46, v56, v46
	v_max_f32_e32 v60, v58, v30
	v_min_f32_e32 v30, v58, v30
	v_max_f32_e32 v62, v59, v28
	v_min_f32_e32 v28, v59, v28
	v_max_f32_e32 v13, v148, v12
	v_min_f32_e32 v12, v148, v12
	v_max_f32_e32 v44, v6, v111
	v_min_f32_e32 v111, v6, v111
	v_max_f32_e32 v45, v145, v119
	v_min_f32_e32 v119, v145, v119
	v_max_f32_e32 v14, v5, v104
	v_min_f32_e32 v104, v5, v104
	v_max_f32_e32 v96, v146, v15
	v_min_f32_e32 v15, v146, v15
	v_max_f32_e32 v29, v251, v62
	v_min_f32_e32 v62, v251, v62
	v_max_f32_e32 v103, v60, v13
	v_min_f32_e32 v13, v60, v13
	v_max_f32_e32 v61, v46, v28
	v_min_f32_e32 v28, v46, v28
	v_max_f32_e32 v100, v30, v12
	v_min_f32_e32 v12, v30, v12
	v_max_f32_e32 v99, v44, v14
	v_min_f32_e32 v14, v44, v14
	v_max_f32_e32 v2, v45, v96
	v_min_f32_e32 v96, v45, v96
	v_max_f32_e32 v108, v111, v104
	v_min_f32_e32 v104, v111, v104
	v_max_f32_e32 v97, v119, v15
	v_min_f32_e32 v15, v119, v15
	v_max_f32_e32 v250, v29, v103
	v_min_f32_e32 v103, v29, v103
	v_max_f32_e32 v106, v62, v13
	v_min_f32_e32 v13, v62, v13
	v_max_f32_e32 v18, v61, v100
	v_min_f32_e32 v100, v61, v100
	v_max_f32_e32 v98, v28, v12
	v_min_f32_e32 v12, v28, v12
	v_max_f32_e32 v17, v99, v2
	v_min_f32_e32 v2, v99, v2
	v_max_f32_e32 v254, v14, v96
	v_min_f32_e32 v96, v14, v96
	v_max_f32_e32 v125, v108, v97
	v_min_f32_e32 v97, v108, v97
	v_max_f32_e32 v112, v104, v15
	v_min_f32_e32 v15, v104, v15
	v_max_f32_e32 v150, v150, v63
	v_max_f32_e32 v107, v107, v252
	v_max_f32_e32 v19, v19, v20
	v_max_f32_e32 v39, v39, v116
	v_max_f32_e32 v0, v0, v43
	v_max_f32_e32 v41, v41, v53
	v_max_f32_e32 v255, v255, v42
	v_max_f32_e32 v24, v24, v54
	v_max_f32_e32 v38, v38, v40
	v_max_f32_e32 v26, v26, v149
	v_max_f32_e32 v37, v37, v57
	v_max_f32_e32 v27, v27, v16
	v_max_f32_e32 v109, v109, v55
	v_max_f32_e32 v4, v4, v35
	v_max_f32_e32 v101, v101, v113
	v_max_f32_e32 v47, v47, v253
	v_max_f32_e32 v34, v150, v38
	v_min_f32_e32 v38, v150, v38
	v_max_f32_e32 v114, v107, v26
	v_min_f32_e32 v26, v107, v26
	v_max_f32_e32 v32, v19, v37
	v_min_f32_e32 v37, v19, v37
	v_max_f32_e32 v33, v39, v27
	v_min_f32_e32 v27, v39, v27
	v_max_f32_e32 v117, v0, v109
	v_min_f32_e32 v109, v0, v109
	v_max_f32_e32 v1, v41, v4
	v_min_f32_e32 v4, v41, v4
	v_max_f32_e32 v36, v255, v101
	v_min_f32_e32 v101, v255, v101
	v_max_f32_e32 v121, v24, v47
	v_min_f32_e32 v47, v24, v47
	v_max_f32_e32 v50, v34, v117
	v_min_f32_e32 v117, v34, v117
	v_max_f32_e32 v122, v114, v1
	v_min_f32_e32 v1, v114, v1
	v_max_f32_e32 v52, v32, v36
	v_min_f32_e32 v36, v32, v36
	v_max_f32_e32 v48, v33, v121
	v_min_f32_e32 v121, v33, v121
	v_max_f32_e32 v49, v38, v109
	v_min_f32_e32 v109, v38, v109
	v_max_f32_e32 v51, v26, v4
	v_min_f32_e32 v4, v26, v4
	v_max_f32_e32 v127, v37, v101
	v_min_f32_e32 v101, v37, v101
	v_max_f32_e32 v151, v27, v47
	v_min_f32_e32 v47, v27, v47
	v_max_f32_e32 v102, v50, v52
	v_min_f32_e32 v52, v50, v52
	v_max_f32_e32 v3, v122, v48
	v_min_f32_e32 v48, v122, v48
	v_max_f32_e32 v23, v117, v36
	v_min_f32_e32 v36, v117, v36
	v_max_f32_e32 v124, v1, v121
	v_min_f32_e32 v121, v1, v121
	v_max_f32_e32 v25, v49, v127
	v_min_f32_e32 v127, v49, v127
	v_max_f32_e32 v249, v51, v151
	v_min_f32_e32 v151, v51, v151
	v_max_f32_e32 v8, v109, v101
	v_min_f32_e32 v101, v109, v101
	v_max_f32_e32 v22, v4, v47
	v_min_f32_e32 v47, v4, v47
	v_max_f32_e32 v10, v102, v3
	v_min_f32_e32 v3, v102, v3
	v_max_f32_e32 v21, v52, v48
	v_min_f32_e32 v48, v52, v48
	v_max_f32_e32 v11, v23, v124
	v_min_f32_e32 v124, v23, v124
	v_max_f32_e32 v118, v36, v121
	v_min_f32_e32 v121, v36, v121
	v_max_f32_e32 v123, v25, v249
	v_min_f32_e32 v249, v25, v249
	v_max_f32_e32 v110, v127, v151
	v_min_f32_e32 v151, v127, v151
	v_max_f32_e32 v31, v8, v22
	v_min_f32_e32 v22, v8, v22
	v_max_f32_e32 v105, v101, v47
	v_min_f32_e32 v47, v101, v47
	v_max_f32_e32 v250, v250, v47
	v_max_f32_e32 v103, v103, v105
	v_max_f32_e32 v106, v106, v22
	v_max_f32_e32 v13, v13, v31
	v_max_f32_e32 v18, v18, v151
	v_max_f32_e32 v100, v100, v110
	v_max_f32_e32 v98, v98, v249
	v_max_f32_e32 v12, v12, v123
	v_max_f32_e32 v17, v17, v121
	v_max_f32_e32 v2, v2, v118
	v_max_f32_e32 v254, v254, v124
	v_max_f32_e32 v96, v96, v11
	v_max_f32_e32 v125, v125, v48
	v_max_f32_e32 v97, v97, v21
	v_max_f32_e32 v112, v112, v3
	v_max_f32_e32 v15, v15, v10
	v_max_f32_e32 v120, v250, v17
	v_min_f32_e32 v17, v250, v17
	v_max_f32_e32 v126, v103, v2
	v_min_f32_e32 v2, v103, v2
	v_max_f32_e32 v7, v106, v254
	v_min_f32_e32 v254, v106, v254
	v_max_f32_e32 v115, v13, v96
	v_min_f32_e32 v96, v13, v96
	v_max_f32_e32 v9, v18, v125
	v_min_f32_e32 v125, v18, v125
	v_max_f32_e32 v147, v100, v97
	v_min_f32_e32 v97, v100, v97
	v_max_f32_e32 v144, v98, v112
	v_min_f32_e32 v112, v98, v112
	v_max_f32_e32 v56, v12, v15
	v_min_f32_e32 v15, v12, v15
	v_max_f32_e32 v58, v120, v9
	v_min_f32_e32 v9, v120, v9
	v_max_f32_e32 v59, v126, v147
	v_min_f32_e32 v147, v126, v147
	v_max_f32_e32 v148, v7, v144
	v_min_f32_e32 v144, v7, v144
	v_max_f32_e32 v6, v115, v56
	v_min_f32_e32 v56, v115, v56
	v_max_f32_e32 v145, v17, v125
	v_min_f32_e32 v125, v17, v125
	v_max_f32_e32 v5, v2, v97
	v_min_f32_e32 v97, v2, v97
	v_max_f32_e32 v146, v254, v112
	v_min_f32_e32 v112, v254, v112
	v_max_f32_e32 v251, v96, v15
	v_min_f32_e32 v15, v96, v15
	v_max_f32_e32 v60, v58, v148
	v_min_f32_e32 v148, v58, v148
	v_max_f32_e32 v46, v59, v6
	v_min_f32_e32 v6, v59, v6
	v_max_f32_e32 v30, v9, v144
	v_min_f32_e32 v144, v9, v144
	v_max_f32_e32 v44, v147, v56
	v_min_f32_e32 v56, v147, v56
	v_max_f32_e32 v45, v145, v146
	v_min_f32_e32 v146, v145, v146
	v_max_f32_e32 v111, v5, v251
	v_min_f32_e32 v251, v5, v251
	v_max_f32_e32 v119, v125, v112
	v_min_f32_e32 v112, v125, v112
	v_max_f32_e32 v29, v97, v15
	v_min_f32_e32 v15, v97, v15
	v_max_f32_e32 v62, v60, v46
	v_min_f32_e32 v46, v60, v46
	v_max_f32_e32 v61, v148, v6
	v_min_f32_e32 v6, v148, v6
	v_max_f32_e32 v28, v30, v44
	v_min_f32_e32 v44, v30, v44
	v_max_f32_e32 v99, v144, v56
	v_min_f32_e32 v56, v144, v56
	v_max_f32_e32 v14, v45, v111
	v_min_f32_e32 v111, v45, v111
	v_max_f32_e32 v108, v146, v251
	v_min_f32_e32 v251, v146, v251
	v_max_f32_e32 v104, v119, v29
	v_min_f32_e32 v29, v119, v29
	v_max_f32_e32 v253, v112, v15
	v_min_f32_e32 v15, v112, v15
	v_mov_b32_e32 v113, v62
	v_mov_b32_e32 v35, v46
	v_mov_b32_e32 v55, v61
	v_mov_b32_e32 v16, v6
	v_mov_b32_e32 v57, v28
	v_mov_b32_e32 v149, v44
	v_mov_b32_e32 v40, v99
	v_mov_b32_e32 v54, v56
	v_mov_b32_e32 v42, v14
	v_mov_b32_e32 v53, v111
	v_mov_b32_e32 v43, v108
	v_mov_b32_e32 v116, v251
	v_mov_b32_e32 v20, v104
	v_mov_b32_e32 v252, v29
	v_mov_b32_e32 v63, v253
	v_mov_b32_e32 v150, v15
	s_nop 1
	v_permlane32_swap_b32_e32 v62, v113
	v_permlane32_swap_b32_e32 v46, v35
	v_permlane32_swap_b32_e32 v61, v55
	v_permlane32_swap_b32_e32 v6, v16
	v_permlane32_swap_b32_e32 v28, v57
	v_permlane32_swap_b32_e32 v44, v149
	v_permlane32_swap_b32_e32 v99, v40
	v_permlane32_swap_b32_e32 v56, v54
	v_permlane32_swap_b32_e32 v14, v42
	v_permlane32_swap_b32_e32 v111, v53
	v_permlane32_swap_b32_e32 v108, v43
	v_permlane32_swap_b32_e32 v251, v116
	v_permlane32_swap_b32_e32 v104, v20
	v_permlane32_swap_b32_e32 v29, v252
	v_permlane32_swap_b32_e32 v253, v63
	v_permlane32_swap_b32_e32 v15, v150
	s_nop 1
	v_max_f32_e32 v62, v62, v150
	v_max_f32_e32 v46, v46, v63
	v_max_f32_e32 v61, v61, v252
	v_max_f32_e32 v6, v6, v20
	v_max_f32_e32 v28, v28, v116
	v_max_f32_e32 v44, v44, v43
	v_max_f32_e32 v99, v99, v53
	v_max_f32_e32 v56, v56, v42
	v_max_f32_e32 v14, v14, v54
	v_max_f32_e32 v111, v111, v40
	v_max_f32_e32 v108, v108, v149
	v_max_f32_e32 v251, v251, v57
	v_max_f32_e32 v104, v104, v16
	v_max_f32_e32 v29, v29, v55
	v_max_f32_e32 v253, v253, v35
	v_max_f32_e32 v15, v15, v113
	v_max_f32_e32 v107, v62, v14
	v_min_f32_e32 v14, v62, v14
	v_max_f32_e32 v19, v46, v111
	v_min_f32_e32 v111, v46, v111
	v_max_f32_e32 v39, v61, v108
	v_min_f32_e32 v108, v61, v108
	v_max_f32_e32 v0, v6, v251
	v_min_f32_e32 v251, v6, v251
	v_max_f32_e32 v41, v28, v104
	v_min_f32_e32 v104, v28, v104
	v_max_f32_e32 v255, v44, v29
	v_min_f32_e32 v29, v44, v29
	v_max_f32_e32 v24, v99, v253
	v_min_f32_e32 v253, v99, v253
	v_max_f32_e32 v34, v56, v15
	v_min_f32_e32 v15, v56, v15
	v_max_f32_e32 v114, v107, v41
	v_min_f32_e32 v41, v107, v41
	v_max_f32_e32 v32, v19, v255
	v_min_f32_e32 v255, v19, v255
	v_max_f32_e32 v33, v39, v24
	v_min_f32_e32 v24, v39, v24
	v_max_f32_e32 v38, v0, v34
	v_min_f32_e32 v34, v0, v34
	v_max_f32_e32 v26, v14, v104
	v_min_f32_e32 v104, v14, v104
	v_max_f32_e32 v37, v111, v29
	v_min_f32_e32 v29, v111, v29
	v_max_f32_e32 v27, v108, v253
	v_min_f32_e32 v253, v108, v253
	v_max_f32_e32 v50, v251, v15
	v_min_f32_e32 v15, v251, v15
	v_max_f32_e32 v122, v114, v33
	v_min_f32_e32 v33, v114, v33
	v_max_f32_e32 v117, v32, v38
	v_min_f32_e32 v38, v32, v38
	v_max_f32_e32 v1, v41, v24
	v_min_f32_e32 v24, v41, v24
	v_max_f32_e32 v49, v255, v34
	v_min_f32_e32 v34, v255, v34
	v_max_f32_e32 v51, v26, v27
	v_min_f32_e32 v27, v26, v27
	v_max_f32_e32 v109, v37, v50
	v_min_f32_e32 v50, v37, v50
	v_max_f32_e32 v4, v104, v253
	v_min_f32_e32 v253, v104, v253
	v_max_f32_e32 v102, v29, v15
	v_min_f32_e32 v15, v29, v15
	v_max_f32_e32 v128, v122, v117
	v_min_f32_e32 v129, v122, v117
	v_max_f32_e32 v130, v33, v38
	v_min_f32_e32 v131, v33, v38
	v_max_f32_e32 v132, v1, v49
	v_min_f32_e32 v133, v1, v49
	v_max_f32_e32 v134, v24, v34
	v_min_f32_e32 v135, v24, v34
	v_max_f32_e32 v136, v51, v109
	v_min_f32_e32 v137, v51, v109
	v_max_f32_e32 v138, v27, v50
	v_min_f32_e32 v139, v27, v50
	v_max_f32_e32 v140, v4, v102
	v_min_f32_e32 v141, v4, v102
	v_max_f32_e32 v142, v253, v15
	v_min_f32_e32 v143, v253, v15
	s_waitcnt vmcnt(0)
	v_pk_mul_f32 v[160:161], v[160:161], v[176:177]
	v_pk_mul_f32 v[162:163], v[162:163], v[178:179]
	v_pk_mul_f32 v[164:165], v[164:165], v[180:181]
	v_pk_mul_f32 v[166:167], v[166:167], v[182:183]
	v_pk_mul_f32 v[168:169], v[168:169], v[184:185]
	v_pk_mul_f32 v[170:171], v[170:171], v[186:187]
	v_pk_mul_f32 v[172:173], v[172:173], v[188:189]
	v_pk_mul_f32 v[174:175], v[174:175], v[190:191]
	v_max3_f32 v192, |v160|, |v161|, |v162|
	v_max3_f32 v192, |v163|, |v164|, v192
	v_max3_f32 v192, |v165|, |v166|, v192
	v_max3_f32 v192, |v167|, |v168|, v192
	v_max3_f32 v192, |v169|, |v170|, v192
	v_max3_f32 v192, |v171|, |v172|, v192
	v_max3_f32 v192, |v173|, |v174|, v192
	v_max_f32_e64 v192, |v175|, v192
	s_nop 1
	v_mov_b32_dpp v193, v192 quad_perm:[1,0,3,2] row_mask:0xf bank_mask:0xf bound_ctrl:1
	v_max_f32_e32 v192, v192, v193
	s_nop 1
	v_mov_b32_dpp v193, v192 quad_perm:[2,3,0,1] row_mask:0xf bank_mask:0xf bound_ctrl:1
	v_max_f32_e32 v192, v192, v193
	s_nop 1
	v_mov_b32_dpp v193, v192 row_half_mirror row_mask:0xf bank_mask:0xf bound_ctrl:1
	v_max_f32_e32 v192, v192, v193
	s_nop 1
	v_mov_b32_dpp v193, v192 row_mirror row_mask:0xf bank_mask:0xf bound_ctrl:1
	v_max_f32_e32 v192, v192, v193
	v_mov_b32_e32 v193, v192
	s_nop 1
	v_permlane16_swap_b32_e32 v192, v193
	s_nop 1
	v_max_f32_e32 v192, v192, v193
	v_mov_b32_e32 v193, v192
	s_nop 1
	v_permlane32_swap_b32_e32 v192, v193
	s_nop 1
	v_max_f32_e32 v192, v192, v193
	v_max_f32_e32 v192, 0xda24260, v192
	v_mul_f32_e32 v194, 0x3e2aaaab, v192
	global_store_dword v214, v194, s[12:13]
	v_div_scale_f32 v195, s[26:27], v194, v194, 1.0
	v_rcp_f32_e32 v196, v195
	v_div_scale_f32 v204, vcc, 1.0, v194, 1.0
	v_fma_f32 v205, -v195, v196, 1.0
	v_fmac_f32_e32 v196, v205, v196
	v_mul_f32_e32 v205, v204, v196
	v_fma_f32 v206, -v195, v205, v204
	v_fmac_f32_e32 v205, v206, v196
	v_fma_f32 v195, -v195, v205, v204
	s_nop 0
	v_div_fmas_f32 v195, v195, v196, v205
	v_div_fixup_f32 v207, v195, v194, 1.0
	v_mul_f32_e32 v160, v207, v160
	v_mul_f32_e32 v161, v207, v161
	v_mul_f32_e32 v162, v207, v162
	v_mul_f32_e32 v163, v207, v163
	v_mul_f32_e32 v164, v207, v164
	v_mul_f32_e32 v165, v207, v165
	v_mul_f32_e32 v166, v207, v166
	v_mul_f32_e32 v167, v207, v167
	v_mul_f32_e32 v168, v207, v168
	v_mul_f32_e32 v169, v207, v169
	v_mul_f32_e32 v170, v207, v170
	v_mul_f32_e32 v171, v207, v171
	v_mul_f32_e32 v172, v207, v172
	v_mul_f32_e32 v173, v207, v173
	v_mul_f32_e32 v174, v207, v174
	v_mul_f32_e32 v175, v207, v175
	v_mov_b32_e32 v208, 0
	v_mov_b32_e32 v209, 0
	v_mov_b32_e32 v210, 0
	v_mov_b32_e32 v193, 0
	v_cvt_scalef32_pk_fp4_f32 v208, v160, v161, 1.0
	v_cvt_scalef32_pk_fp4_f32 v209, v164, v165, 1.0
	v_cvt_scalef32_pk_fp4_f32 v210, v168, v169, 1.0
	v_cvt_scalef32_pk_fp4_f32 v193, v172, v173, 1.0
	v_cvt_scalef32_pk_fp4_f32 v208, v162, v163, 1.0 op_sel:[0,0,1,0]
	v_cvt_scalef32_pk_fp4_f32 v209, v166, v167, 1.0 op_sel:[0,0,1,0]
	v_cvt_scalef32_pk_fp4_f32 v210, v170, v171, 1.0 op_sel:[0,0,1,0]
	v_cvt_scalef32_pk_fp4_f32 v193, v174, v175, 1.0 op_sel:[0,0,1,0]
	global_store_short v213, v208, s[10:11] nt
	s_add_u32 s14, s10, 0x200000
	s_addc_u32 s15, s11, 0
	global_store_short v213, v209, s[14:15] nt
	s_add_u32 s14, s10, 0x400000
	s_addc_u32 s15, s11, 0
	global_store_short v213, v210, s[14:15] nt
	s_add_u32 s14, s10, 0x600000
	s_addc_u32 s15, s11, 0
	global_store_short v213, v193, s[14:15] nt
	s_add_u32 s10, s10, 0x20000
	s_addc_u32 s11, s11, 0
	s_add_u32 s12, s12, 0x2000
	s_addc_u32 s13, s13, 0
	global_load_dwordx4 v[160:163], v212, s[8:9] offset:0 nt
	global_load_dwordx4 v[164:167], v212, s[8:9] offset:1024 nt
	global_load_dwordx4 v[168:171], v212, s[8:9] offset:2048 nt
	global_load_dwordx4 v[172:175], v212, s[8:9] offset:3072 nt
	s_add_u32 s8, s8, 0x800000
	s_addc_u32 s9, s9, 0
	ds_write_b8 v240, v128 offset:0
	ds_write_b8 v240, v129 offset:1
	ds_write_b8 v240, v130 offset:2
	ds_write_b8 v240, v131 offset:3
	ds_write_b8 v240, v132 offset:4
	ds_write_b8 v240, v133 offset:5
	ds_write_b8 v240, v134 offset:6
	ds_write_b8 v240, v135 offset:7
	ds_write_b8 v240, v136 offset:8
	ds_write_b8 v240, v137 offset:9
	ds_write_b8 v240, v138 offset:10
	ds_write_b8 v240, v139 offset:11
	ds_write_b8 v240, v140 offset:12
	ds_write_b8 v240, v141 offset:13
	ds_write_b8 v240, v142 offset:14
	ds_write_b8 v240, v143 offset:15
	ds_read_b128 v[96:99], v215 offset:32768
	ds_read_b128 v[100:103], v232 offset:32768
	ds_read_b128 v[104:107], v233 offset:32768
	ds_read_b128 v[108:111], v234 offset:32768
	ds_read_b128 v[112:115], v235 offset:32768
	ds_read_b128 v[116:119], v236 offset:32768
	ds_read_b128 v[120:123], v237 offset:32768
	ds_read_b128 v[124:127], v238 offset:32768
	s_waitcnt vmcnt(27)
	s_waitcnt lgkmcnt(4)
	v_mfma_f32_32x32x16_bf16 v[0:15], v[96:99], v[64:67], 0
	v_mfma_f32_32x32x16_bf16 v[0:15], v[100:103], v[68:71], v[0:15]
	v_mfma_f32_32x32x16_bf16 v[0:15], v[104:107], v[72:75], v[0:15]
	v_mfma_f32_32x32x16_bf16 v[0:15], v[108:111], v[76:79], v[0:15]
	ds_read_b128 v[96:99], v215 offset:40960
	ds_read_b128 v[100:103], v232 offset:40960
	ds_read_b128 v[104:107], v233 offset:40960
	ds_read_b128 v[108:111], v234 offset:40960
	s_waitcnt lgkmcnt(4)
	v_mfma_f32_32x32x16_bf16 v[0:15], v[112:115], v[80:83], v[0:15]
	v_mfma_f32_32x32x16_bf16 v[0:15], v[116:119], v[84:87], v[0:15]
	v_mfma_f32_32x32x16_bf16 v[0:15], v[120:123], v[88:91], v[0:15]
	v_mfma_f32_32x32x16_bf16 v[0:15], v[124:127], v[92:95], v[0:15]
	ds_read_b128 v[112:115], v235 offset:40960
	ds_read_b128 v[116:119], v236 offset:40960
	ds_read_b128 v[120:123], v237 offset:40960
	ds_read_b128 v[124:127], v238 offset:40960
	s_waitcnt lgkmcnt(4)
	v_mfma_f32_32x32x16_bf16 v[16:31], v[96:99], v[64:67], 0
	v_mfma_f32_32x32x16_bf16 v[16:31], v[100:103], v[68:71], v[16:31]
	v_mfma_f32_32x32x16_bf16 v[16:31], v[104:107], v[72:75], v[16:31]
	v_mfma_f32_32x32x16_bf16 v[16:31], v[108:111], v[76:79], v[16:31]
	ds_read_b128 v[96:99], v215 offset:49152
	ds_read_b128 v[100:103], v232 offset:49152
	ds_read_b128 v[104:107], v233 offset:49152
	ds_read_b128 v[108:111], v234 offset:49152
	s_waitcnt lgkmcnt(4)
	v_mfma_f32_32x32x16_bf16 v[16:31], v[112:115], v[80:83], v[16:31]
	v_mfma_f32_32x32x16_bf16 v[16:31], v[116:119], v[84:87], v[16:31]
	v_mfma_f32_32x32x16_bf16 v[16:31], v[120:123], v[88:91], v[16:31]
	v_mfma_f32_32x32x16_bf16 v[16:31], v[124:127], v[92:95], v[16:31]
	ds_read_b128 v[112:115], v235 offset:49152
	ds_read_b128 v[116:119], v236 offset:49152
	ds_read_b128 v[120:123], v237 offset:49152
	ds_read_b128 v[124:127], v238 offset:49152
	s_waitcnt lgkmcnt(4)
	v_mfma_f32_32x32x16_bf16 v[32:47], v[96:99], v[64:67], 0
	v_mfma_f32_32x32x16_bf16 v[32:47], v[100:103], v[68:71], v[32:47]
	v_mfma_f32_32x32x16_bf16 v[32:47], v[104:107], v[72:75], v[32:47]
	v_mfma_f32_32x32x16_bf16 v[32:47], v[108:111], v[76:79], v[32:47]
	ds_read_b128 v[96:99], v215 offset:57344
	ds_read_b128 v[100:103], v232 offset:57344
	ds_read_b128 v[104:107], v233 offset:57344
	ds_read_b128 v[108:111], v234 offset:57344
	s_waitcnt lgkmcnt(4)
	v_mfma_f32_32x32x16_bf16 v[32:47], v[112:115], v[80:83], v[32:47]
	v_mfma_f32_32x32x16_bf16 v[32:47], v[116:119], v[84:87], v[32:47]
	v_mfma_f32_32x32x16_bf16 v[32:47], v[120:123], v[88:91], v[32:47]
	v_mfma_f32_32x32x16_bf16 v[32:47], v[124:127], v[92:95], v[32:47]
	ds_read_b128 v[112:115], v235 offset:57344
	ds_read_b128 v[116:119], v236 offset:57344
	ds_read_b128 v[120:123], v237 offset:57344
	ds_read_b128 v[124:127], v238 offset:57344
	s_waitcnt lgkmcnt(4)
	v_mfma_f32_32x32x16_bf16 v[48:63], v[96:99], v[64:67], 0
	v_mfma_f32_32x32x16_bf16 v[48:63], v[100:103], v[68:71], v[48:63]
	v_mfma_f32_32x32x16_bf16 v[48:63], v[104:107], v[72:75], v[48:63]
	v_mfma_f32_32x32x16_bf16 v[48:63], v[108:111], v[76:79], v[48:63]
	s_waitcnt lgkmcnt(0)
	v_mfma_f32_32x32x16_bf16 v[48:63], v[112:115], v[80:83], v[48:63]
	v_mfma_f32_32x32x16_bf16 v[48:63], v[116:119], v[84:87], v[48:63]
	v_mfma_f32_32x32x16_bf16 v[48:63], v[120:123], v[88:91], v[48:63]
	v_mfma_f32_32x32x16_bf16 v[48:63], v[124:127], v[92:95], v[48:63]
	s_nop 11
	v_and_or_b32 v0, v0, s6, v211
	v_or_b32_e32 v0, 0x7b, v0
	v_and_or_b32 v1, v1, s6, v211
	v_or_b32_e32 v1, 0x7a, v1
	v_and_or_b32 v2, v2, s6, v211
	v_or_b32_e32 v2, 0x79, v2
	v_and_or_b32 v3, v3, s6, v211
	v_or_b32_e32 v3, 0x78, v3
	v_and_or_b32 v4, v4, s6, v211
	v_or_b32_e32 v4, 0x73, v4
	v_and_or_b32 v5, v5, s6, v211
	v_or_b32_e32 v5, 0x72, v5
	v_and_or_b32 v6, v6, s6, v211
	v_or_b32_e32 v6, 0x71, v6
	v_and_or_b32 v7, v7, s6, v211
	v_or_b32_e32 v7, 0x70, v7
	v_and_or_b32 v8, v8, s6, v211
	v_or_b32_e32 v8, 0x6b, v8
	v_and_or_b32 v9, v9, s6, v211
	v_or_b32_e32 v9, 0x6a, v9
	v_and_or_b32 v10, v10, s6, v211
	v_or_b32_e32 v10, 0x69, v10
	v_and_or_b32 v11, v11, s6, v211
	v_or_b32_e32 v11, 0x68, v11
	v_and_or_b32 v12, v12, s6, v211
	v_or_b32_e32 v12, 0x63, v12
	v_and_or_b32 v13, v13, s6, v211
	v_or_b32_e32 v13, 0x62, v13
	v_and_or_b32 v14, v14, s6, v211
	v_or_b32_e32 v14, 0x61, v14
	v_and_or_b32 v15, v15, s6, v211
	v_or_b32_e32 v15, 0x60, v15
	v_and_or_b32 v16, v16, s6, v211
	v_or_b32_e32 v16, 0x5b, v16
	v_and_or_b32 v17, v17, s6, v211
	v_or_b32_e32 v17, 0x5a, v17
	v_and_or_b32 v18, v18, s6, v211
	v_or_b32_e32 v18, 0x59, v18
	v_and_or_b32 v19, v19, s6, v211
	v_or_b32_e32 v19, 0x58, v19
	v_and_or_b32 v20, v20, s6, v211
	v_or_b32_e32 v20, 0x53, v20
	v_and_or_b32 v21, v21, s6, v211
	v_or_b32_e32 v21, 0x52, v21
	v_and_or_b32 v22, v22, s6, v211
	v_or_b32_e32 v22, 0x51, v22
	v_and_or_b32 v23, v23, s6, v211
	v_or_b32_e32 v23, 0x50, v23
	v_and_or_b32 v24, v24, s6, v211
	v_or_b32_e32 v24, 0x4b, v24
	v_and_or_b32 v25, v25, s6, v211
	v_or_b32_e32 v25, 0x4a, v25
	v_and_or_b32 v26, v26, s6, v211
	v_or_b32_e32 v26, 0x49, v26
	v_and_or_b32 v27, v27, s6, v211
	v_or_b32_e32 v27, 0x48, v27
	v_and_or_b32 v28, v28, s6, v211
	v_or_b32_e32 v28, 0x43, v28
	v_and_or_b32 v29, v29, s6, v211
	v_or_b32_e32 v29, 0x42, v29
	v_and_or_b32 v30, v30, s6, v211
	v_or_b32_e32 v30, 0x41, v30
	v_and_or_b32 v31, v31, s6, v211
	v_or_b32_e32 v31, 64, v31
	v_and_or_b32 v32, v32, s6, v211
	v_or_b32_e32 v32, 59, v32
	v_and_or_b32 v33, v33, s6, v211
	v_or_b32_e32 v33, 58, v33
	v_and_or_b32 v34, v34, s6, v211
	v_or_b32_e32 v34, 57, v34
	v_and_or_b32 v35, v35, s6, v211
	v_or_b32_e32 v35, 56, v35
	v_and_or_b32 v36, v36, s6, v211
	v_or_b32_e32 v36, 51, v36
	v_and_or_b32 v37, v37, s6, v211
	v_or_b32_e32 v37, 50, v37
	v_and_or_b32 v38, v38, s6, v211
	v_or_b32_e32 v38, 49, v38
	v_and_or_b32 v39, v39, s6, v211
	v_or_b32_e32 v39, 48, v39
	v_and_or_b32 v40, v40, s6, v211
	v_or_b32_e32 v40, 43, v40
	v_and_or_b32 v41, v41, s6, v211
	v_or_b32_e32 v41, 42, v41
	v_and_or_b32 v42, v42, s6, v211
	v_or_b32_e32 v42, 41, v42
	v_and_or_b32 v43, v43, s6, v211
	v_or_b32_e32 v43, 40, v43
	v_and_or_b32 v44, v44, s6, v211
	v_or_b32_e32 v44, 35, v44
	v_and_or_b32 v45, v45, s6, v211
	v_or_b32_e32 v45, 34, v45
	v_and_or_b32 v46, v46, s6, v211
	v_or_b32_e32 v46, 33, v46
	v_and_or_b32 v47, v47, s6, v211
	v_or_b32_e32 v47, 32, v47
	v_and_or_b32 v48, v48, s6, v211
	v_or_b32_e32 v48, 27, v48
	v_and_or_b32 v49, v49, s6, v211
	v_or_b32_e32 v49, 26, v49
	v_and_or_b32 v50, v50, s6, v211
	v_or_b32_e32 v50, 25, v50
	v_and_or_b32 v51, v51, s6, v211
	v_or_b32_e32 v51, 24, v51
	v_and_or_b32 v52, v52, s6, v211
	v_or_b32_e32 v52, 19, v52
	v_and_or_b32 v53, v53, s6, v211
	v_or_b32_e32 v53, 18, v53
	v_and_or_b32 v54, v54, s6, v211
	v_or_b32_e32 v54, 17, v54
	v_and_or_b32 v55, v55, s6, v211
	v_or_b32_e32 v55, 16, v55
	v_and_or_b32 v56, v56, s6, v211
	v_or_b32_e32 v56, 11, v56
	v_and_or_b32 v57, v57, s6, v211
	v_or_b32_e32 v57, 10, v57
	v_and_or_b32 v58, v58, s6, v211
	v_or_b32_e32 v58, 9, v58
	v_and_or_b32 v59, v59, s6, v211
	v_or_b32_e32 v59, 8, v59
	v_and_or_b32 v60, v60, s6, v211
	v_or_b32_e32 v60, 3, v60
	v_and_or_b32 v61, v61, s6, v211
	v_or_b32_e32 v61, 2, v61
	v_and_or_b32 v62, v62, s6, v211
	v_or_b32_e32 v62, 1, v62
	v_and_or_b32 v63, v63, s6, v211
	v_or_b32_e32 v63, 0, v63
	v_max_f32_e32 v144, v0, v13
	v_min_f32_e32 v13, v0, v13
	v_max_f32_e32 v145, v1, v12
	v_min_f32_e32 v12, v1, v12
	v_max_f32_e32 v146, v2, v15
	v_min_f32_e32 v15, v2, v15
	v_max_f32_e32 v147, v3, v14
	v_min_f32_e32 v14, v3, v14
	v_max_f32_e32 v148, v4, v8
	v_min_f32_e32 v8, v4, v8
	v_max_f32_e32 v149, v5, v6
	v_min_f32_e32 v6, v5, v6
	v_max_f32_e32 v150, v7, v11
	v_min_f32_e32 v11, v7, v11
	v_max_f32_e32 v151, v9, v10
	v_min_f32_e32 v10, v9, v10
	v_max_f32_e32 v249, v144, v149
	v_min_f32_e32 v149, v144, v149
	v_max_f32_e32 v250, v145, v150
	v_min_f32_e32 v150, v145, v150
	v_max_f32_e32 v251, v146, v151
	v_min_f32_e32 v151, v146, v151
	v_max_f32_e32 v252, v147, v148
	v_min_f32_e32 v148, v147, v148
	v_max_f32_e32 v253, v6, v13
	v_min_f32_e32 v13, v6, v13
	v_max_f32_e32 v254, v8, v14
	v_min_f32_e32 v14, v8, v14
	v_max_f32_e32 v255, v10, v15
	v_min_f32_e32 v15, v10, v15
	v_max_f32_e32 v96, v11, v12
	v_min_f32_e32 v12, v11, v12
	v_max_f32_e32 v97, v249, v250
	v_min_f32_e32 v250, v249, v250
	v_max_f32_e32 v98, v251, v252
	v_min_f32_e32 v252, v251, v252
	v_max_f32_e32 v99, v148, v149
	v_min_f32_e32 v149, v148, v149
	v_max_f32_e32 v100, v253, v254
	v_min_f32_e32 v254, v253, v254
	v_max_f32_e32 v101, v150, v151
	v_min_f32_e32 v151, v150, v151
	v_max_f32_e32 v102, v255, v96
	v_min_f32_e32 v96, v255, v96
	v_max_f32_e32 v103, v12, v13
	v_min_f32_e32 v13, v12, v13
	v_max_f32_e32 v104, v14, v15
	v_min_f32_e32 v15, v14, v15
	v_max_f32_e32 v105, v97, v98
	v_min_f32_e32 v98, v97, v98
	v_max_f32_e32 v106, v250, v252
	v_min_f32_e32 v252, v250, v252
	v_max_f32_e32 v107, v99, v102
	v_min_f32_e32 v102, v99, v102
	v_max_f32_e32 v108, v149, v96
	v_min_f32_e32 v96, v149, v96
	v_max_f32_e32 v109, v100, v101
	v_min_f32_e32 v101, v100, v101
	v_max_f32_e32 v110, v254, v151
	v_min_f32_e32 v151, v254, v151
	v_max_f32_e32 v111, v103, v104
	v_min_f32_e32 v104, v103, v104
	v_max_f32_e32 v112, v13, v15
	v_min_f32_e32 v15, v13, v15
	v_max_f32_e32 v113, v106, v98
	v_min_f32_e32 v98, v106, v98
	v_max_f32_e32 v114, v252, v111
	v_min_f32_e32 v111, v252, v111
	v_max_f32_e32 v115, v107, v109
	v_min_f32_e32 v109, v107, v109
	v_max_f32_e32 v116, v108, v101
	v_min_f32_e32 v101, v108, v101
	v_max_f32_e32 v117, v110, v102
	v_min_f32_e32 v102, v110, v102
	v_max_f32_e32 v118, v151, v96
	v_min_f32_e32 v96, v151, v96
	v_max_f32_e32 v119, v112, v104
	v_min_f32_e32 v104, v112, v104
	v_max_f32_e32 v120, v113, v115
	v_min_f32_e32 v115, v113, v115
	v_max_f32_e32 v121, v98, v109
	v_min_f32_e32 v109, v98, v109
	v_max_f32_e32 v122, v116, v117
	v_min_f32_e32 v117, v116, v117
	v_max_f32_e32 v123, v101, v102
	v_min_f32_e32 v102, v101, v102
	v_max_f32_e32 v124, v118, v119
	v_min_f32_e32 v119, v118, v119
	v_max_f32_e32 v125, v96, v104
	v_min_f32_e32 v104, v96, v104
	v_max_f32_e32 v126, v121, v115
	v_min_f32_e32 v115, v121, v115
	v_max_f32_e32 v127, v114, v109
	v_min_f32_e32 v109, v114, v109
	v_max_f32_e32 v64, v124, v111
	v_min_f32_e32 v111, v124, v111
	v_max_f32_e32 v65, v125, v119
	v_min_f32_e32 v119, v125, v119
	v_max_f32_e32 v66, v127, v122
	v_min_f32_e32 v122, v127, v122
	v_max_f32_e32 v67, v109, v117
	v_min_f32_e32 v117, v109, v117
	v_max_f32_e32 v68, v123, v64
	v_min_f32_e32 v64, v123, v64
	v_max_f32_e32 v69, v102, v111
	v_min_f32_e32 v111, v102, v111
	v_max_f32_e32 v70, v66, v115
	v_min_f32_e32 v115, v66, v115
	v_max_f32_e32 v71, v122, v67
	v_min_f32_e32 v67, v122, v67
	v_max_f32_e32 v72, v68, v117
	v_min_f32_e32 v117, v68, v117
	v_max_f32_e32 v73, v64, v69
	v_min_f32_e32 v69, v64, v69
	v_max_f32_e32 v74, v65, v111
	v_min_f32_e32 v111, v65, v111
	v_max_f32_e32 v75, v67, v72
	v_min_f32_e32 v72, v67, v72
	v_max_f32_e32 v76, v117, v73
	v_min_f32_e32 v73, v117, v73
	v_max_f32_e32 v77, v16, v29
	v_min_f32_e32 v29, v16, v29
	v_max_f32_e32 v78, v17, v28
	v_min_f32_e32 v28, v17, v28
	v_max_f32_e32 v79, v18, v31
	v_min_f32_e32 v31, v18, v31
	v_max_f32_e32 v80, v19, v30
	v_min_f32_e32 v30, v19, v30
	v_max_f32_e32 v81, v20, v24
	v_min_f32_e32 v24, v20, v24
	v_max_f32_e32 v82, v21, v22
	v_min_f32_e32 v22, v21, v22
	v_max_f32_e32 v83, v23, v27
	v_min_f32_e32 v27, v23, v27
	v_max_f32_e32 v84, v25, v26
	v_min_f32_e32 v26, v25, v26
	v_max_f32_e32 v85, v77, v82
	v_min_f32_e32 v82, v77, v82
	v_max_f32_e32 v86, v78, v83
	v_min_f32_e32 v83, v78, v83
	v_max_f32_e32 v87, v79, v84
	v_min_f32_e32 v84, v79, v84
	v_max_f32_e32 v88, v80, v81
	v_min_f32_e32 v81, v80, v81
	v_max_f32_e32 v89, v22, v29
	v_min_f32_e32 v29, v22, v29
	v_max_f32_e32 v90, v24, v30
	v_min_f32_e32 v30, v24, v30
	v_max_f32_e32 v91, v26, v31
	v_min_f32_e32 v31, v26, v31
	v_max_f32_e32 v92, v27, v28
	v_min_f32_e32 v28, v27, v28
	v_max_f32_e32 v93, v85, v86
	v_min_f32_e32 v86, v85, v86
	v_max_f32_e32 v94, v87, v88
	v_min_f32_e32 v88, v87, v88
	v_max_f32_e32 v95, v81, v82
	v_min_f32_e32 v82, v81, v82
	v_max_f32_e32 v0, v89, v90
	v_min_f32_e32 v90, v89, v90
	v_max_f32_e32 v1, v83, v84
	v_min_f32_e32 v84, v83, v84
	v_max_f32_e32 v2, v91, v92
	v_min_f32_e32 v92, v91, v92
	v_max_f32_e32 v3, v28, v29
	v_min_f32_e32 v29, v28, v29
	v_max_f32_e32 v4, v30, v31
	v_min_f32_e32 v31, v30, v31
	v_max_f32_e32 v5, v93, v94
	v_min_f32_e32 v94, v93, v94
	v_max_f32_e32 v7, v86, v88
	v_min_f32_e32 v88, v86, v88
	v_max_f32_e32 v9, v95, v2
	v_min_f32_e32 v2, v95, v2
	v_max_f32_e32 v144, v82, v92
	v_min_f32_e32 v92, v82, v92
	v_max_f32_e32 v145, v0, v1
	v_min_f32_e32 v1, v0, v1
	v_max_f32_e32 v146, v90, v84
	v_min_f32_e32 v84, v90, v84
	v_max_f32_e32 v147, v3, v4
	v_min_f32_e32 v4, v3, v4
	v_max_f32_e32 v6, v29, v31
	v_min_f32_e32 v31, v29, v31
	v_max_f32_e32 v8, v7, v94
	v_min_f32_e32 v94, v7, v94
	v_max_f32_e32 v10, v88, v147
	v_min_f32_e32 v147, v88, v147
	v_max_f32_e32 v11, v9, v145
	v_min_f32_e32 v145, v9, v145
	v_max_f32_e32 v249, v144, v1
	v_min_f32_e32 v1, v144, v1
	v_max_f32_e32 v251, v146, v2
	v_min_f32_e32 v2, v146, v2
	v_max_f32_e32 v148, v84, v92
	v_min_f32_e32 v92, v84, v92
	v_max_f32_e32 v253, v6, v4
	v_min_f32_e32 v4, v6, v4
	v_max_f32_e32 v150, v8, v11
	v_min_f32_e32 v11, v8, v11
	v_max_f32_e32 v255, v94, v145
	v_min_f32_e32 v145, v94, v145
	v_max_f32_e32 v12, v249, v251
	v_min_f32_e32 v251, v249, v251
	v_max_f32_e32 v14, v1, v2
	v_min_f32_e32 v2, v1, v2
	v_max_f32_e32 v97, v148, v253
	v_min_f32_e32 v253, v148, v253
	v_max_f32_e32 v250, v92, v4
	v_min_f32_e32 v4, v92, v4
	v_max_f32_e32 v99, v255, v11
	v_min_f32_e32 v11, v255, v11
	v_max_f32_e32 v149, v10, v145
	v_min_f32_e32 v145, v10, v145
	v_max_f32_e32 v100, v97, v147
	v_min_f32_e32 v147, v97, v147
	v_max_f32_e32 v254, v250, v253
	v_min_f32_e32 v253, v250, v253
	v_max_f32_e32 v103, v149, v12
	v_min_f32_e32 v12, v149, v12
	v_max_f32_e32 v13, v145, v251
	v_min_f32_e32 v251, v145, v251
	v_max_f32_e32 v106, v14, v100
	v_min_f32_e32 v100, v14, v100
	v_max_f32_e32 v252, v2, v147
	v_min_f32_e32 v147, v2, v147
	v_max_f32_e32 v107, v103, v11
	v_min_f32_e32 v11, v103, v11
	v_max_f32_e32 v108, v12, v13
	v_min_f32_e32 v13, v12, v13
	v_max_f32_e32 v110, v106, v251
	v_min_f32_e32 v251, v106, v251
	v_max_f32_e32 v151, v100, v252
	v_min_f32_e32 v252, v100, v252
	v_max_f32_e32 v112, v254, v147
	v_min_f32_e32 v147, v254, v147
	v_max_f32_e32 v113, v13, v110
	v_min_f32_e32 v110, v13, v110
	v_max_f32_e32 v98, v251, v151
	v_min_f32_e32 v151, v251, v151
	s_waitcnt vmcnt(0)
	v_pk_mul_f32 v[160:161], v[160:161], v[176:177]
	v_pk_mul_f32 v[162:163], v[162:163], v[178:179]
	v_pk_mul_f32 v[164:165], v[164:165], v[180:181]
	v_pk_mul_f32 v[166:167], v[166:167], v[182:183]
	v_pk_mul_f32 v[168:169], v[168:169], v[184:185]
	v_pk_mul_f32 v[170:171], v[170:171], v[186:187]
	v_pk_mul_f32 v[172:173], v[172:173], v[188:189]
	v_pk_mul_f32 v[174:175], v[174:175], v[190:191]
	v_max3_f32 v192, |v160|, |v161|, |v162|
	v_max3_f32 v192, |v163|, |v164|, v192
	v_max3_f32 v192, |v165|, |v166|, v192
	v_max3_f32 v192, |v167|, |v168|, v192
	v_max3_f32 v192, |v169|, |v170|, v192
	v_max3_f32 v192, |v171|, |v172|, v192
	v_max3_f32 v192, |v173|, |v174|, v192
	v_max_f32_e64 v192, |v175|, v192
	s_nop 1
	v_mov_b32_dpp v193, v192 quad_perm:[1,0,3,2] row_mask:0xf bank_mask:0xf bound_ctrl:1
	v_max_f32_e32 v192, v192, v193
	s_nop 1
	v_mov_b32_dpp v193, v192 quad_perm:[2,3,0,1] row_mask:0xf bank_mask:0xf bound_ctrl:1
	v_max_f32_e32 v192, v192, v193
	s_nop 1
	v_mov_b32_dpp v193, v192 row_half_mirror row_mask:0xf bank_mask:0xf bound_ctrl:1
	v_max_f32_e32 v192, v192, v193
	s_nop 1
	v_mov_b32_dpp v193, v192 row_mirror row_mask:0xf bank_mask:0xf bound_ctrl:1
	v_max_f32_e32 v192, v192, v193
	v_mov_b32_e32 v193, v192
	s_nop 1
	v_permlane16_swap_b32_e32 v192, v193
	s_nop 1
	v_max_f32_e32 v192, v192, v193
	v_mov_b32_e32 v193, v192
	s_nop 1
	v_permlane32_swap_b32_e32 v192, v193
	s_nop 1
	v_max_f32_e32 v192, v192, v193
	v_max_f32_e32 v192, 0xda24260, v192
	v_mul_f32_e32 v194, 0x3e2aaaab, v192
	global_store_dword v214, v194, s[12:13]
	v_div_scale_f32 v195, s[26:27], v194, v194, 1.0
	v_rcp_f32_e32 v196, v195
	v_div_scale_f32 v204, vcc, 1.0, v194, 1.0
	v_fma_f32 v205, -v195, v196, 1.0
	v_fmac_f32_e32 v196, v205, v196
	v_mul_f32_e32 v205, v204, v196
	v_fma_f32 v206, -v195, v205, v204
	v_fmac_f32_e32 v205, v206, v196
	v_fma_f32 v195, -v195, v205, v204
	s_nop 0
	v_div_fmas_f32 v195, v195, v196, v205
	v_div_fixup_f32 v207, v195, v194, 1.0
	v_mul_f32_e32 v160, v207, v160
	v_mul_f32_e32 v161, v207, v161
	v_mul_f32_e32 v162, v207, v162
	v_mul_f32_e32 v163, v207, v163
	v_mul_f32_e32 v164, v207, v164
	v_mul_f32_e32 v165, v207, v165
	v_mul_f32_e32 v166, v207, v166
	v_mul_f32_e32 v167, v207, v167
	v_mul_f32_e32 v168, v207, v168
	v_mul_f32_e32 v169, v207, v169
	v_mul_f32_e32 v170, v207, v170
	v_mul_f32_e32 v171, v207, v171
	v_mul_f32_e32 v172, v207, v172
	v_mul_f32_e32 v173, v207, v173
	v_mul_f32_e32 v174, v207, v174
	v_mul_f32_e32 v175, v207, v175
	v_mov_b32_e32 v208, 0
	v_mov_b32_e32 v209, 0
	v_mov_b32_e32 v210, 0
	v_mov_b32_e32 v193, 0
	v_cvt_scalef32_pk_fp4_f32 v208, v160, v161, 1.0
	v_cvt_scalef32_pk_fp4_f32 v209, v164, v165, 1.0
	v_cvt_scalef32_pk_fp4_f32 v210, v168, v169, 1.0
	v_cvt_scalef32_pk_fp4_f32 v193, v172, v173, 1.0
	v_cvt_scalef32_pk_fp4_f32 v208, v162, v163, 1.0 op_sel:[0,0,1,0]
	v_cvt_scalef32_pk_fp4_f32 v209, v166, v167, 1.0 op_sel:[0,0,1,0]
	v_cvt_scalef32_pk_fp4_f32 v210, v170, v171, 1.0 op_sel:[0,0,1,0]
	v_cvt_scalef32_pk_fp4_f32 v193, v174, v175, 1.0 op_sel:[0,0,1,0]
	global_store_short v213, v208, s[10:11] nt
	s_add_u32 s14, s10, 0x200000
	s_addc_u32 s15, s11, 0
	global_store_short v213, v209, s[14:15] nt
	s_add_u32 s14, s10, 0x400000
	s_addc_u32 s15, s11, 0
	global_store_short v213, v210, s[14:15] nt
	s_add_u32 s14, s10, 0x600000
	s_addc_u32 s15, s11, 0
	global_store_short v213, v193, s[14:15] nt
	s_add_u32 s10, s10, 0x20000
	s_addc_u32 s11, s11, 0
	s_add_u32 s12, s12, 0x2000
	s_addc_u32 s13, s13, 0
	global_load_dwordx4 v[160:163], v212, s[8:9] offset:0 nt
	global_load_dwordx4 v[164:167], v212, s[8:9] offset:1024 nt
	global_load_dwordx4 v[168:171], v212, s[8:9] offset:2048 nt
	global_load_dwordx4 v[172:175], v212, s[8:9] offset:3072 nt
	s_add_u32 s8, s8, 0x800000
	s_addc_u32 s9, s9, 0
	v_max_f32_e32 v116, v32, v45
	v_min_f32_e32 v45, v32, v45
	v_max_f32_e32 v101, v33, v44
	v_min_f32_e32 v44, v33, v44
	v_max_f32_e32 v118, v34, v47
	v_min_f32_e32 v47, v34, v47
	v_max_f32_e32 v96, v35, v46
	v_min_f32_e32 v46, v35, v46
	v_max_f32_e32 v121, v36, v40
	v_min_f32_e32 v40, v36, v40
	v_max_f32_e32 v114, v37, v38
	v_min_f32_e32 v38, v37, v38
	v_max_f32_e32 v124, v39, v43
	v_min_f32_e32 v43, v39, v43
	v_max_f32_e32 v125, v41, v42
	v_min_f32_e32 v42, v41, v42
	v_max_f32_e32 v127, v116, v114
	v_min_f32_e32 v114, v116, v114
	v_max_f32_e32 v109, v101, v124
	v_min_f32_e32 v124, v101, v124
	v_max_f32_e32 v123, v118, v125
	v_min_f32_e32 v125, v118, v125
	v_max_f32_e32 v102, v96, v121
	v_min_f32_e32 v121, v96, v121
	v_max_f32_e32 v66, v38, v45
	v_min_f32_e32 v45, v38, v45
	v_max_f32_e32 v122, v40, v46
	v_min_f32_e32 v46, v40, v46
	v_max_f32_e32 v68, v42, v47
	v_min_f32_e32 v47, v42, v47
	v_max_f32_e32 v64, v43, v44
	v_min_f32_e32 v44, v43, v44
	v_max_f32_e32 v65, v127, v109
	v_min_f32_e32 v109, v127, v109
	v_max_f32_e32 v67, v123, v102
	v_min_f32_e32 v102, v123, v102
	v_max_f32_e32 v117, v121, v114
	v_min_f32_e32 v114, v121, v114
	v_max_f32_e32 v16, v66, v122
	v_min_f32_e32 v122, v66, v122
	v_max_f32_e32 v17, v124, v125
	v_min_f32_e32 v125, v124, v125
	v_max_f32_e32 v18, v68, v64
	v_min_f32_e32 v64, v68, v64
	v_max_f32_e32 v19, v44, v45
	v_min_f32_e32 v45, v44, v45
	v_max_f32_e32 v20, v46, v47
	v_min_f32_e32 v47, v46, v47
	v_max_f32_e32 v21, v65, v67
	v_min_f32_e32 v67, v65, v67
	v_max_f32_e32 v23, v109, v102
	v_min_f32_e32 v102, v109, v102
	v_max_f32_e32 v25, v117, v18
	v_min_f32_e32 v18, v117, v18
	v_max_f32_e32 v77, v114, v64
	v_min_f32_e32 v64, v114, v64
	v_max_f32_e32 v78, v16, v17
	v_min_f32_e32 v17, v16, v17
	v_max_f32_e32 v79, v122, v125
	v_min_f32_e32 v125, v122, v125
	v_max_f32_e32 v80, v19, v20
	v_min_f32_e32 v20, v19, v20
	v_max_f32_e32 v22, v45, v47
	v_min_f32_e32 v47, v45, v47
	v_max_f32_e32 v24, v23, v67
	v_min_f32_e32 v67, v23, v67
	v_max_f32_e32 v26, v102, v80
	v_min_f32_e32 v80, v102, v80
	v_max_f32_e32 v27, v25, v78
	v_min_f32_e32 v78, v25, v78
	v_max_f32_e32 v85, v77, v17
	v_min_f32_e32 v17, v77, v17
	v_max_f32_e32 v87, v79, v18
	v_min_f32_e32 v18, v79, v18
	v_max_f32_e32 v81, v125, v64
	v_min_f32_e32 v64, v125, v64
	v_max_f32_e32 v89, v22, v20
	v_min_f32_e32 v20, v22, v20
	v_max_f32_e32 v83, v24, v27
	v_min_f32_e32 v27, v24, v27
	v_max_f32_e32 v91, v67, v78
	v_min_f32_e32 v78, v67, v78
	v_max_f32_e32 v28, v85, v87
	v_min_f32_e32 v87, v85, v87
	v_max_f32_e32 v30, v17, v18
	v_min_f32_e32 v18, v17, v18
	v_max_f32_e32 v93, v81, v89
	v_min_f32_e32 v89, v81, v89
	v_max_f32_e32 v86, v64, v20
	v_min_f32_e32 v20, v64, v20
	v_max_f32_e32 v95, v91, v27
	v_min_f32_e32 v27, v91, v27
	v_max_f32_e32 v82, v26, v78
	v_min_f32_e32 v78, v26, v78
	v_max_f32_e32 v0, v93, v80
	v_min_f32_e32 v80, v93, v80
	v_max_f32_e32 v90, v86, v89
	v_min_f32_e32 v89, v86, v89
	v_max_f32_e32 v3, v82, v28
	v_min_f32_e32 v28, v82, v28
	v_max_f32_e32 v29, v78, v87
	v_min_f32_e32 v87, v78, v87
	v_max_f32_e32 v7, v30, v0
	v_min_f32_e32 v0, v30, v0
	v_max_f32_e32 v88, v18, v80
	v_min_f32_e32 v80, v18, v80
	v_max_f32_e32 v9, v3, v27
	v_min_f32_e32 v27, v3, v27
	v_max_f32_e32 v144, v28, v29
	v_min_f32_e32 v29, v28, v29
	v_max_f32_e32 v146, v7, v87
	v_min_f32_e32 v87, v7, v87
	v_max_f32_e32 v84, v0, v88
	v_min_f32_e32 v88, v0, v88
	v_max_f32_e32 v6, v90, v80
	v_min_f32_e32 v80, v90, v80
	v_max_f32_e32 v8, v29, v146
	v_min_f32_e32 v146, v29, v146
	v_max_f32_e32 v94, v87, v84
	v_min_f32_e32 v84, v87, v84
	v_max_f32_e32 v249, v48, v61
	v_min_f32_e32 v61, v48, v61
	v_max_f32_e32 v1, v49, v60
	v_min_f32_e32 v60, v49, v60
	v_max_f32_e32 v148, v50, v63
	v_min_f32_e32 v63, v50, v63
	v_max_f32_e32 v92, v51, v62
	v_min_f32_e32 v62, v51, v62
	v_max_f32_e32 v255, v52, v56
	v_min_f32_e32 v56, v52, v56
	v_max_f32_e32 v10, v53, v54
	v_min_f32_e32 v54, v53, v54
	v_max_f32_e32 v97, v55, v59
	v_min_f32_e32 v59, v55, v59
	v_max_f32_e32 v250, v57, v58
	v_min_f32_e32 v58, v57, v58
	v_max_f32_e32 v149, v249, v10
	v_min_f32_e32 v10, v249, v10
	v_max_f32_e32 v145, v1, v97
	v_min_f32_e32 v97, v1, v97
	v_max_f32_e32 v14, v148, v250
	v_min_f32_e32 v250, v148, v250
	v_max_f32_e32 v2, v92, v255
	v_min_f32_e32 v255, v92, v255
	v_max_f32_e32 v103, v54, v61
	v_min_f32_e32 v61, v54, v61
	v_max_f32_e32 v12, v56, v62
	v_min_f32_e32 v62, v56, v62
	v_max_f32_e32 v106, v58, v63
	v_min_f32_e32 v63, v58, v63
	v_max_f32_e32 v100, v59, v60
	v_min_f32_e32 v60, v59, v60
	v_max_f32_e32 v254, v149, v145
	v_min_f32_e32 v145, v149, v145
	v_max_f32_e32 v13, v14, v2
	v_min_f32_e32 v2, v14, v2
	v_max_f32_e32 v251, v255, v10
	v_min_f32_e32 v10, v255, v10
	v_max_f32_e32 v32, v103, v12
	v_min_f32_e32 v12, v103, v12
	v_max_f32_e32 v33, v97, v250
	v_min_f32_e32 v250, v97, v250
	v_max_f32_e32 v34, v106, v100
	v_min_f32_e32 v100, v106, v100
	v_max_f32_e32 v35, v60, v61
	v_min_f32_e32 v61, v60, v61
	v_max_f32_e32 v36, v62, v63
	v_min_f32_e32 v63, v62, v63
	v_max_f32_e32 v37, v254, v13
	v_min_f32_e32 v13, v254, v13
	v_max_f32_e32 v39, v145, v2
	v_min_f32_e32 v2, v145, v2
	v_max_f32_e32 v41, v251, v34
	v_min_f32_e32 v34, v251, v34
	v_max_f32_e32 v116, v10, v100
	v_min_f32_e32 v100, v10, v100
	v_max_f32_e32 v101, v32, v33
	v_min_f32_e32 v33, v32, v33
	v_max_f32_e32 v118, v12, v250
	v_min_f32_e32 v250, v12, v250
	v_max_f32_e32 v96, v35, v36
	v_min_f32_e32 v36, v35, v36
	v_max_f32_e32 v38, v61, v63
	v_min_f32_e32 v63, v61, v63
	v_max_f32_e32 v40, v39, v13
	v_min_f32_e32 v13, v39, v13
	v_max_f32_e32 v42, v2, v96
	v_min_f32_e32 v96, v2, v96
	v_max_f32_e32 v43, v41, v101
	v_min_f32_e32 v101, v41, v101
	v_max_f32_e32 v127, v116, v33
	v_min_f32_e32 v33, v116, v33
	v_max_f32_e32 v123, v118, v34
	v_min_f32_e32 v34, v118, v34
	v_max_f32_e32 v121, v250, v100
	v_min_f32_e32 v100, v250, v100
	v_max_f32_e32 v66, v38, v36
	v_min_f32_e32 v36, v38, v36
	v_max_f32_e32 v124, v40, v43
	v_min_f32_e32 v43, v40, v43
	v_max_f32_e32 v68, v13, v101
	v_min_f32_e32 v101, v13, v101
	v_max_f32_e32 v44, v127, v123
	v_min_f32_e32 v123, v127, v123
	v_max_f32_e32 v46, v33, v34
	v_min_f32_e32 v34, v33, v34
	v_max_f32_e32 v65, v121, v66
	v_min_f32_e32 v66, v121, v66
	v_max_f32_e32 v109, v100, v36
	v_min_f32_e32 v36, v100, v36
	v_max_f32_e32 v117, v68, v43
	v_min_f32_e32 v43, v68, v43
	v_max_f32_e32 v114, v42, v101
	v_min_f32_e32 v101, v42, v101
	v_max_f32_e32 v16, v65, v96
	v_min_f32_e32 v96, v65, v96
	v_max_f32_e32 v122, v109, v66
	v_min_f32_e32 v66, v109, v66
	v_max_f32_e32 v19, v114, v44
	v_min_f32_e32 v44, v114, v44
	v_max_f32_e32 v45, v101, v123
	v_min_f32_e32 v123, v101, v123
	v_max_f32_e32 v23, v46, v16
	v_min_f32_e32 v16, v46, v16
	v_max_f32_e32 v102, v34, v96
	v_min_f32_e32 v96, v34, v96
	v_max_f32_e32 v25, v19, v43
	v_min_f32_e32 v43, v19, v43
	v_max_f32_e32 v77, v44, v45
	v_min_f32_e32 v45, v44, v45
	v_max_f32_e32 v79, v23, v123
	v_min_f32_e32 v123, v23, v123
	v_max_f32_e32 v125, v16, v102
	v_min_f32_e32 v102, v16, v102
	v_max_f32_e32 v22, v122, v96
	v_min_f32_e32 v96, v122, v96
	v_max_f32_e32 v24, v45, v79
	v_min_f32_e32 v79, v45, v79
	v_max_f32_e32 v67, v123, v125
	v_min_f32_e32 v125, v123, v125
	s_waitcnt vmcnt(0)
	v_pk_mul_f32 v[160:161], v[160:161], v[176:177]
	v_pk_mul_f32 v[162:163], v[162:163], v[178:179]
	v_pk_mul_f32 v[164:165], v[164:165], v[180:181]
	v_pk_mul_f32 v[166:167], v[166:167], v[182:183]
	v_pk_mul_f32 v[168:169], v[168:169], v[184:185]
	v_pk_mul_f32 v[170:171], v[170:171], v[186:187]
	v_pk_mul_f32 v[172:173], v[172:173], v[188:189]
	v_pk_mul_f32 v[174:175], v[174:175], v[190:191]
	v_max3_f32 v192, |v160|, |v161|, |v162|
	v_max3_f32 v192, |v163|, |v164|, v192
	v_max3_f32 v192, |v165|, |v166|, v192
	v_max3_f32 v192, |v167|, |v168|, v192
	v_max3_f32 v192, |v169|, |v170|, v192
	v_max3_f32 v192, |v171|, |v172|, v192
	v_max3_f32 v192, |v173|, |v174|, v192
	v_max_f32_e64 v192, |v175|, v192
	s_nop 1
	v_mov_b32_dpp v193, v192 quad_perm:[1,0,3,2] row_mask:0xf bank_mask:0xf bound_ctrl:1
	v_max_f32_e32 v192, v192, v193
	s_nop 1
	v_mov_b32_dpp v193, v192 quad_perm:[2,3,0,1] row_mask:0xf bank_mask:0xf bound_ctrl:1
	v_max_f32_e32 v192, v192, v193
	s_nop 1
	v_mov_b32_dpp v193, v192 row_half_mirror row_mask:0xf bank_mask:0xf bound_ctrl:1
	v_max_f32_e32 v192, v192, v193
	s_nop 1
	v_mov_b32_dpp v193, v192 row_mirror row_mask:0xf bank_mask:0xf bound_ctrl:1
	v_max_f32_e32 v192, v192, v193
	v_mov_b32_e32 v193, v192
	s_nop 1
	v_permlane16_swap_b32_e32 v192, v193
	s_nop 1
	v_max_f32_e32 v192, v192, v193
	v_mov_b32_e32 v193, v192
	s_nop 1
	v_permlane32_swap_b32_e32 v192, v193
	s_nop 1
	v_max_f32_e32 v192, v192, v193
	v_max_f32_e32 v192, 0xda24260, v192
	v_mul_f32_e32 v194, 0x3e2aaaab, v192
	global_store_dword v214, v194, s[12:13]
	v_div_scale_f32 v195, s[26:27], v194, v194, 1.0
	v_rcp_f32_e32 v196, v195
	v_div_scale_f32 v204, vcc, 1.0, v194, 1.0
	v_fma_f32 v205, -v195, v196, 1.0
	v_fmac_f32_e32 v196, v205, v196
	v_mul_f32_e32 v205, v204, v196
	v_fma_f32 v206, -v195, v205, v204
	v_fmac_f32_e32 v205, v206, v196
	v_fma_f32 v195, -v195, v205, v204
	s_nop 0
	v_div_fmas_f32 v195, v195, v196, v205
	v_div_fixup_f32 v207, v195, v194, 1.0
	v_mul_f32_e32 v160, v207, v160
	v_mul_f32_e32 v161, v207, v161
	v_mul_f32_e32 v162, v207, v162
	v_mul_f32_e32 v163, v207, v163
	v_mul_f32_e32 v164, v207, v164
	v_mul_f32_e32 v165, v207, v165
	v_mul_f32_e32 v166, v207, v166
	v_mul_f32_e32 v167, v207, v167
	v_mul_f32_e32 v168, v207, v168
	v_mul_f32_e32 v169, v207, v169
	v_mul_f32_e32 v170, v207, v170
	v_mul_f32_e32 v171, v207, v171
	v_mul_f32_e32 v172, v207, v172
	v_mul_f32_e32 v173, v207, v173
	v_mul_f32_e32 v174, v207, v174
	v_mul_f32_e32 v175, v207, v175
	v_mov_b32_e32 v208, 0
	v_mov_b32_e32 v209, 0
	v_mov_b32_e32 v210, 0
	v_mov_b32_e32 v193, 0
	v_cvt_scalef32_pk_fp4_f32 v208, v160, v161, 1.0
	v_cvt_scalef32_pk_fp4_f32 v209, v164, v165, 1.0
	v_cvt_scalef32_pk_fp4_f32 v210, v168, v169, 1.0
	v_cvt_scalef32_pk_fp4_f32 v193, v172, v173, 1.0
	v_cvt_scalef32_pk_fp4_f32 v208, v162, v163, 1.0 op_sel:[0,0,1,0]
	v_cvt_scalef32_pk_fp4_f32 v209, v166, v167, 1.0 op_sel:[0,0,1,0]
	v_cvt_scalef32_pk_fp4_f32 v210, v170, v171, 1.0 op_sel:[0,0,1,0]
	v_cvt_scalef32_pk_fp4_f32 v193, v174, v175, 1.0 op_sel:[0,0,1,0]
	global_store_short v213, v208, s[10:11] nt
	s_add_u32 s14, s10, 0x200000
	s_addc_u32 s15, s11, 0
	global_store_short v213, v209, s[14:15] nt
	s_add_u32 s14, s10, 0x400000
	s_addc_u32 s15, s11, 0
	global_store_short v213, v210, s[14:15] nt
	s_add_u32 s14, s10, 0x600000
	s_addc_u32 s15, s11, 0
	global_store_short v213, v193, s[14:15] nt
	s_add_u32 s10, s10, 0x20000
	s_addc_u32 s11, s11, 0
	s_add_u32 s12, s12, 0x2000
	s_addc_u32 s13, s13, 0
	global_load_dwordx4 v[160:163], v212, s[8:9] offset:0 nt
	global_load_dwordx4 v[164:167], v212, s[8:9] offset:1024 nt
	global_load_dwordx4 v[168:171], v212, s[8:9] offset:2048 nt
	global_load_dwordx4 v[172:175], v212, s[8:9] offset:3072 nt
	s_add_u32 s8, s8, 0x800000
	s_addc_u32 s9, s9, 0
	v_max_f32_e32 v105, v105, v31
	v_max_f32_e32 v120, v120, v4
	v_max_f32_e32 v126, v126, v253
	v_max_f32_e32 v70, v70, v147
	v_max_f32_e32 v115, v115, v112
	v_max_f32_e32 v71, v71, v252
	v_max_f32_e32 v75, v75, v151
	v_max_f32_e32 v72, v72, v98
	v_max_f32_e32 v76, v76, v110
	v_max_f32_e32 v73, v73, v113
	v_max_f32_e32 v69, v69, v108
	v_max_f32_e32 v74, v74, v11
	v_max_f32_e32 v111, v111, v107
	v_max_f32_e32 v119, v119, v99
	v_max_f32_e32 v104, v104, v150
	v_max_f32_e32 v15, v15, v5
	v_max_f32_e32 v85, v105, v76
	v_min_f32_e32 v76, v105, v76
	v_max_f32_e32 v17, v120, v73
	v_min_f32_e32 v73, v120, v73
	v_max_f32_e32 v81, v126, v69
	v_min_f32_e32 v69, v126, v69
	v_max_f32_e32 v64, v70, v74
	v_min_f32_e32 v74, v70, v74
	v_max_f32_e32 v91, v115, v111
	v_min_f32_e32 v111, v115, v111
	v_max_f32_e32 v26, v71, v119
	v_min_f32_e32 v119, v71, v119
	v_max_f32_e32 v93, v75, v104
	v_min_f32_e32 v104, v75, v104
	v_max_f32_e32 v86, v72, v15
	v_min_f32_e32 v15, v72, v15
	v_max_f32_e32 v82, v85, v91
	v_min_f32_e32 v91, v85, v91
	v_max_f32_e32 v78, v17, v26
	v_min_f32_e32 v26, v17, v26
	v_max_f32_e32 v30, v81, v93
	v_min_f32_e32 v93, v81, v93
	v_max_f32_e32 v18, v64, v86
	v_min_f32_e32 v86, v64, v86
	v_max_f32_e32 v3, v76, v111
	v_min_f32_e32 v111, v76, v111
	v_max_f32_e32 v28, v73, v119
	v_min_f32_e32 v119, v73, v119
	v_max_f32_e32 v7, v69, v104
	v_min_f32_e32 v104, v69, v104
	v_max_f32_e32 v0, v74, v15
	v_min_f32_e32 v15, v74, v15
	v_max_f32_e32 v90, v82, v30
	v_min_f32_e32 v30, v82, v30
	v_max_f32_e32 v29, v78, v18
	v_min_f32_e32 v18, v78, v18
	v_max_f32_e32 v87, v91, v93
	v_min_f32_e32 v93, v91, v93
	v_max_f32_e32 v48, v26, v86
	v_min_f32_e32 v86, v26, v86
	v_max_f32_e32 v49, v3, v7
	v_min_f32_e32 v7, v3, v7
	v_max_f32_e32 v50, v28, v0
	v_min_f32_e32 v0, v28, v0
	v_max_f32_e32 v51, v111, v104
	v_min_f32_e32 v104, v111, v104
	v_max_f32_e32 v52, v119, v15
	v_min_f32_e32 v15, v119, v15
	v_max_f32_e32 v53, v90, v29
	v_min_f32_e32 v29, v90, v29
	v_max_f32_e32 v55, v30, v18
	v_min_f32_e32 v18, v30, v18
	v_max_f32_e32 v57, v87, v48
	v_min_f32_e32 v48, v87, v48
	v_max_f32_e32 v249, v93, v86
	v_min_f32_e32 v86, v93, v86
	v_max_f32_e32 v1, v49, v50
	v_min_f32_e32 v50, v49, v50
	v_max_f32_e32 v148, v7, v0
	v_min_f32_e32 v0, v7, v0
	v_max_f32_e32 v92, v51, v52
	v_min_f32_e32 v52, v51, v52
	v_max_f32_e32 v54, v104, v15
	v_min_f32_e32 v15, v104, v15
	v_max_f32_e32 v21, v21, v63
	v_max_f32_e32 v83, v83, v36
	v_max_f32_e32 v95, v95, v66
	v_max_f32_e32 v9, v9, v96
	v_max_f32_e32 v27, v27, v22
	v_max_f32_e32 v144, v144, v102
	v_max_f32_e32 v8, v8, v125
	v_max_f32_e32 v146, v146, v67
	v_max_f32_e32 v94, v94, v79
	v_max_f32_e32 v84, v84, v24
	v_max_f32_e32 v88, v88, v77
	v_max_f32_e32 v6, v6, v43
	v_max_f32_e32 v80, v80, v25
	v_max_f32_e32 v89, v89, v117
	v_max_f32_e32 v20, v20, v124
	v_max_f32_e32 v47, v47, v37
	v_max_f32_e32 v56, v21, v94
	v_min_f32_e32 v94, v21, v94
	v_max_f32_e32 v58, v83, v84
	v_min_f32_e32 v84, v83, v84
	v_max_f32_e32 v59, v95, v88
	v_min_f32_e32 v88, v95, v88
	v_max_f32_e32 v149, v9, v6
	v_min_f32_e32 v6, v9, v6
	v_max_f32_e32 v14, v27, v80
	v_min_f32_e32 v80, v27, v80
	v_max_f32_e32 v255, v144, v89
	v_min_f32_e32 v89, v144, v89
	v_max_f32_e32 v103, v8, v20
	v_min_f32_e32 v20, v8, v20
	v_max_f32_e32 v97, v146, v47
	v_min_f32_e32 v47, v146, v47
	v_max_f32_e32 v106, v56, v14
	v_min_f32_e32 v14, v56, v14
	v_max_f32_e32 v60, v58, v255
	v_min_f32_e32 v255, v58, v255
	v_max_f32_e32 v62, v59, v103
	v_min_f32_e32 v103, v59, v103
	v_max_f32_e32 v254, v149, v97
	v_min_f32_e32 v97, v149, v97
	v_max_f32_e32 v145, v94, v80
	v_min_f32_e32 v80, v94, v80
	v_max_f32_e32 v251, v84, v89
	v_min_f32_e32 v89, v84, v89
	v_max_f32_e32 v10, v88, v20
	v_min_f32_e32 v20, v88, v20
	v_max_f32_e32 v32, v6, v47
	v_min_f32_e32 v47, v6, v47
	v_max_f32_e32 v12, v106, v62
	v_min_f32_e32 v62, v106, v62
	v_max_f32_e32 v35, v60, v254
	v_min_f32_e32 v254, v60, v254
	v_max_f32_e32 v61, v14, v103
	v_min_f32_e32 v103, v14, v103
	v_max_f32_e32 v39, v255, v97
	v_min_f32_e32 v97, v255, v97
	v_max_f32_e32 v2, v145, v10
	v_min_f32_e32 v10, v145, v10
	v_max_f32_e32 v41, v251, v32
	v_min_f32_e32 v32, v251, v32
	v_max_f32_e32 v116, v80, v20
	v_min_f32_e32 v20, v80, v20
	v_max_f32_e32 v118, v89, v47
	v_min_f32_e32 v47, v89, v47
	v_max_f32_e32 v250, v12, v35
	v_min_f32_e32 v35, v12, v35
	v_max_f32_e32 v38, v62, v254
	v_min_f32_e32 v254, v62, v254
	v_max_f32_e32 v40, v61, v39
	v_min_f32_e32 v39, v61, v39
	v_max_f32_e32 v13, v103, v97
	v_min_f32_e32 v97, v103, v97
	v_max_f32_e32 v127, v2, v41
	v_min_f32_e32 v41, v2, v41
	v_max_f32_e32 v33, v10, v32
	v_min_f32_e32 v32, v10, v32
	v_max_f32_e32 v121, v116, v118
	v_min_f32_e32 v118, v116, v118
	v_max_f32_e32 v100, v20, v47
	v_min_f32_e32 v47, v20, v47
	v_max_f32_e32 v53, v53, v47
	v_max_f32_e32 v29, v29, v100
	v_max_f32_e32 v55, v55, v118
	v_max_f32_e32 v18, v18, v121
	v_max_f32_e32 v57, v57, v32
	v_max_f32_e32 v48, v48, v33
	v_max_f32_e32 v249, v249, v41
	v_max_f32_e32 v86, v86, v127
	v_max_f32_e32 v1, v1, v97
	v_max_f32_e32 v50, v50, v13
	v_max_f32_e32 v148, v148, v39
	v_max_f32_e32 v0, v0, v40
	v_max_f32_e32 v92, v92, v254
	v_max_f32_e32 v52, v52, v38
	v_max_f32_e32 v54, v54, v35
	v_max_f32_e32 v15, v15, v250
	v_max_f32_e32 v68, v53, v1
	v_min_f32_e32 v1, v53, v1
	v_max_f32_e32 v42, v29, v50
	v_min_f32_e32 v50, v29, v50
	v_max_f32_e32 v65, v55, v148
	v_min_f32_e32 v148, v55, v148
	v_max_f32_e32 v109, v18, v0
	v_min_f32_e32 v0, v18, v0
	v_max_f32_e32 v114, v57, v92
	v_min_f32_e32 v92, v57, v92
	v_max_f32_e32 v101, v48, v52
	v_min_f32_e32 v52, v48, v52
	v_max_f32_e32 v46, v249, v54
	v_min_f32_e32 v54, v249, v54
	v_max_f32_e32 v34, v86, v15
	v_min_f32_e32 v15, v86, v15
	v_max_f32_e32 v19, v68, v114
	v_min_f32_e32 v114, v68, v114
	v_max_f32_e32 v44, v42, v101
	v_min_f32_e32 v101, v42, v101
	v_max_f32_e32 v23, v65, v46
	v_min_f32_e32 v46, v65, v46
	v_max_f32_e32 v16, v109, v34
	v_min_f32_e32 v34, v109, v34
	v_max_f32_e32 v122, v1, v92
	v_min_f32_e32 v92, v1, v92
	v_max_f32_e32 v45, v50, v52
	v_min_f32_e32 v52, v50, v52
	v_max_f32_e32 v123, v148, v54
	v_min_f32_e32 v54, v148, v54
	v_max_f32_e32 v5, v0, v15
	v_min_f32_e32 v15, v0, v15
	v_max_f32_e32 v150, v19, v23
	v_min_f32_e32 v23, v19, v23
	v_max_f32_e32 v99, v44, v16
	v_min_f32_e32 v16, v44, v16
	v_max_f32_e32 v107, v114, v46
	v_min_f32_e32 v46, v114, v46
	v_max_f32_e32 v11, v101, v34
	v_min_f32_e32 v34, v101, v34
	v_max_f32_e32 v108, v122, v123
	v_min_f32_e32 v123, v122, v123
	v_max_f32_e32 v113, v45, v5
	v_min_f32_e32 v5, v45, v5
	v_max_f32_e32 v110, v92, v54
	v_min_f32_e32 v54, v92, v54
	v_max_f32_e32 v98, v52, v15
	v_min_f32_e32 v15, v52, v15
	v_max_f32_e32 v151, v150, v99
	v_min_f32_e32 v99, v150, v99
	v_max_f32_e32 v252, v23, v16
	v_min_f32_e32 v16, v23, v16
	v_max_f32_e32 v112, v107, v11
	v_min_f32_e32 v11, v107, v11
	v_max_f32_e32 v147, v46, v34
	v_min_f32_e32 v34, v46, v34
	v_max_f32_e32 v253, v108, v113
	v_min_f32_e32 v113, v108, v113
	v_max_f32_e32 v4, v123, v5
	v_min_f32_e32 v5, v123, v5
	v_max_f32_e32 v31, v110, v98
	v_min_f32_e32 v98, v110, v98
	v_max_f32_e32 v105, v54, v15
	v_min_f32_e32 v15, v54, v15
	v_mov_b32_e32 v120, v151
	v_mov_b32_e32 v126, v99
	v_mov_b32_e32 v70, v252
	v_mov_b32_e32 v115, v16
	v_mov_b32_e32 v71, v112
	v_mov_b32_e32 v75, v11
	v_mov_b32_e32 v72, v147
	v_mov_b32_e32 v85, v34
	v_mov_b32_e32 v17, v253
	v_mov_b32_e32 v81, v113
	v_mov_b32_e32 v64, v4
	v_mov_b32_e32 v76, v5
	v_mov_b32_e32 v73, v31
	v_mov_b32_e32 v69, v98
	v_mov_b32_e32 v74, v105
	v_mov_b32_e32 v82, v15
	s_nop 1
	v_permlane32_swap_b32_e32 v151, v120
	v_permlane32_swap_b32_e32 v99, v126
	v_permlane32_swap_b32_e32 v252, v70
	v_permlane32_swap_b32_e32 v16, v115
	v_permlane32_swap_b32_e32 v112, v71
	v_permlane32_swap_b32_e32 v11, v75
	v_permlane32_swap_b32_e32 v147, v72
	v_permlane32_swap_b32_e32 v34, v85
	v_permlane32_swap_b32_e32 v253, v17
	v_permlane32_swap_b32_e32 v113, v81
	v_permlane32_swap_b32_e32 v4, v64
	v_permlane32_swap_b32_e32 v5, v76
	v_permlane32_swap_b32_e32 v31, v73
	v_permlane32_swap_b32_e32 v98, v69
	v_permlane32_swap_b32_e32 v105, v74
	v_permlane32_swap_b32_e32 v15, v82
	s_nop 1
	v_max_f32_e32 v151, v151, v82
	v_max_f32_e32 v99, v99, v74
	v_max_f32_e32 v252, v252, v69
	v_max_f32_e32 v16, v16, v73
	v_max_f32_e32 v112, v112, v76
	v_max_f32_e32 v11, v11, v64
	v_max_f32_e32 v147, v147, v81
	v_max_f32_e32 v34, v34, v17
	v_max_f32_e32 v253, v253, v85
	v_max_f32_e32 v113, v113, v72
	v_max_f32_e32 v4, v4, v75
	v_max_f32_e32 v5, v5, v71
	v_max_f32_e32 v31, v31, v115
	v_max_f32_e32 v98, v98, v70
	v_max_f32_e32 v105, v105, v126
	v_max_f32_e32 v15, v15, v120
	v_max_f32_e32 v78, v151, v253
	v_min_f32_e32 v253, v151, v253
	v_max_f32_e32 v91, v99, v113
	v_min_f32_e32 v113, v99, v113
	v_max_f32_e32 v26, v252, v4
	v_min_f32_e32 v4, v252, v4
	v_max_f32_e32 v3, v16, v5
	v_min_f32_e32 v5, v16, v5
	v_max_f32_e32 v28, v112, v31
	v_min_f32_e32 v31, v112, v31
	v_max_f32_e32 v111, v11, v98
	v_min_f32_e32 v98, v11, v98
	v_max_f32_e32 v119, v147, v105
	v_min_f32_e32 v105, v147, v105
	v_max_f32_e32 v90, v34, v15
	v_min_f32_e32 v15, v34, v15
	v_max_f32_e32 v30, v78, v28
	v_min_f32_e32 v28, v78, v28
	v_max_f32_e32 v87, v91, v111
	v_min_f32_e32 v111, v91, v111
	v_max_f32_e32 v93, v26, v119
	v_min_f32_e32 v119, v26, v119
	v_max_f32_e32 v49, v3, v90
	v_min_f32_e32 v90, v3, v90
	v_max_f32_e32 v7, v253, v31
	v_min_f32_e32 v31, v253, v31
	v_max_f32_e32 v51, v113, v98
	v_min_f32_e32 v98, v113, v98
	v_max_f32_e32 v104, v4, v105
	v_min_f32_e32 v105, v4, v105
	v_max_f32_e32 v37, v5, v15
	v_min_f32_e32 v15, v5, v15
	v_max_f32_e32 v124, v30, v93
	v_min_f32_e32 v93, v30, v93
	v_max_f32_e32 v117, v87, v49
	v_min_f32_e32 v49, v87, v49
	v_max_f32_e32 v25, v28, v119
	v_min_f32_e32 v119, v28, v119
	v_max_f32_e32 v43, v111, v90
	v_min_f32_e32 v90, v111, v90
	v_max_f32_e32 v77, v7, v104
	v_min_f32_e32 v104, v7, v104
	v_max_f32_e32 v24, v51, v37
	v_min_f32_e32 v37, v51, v37
	v_max_f32_e32 v79, v31, v105
	v_min_f32_e32 v105, v31, v105
	v_max_f32_e32 v67, v98, v15
	v_min_f32_e32 v15, v98, v15
	v_max_f32_e32 v125, v124, v117
	v_min_f32_e32 v117, v124, v117
	v_max_f32_e32 v102, v93, v49
	v_min_f32_e32 v49, v93, v49
	v_max_f32_e32 v22, v25, v43
	v_min_f32_e32 v43, v25, v43
	v_max_f32_e32 v96, v119, v90
	v_min_f32_e32 v90, v119, v90
	v_max_f32_e32 v66, v77, v24
	v_min_f32_e32 v24, v77, v24
	v_max_f32_e32 v36, v104, v37
	v_min_f32_e32 v37, v104, v37
	v_max_f32_e32 v63, v79, v67
	v_min_f32_e32 v67, v79, v67
	v_max_f32_e32 v21, v105, v15
	v_min_f32_e32 v15, v105, v15
	s_waitcnt vmcnt(0)
	v_pk_mul_f32 v[160:161], v[160:161], v[176:177]
	v_pk_mul_f32 v[162:163], v[162:163], v[178:179]
	v_pk_mul_f32 v[164:165], v[164:165], v[180:181]
	v_pk_mul_f32 v[166:167], v[166:167], v[182:183]
	v_pk_mul_f32 v[168:169], v[168:169], v[184:185]
	v_pk_mul_f32 v[170:171], v[170:171], v[186:187]
	v_pk_mul_f32 v[172:173], v[172:173], v[188:189]
	v_pk_mul_f32 v[174:175], v[174:175], v[190:191]
	v_max3_f32 v192, |v160|, |v161|, |v162|
	v_max3_f32 v192, |v163|, |v164|, v192
	v_max3_f32 v192, |v165|, |v166|, v192
	v_max3_f32 v192, |v167|, |v168|, v192
	v_max3_f32 v192, |v169|, |v170|, v192
	v_max3_f32 v192, |v171|, |v172|, v192
	v_max3_f32 v192, |v173|, |v174|, v192
	v_max_f32_e64 v192, |v175|, v192
	s_nop 1
	v_mov_b32_dpp v193, v192 quad_perm:[1,0,3,2] row_mask:0xf bank_mask:0xf bound_ctrl:1
	v_max_f32_e32 v192, v192, v193
	s_nop 1
	v_mov_b32_dpp v193, v192 quad_perm:[2,3,0,1] row_mask:0xf bank_mask:0xf bound_ctrl:1
	v_max_f32_e32 v192, v192, v193
	s_nop 1
	v_mov_b32_dpp v193, v192 row_half_mirror row_mask:0xf bank_mask:0xf bound_ctrl:1
	v_max_f32_e32 v192, v192, v193
	s_nop 1
	v_mov_b32_dpp v193, v192 row_mirror row_mask:0xf bank_mask:0xf bound_ctrl:1
	v_max_f32_e32 v192, v192, v193
	v_mov_b32_e32 v193, v192
	s_nop 1
	v_permlane16_swap_b32_e32 v192, v193
	s_nop 1
	v_max_f32_e32 v192, v192, v193
	v_mov_b32_e32 v193, v192
	s_nop 1
	v_permlane32_swap_b32_e32 v192, v193
	s_nop 1
	v_max_f32_e32 v192, v192, v193
	v_max_f32_e32 v192, 0xda24260, v192
	v_mul_f32_e32 v194, 0x3e2aaaab, v192
	global_store_dword v214, v194, s[12:13]
	v_div_scale_f32 v195, s[26:27], v194, v194, 1.0
	v_rcp_f32_e32 v196, v195
	v_div_scale_f32 v204, vcc, 1.0, v194, 1.0
	v_fma_f32 v205, -v195, v196, 1.0
	v_fmac_f32_e32 v196, v205, v196
	v_mul_f32_e32 v205, v204, v196
	v_fma_f32 v206, -v195, v205, v204
	v_fmac_f32_e32 v205, v206, v196
	v_fma_f32 v195, -v195, v205, v204
	s_nop 0
	v_div_fmas_f32 v195, v195, v196, v205
	v_div_fixup_f32 v207, v195, v194, 1.0
	v_mul_f32_e32 v160, v207, v160
	v_mul_f32_e32 v161, v207, v161
	v_mul_f32_e32 v162, v207, v162
	v_mul_f32_e32 v163, v207, v163
	v_mul_f32_e32 v164, v207, v164
	v_mul_f32_e32 v165, v207, v165
	v_mul_f32_e32 v166, v207, v166
	v_mul_f32_e32 v167, v207, v167
	v_mul_f32_e32 v168, v207, v168
	v_mul_f32_e32 v169, v207, v169
	v_mul_f32_e32 v170, v207, v170
	v_mul_f32_e32 v171, v207, v171
	v_mul_f32_e32 v172, v207, v172
	v_mul_f32_e32 v173, v207, v173
	v_mul_f32_e32 v174, v207, v174
	v_mul_f32_e32 v175, v207, v175
	v_mov_b32_e32 v208, 0
	v_mov_b32_e32 v209, 0
	v_mov_b32_e32 v210, 0
	v_mov_b32_e32 v193, 0
	v_cvt_scalef32_pk_fp4_f32 v208, v160, v161, 1.0
	v_cvt_scalef32_pk_fp4_f32 v209, v164, v165, 1.0
	v_cvt_scalef32_pk_fp4_f32 v210, v168, v169, 1.0
	v_cvt_scalef32_pk_fp4_f32 v193, v172, v173, 1.0
	v_cvt_scalef32_pk_fp4_f32 v208, v162, v163, 1.0 op_sel:[0,0,1,0]
	v_cvt_scalef32_pk_fp4_f32 v209, v166, v167, 1.0 op_sel:[0,0,1,0]
	v_cvt_scalef32_pk_fp4_f32 v210, v170, v171, 1.0 op_sel:[0,0,1,0]
	v_cvt_scalef32_pk_fp4_f32 v193, v174, v175, 1.0 op_sel:[0,0,1,0]
	global_store_short v213, v208, s[10:11] nt
	s_add_u32 s14, s10, 0x200000
	s_addc_u32 s15, s11, 0
	global_store_short v213, v209, s[14:15] nt
	s_add_u32 s14, s10, 0x400000
	s_addc_u32 s15, s11, 0
	global_store_short v213, v210, s[14:15] nt
	s_add_u32 s14, s10, 0x600000
	s_addc_u32 s15, s11, 0
	global_store_short v213, v193, s[14:15] nt
	s_add_u32 s10, s10, 0x20000
	s_addc_u32 s11, s11, 0
	s_add_u32 s12, s12, 0x2000
	s_addc_u32 s13, s13, 0
	global_load_dwordx4 v[160:163], v212, s[8:9] offset:0 nt
	global_load_dwordx4 v[164:167], v212, s[8:9] offset:1024 nt
	global_load_dwordx4 v[168:171], v212, s[8:9] offset:2048 nt
	global_load_dwordx4 v[172:175], v212, s[8:9] offset:3072 nt
	s_add_u32 s8, s8, 0x800000
	s_addc_u32 s9, s9, 0
	ds_write_b8 v240, v125 offset:512
	ds_write_b8 v240, v117 offset:513
	ds_write_b8 v240, v102 offset:514
	ds_write_b8 v240, v49 offset:515
	ds_write_b8 v240, v22 offset:516
	ds_write_b8 v240, v43 offset:517
	ds_write_b8 v240, v96 offset:518
	ds_write_b8 v240, v90 offset:519
	ds_write_b8 v240, v66 offset:520
	ds_write_b8 v240, v24 offset:521
	ds_write_b8 v240, v36 offset:522
	ds_write_b8 v240, v37 offset:523
	ds_write_b8 v240, v63 offset:524
	ds_write_b8 v240, v67 offset:525
	ds_write_b8 v240, v21 offset:526
	ds_write_b8 v240, v15 offset:527
	v_cndmask_b32_e64 v0, v128, v125, s[4:5]
	v_cndmask_b32_e64 v17, v125, v128, s[4:5]
	v_cndmask_b32_e64 v1, v129, v117, s[4:5]
	v_cndmask_b32_e64 v18, v117, v129, s[4:5]
	v_cndmask_b32_e64 v2, v130, v102, s[4:5]
	v_cndmask_b32_e64 v19, v102, v130, s[4:5]
	v_cndmask_b32_e64 v3, v131, v49, s[4:5]
	v_cndmask_b32_e64 v20, v49, v131, s[4:5]
	v_cndmask_b32_e64 v4, v132, v22, s[4:5]
	v_cndmask_b32_e64 v23, v22, v132, s[4:5]
	v_cndmask_b32_e64 v5, v133, v43, s[4:5]
	v_cndmask_b32_e64 v25, v43, v133, s[4:5]
	v_cndmask_b32_e64 v6, v134, v96, s[4:5]
	v_cndmask_b32_e64 v26, v96, v134, s[4:5]
	v_cndmask_b32_e64 v7, v135, v90, s[4:5]
	v_cndmask_b32_e64 v27, v90, v135, s[4:5]
	v_cndmask_b32_e64 v8, v136, v66, s[4:5]
	v_cndmask_b32_e64 v28, v66, v136, s[4:5]
	v_cndmask_b32_e64 v9, v137, v24, s[4:5]
	v_cndmask_b32_e64 v29, v24, v137, s[4:5]
	v_cndmask_b32_e64 v10, v138, v36, s[4:5]
	v_cndmask_b32_e64 v30, v36, v138, s[4:5]
	v_cndmask_b32_e64 v11, v139, v37, s[4:5]
	v_cndmask_b32_e64 v31, v37, v139, s[4:5]
	v_cndmask_b32_e64 v12, v140, v63, s[4:5]
	v_cndmask_b32_e64 v32, v63, v140, s[4:5]
	v_cndmask_b32_e64 v13, v141, v67, s[4:5]
	v_cndmask_b32_e64 v33, v67, v141, s[4:5]
	v_cndmask_b32_e64 v14, v142, v21, s[4:5]
	v_cndmask_b32_e64 v34, v21, v142, s[4:5]
	v_cndmask_b32_e64 v16, v143, v15, s[4:5]
	v_cndmask_b32_e64 v35, v15, v143, s[4:5]
	v_and_b32_e32 v0, s6, v0
	v_and_b32_e32 v17, s6, v17
	v_and_b32_e32 v1, s6, v1
	v_and_b32_e32 v18, s6, v18
	v_and_b32_e32 v2, s6, v2
	v_and_b32_e32 v19, s6, v19
	v_and_b32_e32 v3, s6, v3
	v_and_b32_e32 v20, s6, v20
	v_and_b32_e32 v4, s6, v4
	v_and_b32_e32 v23, s6, v23
	v_and_b32_e32 v5, s6, v5
	v_and_b32_e32 v25, s6, v25
	v_and_b32_e32 v6, s6, v6
	v_and_b32_e32 v26, s6, v26
	v_and_b32_e32 v7, s6, v7
	v_and_b32_e32 v27, s6, v27
	v_and_b32_e32 v8, s6, v8
	v_and_b32_e32 v28, s6, v28
	v_and_b32_e32 v9, s6, v9
	v_and_b32_e32 v29, s6, v29
	v_and_b32_e32 v10, s6, v10
	v_and_b32_e32 v30, s6, v30
	v_and_b32_e32 v11, s6, v11
	v_and_b32_e32 v31, s6, v31
	v_and_b32_e32 v12, s6, v12
	v_and_b32_e32 v32, s6, v32
	v_and_b32_e32 v13, s6, v13
	v_and_b32_e32 v33, s6, v33
	v_and_b32_e32 v14, s6, v14
	v_and_b32_e32 v34, s6, v34
	v_and_b32_e32 v16, s6, v16
	v_and_b32_e32 v35, s6, v35
	v_add_f32_e32 v38, v0, v18
	v_and_or_b32 v38, v38, s7, 0
	v_add_f32_e32 v39, v0, v19
	v_and_or_b32 v39, v39, s7, 2
	v_add_f32_e32 v40, v0, v20
	v_and_or_b32 v40, v40, s7, 4
	v_add_f32_e32 v41, v0, v23
	v_and_or_b32 v41, v41, s7, 6
	v_add_f32_e32 v42, v0, v25
	v_and_or_b32 v42, v42, s7, 8
	v_add_f32_e32 v44, v0, v26
	v_and_or_b32 v44, v44, s7, 10
	v_add_f32_e32 v45, v0, v27
	v_and_or_b32 v45, v45, s7, 12
	v_add_f32_e32 v46, v0, v28
	v_and_or_b32 v46, v46, s7, 14
	v_add_f32_e32 v47, v0, v29
	v_and_or_b32 v47, v47, s7, 16
	v_add_f32_e32 v48, v0, v30
	v_and_or_b32 v48, v48, s7, 18
	v_add_f32_e32 v50, v0, v31
	v_and_or_b32 v50, v50, s7, 20
	v_add_f32_e32 v51, v0, v32
	v_and_or_b32 v51, v51, s7, 22
	v_add_f32_e32 v52, v0, v33
	v_and_or_b32 v52, v52, s7, 24
	v_add_f32_e32 v53, v0, v34
	v_and_or_b32 v53, v53, s7, 26
	v_add_f32_e32 v54, v0, v35
	v_and_or_b32 v54, v54, s7, 28
	v_add_f32_e32 v55, v1, v19
	v_and_or_b32 v55, v55, s7, 30
	v_add_f32_e32 v56, v1, v20
	v_and_or_b32 v56, v56, s7, 32
	v_add_f32_e32 v57, v1, v23
	v_and_or_b32 v57, v57, s7, 34
	v_add_f32_e32 v58, v1, v25
	v_and_or_b32 v58, v58, s7, 36
	v_add_f32_e32 v59, v1, v26
	v_and_or_b32 v59, v59, s7, 38
	v_add_f32_e32 v60, v1, v27
	v_and_or_b32 v60, v60, s7, 40
	v_add_f32_e32 v61, v2, v20
	v_and_or_b32 v61, v61, s7, 42
	v_add_f32_e32 v62, v2, v23
	v_and_or_b32 v62, v62, s7, 44
	v_add_f32_e32 v64, v0, v17
	v_and_or_b32 v64, v64, s7, 46
	v_cndmask_b32_e64 v64, v64, v244, s[4:5]
	v_add_f32_e32 v65, v1, v18
	v_and_or_b32 v65, v65, s7, 48
	v_cndmask_b32_e64 v65, v65, v244, s[4:5]
	v_add_f32_e32 v68, v2, v19
	v_and_or_b32 v68, v68, s7, 50
	v_cndmask_b32_e64 v68, v68, v244, s[4:5]
	v_add_f32_e32 v69, v3, v20
	v_and_or_b32 v69, v69, s7, 52
	v_cndmask_b32_e64 v69, v69, v244, s[4:5]
	v_max_f32_e32 v70, v38, v53
	v_min_f32_e32 v53, v38, v53
	v_max_f32_e32 v71, v39, v52
	v_min_f32_e32 v52, v39, v52
	v_max_f32_e32 v72, v40, v55
	v_min_f32_e32 v55, v40, v55
	v_max_f32_e32 v73, v41, v54
	v_min_f32_e32 v54, v41, v54
	v_max_f32_e32 v74, v42, v47
	v_min_f32_e32 v47, v42, v47
	v_max_f32_e32 v75, v44, v45
	v_min_f32_e32 v45, v44, v45
	v_max_f32_e32 v76, v46, v51
	v_min_f32_e32 v51, v46, v51
	v_max_f32_e32 v77, v48, v50
	v_min_f32_e32 v50, v48, v50
	v_max_f32_e32 v78, v70, v75
	v_min_f32_e32 v75, v70, v75
	v_max_f32_e32 v79, v71, v76
	v_min_f32_e32 v76, v71, v76
	v_max_f32_e32 v80, v72, v77
	v_min_f32_e32 v77, v72, v77
	v_max_f32_e32 v81, v73, v74
	v_min_f32_e32 v74, v73, v74
	v_max_f32_e32 v82, v45, v53
	v_min_f32_e32 v53, v45, v53
	v_max_f32_e32 v83, v47, v54
	v_min_f32_e32 v54, v47, v54
	v_max_f32_e32 v84, v50, v55
	v_min_f32_e32 v55, v50, v55
	v_max_f32_e32 v85, v51, v52
	v_min_f32_e32 v52, v51, v52
	v_max_f32_e32 v86, v78, v79
	v_min_f32_e32 v79, v78, v79
	v_max_f32_e32 v87, v80, v81
	v_min_f32_e32 v81, v80, v81
	v_max_f32_e32 v88, v74, v75
	v_min_f32_e32 v75, v74, v75
	v_max_f32_e32 v89, v82, v83
	v_min_f32_e32 v83, v82, v83
	v_max_f32_e32 v91, v76, v77
	v_min_f32_e32 v77, v76, v77
	v_max_f32_e32 v92, v84, v85
	v_min_f32_e32 v85, v84, v85
	v_max_f32_e32 v93, v52, v53
	v_min_f32_e32 v53, v52, v53
	v_max_f32_e32 v94, v54, v55
	v_min_f32_e32 v55, v54, v55
	v_max_f32_e32 v95, v86, v87
	v_min_f32_e32 v87, v86, v87
	v_max_f32_e32 v97, v79, v81
	v_min_f32_e32 v81, v79, v81
	v_max_f32_e32 v98, v88, v92
	v_min_f32_e32 v92, v88, v92
	v_max_f32_e32 v99, v75, v85
	v_min_f32_e32 v85, v75, v85
	v_max_f32_e32 v100, v89, v91
	v_min_f32_e32 v91, v89, v91
	v_max_f32_e32 v101, v83, v77
	v_min_f32_e32 v77, v83, v77
	v_max_f32_e32 v103, v93, v94
	v_min_f32_e32 v94, v93, v94
	v_max_f32_e32 v104, v53, v55
	v_min_f32_e32 v55, v53, v55
	v_max_f32_e32 v105, v97, v87
	v_min_f32_e32 v87, v97, v87
	v_max_f32_e32 v106, v81, v103
	v_min_f32_e32 v103, v81, v103
	v_max_f32_e32 v107, v98, v100
	v_min_f32_e32 v100, v98, v100
	v_max_f32_e32 v108, v99, v91
	v_min_f32_e32 v91, v99, v91
	v_max_f32_e32 v109, v101, v92
	v_min_f32_e32 v92, v101, v92
	v_max_f32_e32 v110, v77, v85
	v_min_f32_e32 v85, v77, v85
	v_max_f32_e32 v111, v104, v94
	v_min_f32_e32 v94, v104, v94
	v_max_f32_e32 v112, v105, v107
	v_min_f32_e32 v107, v105, v107
	v_max_f32_e32 v113, v87, v100
	v_min_f32_e32 v100, v87, v100
	v_max_f32_e32 v114, v108, v109
	v_min_f32_e32 v109, v108, v109
	v_max_f32_e32 v115, v91, v92
	v_min_f32_e32 v92, v91, v92
	v_max_f32_e32 v116, v110, v111
	v_min_f32_e32 v111, v110, v111
	v_max_f32_e32 v118, v85, v94
	v_min_f32_e32 v94, v85, v94
	v_max_f32_e32 v119, v113, v107
	v_min_f32_e32 v107, v113, v107
	v_max_f32_e32 v120, v106, v100
	v_min_f32_e32 v100, v106, v100
	v_max_f32_e32 v121, v116, v103
	v_min_f32_e32 v103, v116, v103
	v_max_f32_e32 v122, v118, v111
	v_min_f32_e32 v111, v118, v111
	v_max_f32_e32 v123, v120, v114
	v_min_f32_e32 v114, v120, v114
	v_max_f32_e32 v124, v100, v109
	v_min_f32_e32 v109, v100, v109
	v_max_f32_e32 v126, v115, v121
	v_min_f32_e32 v121, v115, v121
	v_max_f32_e32 v127, v92, v103
	v_min_f32_e32 v103, v92, v103
	v_max_f32_e32 v144, v123, v107
	v_min_f32_e32 v107, v123, v107
	v_max_f32_e32 v145, v114, v124
	v_min_f32_e32 v124, v114, v124
	v_max_f32_e32 v146, v126, v109
	v_min_f32_e32 v109, v126, v109
	v_max_f32_e32 v147, v121, v127
	v_min_f32_e32 v127, v121, v127
	v_max_f32_e32 v148, v122, v103
	v_min_f32_e32 v103, v122, v103
	v_max_f32_e32 v149, v124, v146
	v_min_f32_e32 v146, v124, v146
	v_max_f32_e32 v150, v109, v147
	v_min_f32_e32 v147, v109, v147
	v_max_f32_e32 v151, v60, v65
	v_min_f32_e32 v65, v60, v65
	v_max_f32_e32 v249, v61, v62
	v_min_f32_e32 v62, v61, v62
	v_max_f32_e32 v250, v68, v69
	v_min_f32_e32 v69, v68, v69
	v_max_f32_e32 v251, v56, v249
	v_min_f32_e32 v249, v56, v249
	v_max_f32_e32 v252, v57, v64
	v_min_f32_e32 v64, v57, v64
	v_max_f32_e32 v253, v58, v250
	v_min_f32_e32 v250, v58, v250
	v_max_f32_e32 v254, v59, v151
	v_min_f32_e32 v151, v59, v151
	v_max_f32_e32 v255, v251, v252
	v_min_f32_e32 v252, v251, v252
	v_max_f32_e32 v128, v253, v254
	v_min_f32_e32 v254, v253, v254
	v_max_f32_e32 v129, v151, v249
	v_min_f32_e32 v249, v151, v249
	v_max_f32_e32 v130, v62, v65
	v_min_f32_e32 v65, v62, v65
	v_max_f32_e32 v131, v64, v250
	v_min_f32_e32 v250, v64, v250
	v_max_f32_e32 v132, v255, v128
	v_min_f32_e32 v128, v255, v128
	v_max_f32_e32 v133, v252, v254
	v_min_f32_e32 v254, v252, v254
	v_max_f32_e32 v134, v129, v69
	v_min_f32_e32 v69, v129, v69
	v_max_f32_e32 v135, v130, v131
	v_min_f32_e32 v131, v130, v131
	v_max_f32_e32 v136, v65, v250
	v_min_f32_e32 v250, v65, v250
	v_max_f32_e32 v137, v133, v128
	v_min_f32_e32 v128, v133, v128
	v_max_f32_e32 v138, v134, v135
	v_min_f32_e32 v135, v134, v135
	v_max_f32_e32 v139, v249, v131
	v_min_f32_e32 v131, v249, v131
	v_max_f32_e32 v140, v136, v69
	v_min_f32_e32 v69, v136, v69
	v_max_f32_e32 v141, v137, v138
	v_min_f32_e32 v138, v137, v138
	v_max_f32_e32 v142, v128, v135
	v_min_f32_e32 v135, v128, v135
	v_max_f32_e32 v143, v139, v140
	v_min_f32_e32 v140, v139, v140
	v_max_f32_e32 v125, v131, v69
	v_min_f32_e32 v69, v131, v69
	v_max_f32_e32 v117, v142, v138
	v_min_f32_e32 v138, v142, v138
	v_max_f32_e32 v102, v254, v135
	v_min_f32_e32 v135, v254, v135
	v_max_f32_e32 v49, v102, v143
	v_min_f32_e32 v143, v102, v143
	v_max_f32_e32 v22, v135, v140
	v_min_f32_e32 v140, v135, v140
	v_max_f32_e32 v43, v125, v250
	v_min_f32_e32 v250, v125, v250
	v_max_f32_e32 v96, v49, v138
	v_min_f32_e32 v138, v49, v138
	v_max_f32_e32 v90, v143, v22
	v_min_f32_e32 v22, v143, v22
	v_max_f32_e32 v66, v43, v140
	v_min_f32_e32 v140, v43, v140
	v_max_f32_e32 v24, v250, v69
	v_min_f32_e32 v69, v250, v69
	v_max_f32_e32 v36, v22, v66
	v_min_f32_e32 v66, v22, v66
	v_max_f32_e32 v37, v140, v24
	v_min_f32_e32 v24, v140, v24
	s_waitcnt vmcnt(0)
	v_pk_mul_f32 v[160:161], v[160:161], v[176:177]
	v_pk_mul_f32 v[162:163], v[162:163], v[178:179]
	v_pk_mul_f32 v[164:165], v[164:165], v[180:181]
	v_pk_mul_f32 v[166:167], v[166:167], v[182:183]
	v_pk_mul_f32 v[168:169], v[168:169], v[184:185]
	v_pk_mul_f32 v[170:171], v[170:171], v[186:187]
	v_pk_mul_f32 v[172:173], v[172:173], v[188:189]
	v_pk_mul_f32 v[174:175], v[174:175], v[190:191]
	v_max3_f32 v192, |v160|, |v161|, |v162|
	v_max3_f32 v192, |v163|, |v164|, v192
	v_max3_f32 v192, |v165|, |v166|, v192
	v_max3_f32 v192, |v167|, |v168|, v192
	v_max3_f32 v192, |v169|, |v170|, v192
	v_max3_f32 v192, |v171|, |v172|, v192
	v_max3_f32 v192, |v173|, |v174|, v192
	v_max_f32_e64 v192, |v175|, v192
	s_nop 1
	v_mov_b32_dpp v193, v192 quad_perm:[1,0,3,2] row_mask:0xf bank_mask:0xf bound_ctrl:1
	v_max_f32_e32 v192, v192, v193
	s_nop 1
	v_mov_b32_dpp v193, v192 quad_perm:[2,3,0,1] row_mask:0xf bank_mask:0xf bound_ctrl:1
	v_max_f32_e32 v192, v192, v193
	s_nop 1
	v_mov_b32_dpp v193, v192 row_half_mirror row_mask:0xf bank_mask:0xf bound_ctrl:1
	v_max_f32_e32 v192, v192, v193
	s_nop 1
	v_mov_b32_dpp v193, v192 row_mirror row_mask:0xf bank_mask:0xf bound_ctrl:1
	v_max_f32_e32 v192, v192, v193
	v_mov_b32_e32 v193, v192
	s_nop 1
	v_permlane16_swap_b32_e32 v192, v193
	s_nop 1
	v_max_f32_e32 v192, v192, v193
	v_mov_b32_e32 v193, v192
	s_nop 1
	v_permlane32_swap_b32_e32 v192, v193
	s_nop 1
	v_max_f32_e32 v192, v192, v193
	v_max_f32_e32 v192, 0xda24260, v192
	v_mul_f32_e32 v194, 0x3e2aaaab, v192
	global_store_dword v214, v194, s[12:13]
	v_div_scale_f32 v195, s[26:27], v194, v194, 1.0
	v_rcp_f32_e32 v196, v195
	v_div_scale_f32 v204, vcc, 1.0, v194, 1.0
	v_fma_f32 v205, -v195, v196, 1.0
	v_fmac_f32_e32 v196, v205, v196
	v_mul_f32_e32 v205, v204, v196
	v_fma_f32 v206, -v195, v205, v204
	v_fmac_f32_e32 v205, v206, v196
	v_fma_f32 v195, -v195, v205, v204
	s_nop 0
	v_div_fmas_f32 v195, v195, v196, v205
	v_div_fixup_f32 v207, v195, v194, 1.0
	v_mul_f32_e32 v160, v207, v160
	v_mul_f32_e32 v161, v207, v161
	v_mul_f32_e32 v162, v207, v162
	v_mul_f32_e32 v163, v207, v163
	v_mul_f32_e32 v164, v207, v164
	v_mul_f32_e32 v165, v207, v165
	v_mul_f32_e32 v166, v207, v166
	v_mul_f32_e32 v167, v207, v167
	v_mul_f32_e32 v168, v207, v168
	v_mul_f32_e32 v169, v207, v169
	v_mul_f32_e32 v170, v207, v170
	v_mul_f32_e32 v171, v207, v171
	v_mul_f32_e32 v172, v207, v172
	v_mul_f32_e32 v173, v207, v173
	v_mul_f32_e32 v174, v207, v174
	v_mul_f32_e32 v175, v207, v175
	v_mov_b32_e32 v208, 0
	v_mov_b32_e32 v209, 0
	v_mov_b32_e32 v210, 0
	v_mov_b32_e32 v193, 0
	v_cvt_scalef32_pk_fp4_f32 v208, v160, v161, 1.0
	v_cvt_scalef32_pk_fp4_f32 v209, v164, v165, 1.0
	v_cvt_scalef32_pk_fp4_f32 v210, v168, v169, 1.0
	v_cvt_scalef32_pk_fp4_f32 v193, v172, v173, 1.0
	v_cvt_scalef32_pk_fp4_f32 v208, v162, v163, 1.0 op_sel:[0,0,1,0]
	v_cvt_scalef32_pk_fp4_f32 v209, v166, v167, 1.0 op_sel:[0,0,1,0]
	v_cvt_scalef32_pk_fp4_f32 v210, v170, v171, 1.0 op_sel:[0,0,1,0]
	v_cvt_scalef32_pk_fp4_f32 v193, v174, v175, 1.0 op_sel:[0,0,1,0]
	global_store_short v213, v208, s[10:11] nt
	s_add_u32 s14, s10, 0x200000
	s_addc_u32 s15, s11, 0
	global_store_short v213, v209, s[14:15] nt
	s_add_u32 s14, s10, 0x400000
	s_addc_u32 s15, s11, 0
	global_store_short v213, v210, s[14:15] nt
	s_add_u32 s14, s10, 0x600000
	s_addc_u32 s15, s11, 0
	global_store_short v213, v193, s[14:15] nt
	s_add_u32 s10, s10, 0x20000
	s_addc_u32 s11, s11, 0
	s_add_u32 s12, s12, 0x2000
	s_addc_u32 s13, s13, 0
	global_load_dwordx4 v[160:163], v212, s[8:9] offset:0 nt
	global_load_dwordx4 v[164:167], v212, s[8:9] offset:1024 nt
	global_load_dwordx4 v[168:171], v212, s[8:9] offset:2048 nt
	global_load_dwordx4 v[172:175], v212, s[8:9] offset:3072 nt
	s_add_u32 s8, s8, 0x800000
	s_addc_u32 s9, s9, 0
	v_max_f32_e32 v145, v145, v69
	v_max_f32_e32 v149, v149, v24
	v_max_f32_e32 v146, v146, v37
	v_max_f32_e32 v150, v150, v66
	v_max_f32_e32 v147, v147, v36
	v_max_f32_e32 v127, v127, v90
	v_max_f32_e32 v148, v148, v138
	v_max_f32_e32 v103, v103, v96
	v_max_f32_e32 v111, v111, v117
	v_max_f32_e32 v94, v94, v141
	v_max_f32_e32 v55, v55, v132
	v_max_f32_e32 v63, v95, v150
	v_min_f32_e32 v150, v95, v150
	v_max_f32_e32 v67, v112, v147
	v_min_f32_e32 v147, v112, v147
	v_max_f32_e32 v21, v119, v127
	v_min_f32_e32 v127, v119, v127
	v_max_f32_e32 v15, v144, v148
	v_min_f32_e32 v148, v144, v148
	v_max_f32_e32 v0, v107, v103
	v_min_f32_e32 v103, v107, v103
	v_max_f32_e32 v1, v145, v111
	v_min_f32_e32 v111, v145, v111
	v_max_f32_e32 v2, v149, v94
	v_min_f32_e32 v94, v149, v94
	v_max_f32_e32 v3, v146, v55
	v_min_f32_e32 v55, v146, v55
	v_max_f32_e32 v4, v63, v0
	v_min_f32_e32 v0, v63, v0
	v_max_f32_e32 v5, v67, v1
	v_min_f32_e32 v1, v67, v1
	v_max_f32_e32 v6, v21, v2
	v_min_f32_e32 v2, v21, v2
	v_max_f32_e32 v7, v15, v3
	v_min_f32_e32 v3, v15, v3
	v_max_f32_e32 v8, v150, v103
	v_min_f32_e32 v103, v150, v103
	v_max_f32_e32 v9, v147, v111
	v_min_f32_e32 v111, v147, v111
	v_max_f32_e32 v10, v127, v94
	v_min_f32_e32 v94, v127, v94
	v_max_f32_e32 v11, v148, v55
	v_min_f32_e32 v55, v148, v55
	v_max_f32_e32 v12, v4, v6
	v_min_f32_e32 v6, v4, v6
	v_max_f32_e32 v13, v5, v7
	v_min_f32_e32 v7, v5, v7
	v_max_f32_e32 v14, v0, v2
	v_min_f32_e32 v2, v0, v2
	v_max_f32_e32 v16, v1, v3
	v_min_f32_e32 v3, v1, v3
	v_max_f32_e32 v17, v8, v10
	v_min_f32_e32 v10, v8, v10
	v_max_f32_e32 v18, v9, v11
	v_min_f32_e32 v11, v9, v11
	v_max_f32_e32 v19, v103, v94
	v_min_f32_e32 v94, v103, v94
	v_max_f32_e32 v20, v111, v55
	v_min_f32_e32 v55, v111, v55
	v_max_f32_e32 v23, v12, v13
	v_min_f32_e32 v13, v12, v13
	v_max_f32_e32 v25, v6, v7
	v_min_f32_e32 v7, v6, v7
	v_max_f32_e32 v26, v14, v16
	v_min_f32_e32 v16, v14, v16
	v_max_f32_e32 v27, v2, v3
	v_min_f32_e32 v3, v2, v3
	v_max_f32_e32 v28, v17, v18
	v_min_f32_e32 v18, v17, v18
	v_max_f32_e32 v29, v10, v11
	v_min_f32_e32 v11, v10, v11
	v_max_f32_e32 v30, v19, v20
	v_min_f32_e32 v20, v19, v20
	v_max_f32_e32 v31, v94, v55
	v_min_f32_e32 v55, v94, v55
	v_or_b32_e32 v23, v23, v245
	v_or_b32_e32 v13, v13, v245
	v_or_b32_e32 v25, v25, v245
	v_or_b32_e32 v7, v7, v245
	v_or_b32_e32 v26, v26, v245
	v_or_b32_e32 v16, v16, v245
	v_or_b32_e32 v27, v27, v245
	v_or_b32_e32 v3, v3, v245
	v_or_b32_e32 v28, v28, v245
	v_or_b32_e32 v18, v18, v245
	v_or_b32_e32 v29, v29, v245
	v_or_b32_e32 v11, v11, v245
	v_or_b32_e32 v30, v30, v245
	v_or_b32_e32 v20, v20, v245
	v_or_b32_e32 v31, v31, v245
	v_or_b32_e32 v55, v55, v245
	v_mov_b32_e32 v32, v23
	v_mov_b32_e32 v33, v13
	v_mov_b32_e32 v34, v25
	v_mov_b32_e32 v35, v7
	v_mov_b32_e32 v38, v26
	v_mov_b32_e32 v39, v16
	v_mov_b32_e32 v40, v27
	v_mov_b32_e32 v41, v3
	v_mov_b32_e32 v42, v28
	v_mov_b32_e32 v44, v18
	v_mov_b32_e32 v46, v29
	v_mov_b32_e32 v48, v11
	v_mov_b32_e32 v70, v30
	v_mov_b32_e32 v71, v20
	v_mov_b32_e32 v72, v31
	v_mov_b32_e32 v73, v55
	s_nop 1
	v_permlane32_swap_b32_e32 v23, v32
	v_permlane32_swap_b32_e32 v13, v33
	v_permlane32_swap_b32_e32 v25, v34
	v_permlane32_swap_b32_e32 v7, v35
	v_permlane32_swap_b32_e32 v26, v38
	v_permlane32_swap_b32_e32 v16, v39
	v_permlane32_swap_b32_e32 v27, v40
	v_permlane32_swap_b32_e32 v3, v41
	v_permlane32_swap_b32_e32 v28, v42
	v_permlane32_swap_b32_e32 v18, v44
	v_permlane32_swap_b32_e32 v29, v46
	v_permlane32_swap_b32_e32 v11, v48
	v_permlane32_swap_b32_e32 v30, v70
	v_permlane32_swap_b32_e32 v20, v71
	v_permlane32_swap_b32_e32 v31, v72
	v_permlane32_swap_b32_e32 v55, v73
	s_nop 1
	v_max_f32_e32 v23, v23, v73
	v_max_f32_e32 v13, v13, v72
	v_max_f32_e32 v25, v25, v71
	v_max_f32_e32 v7, v7, v70
	v_max_f32_e32 v26, v26, v48
	v_max_f32_e32 v16, v16, v46
	v_max_f32_e32 v27, v27, v44
	v_max_f32_e32 v3, v3, v42
	v_max_f32_e32 v28, v28, v41
	v_max_f32_e32 v18, v18, v40
	v_max_f32_e32 v29, v29, v39
	v_max_f32_e32 v11, v11, v38
	v_max_f32_e32 v30, v30, v35
	v_max_f32_e32 v20, v20, v34
	v_max_f32_e32 v31, v31, v33
	v_max_f32_e32 v55, v55, v32
	v_max_f32_e32 v45, v23, v28
	v_min_f32_e32 v28, v23, v28
	v_max_f32_e32 v47, v13, v18
	v_min_f32_e32 v18, v13, v18
	v_max_f32_e32 v50, v25, v29
	v_min_f32_e32 v29, v25, v29
	v_max_f32_e32 v51, v7, v11
	v_min_f32_e32 v11, v7, v11
	v_max_f32_e32 v78, v26, v30
	v_min_f32_e32 v30, v26, v30
	v_max_f32_e32 v80, v16, v20
	v_min_f32_e32 v20, v16, v20
	v_max_f32_e32 v74, v27, v31
	v_min_f32_e32 v31, v27, v31
	v_max_f32_e32 v82, v3, v55
	v_min_f32_e32 v55, v3, v55
	v_max_f32_e32 v76, v45, v78
	v_min_f32_e32 v78, v45, v78
	v_max_f32_e32 v84, v47, v80
	v_min_f32_e32 v80, v47, v80
	v_max_f32_e32 v52, v50, v74
	v_min_f32_e32 v74, v50, v74
	v_max_f32_e32 v54, v51, v82
	v_min_f32_e32 v82, v51, v82
	v_max_f32_e32 v86, v28, v30
	v_min_f32_e32 v30, v28, v30
	v_max_f32_e32 v79, v18, v20
	v_min_f32_e32 v20, v18, v20
	v_max_f32_e32 v88, v29, v31
	v_min_f32_e32 v31, v29, v31
	v_max_f32_e32 v75, v11, v55
	v_min_f32_e32 v55, v11, v55
	v_max_f32_e32 v89, v76, v52
	v_min_f32_e32 v52, v76, v52
	v_max_f32_e32 v83, v84, v54
	v_min_f32_e32 v54, v84, v54
	v_max_f32_e32 v93, v78, v74
	v_min_f32_e32 v74, v78, v74
	v_max_f32_e32 v53, v80, v82
	v_min_f32_e32 v82, v80, v82
	v_max_f32_e32 v97, v86, v88
	v_min_f32_e32 v88, v86, v88
	v_max_f32_e32 v81, v79, v75
	v_min_f32_e32 v75, v79, v75
	v_max_f32_e32 v98, v30, v31
	v_min_f32_e32 v31, v30, v31
	v_max_f32_e32 v99, v20, v55
	v_min_f32_e32 v55, v20, v55
	v_max_f32_e32 v101, v89, v83
	v_min_f32_e32 v83, v89, v83
	v_max_f32_e32 v77, v52, v54
	v_min_f32_e32 v54, v52, v54
	v_max_f32_e32 v104, v93, v53
	v_min_f32_e32 v53, v93, v53
	v_max_f32_e32 v105, v74, v82
	v_min_f32_e32 v82, v74, v82
	v_max_f32_e32 v87, v97, v81
	v_min_f32_e32 v81, v97, v81
	v_max_f32_e32 v108, v88, v75
	v_min_f32_e32 v75, v88, v75
	v_max_f32_e32 v91, v98, v99
	v_min_f32_e32 v99, v98, v99
	v_max_f32_e32 v110, v31, v55
	v_min_f32_e32 v55, v31, v55
	v_and_b32_e32 v85, s7, v101
	v_cndmask_b32_e64 v113, v101, v87, s[4:5]
	v_cndmask_b32_e64 v106, v83, v81, s[4:5]
	v_cndmask_b32_e64 v116, v77, v108, s[4:5]
	v_cndmask_b32_e64 v118, v54, v75, s[4:5]
	v_cndmask_b32_e64 v120, v104, v91, s[4:5]
	v_cndmask_b32_e64 v100, v53, v99, s[4:5]
	v_cndmask_b32_e64 v115, v105, v110, s[4:5]
	v_cndmask_b32_e64 v92, v82, v55, s[4:5]
	v_and_or_b32 v123, v113, 63, v246
	ds_read_u8 v123, v123
	v_and_or_b32 v114, v106, 63, v246
	ds_read_u8 v114, v114
	v_and_or_b32 v126, v116, 63, v246
	ds_read_u8 v126, v126
	v_and_or_b32 v121, v118, 63, v246
	ds_read_u8 v121, v121
	v_and_or_b32 v122, v120, 63, v246
	ds_read_u8 v122, v122
	v_and_or_b32 v124, v100, 63, v246
	ds_read_u8 v124, v124
	v_and_or_b32 v109, v115, 63, v246
	ds_read_u8 v109, v109
	v_and_or_b32 v60, v92, 63, v246
	ds_read_u8 v60, v60
	v_and_b32_e32 v113, s7, v113
	v_sub_f32_e32 v113, v113, v85
	v_mul_f32_e32 v113, 0x3fb8aa3b, v113
	v_exp_f32_e32 v113, v113
	v_and_b32_e32 v106, s7, v106
	v_sub_f32_e32 v106, v106, v85
	v_mul_f32_e32 v106, 0x3fb8aa3b, v106
	v_exp_f32_e32 v106, v106
	v_and_b32_e32 v116, s7, v116
	v_sub_f32_e32 v116, v116, v85
	v_mul_f32_e32 v116, 0x3fb8aa3b, v116
	v_exp_f32_e32 v116, v116
	v_and_b32_e32 v118, s7, v118
	v_sub_f32_e32 v118, v118, v85
	v_mul_f32_e32 v118, 0x3fb8aa3b, v118
	v_exp_f32_e32 v118, v118
	v_and_b32_e32 v120, s7, v120
	v_sub_f32_e32 v120, v120, v85
	v_mul_f32_e32 v120, 0x3fb8aa3b, v120
	v_exp_f32_e32 v120, v120
	v_and_b32_e32 v100, s7, v100
	v_sub_f32_e32 v100, v100, v85
	v_mul_f32_e32 v100, 0x3fb8aa3b, v100
	v_exp_f32_e32 v100, v100
	v_and_b32_e32 v115, s7, v115
	v_sub_f32_e32 v115, v115, v85
	v_mul_f32_e32 v115, 0x3fb8aa3b, v115
	v_exp_f32_e32 v115, v115
	v_and_b32_e32 v92, s7, v92
	v_sub_f32_e32 v92, v92, v85
	v_mul_f32_e32 v92, 0x3fb8aa3b, v92
	v_exp_f32_e32 v92, v92
	s_nop 0
	v_add_f32_e32 v85, v113, v106
	v_add_f32_e32 v85, v85, v116
	v_add_f32_e32 v85, v85, v118
	v_add_f32_e32 v85, v85, v120
	v_add_f32_e32 v85, v85, v100
	v_add_f32_e32 v85, v85, v115
	v_add_f32_e32 v85, v85, v92
	v_mov_b32_e32 v61, v85
	s_nop 1
	v_permlane32_swap_b32_e32 v85, v61
	s_nop 1
	v_add_f32_e32 v85, v85, v61
	s_waitcnt lgkmcnt(0)
	v_bfe_u32 v68, v123, 4, 4
	v_or_b32_e32 v68, v68, v240
	v_and_or_b32 v123, v123, 15, v240
	ds_read_u8 v68, v68
	ds_read_u8 v123, v123 offset:512
	v_bfe_u32 v56, v114, 4, 4
	v_or_b32_e32 v56, v56, v240
	v_and_or_b32 v114, v114, 15, v240
	ds_read_u8 v56, v56
	ds_read_u8 v114, v114 offset:512
	v_bfe_u32 v57, v126, 4, 4
	v_or_b32_e32 v57, v57, v240
	v_and_or_b32 v126, v126, 15, v240
	ds_read_u8 v57, v57
	ds_read_u8 v126, v126 offset:512
	v_bfe_u32 v58, v121, 4, 4
	v_or_b32_e32 v58, v58, v240
	v_and_or_b32 v121, v121, 15, v240
	ds_read_u8 v58, v58
	ds_read_u8 v121, v121 offset:512
	v_bfe_u32 v59, v122, 4, 4
	v_or_b32_e32 v59, v59, v240
	v_and_or_b32 v122, v122, 15, v240
	ds_read_u8 v59, v59
	ds_read_u8 v122, v122 offset:512
	v_bfe_u32 v251, v124, 4, 4
	v_or_b32_e32 v251, v251, v240
	v_and_or_b32 v124, v124, 15, v240
	ds_read_u8 v251, v251
	ds_read_u8 v124, v124 offset:512
	v_bfe_u32 v253, v109, 4, 4
	v_or_b32_e32 v253, v253, v240
	v_and_or_b32 v109, v109, 15, v240
	ds_read_u8 v253, v253
	ds_read_u8 v109, v109 offset:512
	v_bfe_u32 v151, v60, 4, 4
	v_or_b32_e32 v151, v151, v240
	v_and_or_b32 v60, v60, 15, v240
	ds_read_u8 v151, v151
	ds_read_u8 v60, v60 offset:512
	v_div_scale_f32 v134, s[26:27], v85, v85, v113
	v_rcp_f32_e32 v249, v134
	s_nop 0
	v_fma_f32 v136, -v134, v249, 1.0
	v_fmac_f32_e32 v249, v136, v249
	v_div_scale_f32 v136, vcc, v113, v85, v113
	v_mul_f32_e32 v137, v136, v249
	v_fma_f32 v62, -v134, v137, v136
	v_fmac_f32_e32 v137, v62, v249
	v_fma_f32 v136, -v134, v137, v136
	s_nop 0
	v_div_fmas_f32 v136, v136, v249, v137
	v_div_fixup_f32 v62, v136, v85, v113
	v_div_scale_f32 v134, s[26:27], v85, v85, v106
	v_rcp_f32_e32 v249, v134
	s_nop 0
	v_fma_f32 v136, -v134, v249, 1.0
	v_fmac_f32_e32 v249, v136, v249
	v_div_scale_f32 v136, vcc, v106, v85, v106
	v_mul_f32_e32 v137, v136, v249
	v_fma_f32 v64, -v134, v137, v136
	v_fmac_f32_e32 v137, v64, v249
	v_fma_f32 v136, -v134, v137, v136
	s_nop 0
	v_div_fmas_f32 v136, v136, v249, v137
	v_div_fixup_f32 v64, v136, v85, v106
	v_div_scale_f32 v134, s[26:27], v85, v85, v116
	v_rcp_f32_e32 v249, v134
	s_nop 0
	v_fma_f32 v136, -v134, v249, 1.0
	v_fmac_f32_e32 v249, v136, v249
	v_div_scale_f32 v136, vcc, v116, v85, v116
	v_mul_f32_e32 v137, v136, v249
	v_fma_f32 v255, -v134, v137, v136
	v_fmac_f32_e32 v137, v255, v249
	v_fma_f32 v136, -v134, v137, v136
	s_nop 0
	v_div_fmas_f32 v136, v136, v249, v137
	v_div_fixup_f32 v255, v136, v85, v116
	v_div_scale_f32 v134, s[26:27], v85, v85, v118
	v_rcp_f32_e32 v249, v134
	s_nop 0
	v_fma_f32 v136, -v134, v249, 1.0
	v_fmac_f32_e32 v249, v136, v249
	v_div_scale_f32 v136, vcc, v118, v85, v118
	v_mul_f32_e32 v137, v136, v249
	v_fma_f32 v252, -v134, v137, v136
	v_fmac_f32_e32 v137, v252, v249
	v_fma_f32 v136, -v134, v137, v136
	s_nop 0
	v_div_fmas_f32 v136, v136, v249, v137
	v_div_fixup_f32 v252, v136, v85, v118
	v_div_scale_f32 v134, s[26:27], v85, v85, v120
	v_rcp_f32_e32 v249, v134
	s_nop 0
	v_fma_f32 v136, -v134, v249, 1.0
	v_fmac_f32_e32 v249, v136, v249
	v_div_scale_f32 v136, vcc, v120, v85, v120
	v_mul_f32_e32 v137, v136, v249
	v_fma_f32 v129, -v134, v137, v136
	v_fmac_f32_e32 v137, v129, v249
	v_fma_f32 v136, -v134, v137, v136
	s_nop 0
	v_div_fmas_f32 v136, v136, v249, v137
	v_div_fixup_f32 v129, v136, v85, v120
	v_div_scale_f32 v134, s[26:27], v85, v85, v100
	v_rcp_f32_e32 v249, v134
	s_nop 0
	v_fma_f32 v136, -v134, v249, 1.0
	v_fmac_f32_e32 v249, v136, v249
	v_div_scale_f32 v136, vcc, v100, v85, v100
	v_mul_f32_e32 v137, v136, v249
	v_fma_f32 v130, -v134, v137, v136
	v_fmac_f32_e32 v137, v130, v249
	v_fma_f32 v136, -v134, v137, v136
	s_nop 0
	v_div_fmas_f32 v136, v136, v249, v137
	v_div_fixup_f32 v130, v136, v85, v100
	v_div_scale_f32 v134, s[26:27], v85, v85, v115
	v_rcp_f32_e32 v249, v134
	s_nop 0
	v_fma_f32 v136, -v134, v249, 1.0
	v_fmac_f32_e32 v249, v136, v249
	v_div_scale_f32 v136, vcc, v115, v85, v115
	v_mul_f32_e32 v137, v136, v249
	v_fma_f32 v65, -v134, v137, v136
	v_fmac_f32_e32 v137, v65, v249
	v_fma_f32 v136, -v134, v137, v136
	s_nop 0
	v_div_fmas_f32 v136, v136, v249, v137
	v_div_fixup_f32 v65, v136, v85, v115
	v_div_scale_f32 v134, s[26:27], v85, v85, v92
	v_rcp_f32_e32 v249, v134
	s_nop 0
	v_fma_f32 v136, -v134, v249, 1.0
	v_fmac_f32_e32 v249, v136, v249
	v_div_scale_f32 v136, vcc, v92, v85, v92
	v_mul_f32_e32 v137, v136, v249
	v_fma_f32 v133, -v134, v137, v136
	v_fmac_f32_e32 v137, v133, v249
	v_fma_f32 v136, -v134, v137, v136
	s_nop 0
	v_div_fmas_f32 v136, v136, v249, v137
	v_div_fixup_f32 v133, v136, v85, v92
	s_waitcnt lgkmcnt(0)
	v_and_b32_e32 v68, 0x7f, v68
	v_and_b32_e32 v123, 0x7f, v123
	v_lshl_or_b32 v68, v68, 7, v123
	v_xor_b32_e32 v68, 0x3fff, v68
	v_and_b32_e32 v56, 0x7f, v56
	v_and_b32_e32 v114, 0x7f, v114
	v_lshl_or_b32 v56, v56, 7, v114
	v_xor_b32_e32 v56, 0x3fff, v56
	v_and_b32_e32 v57, 0x7f, v57
	v_and_b32_e32 v126, 0x7f, v126
	v_lshl_or_b32 v57, v57, 7, v126
	v_xor_b32_e32 v57, 0x3fff, v57
	v_and_b32_e32 v58, 0x7f, v58
	v_and_b32_e32 v121, 0x7f, v121
	v_lshl_or_b32 v58, v58, 7, v121
	v_xor_b32_e32 v58, 0x3fff, v58
	v_and_b32_e32 v59, 0x7f, v59
	v_and_b32_e32 v122, 0x7f, v122
	v_lshl_or_b32 v59, v59, 7, v122
	v_xor_b32_e32 v59, 0x3fff, v59
	v_and_b32_e32 v251, 0x7f, v251
	v_and_b32_e32 v124, 0x7f, v124
	v_lshl_or_b32 v251, v251, 7, v124
	v_xor_b32_e32 v251, 0x3fff, v251
	v_and_b32_e32 v253, 0x7f, v253
	v_and_b32_e32 v109, 0x7f, v109
	v_lshl_or_b32 v253, v253, 7, v109
	v_xor_b32_e32 v253, 0x3fff, v253
	v_and_b32_e32 v151, 0x7f, v151
	v_and_b32_e32 v60, 0x7f, v60
	v_lshl_or_b32 v151, v151, 7, v60
	v_xor_b32_e32 v151, 0x3fff, v151
	s_waitcnt vmcnt(0)
	v_pk_mul_f32 v[160:161], v[160:161], v[176:177]
	v_pk_mul_f32 v[162:163], v[162:163], v[178:179]
	v_pk_mul_f32 v[164:165], v[164:165], v[180:181]
	v_pk_mul_f32 v[166:167], v[166:167], v[182:183]
	v_pk_mul_f32 v[168:169], v[168:169], v[184:185]
	v_pk_mul_f32 v[170:171], v[170:171], v[186:187]
	v_pk_mul_f32 v[172:173], v[172:173], v[188:189]
	v_pk_mul_f32 v[174:175], v[174:175], v[190:191]
	v_max3_f32 v192, |v160|, |v161|, |v162|
	v_max3_f32 v192, |v163|, |v164|, v192
	v_max3_f32 v192, |v165|, |v166|, v192
	v_max3_f32 v192, |v167|, |v168|, v192
	v_max3_f32 v192, |v169|, |v170|, v192
	v_max3_f32 v192, |v171|, |v172|, v192
	v_max3_f32 v192, |v173|, |v174|, v192
	v_max_f32_e64 v192, |v175|, v192
	s_nop 1
	v_mov_b32_dpp v193, v192 quad_perm:[1,0,3,2] row_mask:0xf bank_mask:0xf bound_ctrl:1
	v_max_f32_e32 v192, v192, v193
	s_nop 1
	v_mov_b32_dpp v193, v192 quad_perm:[2,3,0,1] row_mask:0xf bank_mask:0xf bound_ctrl:1
	v_max_f32_e32 v192, v192, v193
	s_nop 1
	v_mov_b32_dpp v193, v192 row_half_mirror row_mask:0xf bank_mask:0xf bound_ctrl:1
	v_max_f32_e32 v192, v192, v193
	s_nop 1
	v_mov_b32_dpp v193, v192 row_mirror row_mask:0xf bank_mask:0xf bound_ctrl:1
	v_max_f32_e32 v192, v192, v193
	v_mov_b32_e32 v193, v192
	s_nop 1
	v_permlane16_swap_b32_e32 v192, v193
	s_nop 1
	v_max_f32_e32 v192, v192, v193
	v_mov_b32_e32 v193, v192
	s_nop 1
	v_permlane32_swap_b32_e32 v192, v193
	s_nop 1
	v_max_f32_e32 v192, v192, v193
	v_max_f32_e32 v192, 0xda24260, v192
	v_mul_f32_e32 v194, 0x3e2aaaab, v192
	global_store_dword v214, v194, s[12:13]
	v_div_scale_f32 v195, s[26:27], v194, v194, 1.0
	v_rcp_f32_e32 v196, v195
	v_div_scale_f32 v204, vcc, 1.0, v194, 1.0
	v_fma_f32 v205, -v195, v196, 1.0
	v_fmac_f32_e32 v196, v205, v196
	v_mul_f32_e32 v205, v204, v196
	v_fma_f32 v206, -v195, v205, v204
	v_fmac_f32_e32 v205, v206, v196
	v_fma_f32 v195, -v195, v205, v204
	s_nop 0
	v_div_fmas_f32 v195, v195, v196, v205
	v_div_fixup_f32 v207, v195, v194, 1.0
	v_mul_f32_e32 v160, v207, v160
	v_mul_f32_e32 v161, v207, v161
	v_mul_f32_e32 v162, v207, v162
	v_mul_f32_e32 v163, v207, v163
	v_mul_f32_e32 v164, v207, v164
	v_mul_f32_e32 v165, v207, v165
	v_mul_f32_e32 v166, v207, v166
	v_mul_f32_e32 v167, v207, v167
	v_mul_f32_e32 v168, v207, v168
	v_mul_f32_e32 v169, v207, v169
	v_mul_f32_e32 v170, v207, v170
	v_mul_f32_e32 v171, v207, v171
	v_mul_f32_e32 v172, v207, v172
	v_mul_f32_e32 v173, v207, v173
	v_mul_f32_e32 v174, v207, v174
	v_mul_f32_e32 v175, v207, v175
	v_mov_b32_e32 v208, 0
	v_mov_b32_e32 v209, 0
	v_mov_b32_e32 v210, 0
	v_mov_b32_e32 v193, 0
	v_cvt_scalef32_pk_fp4_f32 v208, v160, v161, 1.0
	v_cvt_scalef32_pk_fp4_f32 v209, v164, v165, 1.0
	v_cvt_scalef32_pk_fp4_f32 v210, v168, v169, 1.0
	v_cvt_scalef32_pk_fp4_f32 v193, v172, v173, 1.0
	v_cvt_scalef32_pk_fp4_f32 v208, v162, v163, 1.0 op_sel:[0,0,1,0]
	v_cvt_scalef32_pk_fp4_f32 v209, v166, v167, 1.0 op_sel:[0,0,1,0]
	v_cvt_scalef32_pk_fp4_f32 v210, v170, v171, 1.0 op_sel:[0,0,1,0]
	v_cvt_scalef32_pk_fp4_f32 v193, v174, v175, 1.0 op_sel:[0,0,1,0]
	global_store_short v213, v208, s[10:11] nt
	s_add_u32 s14, s10, 0x200000
	s_addc_u32 s15, s11, 0
	global_store_short v213, v209, s[14:15] nt
	s_add_u32 s14, s10, 0x400000
	s_addc_u32 s15, s11, 0
	global_store_short v213, v210, s[14:15] nt
	s_add_u32 s14, s10, 0x600000
	s_addc_u32 s15, s11, 0
	global_store_short v213, v193, s[14:15] nt
	s_add_u32 s10, s10, 0x20000
	s_addc_u32 s11, s11, 0
	s_add_u32 s12, s12, 0x2000
	s_addc_u32 s13, s13, 0
	s_cmp_eq_u32 s22, 1
	s_cbranch_scc1 .Ltk0_noload7
	global_load_dwordx4 v[160:163], v212, s[8:9] offset:0 nt
	global_load_dwordx4 v[164:167], v212, s[8:9] offset:1024 nt
	global_load_dwordx4 v[168:171], v212, s[8:9] offset:2048 nt
	global_load_dwordx4 v[172:175], v212, s[8:9] offset:3072 nt
	s_add_u32 s8, s8, 0x800000
	s_addc_u32 s9, s9, 0
.Ltk0_noload7:
	v_mov_b32_e32 v0, v68
	v_mov_b32_e32 v1, v56
	v_mov_b32_e32 v2, v57
	v_mov_b32_e32 v3, v58
	global_store_dwordx4 v241, v[0:3], s[28:29] offset:0
	v_mov_b32_e32 v4, v59
	v_mov_b32_e32 v5, v251
	v_mov_b32_e32 v6, v253
	v_mov_b32_e32 v7, v151
	global_store_dwordx4 v241, v[4:7], s[28:29] offset:16
	v_mov_b32_e32 v8, v62
	v_mov_b32_e32 v9, v64
	v_mov_b32_e32 v10, v255
	v_mov_b32_e32 v11, v252
	global_store_dwordx4 v241, v[8:11], s[30:31] offset:0
	v_mov_b32_e32 v12, v129
	v_mov_b32_e32 v13, v130
	v_mov_b32_e32 v14, v65
	v_mov_b32_e32 v15, v133
	global_store_dwordx4 v241, v[12:15], s[30:31] offset:16
	v_add_u32_e32 v215, 0x10000, v215
	v_add_u32_e32 v232, 0x10000, v232
	v_add_u32_e32 v233, 0x10000, v233
	v_add_u32_e32 v234, 0x10000, v234
	v_add_u32_e32 v235, 0x10000, v235
	v_add_u32_e32 v236, 0x10000, v236
	v_add_u32_e32 v237, 0x10000, v237
	v_add_u32_e32 v238, 0x10000, v238
	s_add_i32 s24, s24, 4
	s_add_i32 s22, s22, 1
	s_cmp_lt_u32 s22, 2
	s_cbranch_scc1 .Ltk0_unit

.LBB0_966:
	s_cmp_lt_i32 s56, 15
	s_cselect_b64 s[0:1], -1, 0
	s_and_b64 s[40:41], s[0:1], s[4:5]
	s_andn2_b64 vcc, exec, s[40:41]
	s_cbranch_vccnz .LBB0_1021
	v_mbcnt_lo_u32_b32 v246, -1, 0
	v_mbcnt_hi_u32_b32 v246, -1, v246
	v_readlane_b32 s21, v248, 0
	s_andn2_b32 s26, s21, 63
	v_add_u32_e32 v242, s26, v246
	s_lshr_b32 s21, s21, 6
	s_mov_b32 s4, 0
	s_mov_b32 s5, -1
	s_mov_b32 s6, 0xffffff80
	s_mov_b32 s7, 0xffffffc0
	v_lshrrev_b32_e32 v245, 5, v246
	v_and_b32_e32 v247, 31, v246
	v_lshlrev_b32_e32 v239, 12, v247
	v_lshl_or_b32 v239, v245, 4, v239
	v_lshlrev_b32_e32 v241, 9, v247
	v_lshl_or_b32 v241, v245, 5, v241
	v_lshlrev_b32_e32 v240, 4, v247
	s_lshl_b32 s26, s21, 10
	s_add_i32 s26, s26, 0x20100
	v_add_u32_e32 v240, s26, v240
	v_and_b32_e32 v215, 15, v246
	v_xor_b32_e32 v215, v215, v245
	v_lshlrev_b32_e32 v215, 4, v215
	v_lshl_or_b32 v215, v247, 8, v215
	v_xor_b32_e32 v232, 32, v215
	v_xor_b32_e32 v233, 64, v215
	v_xor_b32_e32 v234, 0x60, v215
	v_xor_b32_e32 v235, 0x80, v215
	v_xor_b32_e32 v236, 0xa0, v215
	v_xor_b32_e32 v237, 0xc0, v215
	v_xor_b32_e32 v238, 0xe0, v215
	v_lshlrev_b32_e32 v247, 2, v245
	v_xor_b32_e32 v211, 4, v247
	v_lshrrev_b32_e32 v243, 4, v242
	v_xor_b32_e32 v247, v243, v242
	v_lshlrev_b32_e32 v242, 4, v242
	v_and_b32_e32 v247, 15, v247
	v_lshlrev_b32_e32 v247, 4, v247
	v_lshl_or_b32 v243, v243, 8, v247
	s_lshr_b32 s26, s2, 6
	s_lshl_b32 s26, s26, 16
	s_add_i32 s26, s26, 0x380000
	s_add_u32 s18, s54, s26
	s_addc_u32 s19, s55, 0
	global_load_dwordx4 v[0:3], v242, s[18:19]
	v_add_u32_e32 v247, 0x2000, v242
	global_load_dwordx4 v[4:7], v247, s[18:19]
	v_add_u32_e32 v247, 0x4000, v242
	global_load_dwordx4 v[8:11], v247, s[18:19]
	v_add_u32_e32 v247, 0x6000, v242
	global_load_dwordx4 v[12:15], v247, s[18:19]
	v_add_u32_e32 v247, 0x8000, v242
	global_load_dwordx4 v[16:19], v247, s[18:19]
	v_add_u32_e32 v247, 0xa000, v242
	global_load_dwordx4 v[20:23], v247, s[18:19]
	v_add_u32_e32 v247, 0xc000, v242
	global_load_dwordx4 v[24:27], v247, s[18:19]
	v_add_u32_e32 v247, 0xe000, v242
	global_load_dwordx4 v[28:31], v247, s[18:19]
	v_add_u32_e32 v247, 0x40000, v242
	global_load_dwordx4 v[32:35], v247, s[18:19]
	v_add_u32_e32 v247, 0x42000, v242
	global_load_dwordx4 v[36:39], v247, s[18:19]
	v_add_u32_e32 v247, 0x44000, v242
	global_load_dwordx4 v[40:43], v247, s[18:19]
	v_add_u32_e32 v247, 0x46000, v242
	global_load_dwordx4 v[44:47], v247, s[18:19]
	v_add_u32_e32 v247, 0x48000, v242
	global_load_dwordx4 v[48:51], v247, s[18:19]
	v_add_u32_e32 v247, 0x4a000, v242
	global_load_dwordx4 v[52:55], v247, s[18:19]
	v_add_u32_e32 v247, 0x4c000, v242
	global_load_dwordx4 v[56:59], v247, s[18:19]
	v_add_u32_e32 v247, 0x4e000, v242
	global_load_dwordx4 v[60:63], v247, s[18:19]
	v_mov_b32_e32 v244, 0xff800000
	v_mov_b32_e32 v247, 0x22100
	v_mov_b32_e32 v128, 0x20021001
	ds_write_b32 v247, v128 offset:0
	v_mov_b32_e32 v128, 0x40043003
	ds_write_b32 v247, v128 offset:4
	v_mov_b32_e32 v128, 0x60065005
	ds_write_b32 v247, v128 offset:8
	v_mov_b32_e32 v128, 0x80087007
	ds_write_b32 v247, v128 offset:12
	v_mov_b32_e32 v128, 0xa00a9009
	ds_write_b32 v247, v128 offset:16
	v_mov_b32_e32 v128, 0xc00cb00b
	ds_write_b32 v247, v128 offset:20
	v_mov_b32_e32 v128, 0xe00ed00d
	ds_write_b32 v247, v128 offset:24
	v_mov_b32_e32 v128, 0x2112f00f
	ds_write_b32 v247, v128 offset:28
	v_mov_b32_e32 v128, 0x41143113
	ds_write_b32 v247, v128 offset:32
	v_mov_b32_e32 v128, 0x61165115
	ds_write_b32 v247, v128 offset:36
	v_mov_b32_e32 v128, 0x32237117
	ds_write_b32 v247, v128 offset:40
	v_mov_b32_e32 v128, 0x4224
	ds_write_b32 v247, v128 offset:44
	v_mov_b32_e32 v128, 0x22221111
	ds_write_b32 v247, v128 offset:48
	v_mov_b32_e32 v128, 0x3333
	ds_write_b32 v247, v128 offset:52
	v_mov_b32_e32 v128, 0
	ds_write_b32 v247, v128 offset:56
	v_mov_b32_e32 v128, 0
	ds_write_b32 v247, v128 offset:60
	s_and_b32 s25, s2, 7
	s_lshl_b32 s25, s25, 3
	s_bfe_u32 s26, s2, 0x30003
	s_add_i32 s25, s25, s26
	s_lshl_b32 s23, s25, 8
	s_lshl_b32 s26, s21, 5
	s_add_i32 s23, s23, s26
	v_lshlrev_b32_e32 v212, 4, v246
	v_lshlrev_b32_e32 v213, 1, v246
	v_mov_b32_e32 v214, 0
	s_lshl_b32 s14, s2, 3
	s_add_i32 s14, s14, s21
	s_and_b32 s15, s14, 1
	s_lshr_b32 s14, s14, 1
	v_readlane_b32 s8, v248, 12
	v_readlane_b32 s9, v248, 13
	s_lshl_b32 s26, s14, 13
	s_lshl_b32 s25, s15, 12
	s_add_i32 s26, s26, s25
	s_add_i32 s26, s26, 0x8000000
	s_add_u32 s8, s8, s26
	s_addc_u32 s9, s9, 0
	v_readlane_b32 s12, v248, 14
	v_readlane_b32 s13, v248, 15
	s_add_i32 s25, s25, 0x2000
	s_add_u32 s12, s12, s25
	s_addc_u32 s13, s13, 0
	global_load_dwordx4 v[176:179], v212, s[12:13] offset:0
	global_load_dwordx4 v[180:183], v212, s[12:13] offset:1024
	global_load_dwordx4 v[184:187], v212, s[12:13] offset:2048
	global_load_dwordx4 v[188:191], v212, s[12:13] offset:3072
	s_lshl_b32 s26, s15, 23
	s_lshl_b32 s25, s14, 7
	s_add_i32 s26, s26, s25
	s_add_i32 s26, s26, 0x10000000
	s_add_u32 s10, s54, s26
	s_addc_u32 s11, s55, 0
	s_lshl_b32 s26, s14, 3
	s_lshl_b32 s25, s15, 2
	s_add_i32 s26, s26, s25
	s_add_i32 s26, s26, 0xa0000
	s_add_u32 s12, s54, s26
	s_addc_u32 s13, s55, 0
	global_load_dwordx4 v[160:163], v212, s[8:9] offset:0 nt
	global_load_dwordx4 v[164:167], v212, s[8:9] offset:1024 nt
	global_load_dwordx4 v[168:171], v212, s[8:9] offset:2048 nt
	global_load_dwordx4 v[172:175], v212, s[8:9] offset:3072 nt
	s_add_u32 s8, s8, 0x800000
	s_addc_u32 s9, s9, 0
	v_mov_b32_e32 v246, 0x22100
	s_lshr_b32 s24, s2, 6
	s_mov_b32 s22, 0
	v_add_u32_e32 v247, 0x10000, v243
	s_waitcnt vmcnt(23)
	ds_write_b128 v243, v[0:3] offset:0
	s_waitcnt vmcnt(22)
	ds_write_b128 v243, v[4:7] offset:8192
	s_waitcnt vmcnt(21)
	ds_write_b128 v243, v[8:11] offset:16384
	s_waitcnt vmcnt(20)
	ds_write_b128 v243, v[12:15] offset:24576
	s_waitcnt vmcnt(19)
	ds_write_b128 v243, v[16:19] offset:32768
	s_waitcnt vmcnt(18)
	ds_write_b128 v243, v[20:23] offset:40960
	s_waitcnt vmcnt(17)
	ds_write_b128 v243, v[24:27] offset:49152
	s_waitcnt vmcnt(16)
	ds_write_b128 v243, v[28:31] offset:57344
	s_waitcnt vmcnt(15)
	ds_write_b128 v247, v[32:35] offset:0
	s_waitcnt vmcnt(14)
	ds_write_b128 v247, v[36:39] offset:8192
	s_waitcnt vmcnt(13)
	ds_write_b128 v247, v[40:43] offset:16384
	s_waitcnt vmcnt(12)
	ds_write_b128 v247, v[44:47] offset:24576
	s_waitcnt vmcnt(11)
	ds_write_b128 v247, v[48:51] offset:32768
	s_waitcnt vmcnt(10)
	ds_write_b128 v247, v[52:55] offset:40960
	s_waitcnt vmcnt(9)
	ds_write_b128 v247, v[56:59] offset:49152
	s_waitcnt vmcnt(8)
	ds_write_b128 v247, v[60:63] offset:57344
	s_waitcnt lgkmcnt(0)
	s_barrier
.Ltk1_unit:
	s_lshl_b32 s26, s24, 9
	s_lshl_b32 s20, s23, 12
	s_add_i32 s26, s26, s20
	s_add_i32 s26, s26, 0x1c000000
	s_add_u32 s16, s54, s26
	s_addc_u32 s17, s55, 0
	s_lshl_b32 s26, s24, 16
	s_add_i32 s26, s26, 0x380000
	s_add_u32 s18, s54, s26
	s_addc_u32 s19, s55, 0
	s_lshl_b32 s20, s23, 9
	s_lshl_b32 s26, s24, 6
	s_add_i32 s20, s20, s26
	s_add_i32 s26, s20, 0x28000000
	s_add_u32 s28, s54, s26
	s_addc_u32 s29, s55, 0
	s_add_i32 s26, s20, 0x28800000
	s_add_u32 s30, s54, s26
	s_addc_u32 s31, s55, 0
	global_load_dwordx4 v[64:67], v239, s[16:17] offset:0
	global_load_dwordx4 v[68:71], v239, s[16:17] offset:32
	global_load_dwordx4 v[72:75], v239, s[16:17] offset:64
	global_load_dwordx4 v[76:79], v239, s[16:17] offset:96
	global_load_dwordx4 v[80:83], v239, s[16:17] offset:128
	global_load_dwordx4 v[84:87], v239, s[16:17] offset:160
	global_load_dwordx4 v[88:91], v239, s[16:17] offset:192
	global_load_dwordx4 v[92:95], v239, s[16:17] offset:224
	ds_read_b128 v[96:99], v215 offset:0
	ds_read_b128 v[100:103], v232 offset:0
	ds_read_b128 v[104:107], v233 offset:0
	ds_read_b128 v[108:111], v234 offset:0
	ds_read_b128 v[112:115], v235 offset:0
	ds_read_b128 v[116:119], v236 offset:0
	ds_read_b128 v[120:123], v237 offset:0
	ds_read_b128 v[124:127], v238 offset:0
	s_waitcnt vmcnt(0)
	s_waitcnt lgkmcnt(4)
	v_mfma_f32_32x32x16_bf16 v[0:15], v[96:99], v[64:67], 0
	v_mfma_f32_32x32x16_bf16 v[0:15], v[100:103], v[68:71], v[0:15]
	v_mfma_f32_32x32x16_bf16 v[0:15], v[104:107], v[72:75], v[0:15]
	v_mfma_f32_32x32x16_bf16 v[0:15], v[108:111], v[76:79], v[0:15]
	ds_read_b128 v[96:99], v215 offset:8192
	ds_read_b128 v[100:103], v232 offset:8192
	ds_read_b128 v[104:107], v233 offset:8192
	ds_read_b128 v[108:111], v234 offset:8192
	s_waitcnt lgkmcnt(4)
	v_mfma_f32_32x32x16_bf16 v[0:15], v[112:115], v[80:83], v[0:15]
	v_mfma_f32_32x32x16_bf16 v[0:15], v[116:119], v[84:87], v[0:15]
	v_mfma_f32_32x32x16_bf16 v[0:15], v[120:123], v[88:91], v[0:15]
	v_mfma_f32_32x32x16_bf16 v[0:15], v[124:127], v[92:95], v[0:15]
	ds_read_b128 v[112:115], v235 offset:8192
	ds_read_b128 v[116:119], v236 offset:8192
	ds_read_b128 v[120:123], v237 offset:8192
	ds_read_b128 v[124:127], v238 offset:8192
	s_waitcnt lgkmcnt(4)
	v_mfma_f32_32x32x16_bf16 v[16:31], v[96:99], v[64:67], 0
	v_mfma_f32_32x32x16_bf16 v[16:31], v[100:103], v[68:71], v[16:31]
	v_mfma_f32_32x32x16_bf16 v[16:31], v[104:107], v[72:75], v[16:31]
	v_mfma_f32_32x32x16_bf16 v[16:31], v[108:111], v[76:79], v[16:31]
	ds_read_b128 v[96:99], v215 offset:16384
	ds_read_b128 v[100:103], v232 offset:16384
	ds_read_b128 v[104:107], v233 offset:16384
	ds_read_b128 v[108:111], v234 offset:16384
	s_waitcnt lgkmcnt(4)
	v_mfma_f32_32x32x16_bf16 v[16:31], v[112:115], v[80:83], v[16:31]
	v_mfma_f32_32x32x16_bf16 v[16:31], v[116:119], v[84:87], v[16:31]
	v_mfma_f32_32x32x16_bf16 v[16:31], v[120:123], v[88:91], v[16:31]
	v_mfma_f32_32x32x16_bf16 v[16:31], v[124:127], v[92:95], v[16:31]
	ds_read_b128 v[112:115], v235 offset:16384
	ds_read_b128 v[116:119], v236 offset:16384
	ds_read_b128 v[120:123], v237 offset:16384
	ds_read_b128 v[124:127], v238 offset:16384
	s_waitcnt lgkmcnt(4)
	v_mfma_f32_32x32x16_bf16 v[32:47], v[96:99], v[64:67], 0
	v_mfma_f32_32x32x16_bf16 v[32:47], v[100:103], v[68:71], v[32:47]
	v_mfma_f32_32x32x16_bf16 v[32:47], v[104:107], v[72:75], v[32:47]
	v_mfma_f32_32x32x16_bf16 v[32:47], v[108:111], v[76:79], v[32:47]
	ds_read_b128 v[96:99], v215 offset:24576
	ds_read_b128 v[100:103], v232 offset:24576
	ds_read_b128 v[104:107], v233 offset:24576
	ds_read_b128 v[108:111], v234 offset:24576
	s_waitcnt lgkmcnt(4)
	v_mfma_f32_32x32x16_bf16 v[32:47], v[112:115], v[80:83], v[32:47]
	v_mfma_f32_32x32x16_bf16 v[32:47], v[116:119], v[84:87], v[32:47]
	v_mfma_f32_32x32x16_bf16 v[32:47], v[120:123], v[88:91], v[32:47]
	v_mfma_f32_32x32x16_bf16 v[32:47], v[124:127], v[92:95], v[32:47]
	ds_read_b128 v[112:115], v235 offset:24576
	ds_read_b128 v[116:119], v236 offset:24576
	ds_read_b128 v[120:123], v237 offset:24576
	ds_read_b128 v[124:127], v238 offset:24576
	s_waitcnt lgkmcnt(4)
	v_mfma_f32_32x32x16_bf16 v[48:63], v[96:99], v[64:67], 0
	v_mfma_f32_32x32x16_bf16 v[48:63], v[100:103], v[68:71], v[48:63]
	v_mfma_f32_32x32x16_bf16 v[48:63], v[104:107], v[72:75], v[48:63]
	v_mfma_f32_32x32x16_bf16 v[48:63], v[108:111], v[76:79], v[48:63]
	s_waitcnt lgkmcnt(0)
	v_mfma_f32_32x32x16_bf16 v[48:63], v[112:115], v[80:83], v[48:63]
	v_mfma_f32_32x32x16_bf16 v[48:63], v[116:119], v[84:87], v[48:63]
	v_mfma_f32_32x32x16_bf16 v[48:63], v[120:123], v[88:91], v[48:63]
	v_mfma_f32_32x32x16_bf16 v[48:63], v[124:127], v[92:95], v[48:63]
	global_load_dwordx4 v[64:67], v239, s[16:17] offset:256
	global_load_dwordx4 v[68:71], v239, s[16:17] offset:288
	global_load_dwordx4 v[72:75], v239, s[16:17] offset:320
	global_load_dwordx4 v[76:79], v239, s[16:17] offset:352
	global_load_dwordx4 v[80:83], v239, s[16:17] offset:384
	global_load_dwordx4 v[84:87], v239, s[16:17] offset:416
	global_load_dwordx4 v[88:91], v239, s[16:17] offset:448
	global_load_dwordx4 v[92:95], v239, s[16:17] offset:480
	s_nop 11
	v_and_or_b32 v0, v0, s6, v211
	v_or_b32_e32 v0, 0x7b, v0
	v_and_or_b32 v1, v1, s6, v211
	v_or_b32_e32 v1, 0x7a, v1
	v_and_or_b32 v2, v2, s6, v211
	v_or_b32_e32 v2, 0x79, v2
	v_and_or_b32 v3, v3, s6, v211
	v_or_b32_e32 v3, 0x78, v3
	v_and_or_b32 v4, v4, s6, v211
	v_or_b32_e32 v4, 0x73, v4
	v_and_or_b32 v5, v5, s6, v211
	v_or_b32_e32 v5, 0x72, v5
	v_and_or_b32 v6, v6, s6, v211
	v_or_b32_e32 v6, 0x71, v6
	v_and_or_b32 v7, v7, s6, v211
	v_or_b32_e32 v7, 0x70, v7
	v_and_or_b32 v8, v8, s6, v211
	v_or_b32_e32 v8, 0x6b, v8
	v_and_or_b32 v9, v9, s6, v211
	v_or_b32_e32 v9, 0x6a, v9
	v_and_or_b32 v10, v10, s6, v211
	v_or_b32_e32 v10, 0x69, v10
	v_and_or_b32 v11, v11, s6, v211
	v_or_b32_e32 v11, 0x68, v11
	v_and_or_b32 v12, v12, s6, v211
	v_or_b32_e32 v12, 0x63, v12
	v_and_or_b32 v13, v13, s6, v211
	v_or_b32_e32 v13, 0x62, v13
	v_and_or_b32 v14, v14, s6, v211
	v_or_b32_e32 v14, 0x61, v14
	v_and_or_b32 v15, v15, s6, v211
	v_or_b32_e32 v15, 0x60, v15
	v_and_or_b32 v16, v16, s6, v211
	v_or_b32_e32 v16, 0x5b, v16
	v_and_or_b32 v17, v17, s6, v211
	v_or_b32_e32 v17, 0x5a, v17
	v_and_or_b32 v18, v18, s6, v211
	v_or_b32_e32 v18, 0x59, v18
	v_and_or_b32 v19, v19, s6, v211
	v_or_b32_e32 v19, 0x58, v19
	v_and_or_b32 v20, v20, s6, v211
	v_or_b32_e32 v20, 0x53, v20
	v_and_or_b32 v21, v21, s6, v211
	v_or_b32_e32 v21, 0x52, v21
	v_and_or_b32 v22, v22, s6, v211
	v_or_b32_e32 v22, 0x51, v22
	v_and_or_b32 v23, v23, s6, v211
	v_or_b32_e32 v23, 0x50, v23
	v_and_or_b32 v24, v24, s6, v211
	v_or_b32_e32 v24, 0x4b, v24
	v_and_or_b32 v25, v25, s6, v211
	v_or_b32_e32 v25, 0x4a, v25
	v_and_or_b32 v26, v26, s6, v211
	v_or_b32_e32 v26, 0x49, v26
	v_and_or_b32 v27, v27, s6, v211
	v_or_b32_e32 v27, 0x48, v27
	v_and_or_b32 v28, v28, s6, v211
	v_or_b32_e32 v28, 0x43, v28
	v_and_or_b32 v29, v29, s6, v211
	v_or_b32_e32 v29, 0x42, v29
	v_and_or_b32 v30, v30, s6, v211
	v_or_b32_e32 v30, 0x41, v30
	v_and_or_b32 v31, v31, s6, v211
	v_or_b32_e32 v31, 64, v31
	v_and_or_b32 v32, v32, s6, v211
	v_or_b32_e32 v32, 59, v32
	v_and_or_b32 v33, v33, s6, v211
	v_or_b32_e32 v33, 58, v33
	v_and_or_b32 v34, v34, s6, v211
	v_or_b32_e32 v34, 57, v34
	v_and_or_b32 v35, v35, s6, v211
	v_or_b32_e32 v35, 56, v35
	v_and_or_b32 v36, v36, s6, v211
	v_or_b32_e32 v36, 51, v36
	v_and_or_b32 v37, v37, s6, v211
	v_or_b32_e32 v37, 50, v37
	v_and_or_b32 v38, v38, s6, v211
	v_or_b32_e32 v38, 49, v38
	v_and_or_b32 v39, v39, s6, v211
	v_or_b32_e32 v39, 48, v39
	v_and_or_b32 v40, v40, s6, v211
	v_or_b32_e32 v40, 43, v40
	v_and_or_b32 v41, v41, s6, v211
	v_or_b32_e32 v41, 42, v41
	v_and_or_b32 v42, v42, s6, v211
	v_or_b32_e32 v42, 41, v42
	v_and_or_b32 v43, v43, s6, v211
	v_or_b32_e32 v43, 40, v43
	v_and_or_b32 v44, v44, s6, v211
	v_or_b32_e32 v44, 35, v44
	v_and_or_b32 v45, v45, s6, v211
	v_or_b32_e32 v45, 34, v45
	v_and_or_b32 v46, v46, s6, v211
	v_or_b32_e32 v46, 33, v46
	v_and_or_b32 v47, v47, s6, v211
	v_or_b32_e32 v47, 32, v47
	v_and_or_b32 v48, v48, s6, v211
	v_or_b32_e32 v48, 27, v48
	v_and_or_b32 v49, v49, s6, v211
	v_or_b32_e32 v49, 26, v49
	v_and_or_b32 v50, v50, s6, v211
	v_or_b32_e32 v50, 25, v50
	v_and_or_b32 v51, v51, s6, v211
	v_or_b32_e32 v51, 24, v51
	v_and_or_b32 v52, v52, s6, v211
	v_or_b32_e32 v52, 19, v52
	v_and_or_b32 v53, v53, s6, v211
	v_or_b32_e32 v53, 18, v53
	v_and_or_b32 v54, v54, s6, v211
	v_or_b32_e32 v54, 17, v54
	v_and_or_b32 v55, v55, s6, v211
	v_or_b32_e32 v55, 16, v55
	v_and_or_b32 v56, v56, s6, v211
	v_or_b32_e32 v56, 11, v56
	v_and_or_b32 v57, v57, s6, v211
	v_or_b32_e32 v57, 10, v57
	v_and_or_b32 v58, v58, s6, v211
	v_or_b32_e32 v58, 9, v58
	v_and_or_b32 v59, v59, s6, v211
	v_or_b32_e32 v59, 8, v59
	v_and_or_b32 v60, v60, s6, v211
	v_or_b32_e32 v60, 3, v60
	v_and_or_b32 v61, v61, s6, v211
	v_or_b32_e32 v61, 2, v61
	v_and_or_b32 v62, v62, s6, v211
	v_or_b32_e32 v62, 1, v62
	v_and_or_b32 v63, v63, s6, v211
	v_or_b32_e32 v63, 0, v63
	v_max_f32_e32 v144, v0, v13
	v_min_f32_e32 v13, v0, v13
	v_max_f32_e32 v145, v1, v12
	v_min_f32_e32 v12, v1, v12
	v_max_f32_e32 v146, v2, v15
	v_min_f32_e32 v15, v2, v15
	v_max_f32_e32 v147, v3, v14
	v_min_f32_e32 v14, v3, v14
	v_max_f32_e32 v148, v4, v8
	v_min_f32_e32 v8, v4, v8
	v_max_f32_e32 v149, v5, v6
	v_min_f32_e32 v6, v5, v6
	v_max_f32_e32 v150, v7, v11
	v_min_f32_e32 v11, v7, v11
	v_max_f32_e32 v151, v9, v10
	v_min_f32_e32 v10, v9, v10
	v_max_f32_e32 v249, v144, v149
	v_min_f32_e32 v149, v144, v149
	v_max_f32_e32 v250, v145, v150
	v_min_f32_e32 v150, v145, v150
	v_max_f32_e32 v251, v146, v151
	v_min_f32_e32 v151, v146, v151
	v_max_f32_e32 v252, v147, v148
	v_min_f32_e32 v148, v147, v148
	v_max_f32_e32 v253, v6, v13
	v_min_f32_e32 v13, v6, v13
	v_max_f32_e32 v254, v8, v14
	v_min_f32_e32 v14, v8, v14
	v_max_f32_e32 v255, v10, v15
	v_min_f32_e32 v15, v10, v15
	v_max_f32_e32 v96, v11, v12
	v_min_f32_e32 v12, v11, v12
	v_max_f32_e32 v97, v249, v250
	v_min_f32_e32 v250, v249, v250
	v_max_f32_e32 v98, v251, v252
	v_min_f32_e32 v252, v251, v252
	v_max_f32_e32 v99, v148, v149
	v_min_f32_e32 v149, v148, v149
	v_max_f32_e32 v100, v253, v254
	v_min_f32_e32 v254, v253, v254
	v_max_f32_e32 v101, v150, v151
	v_min_f32_e32 v151, v150, v151
	v_max_f32_e32 v102, v255, v96
	v_min_f32_e32 v96, v255, v96
	v_max_f32_e32 v103, v12, v13
	v_min_f32_e32 v13, v12, v13
	v_max_f32_e32 v104, v14, v15
	v_min_f32_e32 v15, v14, v15
	v_max_f32_e32 v105, v97, v98
	v_min_f32_e32 v98, v97, v98
	v_max_f32_e32 v106, v250, v252
	v_min_f32_e32 v252, v250, v252
	v_max_f32_e32 v107, v99, v102
	v_min_f32_e32 v102, v99, v102
	v_max_f32_e32 v108, v149, v96
	v_min_f32_e32 v96, v149, v96
	v_max_f32_e32 v109, v100, v101
	v_min_f32_e32 v101, v100, v101
	v_max_f32_e32 v110, v254, v151
	v_min_f32_e32 v151, v254, v151
	v_max_f32_e32 v111, v103, v104
	v_min_f32_e32 v104, v103, v104
	v_max_f32_e32 v112, v13, v15
	v_min_f32_e32 v15, v13, v15
	v_max_f32_e32 v113, v106, v98
	v_min_f32_e32 v98, v106, v98
	v_max_f32_e32 v114, v252, v111
	v_min_f32_e32 v111, v252, v111
	v_max_f32_e32 v115, v107, v109
	v_min_f32_e32 v109, v107, v109
	v_max_f32_e32 v116, v108, v101
	v_min_f32_e32 v101, v108, v101
	v_max_f32_e32 v117, v110, v102
	v_min_f32_e32 v102, v110, v102
	v_max_f32_e32 v118, v151, v96
	v_min_f32_e32 v96, v151, v96
	v_max_f32_e32 v119, v112, v104
	v_min_f32_e32 v104, v112, v104
	v_max_f32_e32 v120, v113, v115
	v_min_f32_e32 v115, v113, v115
	v_max_f32_e32 v121, v98, v109
	v_min_f32_e32 v109, v98, v109
	v_max_f32_e32 v122, v116, v117
	v_min_f32_e32 v117, v116, v117
	v_max_f32_e32 v123, v101, v102
	v_min_f32_e32 v102, v101, v102
	v_max_f32_e32 v124, v118, v119
	v_min_f32_e32 v119, v118, v119
	v_max_f32_e32 v125, v96, v104
	v_min_f32_e32 v104, v96, v104
	v_max_f32_e32 v126, v121, v115
	v_min_f32_e32 v115, v121, v115
	v_max_f32_e32 v127, v114, v109
	v_min_f32_e32 v109, v114, v109
	v_max_f32_e32 v0, v124, v111
	v_min_f32_e32 v111, v124, v111
	v_max_f32_e32 v1, v125, v119
	v_min_f32_e32 v119, v125, v119
	v_max_f32_e32 v2, v127, v122
	v_min_f32_e32 v122, v127, v122
	v_max_f32_e32 v3, v109, v117
	v_min_f32_e32 v117, v109, v117
	v_max_f32_e32 v4, v123, v0
	v_min_f32_e32 v0, v123, v0
	v_max_f32_e32 v5, v102, v111
	v_min_f32_e32 v111, v102, v111
	v_max_f32_e32 v7, v2, v115
	v_min_f32_e32 v115, v2, v115
	v_max_f32_e32 v9, v122, v3
	v_min_f32_e32 v3, v122, v3
	v_max_f32_e32 v144, v4, v117
	v_min_f32_e32 v117, v4, v117
	v_max_f32_e32 v145, v0, v5
	v_min_f32_e32 v5, v0, v5
	v_max_f32_e32 v146, v1, v111
	v_min_f32_e32 v111, v1, v111
	v_max_f32_e32 v147, v3, v144
	v_min_f32_e32 v144, v3, v144
	v_max_f32_e32 v6, v117, v145
	v_min_f32_e32 v145, v117, v145
	v_max_f32_e32 v8, v16, v29
	v_min_f32_e32 v29, v16, v29
	v_max_f32_e32 v10, v17, v28
	v_min_f32_e32 v28, v17, v28
	v_max_f32_e32 v11, v18, v31
	v_min_f32_e32 v31, v18, v31
	v_max_f32_e32 v249, v19, v30
	v_min_f32_e32 v30, v19, v30
	v_max_f32_e32 v251, v20, v24
	v_min_f32_e32 v24, v20, v24
	v_max_f32_e32 v148, v21, v22
	v_min_f32_e32 v22, v21, v22
	v_max_f32_e32 v253, v23, v27
	v_min_f32_e32 v27, v23, v27
	v_max_f32_e32 v150, v25, v26
	v_min_f32_e32 v26, v25, v26
	v_max_f32_e32 v255, v8, v148
	v_min_f32_e32 v148, v8, v148
	v_max_f32_e32 v12, v10, v253
	v_min_f32_e32 v253, v10, v253
	v_max_f32_e32 v14, v11, v150
	v_min_f32_e32 v150, v11, v150
	v_max_f32_e32 v97, v249, v251
	v_min_f32_e32 v251, v249, v251
	v_max_f32_e32 v250, v22, v29
	v_min_f32_e32 v29, v22, v29
	v_max_f32_e32 v99, v24, v30
	v_min_f32_e32 v30, v24, v30
	v_max_f32_e32 v149, v26, v31
	v_min_f32_e32 v31, v26, v31
	v_max_f32_e32 v100, v27, v28
	v_min_f32_e32 v28, v27, v28
	v_max_f32_e32 v254, v255, v12
	v_min_f32_e32 v12, v255, v12
	v_max_f32_e32 v103, v14, v97
	v_min_f32_e32 v97, v14, v97
	v_max_f32_e32 v13, v251, v148
	v_min_f32_e32 v148, v251, v148
	v_max_f32_e32 v106, v250, v99
	v_min_f32_e32 v99, v250, v99
	v_max_f32_e32 v252, v253, v150
	v_min_f32_e32 v150, v253, v150
	v_max_f32_e32 v107, v149, v100
	v_min_f32_e32 v100, v149, v100
	v_max_f32_e32 v108, v28, v29
	v_min_f32_e32 v29, v28, v29
	v_max_f32_e32 v110, v30, v31
	v_min_f32_e32 v31, v30, v31
	v_max_f32_e32 v151, v254, v103
	v_min_f32_e32 v103, v254, v103
	v_max_f32_e32 v112, v12, v97
	v_min_f32_e32 v97, v12, v97
	v_max_f32_e32 v113, v13, v107
	v_min_f32_e32 v107, v13, v107
	v_max_f32_e32 v98, v148, v100
	v_min_f32_e32 v100, v148, v100
	v_max_f32_e32 v116, v106, v252
	v_min_f32_e32 v252, v106, v252
	v_max_f32_e32 v101, v99, v150
	v_min_f32_e32 v150, v99, v150
	v_max_f32_e32 v118, v108, v110
	v_min_f32_e32 v110, v108, v110
	v_max_f32_e32 v96, v29, v31
	v_min_f32_e32 v31, v29, v31
	v_max_f32_e32 v121, v112, v103
	v_min_f32_e32 v103, v112, v103
	v_max_f32_e32 v114, v97, v118
	v_min_f32_e32 v118, v97, v118
	v_max_f32_e32 v124, v113, v116
	v_min_f32_e32 v116, v113, v116
	v_max_f32_e32 v125, v98, v252
	v_min_f32_e32 v252, v98, v252
	v_max_f32_e32 v127, v101, v107
	v_min_f32_e32 v107, v101, v107
	v_max_f32_e32 v109, v150, v100
	v_min_f32_e32 v100, v150, v100
	v_max_f32_e32 v123, v96, v110
	v_min_f32_e32 v110, v96, v110
	v_max_f32_e32 v102, v121, v124
	v_min_f32_e32 v124, v121, v124
	v_max_f32_e32 v2, v103, v116
	v_min_f32_e32 v116, v103, v116
	v_max_f32_e32 v122, v125, v127
	v_min_f32_e32 v127, v125, v127
	v_max_f32_e32 v4, v252, v107
	v_min_f32_e32 v107, v252, v107
	v_max_f32_e32 v0, v109, v123
	v_min_f32_e32 v123, v109, v123
	v_max_f32_e32 v1, v100, v110
	v_min_f32_e32 v110, v100, v110
	v_max_f32_e32 v3, v2, v124
	v_min_f32_e32 v124, v2, v124
	v_max_f32_e32 v117, v114, v116
	v_min_f32_e32 v116, v114, v116
	v_max_f32_e32 v16, v0, v118
	v_min_f32_e32 v118, v0, v118
	v_max_f32_e32 v17, v1, v123
	v_min_f32_e32 v123, v1, v123
	v_max_f32_e32 v18, v117, v122
	v_min_f32_e32 v122, v117, v122
	v_max_f32_e32 v19, v116, v127
	v_min_f32_e32 v127, v116, v127
	v_max_f32_e32 v20, v4, v16
	v_min_f32_e32 v16, v4, v16
	v_max_f32_e32 v21, v107, v118
	v_min_f32_e32 v118, v107, v118
	v_max_f32_e32 v23, v18, v124
	v_min_f32_e32 v124, v18, v124
	v_max_f32_e32 v25, v122, v19
	v_min_f32_e32 v19, v122, v19
	v_max_f32_e32 v8, v20, v127
	v_min_f32_e32 v127, v20, v127
	v_max_f32_e32 v10, v16, v21
	v_min_f32_e32 v21, v16, v21
	v_max_f32_e32 v11, v17, v118
	v_min_f32_e32 v118, v17, v118
	v_max_f32_e32 v249, v19, v8
	v_min_f32_e32 v8, v19, v8
	v_max_f32_e32 v22, v127, v10
	v_min_f32_e32 v10, v127, v10
	s_waitcnt vmcnt(16)
	v_pk_mul_f32 v[160:161], v[160:161], v[176:177]
	v_pk_mul_f32 v[162:163], v[162:163], v[178:179]
	v_pk_mul_f32 v[164:165], v[164:165], v[180:181]
	v_pk_mul_f32 v[166:167], v[166:167], v[182:183]
	v_pk_mul_f32 v[168:169], v[168:169], v[184:185]
	v_pk_mul_f32 v[170:171], v[170:171], v[186:187]
	v_pk_mul_f32 v[172:173], v[172:173], v[188:189]
	v_pk_mul_f32 v[174:175], v[174:175], v[190:191]
	v_max3_f32 v192, |v160|, |v161|, |v162|
	v_max3_f32 v192, |v163|, |v164|, v192
	v_max3_f32 v192, |v165|, |v166|, v192
	v_max3_f32 v192, |v167|, |v168|, v192
	v_max3_f32 v192, |v169|, |v170|, v192
	v_max3_f32 v192, |v171|, |v172|, v192
	v_max3_f32 v192, |v173|, |v174|, v192
	v_max_f32_e64 v192, |v175|, v192
	s_nop 1
	v_mov_b32_dpp v193, v192 quad_perm:[1,0,3,2] row_mask:0xf bank_mask:0xf bound_ctrl:1
	v_max_f32_e32 v192, v192, v193
	s_nop 1
	v_mov_b32_dpp v193, v192 quad_perm:[2,3,0,1] row_mask:0xf bank_mask:0xf bound_ctrl:1
	v_max_f32_e32 v192, v192, v193
	s_nop 1
	v_mov_b32_dpp v193, v192 row_half_mirror row_mask:0xf bank_mask:0xf bound_ctrl:1
	v_max_f32_e32 v192, v192, v193
	s_nop 1
	v_mov_b32_dpp v193, v192 row_mirror row_mask:0xf bank_mask:0xf bound_ctrl:1
	v_max_f32_e32 v192, v192, v193
	v_mov_b32_e32 v193, v192
	s_nop 1
	v_permlane16_swap_b32_e32 v192, v193
	s_nop 1
	v_max_f32_e32 v192, v192, v193
	v_mov_b32_e32 v193, v192
	s_nop 1
	v_permlane32_swap_b32_e32 v192, v193
	s_nop 1
	v_max_f32_e32 v192, v192, v193
	v_max_f32_e32 v192, 0xda24260, v192
	v_mul_f32_e32 v194, 0x3e2aaaab, v192
	global_store_dword v214, v194, s[12:13]
	v_div_scale_f32 v195, s[26:27], v194, v194, 1.0
	v_rcp_f32_e32 v196, v195
	v_div_scale_f32 v204, vcc, 1.0, v194, 1.0
	v_fma_f32 v205, -v195, v196, 1.0
	v_fmac_f32_e32 v196, v205, v196
	v_mul_f32_e32 v205, v204, v196
	v_fma_f32 v206, -v195, v205, v204
	v_fmac_f32_e32 v205, v206, v196
	v_fma_f32 v195, -v195, v205, v204
	s_nop 0
	v_div_fmas_f32 v195, v195, v196, v205
	v_div_fixup_f32 v207, v195, v194, 1.0
	v_mul_f32_e32 v160, v207, v160
	v_mul_f32_e32 v161, v207, v161
	v_mul_f32_e32 v162, v207, v162
	v_mul_f32_e32 v163, v207, v163
	v_mul_f32_e32 v164, v207, v164
	v_mul_f32_e32 v165, v207, v165
	v_mul_f32_e32 v166, v207, v166
	v_mul_f32_e32 v167, v207, v167
	v_mul_f32_e32 v168, v207, v168
	v_mul_f32_e32 v169, v207, v169
	v_mul_f32_e32 v170, v207, v170
	v_mul_f32_e32 v171, v207, v171
	v_mul_f32_e32 v172, v207, v172
	v_mul_f32_e32 v173, v207, v173
	v_mul_f32_e32 v174, v207, v174
	v_mul_f32_e32 v175, v207, v175
	v_mov_b32_e32 v208, 0
	v_mov_b32_e32 v209, 0
	v_mov_b32_e32 v210, 0
	v_mov_b32_e32 v193, 0
	v_cvt_scalef32_pk_fp4_f32 v208, v160, v161, 1.0
	v_cvt_scalef32_pk_fp4_f32 v209, v164, v165, 1.0
	v_cvt_scalef32_pk_fp4_f32 v210, v168, v169, 1.0
	v_cvt_scalef32_pk_fp4_f32 v193, v172, v173, 1.0
	v_cvt_scalef32_pk_fp4_f32 v208, v162, v163, 1.0 op_sel:[0,0,1,0]
	v_cvt_scalef32_pk_fp4_f32 v209, v166, v167, 1.0 op_sel:[0,0,1,0]
	v_cvt_scalef32_pk_fp4_f32 v210, v170, v171, 1.0 op_sel:[0,0,1,0]
	v_cvt_scalef32_pk_fp4_f32 v193, v174, v175, 1.0 op_sel:[0,0,1,0]
	global_store_short v213, v208, s[10:11] nt
	s_add_u32 s14, s10, 0x200000
	s_addc_u32 s15, s11, 0
	global_store_short v213, v209, s[14:15] nt
	s_add_u32 s14, s10, 0x400000
	s_addc_u32 s15, s11, 0
	global_store_short v213, v210, s[14:15] nt
	s_add_u32 s14, s10, 0x600000
	s_addc_u32 s15, s11, 0
	global_store_short v213, v193, s[14:15] nt
	s_add_u32 s10, s10, 0x20000
	s_addc_u32 s11, s11, 0
	s_add_u32 s12, s12, 0x2000
	s_addc_u32 s13, s13, 0
	global_load_dwordx4 v[160:163], v212, s[8:9] offset:0 nt
	global_load_dwordx4 v[164:167], v212, s[8:9] offset:1024 nt
	global_load_dwordx4 v[168:171], v212, s[8:9] offset:2048 nt
	global_load_dwordx4 v[172:175], v212, s[8:9] offset:3072 nt
	s_add_u32 s8, s8, 0x800000
	s_addc_u32 s9, s9, 0
	v_max_f32_e32 v24, v32, v45
	v_min_f32_e32 v45, v32, v45
	v_max_f32_e32 v26, v33, v44
	v_min_f32_e32 v44, v33, v44
	v_max_f32_e32 v27, v34, v47
	v_min_f32_e32 v47, v34, v47
	v_max_f32_e32 v255, v35, v46
	v_min_f32_e32 v46, v35, v46
	v_max_f32_e32 v14, v36, v40
	v_min_f32_e32 v40, v36, v40
	v_max_f32_e32 v251, v37, v38
	v_min_f32_e32 v38, v37, v38
	v_max_f32_e32 v250, v39, v43
	v_min_f32_e32 v43, v39, v43
	v_max_f32_e32 v253, v41, v42
	v_min_f32_e32 v42, v41, v42
	v_max_f32_e32 v149, v24, v251
	v_min_f32_e32 v251, v24, v251
	v_max_f32_e32 v28, v26, v250
	v_min_f32_e32 v250, v26, v250
	v_max_f32_e32 v30, v27, v253
	v_min_f32_e32 v253, v27, v253
	v_max_f32_e32 v254, v255, v14
	v_min_f32_e32 v14, v255, v14
	v_max_f32_e32 v12, v38, v45
	v_min_f32_e32 v45, v38, v45
	v_max_f32_e32 v13, v40, v46
	v_min_f32_e32 v46, v40, v46
	v_max_f32_e32 v148, v42, v47
	v_min_f32_e32 v47, v42, v47
	v_max_f32_e32 v106, v43, v44
	v_min_f32_e32 v44, v43, v44
	v_max_f32_e32 v99, v149, v28
	v_min_f32_e32 v28, v149, v28
	v_max_f32_e32 v108, v30, v254
	v_min_f32_e32 v254, v30, v254
	v_max_f32_e32 v29, v14, v251
	v_min_f32_e32 v251, v14, v251
	v_max_f32_e32 v112, v12, v13
	v_min_f32_e32 v13, v12, v13
	v_max_f32_e32 v97, v250, v253
	v_min_f32_e32 v253, v250, v253
	v_max_f32_e32 v113, v148, v106
	v_min_f32_e32 v106, v148, v106
	v_max_f32_e32 v98, v44, v45
	v_min_f32_e32 v45, v44, v45
	v_max_f32_e32 v101, v46, v47
	v_min_f32_e32 v47, v46, v47
	v_max_f32_e32 v150, v99, v108
	v_min_f32_e32 v108, v99, v108
	v_max_f32_e32 v96, v28, v254
	v_min_f32_e32 v254, v28, v254
	v_max_f32_e32 v121, v29, v113
	v_min_f32_e32 v113, v29, v113
	v_max_f32_e32 v103, v251, v106
	v_min_f32_e32 v106, v251, v106
	v_max_f32_e32 v125, v112, v97
	v_min_f32_e32 v97, v112, v97
	v_max_f32_e32 v252, v13, v253
	v_min_f32_e32 v253, v13, v253
	v_max_f32_e32 v109, v98, v101
	v_min_f32_e32 v101, v98, v101
	v_max_f32_e32 v100, v45, v47
	v_min_f32_e32 v47, v45, v47
	v_max_f32_e32 v2, v96, v108
	v_min_f32_e32 v108, v96, v108
	v_max_f32_e32 v114, v254, v109
	v_min_f32_e32 v109, v254, v109
	v_max_f32_e32 v0, v121, v125
	v_min_f32_e32 v125, v121, v125
	v_max_f32_e32 v1, v103, v97
	v_min_f32_e32 v97, v103, v97
	v_max_f32_e32 v117, v252, v113
	v_min_f32_e32 v113, v252, v113
	v_max_f32_e32 v116, v253, v106
	v_min_f32_e32 v106, v253, v106
	v_max_f32_e32 v4, v100, v101
	v_min_f32_e32 v101, v100, v101
	v_max_f32_e32 v107, v2, v0
	v_min_f32_e32 v0, v2, v0
	v_max_f32_e32 v18, v108, v125
	v_min_f32_e32 v125, v108, v125
	v_max_f32_e32 v122, v1, v117
	v_min_f32_e32 v117, v1, v117
	v_max_f32_e32 v20, v97, v113
	v_min_f32_e32 v113, v97, v113
	v_max_f32_e32 v16, v116, v4
	v_min_f32_e32 v4, v116, v4
	v_max_f32_e32 v17, v106, v101
	v_min_f32_e32 v101, v106, v101
	v_max_f32_e32 v19, v18, v0
	v_min_f32_e32 v0, v18, v0
	v_max_f32_e32 v127, v114, v125
	v_min_f32_e32 v125, v114, v125
	v_max_f32_e32 v32, v16, v109
	v_min_f32_e32 v109, v16, v109
	v_max_f32_e32 v33, v17, v4
	v_min_f32_e32 v4, v17, v4
	v_max_f32_e32 v34, v127, v122
	v_min_f32_e32 v122, v127, v122
	v_max_f32_e32 v35, v125, v117
	v_min_f32_e32 v117, v125, v117
	v_max_f32_e32 v36, v20, v32
	v_min_f32_e32 v32, v20, v32
	v_max_f32_e32 v37, v113, v109
	v_min_f32_e32 v109, v113, v109
	v_max_f32_e32 v39, v34, v0
	v_min_f32_e32 v0, v34, v0
	v_max_f32_e32 v41, v122, v35
	v_min_f32_e32 v35, v122, v35
	v_max_f32_e32 v24, v36, v117
	v_min_f32_e32 v117, v36, v117
	v_max_f32_e32 v26, v32, v37
	v_min_f32_e32 v37, v32, v37
	v_max_f32_e32 v27, v33, v109
	v_min_f32_e32 v109, v33, v109
	v_max_f32_e32 v255, v35, v24
	v_min_f32_e32 v24, v35, v24
	v_max_f32_e32 v38, v117, v26
	v_min_f32_e32 v26, v117, v26
	v_max_f32_e32 v40, v48, v61
	v_min_f32_e32 v61, v48, v61
	v_max_f32_e32 v42, v49, v60
	v_min_f32_e32 v60, v49, v60
	v_max_f32_e32 v43, v50, v63
	v_min_f32_e32 v63, v50, v63
	v_max_f32_e32 v149, v51, v62
	v_min_f32_e32 v62, v51, v62
	v_max_f32_e32 v30, v52, v56
	v_min_f32_e32 v56, v52, v56
	v_max_f32_e32 v14, v53, v54
	v_min_f32_e32 v54, v53, v54
	v_max_f32_e32 v12, v55, v59
	v_min_f32_e32 v59, v55, v59
	v_max_f32_e32 v250, v57, v58
	v_min_f32_e32 v58, v57, v58
	v_max_f32_e32 v148, v40, v14
	v_min_f32_e32 v14, v40, v14
	v_max_f32_e32 v44, v42, v12
	v_min_f32_e32 v12, v42, v12
	v_max_f32_e32 v46, v43, v250
	v_min_f32_e32 v250, v43, v250
	v_max_f32_e32 v99, v149, v30
	v_min_f32_e32 v30, v149, v30
	v_max_f32_e32 v28, v54, v61
	v_min_f32_e32 v61, v54, v61
	v_max_f32_e32 v29, v56, v62
	v_min_f32_e32 v62, v56, v62
	v_max_f32_e32 v251, v58, v63
	v_min_f32_e32 v63, v58, v63
	v_max_f32_e32 v112, v59, v60
	v_min_f32_e32 v60, v59, v60
	v_max_f32_e32 v13, v148, v44
	v_min_f32_e32 v44, v148, v44
	v_max_f32_e32 v98, v46, v99
	v_min_f32_e32 v99, v46, v99
	v_max_f32_e32 v45, v30, v14
	v_min_f32_e32 v14, v30, v14
	v_max_f32_e32 v96, v28, v29
	v_min_f32_e32 v29, v28, v29
	v_max_f32_e32 v254, v12, v250
	v_min_f32_e32 v250, v12, v250
	v_max_f32_e32 v121, v251, v112
	v_min_f32_e32 v112, v251, v112
	v_max_f32_e32 v103, v60, v61
	v_min_f32_e32 v61, v60, v61
	v_max_f32_e32 v252, v62, v63
	v_min_f32_e32 v63, v62, v63
	v_max_f32_e32 v253, v13, v98
	v_min_f32_e32 v98, v13, v98
	v_max_f32_e32 v100, v44, v99
	v_min_f32_e32 v99, v44, v99
	v_max_f32_e32 v2, v45, v121
	v_min_f32_e32 v121, v45, v121
	v_max_f32_e32 v108, v14, v112
	v_min_f32_e32 v112, v14, v112
	v_max_f32_e32 v1, v96, v254
	v_min_f32_e32 v254, v96, v254
	v_max_f32_e32 v97, v29, v250
	v_min_f32_e32 v250, v29, v250
	v_max_f32_e32 v116, v103, v252
	v_min_f32_e32 v252, v103, v252
	v_max_f32_e32 v106, v61, v63
	v_min_f32_e32 v63, v61, v63
	v_max_f32_e32 v18, v100, v98
	v_min_f32_e32 v98, v100, v98
	v_max_f32_e32 v114, v99, v116
	v_min_f32_e32 v116, v99, v116
	v_max_f32_e32 v16, v2, v1
	v_min_f32_e32 v1, v2, v1
	v_max_f32_e32 v17, v108, v254
	v_min_f32_e32 v254, v108, v254
	v_max_f32_e32 v127, v97, v121
	v_min_f32_e32 v121, v97, v121
	v_max_f32_e32 v125, v250, v112
	v_min_f32_e32 v112, v250, v112
	v_max_f32_e32 v20, v106, v252
	v_min_f32_e32 v252, v106, v252
	v_max_f32_e32 v113, v18, v16
	v_min_f32_e32 v16, v18, v16
	v_max_f32_e32 v34, v98, v1
	v_min_f32_e32 v1, v98, v1
	v_max_f32_e32 v122, v17, v127
	v_min_f32_e32 v127, v17, v127
	v_max_f32_e32 v36, v254, v121
	v_min_f32_e32 v121, v254, v121
	v_max_f32_e32 v32, v125, v20
	v_min_f32_e32 v20, v125, v20
	v_max_f32_e32 v33, v112, v252
	v_min_f32_e32 v252, v112, v252
	v_max_f32_e32 v35, v34, v16
	v_min_f32_e32 v16, v34, v16
	v_max_f32_e32 v117, v114, v1
	v_min_f32_e32 v1, v114, v1
	v_max_f32_e32 v48, v32, v116
	v_min_f32_e32 v116, v32, v116
	v_max_f32_e32 v49, v33, v20
	v_min_f32_e32 v20, v33, v20
	v_max_f32_e32 v50, v117, v122
	v_min_f32_e32 v122, v117, v122
	v_max_f32_e32 v51, v1, v127
	v_min_f32_e32 v127, v1, v127
	v_max_f32_e32 v52, v36, v48
	v_min_f32_e32 v48, v36, v48
	v_max_f32_e32 v53, v121, v116
	v_min_f32_e32 v116, v121, v116
	v_max_f32_e32 v55, v50, v16
	v_min_f32_e32 v16, v50, v16
	v_max_f32_e32 v57, v122, v51
	v_min_f32_e32 v51, v122, v51
	v_max_f32_e32 v40, v52, v127
	v_min_f32_e32 v127, v52, v127
	v_max_f32_e32 v42, v48, v53
	v_min_f32_e32 v53, v48, v53
	v_max_f32_e32 v43, v49, v116
	v_min_f32_e32 v116, v49, v116
	v_max_f32_e32 v149, v51, v40
	v_min_f32_e32 v40, v51, v40
	v_max_f32_e32 v54, v127, v42
	v_min_f32_e32 v42, v127, v42
	s_waitcnt vmcnt(0)
	v_pk_mul_f32 v[160:161], v[160:161], v[176:177]
	v_pk_mul_f32 v[162:163], v[162:163], v[178:179]
	v_pk_mul_f32 v[164:165], v[164:165], v[180:181]
	v_pk_mul_f32 v[166:167], v[166:167], v[182:183]
	v_pk_mul_f32 v[168:169], v[168:169], v[184:185]
	v_pk_mul_f32 v[170:171], v[170:171], v[186:187]
	v_pk_mul_f32 v[172:173], v[172:173], v[188:189]
	v_pk_mul_f32 v[174:175], v[174:175], v[190:191]
	v_max3_f32 v192, |v160|, |v161|, |v162|
	v_max3_f32 v192, |v163|, |v164|, v192
	v_max3_f32 v192, |v165|, |v166|, v192
	v_max3_f32 v192, |v167|, |v168|, v192
	v_max3_f32 v192, |v169|, |v170|, v192
	v_max3_f32 v192, |v171|, |v172|, v192
	v_max3_f32 v192, |v173|, |v174|, v192
	v_max_f32_e64 v192, |v175|, v192
	s_nop 1
	v_mov_b32_dpp v193, v192 quad_perm:[1,0,3,2] row_mask:0xf bank_mask:0xf bound_ctrl:1
	v_max_f32_e32 v192, v192, v193
	s_nop 1
	v_mov_b32_dpp v193, v192 quad_perm:[2,3,0,1] row_mask:0xf bank_mask:0xf bound_ctrl:1
	v_max_f32_e32 v192, v192, v193
	s_nop 1
	v_mov_b32_dpp v193, v192 row_half_mirror row_mask:0xf bank_mask:0xf bound_ctrl:1
	v_max_f32_e32 v192, v192, v193
	s_nop 1
	v_mov_b32_dpp v193, v192 row_mirror row_mask:0xf bank_mask:0xf bound_ctrl:1
	v_max_f32_e32 v192, v192, v193
	v_mov_b32_e32 v193, v192
	s_nop 1
	v_permlane16_swap_b32_e32 v192, v193
	s_nop 1
	v_max_f32_e32 v192, v192, v193
	v_mov_b32_e32 v193, v192
	s_nop 1
	v_permlane32_swap_b32_e32 v192, v193
	s_nop 1
	v_max_f32_e32 v192, v192, v193
	v_max_f32_e32 v192, 0xda24260, v192
	v_mul_f32_e32 v194, 0x3e2aaaab, v192
	global_store_dword v214, v194, s[12:13]
	v_div_scale_f32 v195, s[26:27], v194, v194, 1.0
	v_rcp_f32_e32 v196, v195
	v_div_scale_f32 v204, vcc, 1.0, v194, 1.0
	v_fma_f32 v205, -v195, v196, 1.0
	v_fmac_f32_e32 v196, v205, v196
	v_mul_f32_e32 v205, v204, v196
	v_fma_f32 v206, -v195, v205, v204
	v_fmac_f32_e32 v205, v206, v196
	v_fma_f32 v195, -v195, v205, v204
	s_nop 0
	v_div_fmas_f32 v195, v195, v196, v205
	v_div_fixup_f32 v207, v195, v194, 1.0
	v_mul_f32_e32 v160, v207, v160
	v_mul_f32_e32 v161, v207, v161
	v_mul_f32_e32 v162, v207, v162
	v_mul_f32_e32 v163, v207, v163
	v_mul_f32_e32 v164, v207, v164
	v_mul_f32_e32 v165, v207, v165
	v_mul_f32_e32 v166, v207, v166
	v_mul_f32_e32 v167, v207, v167
	v_mul_f32_e32 v168, v207, v168
	v_mul_f32_e32 v169, v207, v169
	v_mul_f32_e32 v170, v207, v170
	v_mul_f32_e32 v171, v207, v171
	v_mul_f32_e32 v172, v207, v172
	v_mul_f32_e32 v173, v207, v173
	v_mul_f32_e32 v174, v207, v174
	v_mul_f32_e32 v175, v207, v175
	v_mov_b32_e32 v208, 0
	v_mov_b32_e32 v209, 0
	v_mov_b32_e32 v210, 0
	v_mov_b32_e32 v193, 0
	v_cvt_scalef32_pk_fp4_f32 v208, v160, v161, 1.0
	v_cvt_scalef32_pk_fp4_f32 v209, v164, v165, 1.0
	v_cvt_scalef32_pk_fp4_f32 v210, v168, v169, 1.0
	v_cvt_scalef32_pk_fp4_f32 v193, v172, v173, 1.0
	v_cvt_scalef32_pk_fp4_f32 v208, v162, v163, 1.0 op_sel:[0,0,1,0]
	v_cvt_scalef32_pk_fp4_f32 v209, v166, v167, 1.0 op_sel:[0,0,1,0]
	v_cvt_scalef32_pk_fp4_f32 v210, v170, v171, 1.0 op_sel:[0,0,1,0]
	v_cvt_scalef32_pk_fp4_f32 v193, v174, v175, 1.0 op_sel:[0,0,1,0]
	global_store_short v213, v208, s[10:11] nt
	s_add_u32 s14, s10, 0x200000
	s_addc_u32 s15, s11, 0
	global_store_short v213, v209, s[14:15] nt
	s_add_u32 s14, s10, 0x400000
	s_addc_u32 s15, s11, 0
	global_store_short v213, v210, s[14:15] nt
	s_add_u32 s14, s10, 0x600000
	s_addc_u32 s15, s11, 0
	global_store_short v213, v193, s[14:15] nt
	s_add_u32 s10, s10, 0x20000
	s_addc_u32 s11, s11, 0
	s_add_u32 s12, s12, 0x2000
	s_addc_u32 s13, s13, 0
	global_load_dwordx4 v[160:163], v212, s[8:9] offset:0 nt
	global_load_dwordx4 v[164:167], v212, s[8:9] offset:1024 nt
	global_load_dwordx4 v[168:171], v212, s[8:9] offset:2048 nt
	global_load_dwordx4 v[172:175], v212, s[8:9] offset:3072 nt
	s_add_u32 s8, s8, 0x800000
	s_addc_u32 s9, s9, 0
	v_max_f32_e32 v105, v105, v31
	v_max_f32_e32 v120, v120, v110
	v_max_f32_e32 v126, v126, v123
	v_max_f32_e32 v7, v7, v118
	v_max_f32_e32 v115, v115, v11
	v_max_f32_e32 v9, v9, v21
	v_max_f32_e32 v147, v147, v10
	v_max_f32_e32 v144, v144, v22
	v_max_f32_e32 v6, v6, v8
	v_max_f32_e32 v145, v145, v249
	v_max_f32_e32 v5, v5, v25
	v_max_f32_e32 v146, v146, v124
	v_max_f32_e32 v111, v111, v23
	v_max_f32_e32 v119, v119, v3
	v_max_f32_e32 v104, v104, v102
	v_max_f32_e32 v15, v15, v151
	v_max_f32_e32 v56, v105, v6
	v_min_f32_e32 v6, v105, v6
	v_max_f32_e32 v58, v120, v145
	v_min_f32_e32 v145, v120, v145
	v_max_f32_e32 v59, v126, v5
	v_min_f32_e32 v5, v126, v5
	v_max_f32_e32 v148, v7, v146
	v_min_f32_e32 v146, v7, v146
	v_max_f32_e32 v46, v115, v111
	v_min_f32_e32 v111, v115, v111
	v_max_f32_e32 v30, v9, v119
	v_min_f32_e32 v119, v9, v119
	v_max_f32_e32 v28, v147, v104
	v_min_f32_e32 v104, v147, v104
	v_max_f32_e32 v12, v144, v15
	v_min_f32_e32 v15, v144, v15
	v_max_f32_e32 v251, v56, v46
	v_min_f32_e32 v46, v56, v46
	v_max_f32_e32 v60, v58, v30
	v_min_f32_e32 v30, v58, v30
	v_max_f32_e32 v62, v59, v28
	v_min_f32_e32 v28, v59, v28
	v_max_f32_e32 v13, v148, v12
	v_min_f32_e32 v12, v148, v12
	v_max_f32_e32 v44, v6, v111
	v_min_f32_e32 v111, v6, v111
	v_max_f32_e32 v45, v145, v119
	v_min_f32_e32 v119, v145, v119
	v_max_f32_e32 v14, v5, v104
	v_min_f32_e32 v104, v5, v104
	v_max_f32_e32 v96, v146, v15
	v_min_f32_e32 v15, v146, v15
	v_max_f32_e32 v29, v251, v62
	v_min_f32_e32 v62, v251, v62
	v_max_f32_e32 v103, v60, v13
	v_min_f32_e32 v13, v60, v13
	v_max_f32_e32 v61, v46, v28
	v_min_f32_e32 v28, v46, v28
	v_max_f32_e32 v100, v30, v12
	v_min_f32_e32 v12, v30, v12
	v_max_f32_e32 v99, v44, v14
	v_min_f32_e32 v14, v44, v14
	v_max_f32_e32 v2, v45, v96
	v_min_f32_e32 v96, v45, v96
	v_max_f32_e32 v108, v111, v104
	v_min_f32_e32 v104, v111, v104
	v_max_f32_e32 v97, v119, v15
	v_min_f32_e32 v15, v119, v15
	v_max_f32_e32 v250, v29, v103
	v_min_f32_e32 v103, v29, v103
	v_max_f32_e32 v106, v62, v13
	v_min_f32_e32 v13, v62, v13
	v_max_f32_e32 v18, v61, v100
	v_min_f32_e32 v100, v61, v100
	v_max_f32_e32 v98, v28, v12
	v_min_f32_e32 v12, v28, v12
	v_max_f32_e32 v17, v99, v2
	v_min_f32_e32 v2, v99, v2
	v_max_f32_e32 v254, v14, v96
	v_min_f32_e32 v96, v14, v96
	v_max_f32_e32 v125, v108, v97
	v_min_f32_e32 v97, v108, v97
	v_max_f32_e32 v112, v104, v15
	v_min_f32_e32 v15, v104, v15
	v_max_f32_e32 v150, v150, v63
	v_max_f32_e32 v107, v107, v252
	v_max_f32_e32 v19, v19, v20
	v_max_f32_e32 v39, v39, v116
	v_max_f32_e32 v0, v0, v43
	v_max_f32_e32 v41, v41, v53
	v_max_f32_e32 v255, v255, v42
	v_max_f32_e32 v24, v24, v54
	v_max_f32_e32 v38, v38, v40
	v_max_f32_e32 v26, v26, v149
	v_max_f32_e32 v37, v37, v57
	v_max_f32_e32 v27, v27, v16
	v_max_f32_e32 v109, v109, v55
	v_max_f32_e32 v4, v4, v35
	v_max_f32_e32 v101, v101, v113
	v_max_f32_e32 v47, v47, v253
	v_max_f32_e32 v34, v150, v38
	v_min_f32_e32 v38, v150, v38
	v_max_f32_e32 v114, v107, v26
	v_min_f32_e32 v26, v107, v26
	v_max_f32_e32 v32, v19, v37
	v_min_f32_e32 v37, v19, v37
	v_max_f32_e32 v33, v39, v27
	v_min_f32_e32 v27, v39, v27
	v_max_f32_e32 v117, v0, v109
	v_min_f32_e32 v109, v0, v109
	v_max_f32_e32 v1, v41, v4
	v_min_f32_e32 v4, v41, v4
	v_max_f32_e32 v36, v255, v101
	v_min_f32_e32 v101, v255, v101
	v_max_f32_e32 v121, v24, v47
	v_min_f32_e32 v47, v24, v47
	v_max_f32_e32 v50, v34, v117
	v_min_f32_e32 v117, v34, v117
	v_max_f32_e32 v122, v114, v1
	v_min_f32_e32 v1, v114, v1
	v_max_f32_e32 v52, v32, v36
	v_min_f32_e32 v36, v32, v36
	v_max_f32_e32 v48, v33, v121
	v_min_f32_e32 v121, v33, v121
	v_max_f32_e32 v49, v38, v109
	v_min_f32_e32 v109, v38, v109
	v_max_f32_e32 v51, v26, v4
	v_min_f32_e32 v4, v26, v4
	v_max_f32_e32 v127, v37, v101
	v_min_f32_e32 v101, v37, v101
	v_max_f32_e32 v151, v27, v47
	v_min_f32_e32 v47, v27, v47
	v_max_f32_e32 v102, v50, v52
	v_min_f32_e32 v52, v50, v52
	v_max_f32_e32 v3, v122, v48
	v_min_f32_e32 v48, v122, v48
	v_max_f32_e32 v23, v117, v36
	v_min_f32_e32 v36, v117, v36
	v_max_f32_e32 v124, v1, v121
	v_min_f32_e32 v121, v1, v121
	v_max_f32_e32 v25, v49, v127
	v_min_f32_e32 v127, v49, v127
	v_max_f32_e32 v249, v51, v151
	v_min_f32_e32 v151, v51, v151
	v_max_f32_e32 v8, v109, v101
	v_min_f32_e32 v101, v109, v101
	v_max_f32_e32 v22, v4, v47
	v_min_f32_e32 v47, v4, v47
	v_max_f32_e32 v10, v102, v3
	v_min_f32_e32 v3, v102, v3
	v_max_f32_e32 v21, v52, v48
	v_min_f32_e32 v48, v52, v48
	v_max_f32_e32 v11, v23, v124
	v_min_f32_e32 v124, v23, v124
	v_max_f32_e32 v118, v36, v121
	v_min_f32_e32 v121, v36, v121
	v_max_f32_e32 v123, v25, v249
	v_min_f32_e32 v249, v25, v249
	v_max_f32_e32 v110, v127, v151
	v_min_f32_e32 v151, v127, v151
	v_max_f32_e32 v31, v8, v22
	v_min_f32_e32 v22, v8, v22
	v_max_f32_e32 v105, v101, v47
	v_min_f32_e32 v47, v101, v47
	v_max_f32_e32 v250, v250, v47
	v_max_f32_e32 v103, v103, v105
	v_max_f32_e32 v106, v106, v22
	v_max_f32_e32 v13, v13, v31
	v_max_f32_e32 v18, v18, v151
	v_max_f32_e32 v100, v100, v110
	v_max_f32_e32 v98, v98, v249
	v_max_f32_e32 v12, v12, v123
	v_max_f32_e32 v17, v17, v121
	v_max_f32_e32 v2, v2, v118
	v_max_f32_e32 v254, v254, v124
	v_max_f32_e32 v96, v96, v11
	v_max_f32_e32 v125, v125, v48
	v_max_f32_e32 v97, v97, v21
	v_max_f32_e32 v112, v112, v3
	v_max_f32_e32 v15, v15, v10
	v_max_f32_e32 v120, v250, v17
	v_min_f32_e32 v17, v250, v17
	v_max_f32_e32 v126, v103, v2
	v_min_f32_e32 v2, v103, v2
	v_max_f32_e32 v7, v106, v254
	v_min_f32_e32 v254, v106, v254
	v_max_f32_e32 v115, v13, v96
	v_min_f32_e32 v96, v13, v96
	v_max_f32_e32 v9, v18, v125
	v_min_f32_e32 v125, v18, v125
	v_max_f32_e32 v147, v100, v97
	v_min_f32_e32 v97, v100, v97
	v_max_f32_e32 v144, v98, v112
	v_min_f32_e32 v112, v98, v112
	v_max_f32_e32 v56, v12, v15
	v_min_f32_e32 v15, v12, v15
	v_max_f32_e32 v58, v120, v9
	v_min_f32_e32 v9, v120, v9
	v_max_f32_e32 v59, v126, v147
	v_min_f32_e32 v147, v126, v147
	v_max_f32_e32 v148, v7, v144
	v_min_f32_e32 v144, v7, v144
	v_max_f32_e32 v6, v115, v56
	v_min_f32_e32 v56, v115, v56
	v_max_f32_e32 v145, v17, v125
	v_min_f32_e32 v125, v17, v125
	v_max_f32_e32 v5, v2, v97
	v_min_f32_e32 v97, v2, v97
	v_max_f32_e32 v146, v254, v112
	v_min_f32_e32 v112, v254, v112
	v_max_f32_e32 v251, v96, v15
	v_min_f32_e32 v15, v96, v15
	v_max_f32_e32 v60, v58, v148
	v_min_f32_e32 v148, v58, v148
	v_max_f32_e32 v46, v59, v6
	v_min_f32_e32 v6, v59, v6
	v_max_f32_e32 v30, v9, v144
	v_min_f32_e32 v144, v9, v144
	v_max_f32_e32 v44, v147, v56
	v_min_f32_e32 v56, v147, v56
	v_max_f32_e32 v45, v145, v146
	v_min_f32_e32 v146, v145, v146
	v_max_f32_e32 v111, v5, v251
	v_min_f32_e32 v251, v5, v251
	v_max_f32_e32 v119, v125, v112
	v_min_f32_e32 v112, v125, v112
	v_max_f32_e32 v29, v97, v15
	v_min_f32_e32 v15, v97, v15
	v_max_f32_e32 v62, v60, v46
	v_min_f32_e32 v46, v60, v46
	v_max_f32_e32 v61, v148, v6
	v_min_f32_e32 v6, v148, v6
	v_max_f32_e32 v28, v30, v44
	v_min_f32_e32 v44, v30, v44
	v_max_f32_e32 v99, v144, v56
	v_min_f32_e32 v56, v144, v56
	v_max_f32_e32 v14, v45, v111
	v_min_f32_e32 v111, v45, v111
	v_max_f32_e32 v108, v146, v251
	v_min_f32_e32 v251, v146, v251
	v_max_f32_e32 v104, v119, v29
	v_min_f32_e32 v29, v119, v29
	v_max_f32_e32 v253, v112, v15
	v_min_f32_e32 v15, v112, v15
	v_mov_b32_e32 v113, v62
	v_mov_b32_e32 v35, v46
	v_mov_b32_e32 v55, v61
	v_mov_b32_e32 v16, v6
	v_mov_b32_e32 v57, v28
	v_mov_b32_e32 v149, v44
	v_mov_b32_e32 v40, v99
	v_mov_b32_e32 v54, v56
	v_mov_b32_e32 v42, v14
	v_mov_b32_e32 v53, v111
	v_mov_b32_e32 v43, v108
	v_mov_b32_e32 v116, v251
	v_mov_b32_e32 v20, v104
	v_mov_b32_e32 v252, v29
	v_mov_b32_e32 v63, v253
	v_mov_b32_e32 v150, v15
	s_nop 1
	v_permlane32_swap_b32_e32 v62, v113
	v_permlane32_swap_b32_e32 v46, v35
	v_permlane32_swap_b32_e32 v61, v55
	v_permlane32_swap_b32_e32 v6, v16
	v_permlane32_swap_b32_e32 v28, v57
	v_permlane32_swap_b32_e32 v44, v149
	v_permlane32_swap_b32_e32 v99, v40
	v_permlane32_swap_b32_e32 v56, v54
	v_permlane32_swap_b32_e32 v14, v42
	v_permlane32_swap_b32_e32 v111, v53
	v_permlane32_swap_b32_e32 v108, v43
	v_permlane32_swap_b32_e32 v251, v116
	v_permlane32_swap_b32_e32 v104, v20
	v_permlane32_swap_b32_e32 v29, v252
	v_permlane32_swap_b32_e32 v253, v63
	v_permlane32_swap_b32_e32 v15, v150
	s_nop 1
	v_max_f32_e32 v62, v62, v150
	v_max_f32_e32 v46, v46, v63
	v_max_f32_e32 v61, v61, v252
	v_max_f32_e32 v6, v6, v20
	v_max_f32_e32 v28, v28, v116
	v_max_f32_e32 v44, v44, v43
	v_max_f32_e32 v99, v99, v53
	v_max_f32_e32 v56, v56, v42
	v_max_f32_e32 v14, v14, v54
	v_max_f32_e32 v111, v111, v40
	v_max_f32_e32 v108, v108, v149
	v_max_f32_e32 v251, v251, v57
	v_max_f32_e32 v104, v104, v16
	v_max_f32_e32 v29, v29, v55
	v_max_f32_e32 v253, v253, v35
	v_max_f32_e32 v15, v15, v113
	v_max_f32_e32 v107, v62, v14
	v_min_f32_e32 v14, v62, v14
	v_max_f32_e32 v19, v46, v111
	v_min_f32_e32 v111, v46, v111
	v_max_f32_e32 v39, v61, v108
	v_min_f32_e32 v108, v61, v108
	v_max_f32_e32 v0, v6, v251
	v_min_f32_e32 v251, v6, v251
	v_max_f32_e32 v41, v28, v104
	v_min_f32_e32 v104, v28, v104
	v_max_f32_e32 v255, v44, v29
	v_min_f32_e32 v29, v44, v29
	v_max_f32_e32 v24, v99, v253
	v_min_f32_e32 v253, v99, v253
	v_max_f32_e32 v34, v56, v15
	v_min_f32_e32 v15, v56, v15
	v_max_f32_e32 v114, v107, v41
	v_min_f32_e32 v41, v107, v41
	v_max_f32_e32 v32, v19, v255
	v_min_f32_e32 v255, v19, v255
	v_max_f32_e32 v33, v39, v24
	v_min_f32_e32 v24, v39, v24
	v_max_f32_e32 v38, v0, v34
	v_min_f32_e32 v34, v0, v34
	v_max_f32_e32 v26, v14, v104
	v_min_f32_e32 v104, v14, v104
	v_max_f32_e32 v37, v111, v29
	v_min_f32_e32 v29, v111, v29
	v_max_f32_e32 v27, v108, v253
	v_min_f32_e32 v253, v108, v253
	v_max_f32_e32 v50, v251, v15
	v_min_f32_e32 v15, v251, v15
	v_max_f32_e32 v122, v114, v33
	v_min_f32_e32 v33, v114, v33
	v_max_f32_e32 v117, v32, v38
	v_min_f32_e32 v38, v32, v38
	v_max_f32_e32 v1, v41, v24
	v_min_f32_e32 v24, v41, v24
	v_max_f32_e32 v49, v255, v34
	v_min_f32_e32 v34, v255, v34
	v_max_f32_e32 v51, v26, v27
	v_min_f32_e32 v27, v26, v27
	v_max_f32_e32 v109, v37, v50
	v_min_f32_e32 v50, v37, v50
	v_max_f32_e32 v4, v104, v253
	v_min_f32_e32 v253, v104, v253
	v_max_f32_e32 v102, v29, v15
	v_min_f32_e32 v15, v29, v15
	v_max_f32_e32 v128, v122, v117
	v_min_f32_e32 v129, v122, v117
	v_max_f32_e32 v130, v33, v38
	v_min_f32_e32 v131, v33, v38
	v_max_f32_e32 v132, v1, v49
	v_min_f32_e32 v133, v1, v49
	v_max_f32_e32 v134, v24, v34
	v_min_f32_e32 v135, v24, v34
	v_max_f32_e32 v136, v51, v109
	v_min_f32_e32 v137, v51, v109
	v_max_f32_e32 v138, v27, v50
	v_min_f32_e32 v139, v27, v50
	v_max_f32_e32 v140, v4, v102
	v_min_f32_e32 v141, v4, v102
	v_max_f32_e32 v142, v253, v15
	v_min_f32_e32 v143, v253, v15
	s_waitcnt vmcnt(0)
	v_pk_mul_f32 v[160:161], v[160:161], v[176:177]
	v_pk_mul_f32 v[162:163], v[162:163], v[178:179]
	v_pk_mul_f32 v[164:165], v[164:165], v[180:181]
	v_pk_mul_f32 v[166:167], v[166:167], v[182:183]
	v_pk_mul_f32 v[168:169], v[168:169], v[184:185]
	v_pk_mul_f32 v[170:171], v[170:171], v[186:187]
	v_pk_mul_f32 v[172:173], v[172:173], v[188:189]
	v_pk_mul_f32 v[174:175], v[174:175], v[190:191]
	v_max3_f32 v192, |v160|, |v161|, |v162|
	v_max3_f32 v192, |v163|, |v164|, v192
	v_max3_f32 v192, |v165|, |v166|, v192
	v_max3_f32 v192, |v167|, |v168|, v192
	v_max3_f32 v192, |v169|, |v170|, v192
	v_max3_f32 v192, |v171|, |v172|, v192
	v_max3_f32 v192, |v173|, |v174|, v192
	v_max_f32_e64 v192, |v175|, v192
	s_nop 1
	v_mov_b32_dpp v193, v192 quad_perm:[1,0,3,2] row_mask:0xf bank_mask:0xf bound_ctrl:1
	v_max_f32_e32 v192, v192, v193
	s_nop 1
	v_mov_b32_dpp v193, v192 quad_perm:[2,3,0,1] row_mask:0xf bank_mask:0xf bound_ctrl:1
	v_max_f32_e32 v192, v192, v193
	s_nop 1
	v_mov_b32_dpp v193, v192 row_half_mirror row_mask:0xf bank_mask:0xf bound_ctrl:1
	v_max_f32_e32 v192, v192, v193
	s_nop 1
	v_mov_b32_dpp v193, v192 row_mirror row_mask:0xf bank_mask:0xf bound_ctrl:1
	v_max_f32_e32 v192, v192, v193
	v_mov_b32_e32 v193, v192
	s_nop 1
	v_permlane16_swap_b32_e32 v192, v193
	s_nop 1
	v_max_f32_e32 v192, v192, v193
	v_mov_b32_e32 v193, v192
	s_nop 1
	v_permlane32_swap_b32_e32 v192, v193
	s_nop 1
	v_max_f32_e32 v192, v192, v193
	v_max_f32_e32 v192, 0xda24260, v192
	v_mul_f32_e32 v194, 0x3e2aaaab, v192
	global_store_dword v214, v194, s[12:13]
	v_div_scale_f32 v195, s[26:27], v194, v194, 1.0
	v_rcp_f32_e32 v196, v195
	v_div_scale_f32 v204, vcc, 1.0, v194, 1.0
	v_fma_f32 v205, -v195, v196, 1.0
	v_fmac_f32_e32 v196, v205, v196
	v_mul_f32_e32 v205, v204, v196
	v_fma_f32 v206, -v195, v205, v204
	v_fmac_f32_e32 v205, v206, v196
	v_fma_f32 v195, -v195, v205, v204
	s_nop 0
	v_div_fmas_f32 v195, v195, v196, v205
	v_div_fixup_f32 v207, v195, v194, 1.0
	v_mul_f32_e32 v160, v207, v160
	v_mul_f32_e32 v161, v207, v161
	v_mul_f32_e32 v162, v207, v162
	v_mul_f32_e32 v163, v207, v163
	v_mul_f32_e32 v164, v207, v164
	v_mul_f32_e32 v165, v207, v165
	v_mul_f32_e32 v166, v207, v166
	v_mul_f32_e32 v167, v207, v167
	v_mul_f32_e32 v168, v207, v168
	v_mul_f32_e32 v169, v207, v169
	v_mul_f32_e32 v170, v207, v170
	v_mul_f32_e32 v171, v207, v171
	v_mul_f32_e32 v172, v207, v172
	v_mul_f32_e32 v173, v207, v173
	v_mul_f32_e32 v174, v207, v174
	v_mul_f32_e32 v175, v207, v175
	v_mov_b32_e32 v208, 0
	v_mov_b32_e32 v209, 0
	v_mov_b32_e32 v210, 0
	v_mov_b32_e32 v193, 0
	v_cvt_scalef32_pk_fp4_f32 v208, v160, v161, 1.0
	v_cvt_scalef32_pk_fp4_f32 v209, v164, v165, 1.0
	v_cvt_scalef32_pk_fp4_f32 v210, v168, v169, 1.0
	v_cvt_scalef32_pk_fp4_f32 v193, v172, v173, 1.0
	v_cvt_scalef32_pk_fp4_f32 v208, v162, v163, 1.0 op_sel:[0,0,1,0]
	v_cvt_scalef32_pk_fp4_f32 v209, v166, v167, 1.0 op_sel:[0,0,1,0]
	v_cvt_scalef32_pk_fp4_f32 v210, v170, v171, 1.0 op_sel:[0,0,1,0]
	v_cvt_scalef32_pk_fp4_f32 v193, v174, v175, 1.0 op_sel:[0,0,1,0]
	global_store_short v213, v208, s[10:11] nt
	s_add_u32 s14, s10, 0x200000
	s_addc_u32 s15, s11, 0
	global_store_short v213, v209, s[14:15] nt
	s_add_u32 s14, s10, 0x400000
	s_addc_u32 s15, s11, 0
	global_store_short v213, v210, s[14:15] nt
	s_add_u32 s14, s10, 0x600000
	s_addc_u32 s15, s11, 0
	global_store_short v213, v193, s[14:15] nt
	s_add_u32 s10, s10, 0x20000
	s_addc_u32 s11, s11, 0
	s_add_u32 s12, s12, 0x2000
	s_addc_u32 s13, s13, 0
	global_load_dwordx4 v[160:163], v212, s[8:9] offset:0 nt
	global_load_dwordx4 v[164:167], v212, s[8:9] offset:1024 nt
	global_load_dwordx4 v[168:171], v212, s[8:9] offset:2048 nt
	global_load_dwordx4 v[172:175], v212, s[8:9] offset:3072 nt
	s_add_u32 s8, s8, 0x800000
	s_addc_u32 s9, s9, 0
	ds_write_b8 v240, v128 offset:0
	ds_write_b8 v240, v129 offset:1
	ds_write_b8 v240, v130 offset:2
	ds_write_b8 v240, v131 offset:3
	ds_write_b8 v240, v132 offset:4
	ds_write_b8 v240, v133 offset:5
	ds_write_b8 v240, v134 offset:6
	ds_write_b8 v240, v135 offset:7
	ds_write_b8 v240, v136 offset:8
	ds_write_b8 v240, v137 offset:9
	ds_write_b8 v240, v138 offset:10
	ds_write_b8 v240, v139 offset:11
	ds_write_b8 v240, v140 offset:12
	ds_write_b8 v240, v141 offset:13
	ds_write_b8 v240, v142 offset:14
	ds_write_b8 v240, v143 offset:15
	ds_read_b128 v[96:99], v215 offset:32768
	ds_read_b128 v[100:103], v232 offset:32768
	ds_read_b128 v[104:107], v233 offset:32768
	ds_read_b128 v[108:111], v234 offset:32768
	ds_read_b128 v[112:115], v235 offset:32768
	ds_read_b128 v[116:119], v236 offset:32768
	ds_read_b128 v[120:123], v237 offset:32768
	ds_read_b128 v[124:127], v238 offset:32768
	s_waitcnt vmcnt(27)
	s_waitcnt lgkmcnt(4)
	v_mfma_f32_32x32x16_bf16 v[0:15], v[96:99], v[64:67], 0
	v_mfma_f32_32x32x16_bf16 v[0:15], v[100:103], v[68:71], v[0:15]
	v_mfma_f32_32x32x16_bf16 v[0:15], v[104:107], v[72:75], v[0:15]
	v_mfma_f32_32x32x16_bf16 v[0:15], v[108:111], v[76:79], v[0:15]
	ds_read_b128 v[96:99], v215 offset:40960
	ds_read_b128 v[100:103], v232 offset:40960
	ds_read_b128 v[104:107], v233 offset:40960
	ds_read_b128 v[108:111], v234 offset:40960
	s_waitcnt lgkmcnt(4)
	v_mfma_f32_32x32x16_bf16 v[0:15], v[112:115], v[80:83], v[0:15]
	v_mfma_f32_32x32x16_bf16 v[0:15], v[116:119], v[84:87], v[0:15]
	v_mfma_f32_32x32x16_bf16 v[0:15], v[120:123], v[88:91], v[0:15]
	v_mfma_f32_32x32x16_bf16 v[0:15], v[124:127], v[92:95], v[0:15]
	ds_read_b128 v[112:115], v235 offset:40960
	ds_read_b128 v[116:119], v236 offset:40960
	ds_read_b128 v[120:123], v237 offset:40960
	ds_read_b128 v[124:127], v238 offset:40960
	s_waitcnt lgkmcnt(4)
	v_mfma_f32_32x32x16_bf16 v[16:31], v[96:99], v[64:67], 0
	v_mfma_f32_32x32x16_bf16 v[16:31], v[100:103], v[68:71], v[16:31]
	v_mfma_f32_32x32x16_bf16 v[16:31], v[104:107], v[72:75], v[16:31]
	v_mfma_f32_32x32x16_bf16 v[16:31], v[108:111], v[76:79], v[16:31]
	ds_read_b128 v[96:99], v215 offset:49152
	ds_read_b128 v[100:103], v232 offset:49152
	ds_read_b128 v[104:107], v233 offset:49152
	ds_read_b128 v[108:111], v234 offset:49152
	s_waitcnt lgkmcnt(4)
	v_mfma_f32_32x32x16_bf16 v[16:31], v[112:115], v[80:83], v[16:31]
	v_mfma_f32_32x32x16_bf16 v[16:31], v[116:119], v[84:87], v[16:31]
	v_mfma_f32_32x32x16_bf16 v[16:31], v[120:123], v[88:91], v[16:31]
	v_mfma_f32_32x32x16_bf16 v[16:31], v[124:127], v[92:95], v[16:31]
	ds_read_b128 v[112:115], v235 offset:49152
	ds_read_b128 v[116:119], v236 offset:49152
	ds_read_b128 v[120:123], v237 offset:49152
	ds_read_b128 v[124:127], v238 offset:49152
	s_waitcnt lgkmcnt(4)
	v_mfma_f32_32x32x16_bf16 v[32:47], v[96:99], v[64:67], 0
	v_mfma_f32_32x32x16_bf16 v[32:47], v[100:103], v[68:71], v[32:47]
	v_mfma_f32_32x32x16_bf16 v[32:47], v[104:107], v[72:75], v[32:47]
	v_mfma_f32_32x32x16_bf16 v[32:47], v[108:111], v[76:79], v[32:47]
	ds_read_b128 v[96:99], v215 offset:57344
	ds_read_b128 v[100:103], v232 offset:57344
	ds_read_b128 v[104:107], v233 offset:57344
	ds_read_b128 v[108:111], v234 offset:57344
	s_waitcnt lgkmcnt(4)
	v_mfma_f32_32x32x16_bf16 v[32:47], v[112:115], v[80:83], v[32:47]
	v_mfma_f32_32x32x16_bf16 v[32:47], v[116:119], v[84:87], v[32:47]
	v_mfma_f32_32x32x16_bf16 v[32:47], v[120:123], v[88:91], v[32:47]
	v_mfma_f32_32x32x16_bf16 v[32:47], v[124:127], v[92:95], v[32:47]
	ds_read_b128 v[112:115], v235 offset:57344
	ds_read_b128 v[116:119], v236 offset:57344
	ds_read_b128 v[120:123], v237 offset:57344
	ds_read_b128 v[124:127], v238 offset:57344
	s_waitcnt lgkmcnt(4)
	v_mfma_f32_32x32x16_bf16 v[48:63], v[96:99], v[64:67], 0
	v_mfma_f32_32x32x16_bf16 v[48:63], v[100:103], v[68:71], v[48:63]
	v_mfma_f32_32x32x16_bf16 v[48:63], v[104:107], v[72:75], v[48:63]
	v_mfma_f32_32x32x16_bf16 v[48:63], v[108:111], v[76:79], v[48:63]
	s_waitcnt lgkmcnt(0)
	v_mfma_f32_32x32x16_bf16 v[48:63], v[112:115], v[80:83], v[48:63]
	v_mfma_f32_32x32x16_bf16 v[48:63], v[116:119], v[84:87], v[48:63]
	v_mfma_f32_32x32x16_bf16 v[48:63], v[120:123], v[88:91], v[48:63]
	v_mfma_f32_32x32x16_bf16 v[48:63], v[124:127], v[92:95], v[48:63]
	s_nop 11
	v_and_or_b32 v0, v0, s6, v211
	v_or_b32_e32 v0, 0x7b, v0
	v_and_or_b32 v1, v1, s6, v211
	v_or_b32_e32 v1, 0x7a, v1
	v_and_or_b32 v2, v2, s6, v211
	v_or_b32_e32 v2, 0x79, v2
	v_and_or_b32 v3, v3, s6, v211
	v_or_b32_e32 v3, 0x78, v3
	v_and_or_b32 v4, v4, s6, v211
	v_or_b32_e32 v4, 0x73, v4
	v_and_or_b32 v5, v5, s6, v211
	v_or_b32_e32 v5, 0x72, v5
	v_and_or_b32 v6, v6, s6, v211
	v_or_b32_e32 v6, 0x71, v6
	v_and_or_b32 v7, v7, s6, v211
	v_or_b32_e32 v7, 0x70, v7
	v_and_or_b32 v8, v8, s6, v211
	v_or_b32_e32 v8, 0x6b, v8
	v_and_or_b32 v9, v9, s6, v211
	v_or_b32_e32 v9, 0x6a, v9
	v_and_or_b32 v10, v10, s6, v211
	v_or_b32_e32 v10, 0x69, v10
	v_and_or_b32 v11, v11, s6, v211
	v_or_b32_e32 v11, 0x68, v11
	v_and_or_b32 v12, v12, s6, v211
	v_or_b32_e32 v12, 0x63, v12
	v_and_or_b32 v13, v13, s6, v211
	v_or_b32_e32 v13, 0x62, v13
	v_and_or_b32 v14, v14, s6, v211
	v_or_b32_e32 v14, 0x61, v14
	v_and_or_b32 v15, v15, s6, v211
	v_or_b32_e32 v15, 0x60, v15
	v_and_or_b32 v16, v16, s6, v211
	v_or_b32_e32 v16, 0x5b, v16
	v_and_or_b32 v17, v17, s6, v211
	v_or_b32_e32 v17, 0x5a, v17
	v_and_or_b32 v18, v18, s6, v211
	v_or_b32_e32 v18, 0x59, v18
	v_and_or_b32 v19, v19, s6, v211
	v_or_b32_e32 v19, 0x58, v19
	v_and_or_b32 v20, v20, s6, v211
	v_or_b32_e32 v20, 0x53, v20
	v_and_or_b32 v21, v21, s6, v211
	v_or_b32_e32 v21, 0x52, v21
	v_and_or_b32 v22, v22, s6, v211
	v_or_b32_e32 v22, 0x51, v22
	v_and_or_b32 v23, v23, s6, v211
	v_or_b32_e32 v23, 0x50, v23
	v_and_or_b32 v24, v24, s6, v211
	v_or_b32_e32 v24, 0x4b, v24
	v_and_or_b32 v25, v25, s6, v211
	v_or_b32_e32 v25, 0x4a, v25
	v_and_or_b32 v26, v26, s6, v211
	v_or_b32_e32 v26, 0x49, v26
	v_and_or_b32 v27, v27, s6, v211
	v_or_b32_e32 v27, 0x48, v27
	v_and_or_b32 v28, v28, s6, v211
	v_or_b32_e32 v28, 0x43, v28
	v_and_or_b32 v29, v29, s6, v211
	v_or_b32_e32 v29, 0x42, v29
	v_and_or_b32 v30, v30, s6, v211
	v_or_b32_e32 v30, 0x41, v30
	v_and_or_b32 v31, v31, s6, v211
	v_or_b32_e32 v31, 64, v31
	v_and_or_b32 v32, v32, s6, v211
	v_or_b32_e32 v32, 59, v32
	v_and_or_b32 v33, v33, s6, v211
	v_or_b32_e32 v33, 58, v33
	v_and_or_b32 v34, v34, s6, v211
	v_or_b32_e32 v34, 57, v34
	v_and_or_b32 v35, v35, s6, v211
	v_or_b32_e32 v35, 56, v35
	v_and_or_b32 v36, v36, s6, v211
	v_or_b32_e32 v36, 51, v36
	v_and_or_b32 v37, v37, s6, v211
	v_or_b32_e32 v37, 50, v37
	v_and_or_b32 v38, v38, s6, v211
	v_or_b32_e32 v38, 49, v38
	v_and_or_b32 v39, v39, s6, v211
	v_or_b32_e32 v39, 48, v39
	v_and_or_b32 v40, v40, s6, v211
	v_or_b32_e32 v40, 43, v40
	v_and_or_b32 v41, v41, s6, v211
	v_or_b32_e32 v41, 42, v41
	v_and_or_b32 v42, v42, s6, v211
	v_or_b32_e32 v42, 41, v42
	v_and_or_b32 v43, v43, s6, v211
	v_or_b32_e32 v43, 40, v43
	v_and_or_b32 v44, v44, s6, v211
	v_or_b32_e32 v44, 35, v44
	v_and_or_b32 v45, v45, s6, v211
	v_or_b32_e32 v45, 34, v45
	v_and_or_b32 v46, v46, s6, v211
	v_or_b32_e32 v46, 33, v46
	v_and_or_b32 v47, v47, s6, v211
	v_or_b32_e32 v47, 32, v47
	v_and_or_b32 v48, v48, s6, v211
	v_or_b32_e32 v48, 27, v48
	v_and_or_b32 v49, v49, s6, v211
	v_or_b32_e32 v49, 26, v49
	v_and_or_b32 v50, v50, s6, v211
	v_or_b32_e32 v50, 25, v50
	v_and_or_b32 v51, v51, s6, v211
	v_or_b32_e32 v51, 24, v51
	v_and_or_b32 v52, v52, s6, v211
	v_or_b32_e32 v52, 19, v52
	v_and_or_b32 v53, v53, s6, v211
	v_or_b32_e32 v53, 18, v53
	v_and_or_b32 v54, v54, s6, v211
	v_or_b32_e32 v54, 17, v54
	v_and_or_b32 v55, v55, s6, v211
	v_or_b32_e32 v55, 16, v55
	v_and_or_b32 v56, v56, s6, v211
	v_or_b32_e32 v56, 11, v56
	v_and_or_b32 v57, v57, s6, v211
	v_or_b32_e32 v57, 10, v57
	v_and_or_b32 v58, v58, s6, v211
	v_or_b32_e32 v58, 9, v58
	v_and_or_b32 v59, v59, s6, v211
	v_or_b32_e32 v59, 8, v59
	v_and_or_b32 v60, v60, s6, v211
	v_or_b32_e32 v60, 3, v60
	v_and_or_b32 v61, v61, s6, v211
	v_or_b32_e32 v61, 2, v61
	v_and_or_b32 v62, v62, s6, v211
	v_or_b32_e32 v62, 1, v62
	v_and_or_b32 v63, v63, s6, v211
	v_or_b32_e32 v63, 0, v63
	v_max_f32_e32 v144, v0, v13
	v_min_f32_e32 v13, v0, v13
	v_max_f32_e32 v145, v1, v12
	v_min_f32_e32 v12, v1, v12
	v_max_f32_e32 v146, v2, v15
	v_min_f32_e32 v15, v2, v15
	v_max_f32_e32 v147, v3, v14
	v_min_f32_e32 v14, v3, v14
	v_max_f32_e32 v148, v4, v8
	v_min_f32_e32 v8, v4, v8
	v_max_f32_e32 v149, v5, v6
	v_min_f32_e32 v6, v5, v6
	v_max_f32_e32 v150, v7, v11
	v_min_f32_e32 v11, v7, v11
	v_max_f32_e32 v151, v9, v10
	v_min_f32_e32 v10, v9, v10
	v_max_f32_e32 v249, v144, v149
	v_min_f32_e32 v149, v144, v149
	v_max_f32_e32 v250, v145, v150
	v_min_f32_e32 v150, v145, v150
	v_max_f32_e32 v251, v146, v151
	v_min_f32_e32 v151, v146, v151
	v_max_f32_e32 v252, v147, v148
	v_min_f32_e32 v148, v147, v148
	v_max_f32_e32 v253, v6, v13
	v_min_f32_e32 v13, v6, v13
	v_max_f32_e32 v254, v8, v14
	v_min_f32_e32 v14, v8, v14
	v_max_f32_e32 v255, v10, v15
	v_min_f32_e32 v15, v10, v15
	v_max_f32_e32 v96, v11, v12
	v_min_f32_e32 v12, v11, v12
	v_max_f32_e32 v97, v249, v250
	v_min_f32_e32 v250, v249, v250
	v_max_f32_e32 v98, v251, v252
	v_min_f32_e32 v252, v251, v252
	v_max_f32_e32 v99, v148, v149
	v_min_f32_e32 v149, v148, v149
	v_max_f32_e32 v100, v253, v254
	v_min_f32_e32 v254, v253, v254
	v_max_f32_e32 v101, v150, v151
	v_min_f32_e32 v151, v150, v151
	v_max_f32_e32 v102, v255, v96
	v_min_f32_e32 v96, v255, v96
	v_max_f32_e32 v103, v12, v13
	v_min_f32_e32 v13, v12, v13
	v_max_f32_e32 v104, v14, v15
	v_min_f32_e32 v15, v14, v15
	v_max_f32_e32 v105, v97, v98
	v_min_f32_e32 v98, v97, v98
	v_max_f32_e32 v106, v250, v252
	v_min_f32_e32 v252, v250, v252
	v_max_f32_e32 v107, v99, v102
	v_min_f32_e32 v102, v99, v102
	v_max_f32_e32 v108, v149, v96
	v_min_f32_e32 v96, v149, v96
	v_max_f32_e32 v109, v100, v101
	v_min_f32_e32 v101, v100, v101
	v_max_f32_e32 v110, v254, v151
	v_min_f32_e32 v151, v254, v151
	v_max_f32_e32 v111, v103, v104
	v_min_f32_e32 v104, v103, v104
	v_max_f32_e32 v112, v13, v15
	v_min_f32_e32 v15, v13, v15
	v_max_f32_e32 v113, v106, v98
	v_min_f32_e32 v98, v106, v98
	v_max_f32_e32 v114, v252, v111
	v_min_f32_e32 v111, v252, v111
	v_max_f32_e32 v115, v107, v109
	v_min_f32_e32 v109, v107, v109
	v_max_f32_e32 v116, v108, v101
	v_min_f32_e32 v101, v108, v101
	v_max_f32_e32 v117, v110, v102
	v_min_f32_e32 v102, v110, v102
	v_max_f32_e32 v118, v151, v96
	v_min_f32_e32 v96, v151, v96
	v_max_f32_e32 v119, v112, v104
	v_min_f32_e32 v104, v112, v104
	v_max_f32_e32 v120, v113, v115
	v_min_f32_e32 v115, v113, v115
	v_max_f32_e32 v121, v98, v109
	v_min_f32_e32 v109, v98, v109
	v_max_f32_e32 v122, v116, v117
	v_min_f32_e32 v117, v116, v117
	v_max_f32_e32 v123, v101, v102
	v_min_f32_e32 v102, v101, v102
	v_max_f32_e32 v124, v118, v119
	v_min_f32_e32 v119, v118, v119
	v_max_f32_e32 v125, v96, v104
	v_min_f32_e32 v104, v96, v104
	v_max_f32_e32 v126, v121, v115
	v_min_f32_e32 v115, v121, v115
	v_max_f32_e32 v127, v114, v109
	v_min_f32_e32 v109, v114, v109
	v_max_f32_e32 v64, v124, v111
	v_min_f32_e32 v111, v124, v111
	v_max_f32_e32 v65, v125, v119
	v_min_f32_e32 v119, v125, v119
	v_max_f32_e32 v66, v127, v122
	v_min_f32_e32 v122, v127, v122
	v_max_f32_e32 v67, v109, v117
	v_min_f32_e32 v117, v109, v117
	v_max_f32_e32 v68, v123, v64
	v_min_f32_e32 v64, v123, v64
	v_max_f32_e32 v69, v102, v111
	v_min_f32_e32 v111, v102, v111
	v_max_f32_e32 v70, v66, v115
	v_min_f32_e32 v115, v66, v115
	v_max_f32_e32 v71, v122, v67
	v_min_f32_e32 v67, v122, v67
	v_max_f32_e32 v72, v68, v117
	v_min_f32_e32 v117, v68, v117
	v_max_f32_e32 v73, v64, v69
	v_min_f32_e32 v69, v64, v69
	v_max_f32_e32 v74, v65, v111
	v_min_f32_e32 v111, v65, v111
	v_max_f32_e32 v75, v67, v72
	v_min_f32_e32 v72, v67, v72
	v_max_f32_e32 v76, v117, v73
	v_min_f32_e32 v73, v117, v73
	v_max_f32_e32 v77, v16, v29
	v_min_f32_e32 v29, v16, v29
	v_max_f32_e32 v78, v17, v28
	v_min_f32_e32 v28, v17, v28
	v_max_f32_e32 v79, v18, v31
	v_min_f32_e32 v31, v18, v31
	v_max_f32_e32 v80, v19, v30
	v_min_f32_e32 v30, v19, v30
	v_max_f32_e32 v81, v20, v24
	v_min_f32_e32 v24, v20, v24
	v_max_f32_e32 v82, v21, v22
	v_min_f32_e32 v22, v21, v22
	v_max_f32_e32 v83, v23, v27
	v_min_f32_e32 v27, v23, v27
	v_max_f32_e32 v84, v25, v26
	v_min_f32_e32 v26, v25, v26
	v_max_f32_e32 v85, v77, v82
	v_min_f32_e32 v82, v77, v82
	v_max_f32_e32 v86, v78, v83
	v_min_f32_e32 v83, v78, v83
	v_max_f32_e32 v87, v79, v84
	v_min_f32_e32 v84, v79, v84
	v_max_f32_e32 v88, v80, v81
	v_min_f32_e32 v81, v80, v81
	v_max_f32_e32 v89, v22, v29
	v_min_f32_e32 v29, v22, v29
	v_max_f32_e32 v90, v24, v30
	v_min_f32_e32 v30, v24, v30
	v_max_f32_e32 v91, v26, v31
	v_min_f32_e32 v31, v26, v31
	v_max_f32_e32 v92, v27, v28
	v_min_f32_e32 v28, v27, v28
	v_max_f32_e32 v93, v85, v86
	v_min_f32_e32 v86, v85, v86
	v_max_f32_e32 v94, v87, v88
	v_min_f32_e32 v88, v87, v88
	v_max_f32_e32 v95, v81, v82
	v_min_f32_e32 v82, v81, v82
	v_max_f32_e32 v0, v89, v90
	v_min_f32_e32 v90, v89, v90
	v_max_f32_e32 v1, v83, v84
	v_min_f32_e32 v84, v83, v84
	v_max_f32_e32 v2, v91, v92
	v_min_f32_e32 v92, v91, v92
	v_max_f32_e32 v3, v28, v29
	v_min_f32_e32 v29, v28, v29
	v_max_f32_e32 v4, v30, v31
	v_min_f32_e32 v31, v30, v31
	v_max_f32_e32 v5, v93, v94
	v_min_f32_e32 v94, v93, v94
	v_max_f32_e32 v7, v86, v88
	v_min_f32_e32 v88, v86, v88
	v_max_f32_e32 v9, v95, v2
	v_min_f32_e32 v2, v95, v2
	v_max_f32_e32 v144, v82, v92
	v_min_f32_e32 v92, v82, v92
	v_max_f32_e32 v145, v0, v1
	v_min_f32_e32 v1, v0, v1
	v_max_f32_e32 v146, v90, v84
	v_min_f32_e32 v84, v90, v84
	v_max_f32_e32 v147, v3, v4
	v_min_f32_e32 v4, v3, v4
	v_max_f32_e32 v6, v29, v31
	v_min_f32_e32 v31, v29, v31
	v_max_f32_e32 v8, v7, v94
	v_min_f32_e32 v94, v7, v94
	v_max_f32_e32 v10, v88, v147
	v_min_f32_e32 v147, v88, v147
	v_max_f32_e32 v11, v9, v145
	v_min_f32_e32 v145, v9, v145
	v_max_f32_e32 v249, v144, v1
	v_min_f32_e32 v1, v144, v1
	v_max_f32_e32 v251, v146, v2
	v_min_f32_e32 v2, v146, v2
	v_max_f32_e32 v148, v84, v92
	v_min_f32_e32 v92, v84, v92
	v_max_f32_e32 v253, v6, v4
	v_min_f32_e32 v4, v6, v4
	v_max_f32_e32 v150, v8, v11
	v_min_f32_e32 v11, v8, v11
	v_max_f32_e32 v255, v94, v145
	v_min_f32_e32 v145, v94, v145
	v_max_f32_e32 v12, v249, v251
	v_min_f32_e32 v251, v249, v251
	v_max_f32_e32 v14, v1, v2
	v_min_f32_e32 v2, v1, v2
	v_max_f32_e32 v97, v148, v253
	v_min_f32_e32 v253, v148, v253
	v_max_f32_e32 v250, v92, v4
	v_min_f32_e32 v4, v92, v4
	v_max_f32_e32 v99, v255, v11
	v_min_f32_e32 v11, v255, v11
	v_max_f32_e32 v149, v10, v145
	v_min_f32_e32 v145, v10, v145
	v_max_f32_e32 v100, v97, v147
	v_min_f32_e32 v147, v97, v147
	v_max_f32_e32 v254, v250, v253
	v_min_f32_e32 v253, v250, v253
	v_max_f32_e32 v103, v149, v12
	v_min_f32_e32 v12, v149, v12
	v_max_f32_e32 v13, v145, v251
	v_min_f32_e32 v251, v145, v251
	v_max_f32_e32 v106, v14, v100
	v_min_f32_e32 v100, v14, v100
	v_max_f32_e32 v252, v2, v147
	v_min_f32_e32 v147, v2, v147
	v_max_f32_e32 v107, v103, v11
	v_min_f32_e32 v11, v103, v11
	v_max_f32_e32 v108, v12, v13
	v_min_f32_e32 v13, v12, v13
	v_max_f32_e32 v110, v106, v251
	v_min_f32_e32 v251, v106, v251
	v_max_f32_e32 v151, v100, v252
	v_min_f32_e32 v252, v100, v252
	v_max_f32_e32 v112, v254, v147
	v_min_f32_e32 v147, v254, v147
	v_max_f32_e32 v113, v13, v110
	v_min_f32_e32 v110, v13, v110
	v_max_f32_e32 v98, v251, v151
	v_min_f32_e32 v151, v251, v151
	s_waitcnt vmcnt(0)
	v_pk_mul_f32 v[160:161], v[160:161], v[176:177]
	v_pk_mul_f32 v[162:163], v[162:163], v[178:179]
	v_pk_mul_f32 v[164:165], v[164:165], v[180:181]
	v_pk_mul_f32 v[166:167], v[166:167], v[182:183]
	v_pk_mul_f32 v[168:169], v[168:169], v[184:185]
	v_pk_mul_f32 v[170:171], v[170:171], v[186:187]
	v_pk_mul_f32 v[172:173], v[172:173], v[188:189]
	v_pk_mul_f32 v[174:175], v[174:175], v[190:191]
	v_max3_f32 v192, |v160|, |v161|, |v162|
	v_max3_f32 v192, |v163|, |v164|, v192
	v_max3_f32 v192, |v165|, |v166|, v192
	v_max3_f32 v192, |v167|, |v168|, v192
	v_max3_f32 v192, |v169|, |v170|, v192
	v_max3_f32 v192, |v171|, |v172|, v192
	v_max3_f32 v192, |v173|, |v174|, v192
	v_max_f32_e64 v192, |v175|, v192
	s_nop 1
	v_mov_b32_dpp v193, v192 quad_perm:[1,0,3,2] row_mask:0xf bank_mask:0xf bound_ctrl:1
	v_max_f32_e32 v192, v192, v193
	s_nop 1
	v_mov_b32_dpp v193, v192 quad_perm:[2,3,0,1] row_mask:0xf bank_mask:0xf bound_ctrl:1
	v_max_f32_e32 v192, v192, v193
	s_nop 1
	v_mov_b32_dpp v193, v192 row_half_mirror row_mask:0xf bank_mask:0xf bound_ctrl:1
	v_max_f32_e32 v192, v192, v193
	s_nop 1
	v_mov_b32_dpp v193, v192 row_mirror row_mask:0xf bank_mask:0xf bound_ctrl:1
	v_max_f32_e32 v192, v192, v193
	v_mov_b32_e32 v193, v192
	s_nop 1
	v_permlane16_swap_b32_e32 v192, v193
	s_nop 1
	v_max_f32_e32 v192, v192, v193
	v_mov_b32_e32 v193, v192
	s_nop 1
	v_permlane32_swap_b32_e32 v192, v193
	s_nop 1
	v_max_f32_e32 v192, v192, v193
	v_max_f32_e32 v192, 0xda24260, v192
	v_mul_f32_e32 v194, 0x3e2aaaab, v192
	global_store_dword v214, v194, s[12:13]
	v_div_scale_f32 v195, s[26:27], v194, v194, 1.0
	v_rcp_f32_e32 v196, v195
	v_div_scale_f32 v204, vcc, 1.0, v194, 1.0
	v_fma_f32 v205, -v195, v196, 1.0
	v_fmac_f32_e32 v196, v205, v196
	v_mul_f32_e32 v205, v204, v196
	v_fma_f32 v206, -v195, v205, v204
	v_fmac_f32_e32 v205, v206, v196
	v_fma_f32 v195, -v195, v205, v204
	s_nop 0
	v_div_fmas_f32 v195, v195, v196, v205
	v_div_fixup_f32 v207, v195, v194, 1.0
	v_mul_f32_e32 v160, v207, v160
	v_mul_f32_e32 v161, v207, v161
	v_mul_f32_e32 v162, v207, v162
	v_mul_f32_e32 v163, v207, v163
	v_mul_f32_e32 v164, v207, v164
	v_mul_f32_e32 v165, v207, v165
	v_mul_f32_e32 v166, v207, v166
	v_mul_f32_e32 v167, v207, v167
	v_mul_f32_e32 v168, v207, v168
	v_mul_f32_e32 v169, v207, v169
	v_mul_f32_e32 v170, v207, v170
	v_mul_f32_e32 v171, v207, v171
	v_mul_f32_e32 v172, v207, v172
	v_mul_f32_e32 v173, v207, v173
	v_mul_f32_e32 v174, v207, v174
	v_mul_f32_e32 v175, v207, v175
	v_mov_b32_e32 v208, 0
	v_mov_b32_e32 v209, 0
	v_mov_b32_e32 v210, 0
	v_mov_b32_e32 v193, 0
	v_cvt_scalef32_pk_fp4_f32 v208, v160, v161, 1.0
	v_cvt_scalef32_pk_fp4_f32 v209, v164, v165, 1.0
	v_cvt_scalef32_pk_fp4_f32 v210, v168, v169, 1.0
	v_cvt_scalef32_pk_fp4_f32 v193, v172, v173, 1.0
	v_cvt_scalef32_pk_fp4_f32 v208, v162, v163, 1.0 op_sel:[0,0,1,0]
	v_cvt_scalef32_pk_fp4_f32 v209, v166, v167, 1.0 op_sel:[0,0,1,0]
	v_cvt_scalef32_pk_fp4_f32 v210, v170, v171, 1.0 op_sel:[0,0,1,0]
	v_cvt_scalef32_pk_fp4_f32 v193, v174, v175, 1.0 op_sel:[0,0,1,0]
	global_store_short v213, v208, s[10:11] nt
	s_add_u32 s14, s10, 0x200000
	s_addc_u32 s15, s11, 0
	global_store_short v213, v209, s[14:15] nt
	s_add_u32 s14, s10, 0x400000
	s_addc_u32 s15, s11, 0
	global_store_short v213, v210, s[14:15] nt
	s_add_u32 s14, s10, 0x600000
	s_addc_u32 s15, s11, 0
	global_store_short v213, v193, s[14:15] nt
	s_add_u32 s10, s10, 0x20000
	s_addc_u32 s11, s11, 0
	s_add_u32 s12, s12, 0x2000
	s_addc_u32 s13, s13, 0
	global_load_dwordx4 v[160:163], v212, s[8:9] offset:0 nt
	global_load_dwordx4 v[164:167], v212, s[8:9] offset:1024 nt
	global_load_dwordx4 v[168:171], v212, s[8:9] offset:2048 nt
	global_load_dwordx4 v[172:175], v212, s[8:9] offset:3072 nt
	s_add_u32 s8, s8, 0x800000
	s_addc_u32 s9, s9, 0
	v_max_f32_e32 v116, v32, v45
	v_min_f32_e32 v45, v32, v45
	v_max_f32_e32 v101, v33, v44
	v_min_f32_e32 v44, v33, v44
	v_max_f32_e32 v118, v34, v47
	v_min_f32_e32 v47, v34, v47
	v_max_f32_e32 v96, v35, v46
	v_min_f32_e32 v46, v35, v46
	v_max_f32_e32 v121, v36, v40
	v_min_f32_e32 v40, v36, v40
	v_max_f32_e32 v114, v37, v38
	v_min_f32_e32 v38, v37, v38
	v_max_f32_e32 v124, v39, v43
	v_min_f32_e32 v43, v39, v43
	v_max_f32_e32 v125, v41, v42
	v_min_f32_e32 v42, v41, v42
	v_max_f32_e32 v127, v116, v114
	v_min_f32_e32 v114, v116, v114
	v_max_f32_e32 v109, v101, v124
	v_min_f32_e32 v124, v101, v124
	v_max_f32_e32 v123, v118, v125
	v_min_f32_e32 v125, v118, v125
	v_max_f32_e32 v102, v96, v121
	v_min_f32_e32 v121, v96, v121
	v_max_f32_e32 v66, v38, v45
	v_min_f32_e32 v45, v38, v45
	v_max_f32_e32 v122, v40, v46
	v_min_f32_e32 v46, v40, v46
	v_max_f32_e32 v68, v42, v47
	v_min_f32_e32 v47, v42, v47
	v_max_f32_e32 v64, v43, v44
	v_min_f32_e32 v44, v43, v44
	v_max_f32_e32 v65, v127, v109
	v_min_f32_e32 v109, v127, v109
	v_max_f32_e32 v67, v123, v102
	v_min_f32_e32 v102, v123, v102
	v_max_f32_e32 v117, v121, v114
	v_min_f32_e32 v114, v121, v114
	v_max_f32_e32 v16, v66, v122
	v_min_f32_e32 v122, v66, v122
	v_max_f32_e32 v17, v124, v125
	v_min_f32_e32 v125, v124, v125
	v_max_f32_e32 v18, v68, v64
	v_min_f32_e32 v64, v68, v64
	v_max_f32_e32 v19, v44, v45
	v_min_f32_e32 v45, v44, v45
	v_max_f32_e32 v20, v46, v47
	v_min_f32_e32 v47, v46, v47
	v_max_f32_e32 v21, v65, v67
	v_min_f32_e32 v67, v65, v67
	v_max_f32_e32 v23, v109, v102
	v_min_f32_e32 v102, v109, v102
	v_max_f32_e32 v25, v117, v18
	v_min_f32_e32 v18, v117, v18
	v_max_f32_e32 v77, v114, v64
	v_min_f32_e32 v64, v114, v64
	v_max_f32_e32 v78, v16, v17
	v_min_f32_e32 v17, v16, v17
	v_max_f32_e32 v79, v122, v125
	v_min_f32_e32 v125, v122, v125
	v_max_f32_e32 v80, v19, v20
	v_min_f32_e32 v20, v19, v20
	v_max_f32_e32 v22, v45, v47
	v_min_f32_e32 v47, v45, v47
	v_max_f32_e32 v24, v23, v67
	v_min_f32_e32 v67, v23, v67
	v_max_f32_e32 v26, v102, v80
	v_min_f32_e32 v80, v102, v80
	v_max_f32_e32 v27, v25, v78
	v_min_f32_e32 v78, v25, v78
	v_max_f32_e32 v85, v77, v17
	v_min_f32_e32 v17, v77, v17
	v_max_f32_e32 v87, v79, v18
	v_min_f32_e32 v18, v79, v18
	v_max_f32_e32 v81, v125, v64
	v_min_f32_e32 v64, v125, v64
	v_max_f32_e32 v89, v22, v20
	v_min_f32_e32 v20, v22, v20
	v_max_f32_e32 v83, v24, v27
	v_min_f32_e32 v27, v24, v27
	v_max_f32_e32 v91, v67, v78
	v_min_f32_e32 v78, v67, v78
	v_max_f32_e32 v28, v85, v87
	v_min_f32_e32 v87, v85, v87
	v_max_f32_e32 v30, v17, v18
	v_min_f32_e32 v18, v17, v18
	v_max_f32_e32 v93, v81, v89
	v_min_f32_e32 v89, v81, v89
	v_max_f32_e32 v86, v64, v20
	v_min_f32_e32 v20, v64, v20
	v_max_f32_e32 v95, v91, v27
	v_min_f32_e32 v27, v91, v27
	v_max_f32_e32 v82, v26, v78
	v_min_f32_e32 v78, v26, v78
	v_max_f32_e32 v0, v93, v80
	v_min_f32_e32 v80, v93, v80
	v_max_f32_e32 v90, v86, v89
	v_min_f32_e32 v89, v86, v89
	v_max_f32_e32 v3, v82, v28
	v_min_f32_e32 v28, v82, v28
	v_max_f32_e32 v29, v78, v87
	v_min_f32_e32 v87, v78, v87
	v_max_f32_e32 v7, v30, v0
	v_min_f32_e32 v0, v30, v0
	v_max_f32_e32 v88, v18, v80
	v_min_f32_e32 v80, v18, v80
	v_max_f32_e32 v9, v3, v27
	v_min_f32_e32 v27, v3, v27
	v_max_f32_e32 v144, v28, v29
	v_min_f32_e32 v29, v28, v29
	v_max_f32_e32 v146, v7, v87
	v_min_f32_e32 v87, v7, v87
	v_max_f32_e32 v84, v0, v88
	v_min_f32_e32 v88, v0, v88
	v_max_f32_e32 v6, v90, v80
	v_min_f32_e32 v80, v90, v80
	v_max_f32_e32 v8, v29, v146
	v_min_f32_e32 v146, v29, v146
	v_max_f32_e32 v94, v87, v84
	v_min_f32_e32 v84, v87, v84
	v_max_f32_e32 v249, v48, v61
	v_min_f32_e32 v61, v48, v61
	v_max_f32_e32 v1, v49, v60
	v_min_f32_e32 v60, v49, v60
	v_max_f32_e32 v148, v50, v63
	v_min_f32_e32 v63, v50, v63
	v_max_f32_e32 v92, v51, v62
	v_min_f32_e32 v62, v51, v62
	v_max_f32_e32 v255, v52, v56
	v_min_f32_e32 v56, v52, v56
	v_max_f32_e32 v10, v53, v54
	v_min_f32_e32 v54, v53, v54
	v_max_f32_e32 v97, v55, v59
	v_min_f32_e32 v59, v55, v59
	v_max_f32_e32 v250, v57, v58
	v_min_f32_e32 v58, v57, v58
	v_max_f32_e32 v149, v249, v10
	v_min_f32_e32 v10, v249, v10
	v_max_f32_e32 v145, v1, v97
	v_min_f32_e32 v97, v1, v97
	v_max_f32_e32 v14, v148, v250
	v_min_f32_e32 v250, v148, v250
	v_max_f32_e32 v2, v92, v255
	v_min_f32_e32 v255, v92, v255
	v_max_f32_e32 v103, v54, v61
	v_min_f32_e32 v61, v54, v61
	v_max_f32_e32 v12, v56, v62
	v_min_f32_e32 v62, v56, v62
	v_max_f32_e32 v106, v58, v63
	v_min_f32_e32 v63, v58, v63
	v_max_f32_e32 v100, v59, v60
	v_min_f32_e32 v60, v59, v60
	v_max_f32_e32 v254, v149, v145
	v_min_f32_e32 v145, v149, v145
	v_max_f32_e32 v13, v14, v2
	v_min_f32_e32 v2, v14, v2
	v_max_f32_e32 v251, v255, v10
	v_min_f32_e32 v10, v255, v10
	v_max_f32_e32 v32, v103, v12
	v_min_f32_e32 v12, v103, v12
	v_max_f32_e32 v33, v97, v250
	v_min_f32_e32 v250, v97, v250
	v_max_f32_e32 v34, v106, v100
	v_min_f32_e32 v100, v106, v100
	v_max_f32_e32 v35, v60, v61
	v_min_f32_e32 v61, v60, v61
	v_max_f32_e32 v36, v62, v63
	v_min_f32_e32 v63, v62, v63
	v_max_f32_e32 v37, v254, v13
	v_min_f32_e32 v13, v254, v13
	v_max_f32_e32 v39, v145, v2
	v_min_f32_e32 v2, v145, v2
	v_max_f32_e32 v41, v251, v34
	v_min_f32_e32 v34, v251, v34
	v_max_f32_e32 v116, v10, v100
	v_min_f32_e32 v100, v10, v100
	v_max_f32_e32 v101, v32, v33
	v_min_f32_e32 v33, v32, v33
	v_max_f32_e32 v118, v12, v250
	v_min_f32_e32 v250, v12, v250
	v_max_f32_e32 v96, v35, v36
	v_min_f32_e32 v36, v35, v36
	v_max_f32_e32 v38, v61, v63
	v_min_f32_e32 v63, v61, v63
	v_max_f32_e32 v40, v39, v13
	v_min_f32_e32 v13, v39, v13
	v_max_f32_e32 v42, v2, v96
	v_min_f32_e32 v96, v2, v96
	v_max_f32_e32 v43, v41, v101
	v_min_f32_e32 v101, v41, v101
	v_max_f32_e32 v127, v116, v33
	v_min_f32_e32 v33, v116, v33
	v_max_f32_e32 v123, v118, v34
	v_min_f32_e32 v34, v118, v34
	v_max_f32_e32 v121, v250, v100
	v_min_f32_e32 v100, v250, v100
	v_max_f32_e32 v66, v38, v36
	v_min_f32_e32 v36, v38, v36
	v_max_f32_e32 v124, v40, v43
	v_min_f32_e32 v43, v40, v43
	v_max_f32_e32 v68, v13, v101
	v_min_f32_e32 v101, v13, v101
	v_max_f32_e32 v44, v127, v123
	v_min_f32_e32 v123, v127, v123
	v_max_f32_e32 v46, v33, v34
	v_min_f32_e32 v34, v33, v34
	v_max_f32_e32 v65, v121, v66
	v_min_f32_e32 v66, v121, v66
	v_max_f32_e32 v109, v100, v36
	v_min_f32_e32 v36, v100, v36
	v_max_f32_e32 v117, v68, v43
	v_min_f32_e32 v43, v68, v43
	v_max_f32_e32 v114, v42, v101
	v_min_f32_e32 v101, v42, v101
	v_max_f32_e32 v16, v65, v96
	v_min_f32_e32 v96, v65, v96
	v_max_f32_e32 v122, v109, v66
	v_min_f32_e32 v66, v109, v66
	v_max_f32_e32 v19, v114, v44
	v_min_f32_e32 v44, v114, v44
	v_max_f32_e32 v45, v101, v123
	v_min_f32_e32 v123, v101, v123
	v_max_f32_e32 v23, v46, v16
	v_min_f32_e32 v16, v46, v16
	v_max_f32_e32 v102, v34, v96
	v_min_f32_e32 v96, v34, v96
	v_max_f32_e32 v25, v19, v43
	v_min_f32_e32 v43, v19, v43
	v_max_f32_e32 v77, v44, v45
	v_min_f32_e32 v45, v44, v45
	v_max_f32_e32 v79, v23, v123
	v_min_f32_e32 v123, v23, v123
	v_max_f32_e32 v125, v16, v102
	v_min_f32_e32 v102, v16, v102
	v_max_f32_e32 v22, v122, v96
	v_min_f32_e32 v96, v122, v96
	v_max_f32_e32 v24, v45, v79
	v_min_f32_e32 v79, v45, v79
	v_max_f32_e32 v67, v123, v125
	v_min_f32_e32 v125, v123, v125
	s_waitcnt vmcnt(0)
	v_pk_mul_f32 v[160:161], v[160:161], v[176:177]
	v_pk_mul_f32 v[162:163], v[162:163], v[178:179]
	v_pk_mul_f32 v[164:165], v[164:165], v[180:181]
	v_pk_mul_f32 v[166:167], v[166:167], v[182:183]
	v_pk_mul_f32 v[168:169], v[168:169], v[184:185]
	v_pk_mul_f32 v[170:171], v[170:171], v[186:187]
	v_pk_mul_f32 v[172:173], v[172:173], v[188:189]
	v_pk_mul_f32 v[174:175], v[174:175], v[190:191]
	v_max3_f32 v192, |v160|, |v161|, |v162|
	v_max3_f32 v192, |v163|, |v164|, v192
	v_max3_f32 v192, |v165|, |v166|, v192
	v_max3_f32 v192, |v167|, |v168|, v192
	v_max3_f32 v192, |v169|, |v170|, v192
	v_max3_f32 v192, |v171|, |v172|, v192
	v_max3_f32 v192, |v173|, |v174|, v192
	v_max_f32_e64 v192, |v175|, v192
	s_nop 1
	v_mov_b32_dpp v193, v192 quad_perm:[1,0,3,2] row_mask:0xf bank_mask:0xf bound_ctrl:1
	v_max_f32_e32 v192, v192, v193
	s_nop 1
	v_mov_b32_dpp v193, v192 quad_perm:[2,3,0,1] row_mask:0xf bank_mask:0xf bound_ctrl:1
	v_max_f32_e32 v192, v192, v193
	s_nop 1
	v_mov_b32_dpp v193, v192 row_half_mirror row_mask:0xf bank_mask:0xf bound_ctrl:1
	v_max_f32_e32 v192, v192, v193
	s_nop 1
	v_mov_b32_dpp v193, v192 row_mirror row_mask:0xf bank_mask:0xf bound_ctrl:1
	v_max_f32_e32 v192, v192, v193
	v_mov_b32_e32 v193, v192
	s_nop 1
	v_permlane16_swap_b32_e32 v192, v193
	s_nop 1
	v_max_f32_e32 v192, v192, v193
	v_mov_b32_e32 v193, v192
	s_nop 1
	v_permlane32_swap_b32_e32 v192, v193
	s_nop 1
	v_max_f32_e32 v192, v192, v193
	v_max_f32_e32 v192, 0xda24260, v192
	v_mul_f32_e32 v194, 0x3e2aaaab, v192
	global_store_dword v214, v194, s[12:13]
	v_div_scale_f32 v195, s[26:27], v194, v194, 1.0
	v_rcp_f32_e32 v196, v195
	v_div_scale_f32 v204, vcc, 1.0, v194, 1.0
	v_fma_f32 v205, -v195, v196, 1.0
	v_fmac_f32_e32 v196, v205, v196
	v_mul_f32_e32 v205, v204, v196
	v_fma_f32 v206, -v195, v205, v204
	v_fmac_f32_e32 v205, v206, v196
	v_fma_f32 v195, -v195, v205, v204
	s_nop 0
	v_div_fmas_f32 v195, v195, v196, v205
	v_div_fixup_f32 v207, v195, v194, 1.0
	v_mul_f32_e32 v160, v207, v160
	v_mul_f32_e32 v161, v207, v161
	v_mul_f32_e32 v162, v207, v162
	v_mul_f32_e32 v163, v207, v163
	v_mul_f32_e32 v164, v207, v164
	v_mul_f32_e32 v165, v207, v165
	v_mul_f32_e32 v166, v207, v166
	v_mul_f32_e32 v167, v207, v167
	v_mul_f32_e32 v168, v207, v168
	v_mul_f32_e32 v169, v207, v169
	v_mul_f32_e32 v170, v207, v170
	v_mul_f32_e32 v171, v207, v171
	v_mul_f32_e32 v172, v207, v172
	v_mul_f32_e32 v173, v207, v173
	v_mul_f32_e32 v174, v207, v174
	v_mul_f32_e32 v175, v207, v175
	v_mov_b32_e32 v208, 0
	v_mov_b32_e32 v209, 0
	v_mov_b32_e32 v210, 0
	v_mov_b32_e32 v193, 0
	v_cvt_scalef32_pk_fp4_f32 v208, v160, v161, 1.0
	v_cvt_scalef32_pk_fp4_f32 v209, v164, v165, 1.0
	v_cvt_scalef32_pk_fp4_f32 v210, v168, v169, 1.0
	v_cvt_scalef32_pk_fp4_f32 v193, v172, v173, 1.0
	v_cvt_scalef32_pk_fp4_f32 v208, v162, v163, 1.0 op_sel:[0,0,1,0]
	v_cvt_scalef32_pk_fp4_f32 v209, v166, v167, 1.0 op_sel:[0,0,1,0]
	v_cvt_scalef32_pk_fp4_f32 v210, v170, v171, 1.0 op_sel:[0,0,1,0]
	v_cvt_scalef32_pk_fp4_f32 v193, v174, v175, 1.0 op_sel:[0,0,1,0]
	global_store_short v213, v208, s[10:11] nt
	s_add_u32 s14, s10, 0x200000
	s_addc_u32 s15, s11, 0
	global_store_short v213, v209, s[14:15] nt
	s_add_u32 s14, s10, 0x400000
	s_addc_u32 s15, s11, 0
	global_store_short v213, v210, s[14:15] nt
	s_add_u32 s14, s10, 0x600000
	s_addc_u32 s15, s11, 0
	global_store_short v213, v193, s[14:15] nt
	s_add_u32 s10, s10, 0x20000
	s_addc_u32 s11, s11, 0
	s_add_u32 s12, s12, 0x2000
	s_addc_u32 s13, s13, 0
	global_load_dwordx4 v[160:163], v212, s[8:9] offset:0 nt
	global_load_dwordx4 v[164:167], v212, s[8:9] offset:1024 nt
	global_load_dwordx4 v[168:171], v212, s[8:9] offset:2048 nt
	global_load_dwordx4 v[172:175], v212, s[8:9] offset:3072 nt
	s_add_u32 s8, s8, 0x800000
	s_addc_u32 s9, s9, 0
	v_max_f32_e32 v105, v105, v31
	v_max_f32_e32 v120, v120, v4
	v_max_f32_e32 v126, v126, v253
	v_max_f32_e32 v70, v70, v147
	v_max_f32_e32 v115, v115, v112
	v_max_f32_e32 v71, v71, v252
	v_max_f32_e32 v75, v75, v151
	v_max_f32_e32 v72, v72, v98
	v_max_f32_e32 v76, v76, v110
	v_max_f32_e32 v73, v73, v113
	v_max_f32_e32 v69, v69, v108
	v_max_f32_e32 v74, v74, v11
	v_max_f32_e32 v111, v111, v107
	v_max_f32_e32 v119, v119, v99
	v_max_f32_e32 v104, v104, v150
	v_max_f32_e32 v15, v15, v5
	v_max_f32_e32 v85, v105, v76
	v_min_f32_e32 v76, v105, v76
	v_max_f32_e32 v17, v120, v73
	v_min_f32_e32 v73, v120, v73
	v_max_f32_e32 v81, v126, v69
	v_min_f32_e32 v69, v126, v69
	v_max_f32_e32 v64, v70, v74
	v_min_f32_e32 v74, v70, v74
	v_max_f32_e32 v91, v115, v111
	v_min_f32_e32 v111, v115, v111
	v_max_f32_e32 v26, v71, v119
	v_min_f32_e32 v119, v71, v119
	v_max_f32_e32 v93, v75, v104
	v_min_f32_e32 v104, v75, v104
	v_max_f32_e32 v86, v72, v15
	v_min_f32_e32 v15, v72, v15
	v_max_f32_e32 v82, v85, v91
	v_min_f32_e32 v91, v85, v91
	v_max_f32_e32 v78, v17, v26
	v_min_f32_e32 v26, v17, v26
	v_max_f32_e32 v30, v81, v93
	v_min_f32_e32 v93, v81, v93
	v_max_f32_e32 v18, v64, v86
	v_min_f32_e32 v86, v64, v86
	v_max_f32_e32 v3, v76, v111
	v_min_f32_e32 v111, v76, v111
	v_max_f32_e32 v28, v73, v119
	v_min_f32_e32 v119, v73, v119
	v_max_f32_e32 v7, v69, v104
	v_min_f32_e32 v104, v69, v104
	v_max_f32_e32 v0, v74, v15
	v_min_f32_e32 v15, v74, v15
	v_max_f32_e32 v90, v82, v30
	v_min_f32_e32 v30, v82, v30
	v_max_f32_e32 v29, v78, v18
	v_min_f32_e32 v18, v78, v18
	v_max_f32_e32 v87, v91, v93
	v_min_f32_e32 v93, v91, v93
	v_max_f32_e32 v48, v26, v86
	v_min_f32_e32 v86, v26, v86
	v_max_f32_e32 v49, v3, v7
	v_min_f32_e32 v7, v3, v7
	v_max_f32_e32 v50, v28, v0
	v_min_f32_e32 v0, v28, v0
	v_max_f32_e32 v51, v111, v104
	v_min_f32_e32 v104, v111, v104
	v_max_f32_e32 v52, v119, v15
	v_min_f32_e32 v15, v119, v15
	v_max_f32_e32 v53, v90, v29
	v_min_f32_e32 v29, v90, v29
	v_max_f32_e32 v55, v30, v18
	v_min_f32_e32 v18, v30, v18
	v_max_f32_e32 v57, v87, v48
	v_min_f32_e32 v48, v87, v48
	v_max_f32_e32 v249, v93, v86
	v_min_f32_e32 v86, v93, v86
	v_max_f32_e32 v1, v49, v50
	v_min_f32_e32 v50, v49, v50
	v_max_f32_e32 v148, v7, v0
	v_min_f32_e32 v0, v7, v0
	v_max_f32_e32 v92, v51, v52
	v_min_f32_e32 v52, v51, v52
	v_max_f32_e32 v54, v104, v15
	v_min_f32_e32 v15, v104, v15
	v_max_f32_e32 v21, v21, v63
	v_max_f32_e32 v83, v83, v36
	v_max_f32_e32 v95, v95, v66
	v_max_f32_e32 v9, v9, v96
	v_max_f32_e32 v27, v27, v22
	v_max_f32_e32 v144, v144, v102
	v_max_f32_e32 v8, v8, v125
	v_max_f32_e32 v146, v146, v67
	v_max_f32_e32 v94, v94, v79
	v_max_f32_e32 v84, v84, v24
	v_max_f32_e32 v88, v88, v77
	v_max_f32_e32 v6, v6, v43
	v_max_f32_e32 v80, v80, v25
	v_max_f32_e32 v89, v89, v117
	v_max_f32_e32 v20, v20, v124
	v_max_f32_e32 v47, v47, v37
	v_max_f32_e32 v56, v21, v94
	v_min_f32_e32 v94, v21, v94
	v_max_f32_e32 v58, v83, v84
	v_min_f32_e32 v84, v83, v84
	v_max_f32_e32 v59, v95, v88
	v_min_f32_e32 v88, v95, v88
	v_max_f32_e32 v149, v9, v6
	v_min_f32_e32 v6, v9, v6
	v_max_f32_e32 v14, v27, v80
	v_min_f32_e32 v80, v27, v80
	v_max_f32_e32 v255, v144, v89
	v_min_f32_e32 v89, v144, v89
	v_max_f32_e32 v103, v8, v20
	v_min_f32_e32 v20, v8, v20
	v_max_f32_e32 v97, v146, v47
	v_min_f32_e32 v47, v146, v47
	v_max_f32_e32 v106, v56, v14
	v_min_f32_e32 v14, v56, v14
	v_max_f32_e32 v60, v58, v255
	v_min_f32_e32 v255, v58, v255
	v_max_f32_e32 v62, v59, v103
	v_min_f32_e32 v103, v59, v103
	v_max_f32_e32 v254, v149, v97
	v_min_f32_e32 v97, v149, v97
	v_max_f32_e32 v145, v94, v80
	v_min_f32_e32 v80, v94, v80
	v_max_f32_e32 v251, v84, v89
	v_min_f32_e32 v89, v84, v89
	v_max_f32_e32 v10, v88, v20
	v_min_f32_e32 v20, v88, v20
	v_max_f32_e32 v32, v6, v47
	v_min_f32_e32 v47, v6, v47
	v_max_f32_e32 v12, v106, v62
	v_min_f32_e32 v62, v106, v62
	v_max_f32_e32 v35, v60, v254
	v_min_f32_e32 v254, v60, v254
	v_max_f32_e32 v61, v14, v103
	v_min_f32_e32 v103, v14, v103
	v_max_f32_e32 v39, v255, v97
	v_min_f32_e32 v97, v255, v97
	v_max_f32_e32 v2, v145, v10
	v_min_f32_e32 v10, v145, v10
	v_max_f32_e32 v41, v251, v32
	v_min_f32_e32 v32, v251, v32
	v_max_f32_e32 v116, v80, v20
	v_min_f32_e32 v20, v80, v20
	v_max_f32_e32 v118, v89, v47
	v_min_f32_e32 v47, v89, v47
	v_max_f32_e32 v250, v12, v35
	v_min_f32_e32 v35, v12, v35
	v_max_f32_e32 v38, v62, v254
	v_min_f32_e32 v254, v62, v254
	v_max_f32_e32 v40, v61, v39
	v_min_f32_e32 v39, v61, v39
	v_max_f32_e32 v13, v103, v97
	v_min_f32_e32 v97, v103, v97
	v_max_f32_e32 v127, v2, v41
	v_min_f32_e32 v41, v2, v41
	v_max_f32_e32 v33, v10, v32
	v_min_f32_e32 v32, v10, v32
	v_max_f32_e32 v121, v116, v118
	v_min_f32_e32 v118, v116, v118
	v_max_f32_e32 v100, v20, v47
	v_min_f32_e32 v47, v20, v47
	v_max_f32_e32 v53, v53, v47
	v_max_f32_e32 v29, v29, v100
	v_max_f32_e32 v55, v55, v118
	v_max_f32_e32 v18, v18, v121
	v_max_f32_e32 v57, v57, v32
	v_max_f32_e32 v48, v48, v33
	v_max_f32_e32 v249, v249, v41
	v_max_f32_e32 v86, v86, v127
	v_max_f32_e32 v1, v1, v97
	v_max_f32_e32 v50, v50, v13
	v_max_f32_e32 v148, v148, v39
	v_max_f32_e32 v0, v0, v40
	v_max_f32_e32 v92, v92, v254
	v_max_f32_e32 v52, v52, v38
	v_max_f32_e32 v54, v54, v35
	v_max_f32_e32 v15, v15, v250
	v_max_f32_e32 v68, v53, v1
	v_min_f32_e32 v1, v53, v1
	v_max_f32_e32 v42, v29, v50
	v_min_f32_e32 v50, v29, v50
	v_max_f32_e32 v65, v55, v148
	v_min_f32_e32 v148, v55, v148
	v_max_f32_e32 v109, v18, v0
	v_min_f32_e32 v0, v18, v0
	v_max_f32_e32 v114, v57, v92
	v_min_f32_e32 v92, v57, v92
	v_max_f32_e32 v101, v48, v52
	v_min_f32_e32 v52, v48, v52
	v_max_f32_e32 v46, v249, v54
	v_min_f32_e32 v54, v249, v54
	v_max_f32_e32 v34, v86, v15
	v_min_f32_e32 v15, v86, v15
	v_max_f32_e32 v19, v68, v114
	v_min_f32_e32 v114, v68, v114
	v_max_f32_e32 v44, v42, v101
	v_min_f32_e32 v101, v42, v101
	v_max_f32_e32 v23, v65, v46
	v_min_f32_e32 v46, v65, v46
	v_max_f32_e32 v16, v109, v34
	v_min_f32_e32 v34, v109, v34
	v_max_f32_e32 v122, v1, v92
	v_min_f32_e32 v92, v1, v92
	v_max_f32_e32 v45, v50, v52
	v_min_f32_e32 v52, v50, v52
	v_max_f32_e32 v123, v148, v54
	v_min_f32_e32 v54, v148, v54
	v_max_f32_e32 v5, v0, v15
	v_min_f32_e32 v15, v0, v15
	v_max_f32_e32 v150, v19, v23
	v_min_f32_e32 v23, v19, v23
	v_max_f32_e32 v99, v44, v16
	v_min_f32_e32 v16, v44, v16
	v_max_f32_e32 v107, v114, v46
	v_min_f32_e32 v46, v114, v46
	v_max_f32_e32 v11, v101, v34
	v_min_f32_e32 v34, v101, v34
	v_max_f32_e32 v108, v122, v123
	v_min_f32_e32 v123, v122, v123
	v_max_f32_e32 v113, v45, v5
	v_min_f32_e32 v5, v45, v5
	v_max_f32_e32 v110, v92, v54
	v_min_f32_e32 v54, v92, v54
	v_max_f32_e32 v98, v52, v15
	v_min_f32_e32 v15, v52, v15
	v_max_f32_e32 v151, v150, v99
	v_min_f32_e32 v99, v150, v99
	v_max_f32_e32 v252, v23, v16
	v_min_f32_e32 v16, v23, v16
	v_max_f32_e32 v112, v107, v11
	v_min_f32_e32 v11, v107, v11
	v_max_f32_e32 v147, v46, v34
	v_min_f32_e32 v34, v46, v34
	v_max_f32_e32 v253, v108, v113
	v_min_f32_e32 v113, v108, v113
	v_max_f32_e32 v4, v123, v5
	v_min_f32_e32 v5, v123, v5
	v_max_f32_e32 v31, v110, v98
	v_min_f32_e32 v98, v110, v98
	v_max_f32_e32 v105, v54, v15
	v_min_f32_e32 v15, v54, v15
	v_mov_b32_e32 v120, v151
	v_mov_b32_e32 v126, v99
	v_mov_b32_e32 v70, v252
	v_mov_b32_e32 v115, v16
	v_mov_b32_e32 v71, v112
	v_mov_b32_e32 v75, v11
	v_mov_b32_e32 v72, v147
	v_mov_b32_e32 v85, v34
	v_mov_b32_e32 v17, v253
	v_mov_b32_e32 v81, v113
	v_mov_b32_e32 v64, v4
	v_mov_b32_e32 v76, v5
	v_mov_b32_e32 v73, v31
	v_mov_b32_e32 v69, v98
	v_mov_b32_e32 v74, v105
	v_mov_b32_e32 v82, v15
	s_nop 1
	v_permlane32_swap_b32_e32 v151, v120
	v_permlane32_swap_b32_e32 v99, v126
	v_permlane32_swap_b32_e32 v252, v70
	v_permlane32_swap_b32_e32 v16, v115
	v_permlane32_swap_b32_e32 v112, v71
	v_permlane32_swap_b32_e32 v11, v75
	v_permlane32_swap_b32_e32 v147, v72
	v_permlane32_swap_b32_e32 v34, v85
	v_permlane32_swap_b32_e32 v253, v17
	v_permlane32_swap_b32_e32 v113, v81
	v_permlane32_swap_b32_e32 v4, v64
	v_permlane32_swap_b32_e32 v5, v76
	v_permlane32_swap_b32_e32 v31, v73
	v_permlane32_swap_b32_e32 v98, v69
	v_permlane32_swap_b32_e32 v105, v74
	v_permlane32_swap_b32_e32 v15, v82
	s_nop 1
	v_max_f32_e32 v151, v151, v82
	v_max_f32_e32 v99, v99, v74
	v_max_f32_e32 v252, v252, v69
	v_max_f32_e32 v16, v16, v73
	v_max_f32_e32 v112, v112, v76
	v_max_f32_e32 v11, v11, v64
	v_max_f32_e32 v147, v147, v81
	v_max_f32_e32 v34, v34, v17
	v_max_f32_e32 v253, v253, v85
	v_max_f32_e32 v113, v113, v72
	v_max_f32_e32 v4, v4, v75
	v_max_f32_e32 v5, v5, v71
	v_max_f32_e32 v31, v31, v115
	v_max_f32_e32 v98, v98, v70
	v_max_f32_e32 v105, v105, v126
	v_max_f32_e32 v15, v15, v120
	v_max_f32_e32 v78, v151, v253
	v_min_f32_e32 v253, v151, v253
	v_max_f32_e32 v91, v99, v113
	v_min_f32_e32 v113, v99, v113
	v_max_f32_e32 v26, v252, v4
	v_min_f32_e32 v4, v252, v4
	v_max_f32_e32 v3, v16, v5
	v_min_f32_e32 v5, v16, v5
	v_max_f32_e32 v28, v112, v31
	v_min_f32_e32 v31, v112, v31
	v_max_f32_e32 v111, v11, v98
	v_min_f32_e32 v98, v11, v98
	v_max_f32_e32 v119, v147, v105
	v_min_f32_e32 v105, v147, v105
	v_max_f32_e32 v90, v34, v15
	v_min_f32_e32 v15, v34, v15
	v_max_f32_e32 v30, v78, v28
	v_min_f32_e32 v28, v78, v28
	v_max_f32_e32 v87, v91, v111
	v_min_f32_e32 v111, v91, v111
	v_max_f32_e32 v93, v26, v119
	v_min_f32_e32 v119, v26, v119
	v_max_f32_e32 v49, v3, v90
	v_min_f32_e32 v90, v3, v90
	v_max_f32_e32 v7, v253, v31
	v_min_f32_e32 v31, v253, v31
	v_max_f32_e32 v51, v113, v98
	v_min_f32_e32 v98, v113, v98
	v_max_f32_e32 v104, v4, v105
	v_min_f32_e32 v105, v4, v105
	v_max_f32_e32 v37, v5, v15
	v_min_f32_e32 v15, v5, v15
	v_max_f32_e32 v124, v30, v93
	v_min_f32_e32 v93, v30, v93
	v_max_f32_e32 v117, v87, v49
	v_min_f32_e32 v49, v87, v49
	v_max_f32_e32 v25, v28, v119
	v_min_f32_e32 v119, v28, v119
	v_max_f32_e32 v43, v111, v90
	v_min_f32_e32 v90, v111, v90
	v_max_f32_e32 v77, v7, v104
	v_min_f32_e32 v104, v7, v104
	v_max_f32_e32 v24, v51, v37
	v_min_f32_e32 v37, v51, v37
	v_max_f32_e32 v79, v31, v105
	v_min_f32_e32 v105, v31, v105
	v_max_f32_e32 v67, v98, v15
	v_min_f32_e32 v15, v98, v15
	v_max_f32_e32 v125, v124, v117
	v_min_f32_e32 v117, v124, v117
	v_max_f32_e32 v102, v93, v49
	v_min_f32_e32 v49, v93, v49
	v_max_f32_e32 v22, v25, v43
	v_min_f32_e32 v43, v25, v43
	v_max_f32_e32 v96, v119, v90
	v_min_f32_e32 v90, v119, v90
	v_max_f32_e32 v66, v77, v24
	v_min_f32_e32 v24, v77, v24
	v_max_f32_e32 v36, v104, v37
	v_min_f32_e32 v37, v104, v37
	v_max_f32_e32 v63, v79, v67
	v_min_f32_e32 v67, v79, v67
	v_max_f32_e32 v21, v105, v15
	v_min_f32_e32 v15, v105, v15
	s_waitcnt vmcnt(0)
	v_pk_mul_f32 v[160:161], v[160:161], v[176:177]
	v_pk_mul_f32 v[162:163], v[162:163], v[178:179]
	v_pk_mul_f32 v[164:165], v[164:165], v[180:181]
	v_pk_mul_f32 v[166:167], v[166:167], v[182:183]
	v_pk_mul_f32 v[168:169], v[168:169], v[184:185]
	v_pk_mul_f32 v[170:171], v[170:171], v[186:187]
	v_pk_mul_f32 v[172:173], v[172:173], v[188:189]
	v_pk_mul_f32 v[174:175], v[174:175], v[190:191]
	v_max3_f32 v192, |v160|, |v161|, |v162|
	v_max3_f32 v192, |v163|, |v164|, v192
	v_max3_f32 v192, |v165|, |v166|, v192
	v_max3_f32 v192, |v167|, |v168|, v192
	v_max3_f32 v192, |v169|, |v170|, v192
	v_max3_f32 v192, |v171|, |v172|, v192
	v_max3_f32 v192, |v173|, |v174|, v192
	v_max_f32_e64 v192, |v175|, v192
	s_nop 1
	v_mov_b32_dpp v193, v192 quad_perm:[1,0,3,2] row_mask:0xf bank_mask:0xf bound_ctrl:1
	v_max_f32_e32 v192, v192, v193
	s_nop 1
	v_mov_b32_dpp v193, v192 quad_perm:[2,3,0,1] row_mask:0xf bank_mask:0xf bound_ctrl:1
	v_max_f32_e32 v192, v192, v193
	s_nop 1
	v_mov_b32_dpp v193, v192 row_half_mirror row_mask:0xf bank_mask:0xf bound_ctrl:1
	v_max_f32_e32 v192, v192, v193
	s_nop 1
	v_mov_b32_dpp v193, v192 row_mirror row_mask:0xf bank_mask:0xf bound_ctrl:1
	v_max_f32_e32 v192, v192, v193
	v_mov_b32_e32 v193, v192
	s_nop 1
	v_permlane16_swap_b32_e32 v192, v193
	s_nop 1
	v_max_f32_e32 v192, v192, v193
	v_mov_b32_e32 v193, v192
	s_nop 1
	v_permlane32_swap_b32_e32 v192, v193
	s_nop 1
	v_max_f32_e32 v192, v192, v193
	v_max_f32_e32 v192, 0xda24260, v192
	v_mul_f32_e32 v194, 0x3e2aaaab, v192
	global_store_dword v214, v194, s[12:13]
	v_div_scale_f32 v195, s[26:27], v194, v194, 1.0
	v_rcp_f32_e32 v196, v195
	v_div_scale_f32 v204, vcc, 1.0, v194, 1.0
	v_fma_f32 v205, -v195, v196, 1.0
	v_fmac_f32_e32 v196, v205, v196
	v_mul_f32_e32 v205, v204, v196
	v_fma_f32 v206, -v195, v205, v204
	v_fmac_f32_e32 v205, v206, v196
	v_fma_f32 v195, -v195, v205, v204
	s_nop 0
	v_div_fmas_f32 v195, v195, v196, v205
	v_div_fixup_f32 v207, v195, v194, 1.0
	v_mul_f32_e32 v160, v207, v160
	v_mul_f32_e32 v161, v207, v161
	v_mul_f32_e32 v162, v207, v162
	v_mul_f32_e32 v163, v207, v163
	v_mul_f32_e32 v164, v207, v164
	v_mul_f32_e32 v165, v207, v165
	v_mul_f32_e32 v166, v207, v166
	v_mul_f32_e32 v167, v207, v167
	v_mul_f32_e32 v168, v207, v168
	v_mul_f32_e32 v169, v207, v169
	v_mul_f32_e32 v170, v207, v170
	v_mul_f32_e32 v171, v207, v171
	v_mul_f32_e32 v172, v207, v172
	v_mul_f32_e32 v173, v207, v173
	v_mul_f32_e32 v174, v207, v174
	v_mul_f32_e32 v175, v207, v175
	v_mov_b32_e32 v208, 0
	v_mov_b32_e32 v209, 0
	v_mov_b32_e32 v210, 0
	v_mov_b32_e32 v193, 0
	v_cvt_scalef32_pk_fp4_f32 v208, v160, v161, 1.0
	v_cvt_scalef32_pk_fp4_f32 v209, v164, v165, 1.0
	v_cvt_scalef32_pk_fp4_f32 v210, v168, v169, 1.0
	v_cvt_scalef32_pk_fp4_f32 v193, v172, v173, 1.0
	v_cvt_scalef32_pk_fp4_f32 v208, v162, v163, 1.0 op_sel:[0,0,1,0]
	v_cvt_scalef32_pk_fp4_f32 v209, v166, v167, 1.0 op_sel:[0,0,1,0]
	v_cvt_scalef32_pk_fp4_f32 v210, v170, v171, 1.0 op_sel:[0,0,1,0]
	v_cvt_scalef32_pk_fp4_f32 v193, v174, v175, 1.0 op_sel:[0,0,1,0]
	global_store_short v213, v208, s[10:11] nt
	s_add_u32 s14, s10, 0x200000
	s_addc_u32 s15, s11, 0
	global_store_short v213, v209, s[14:15] nt
	s_add_u32 s14, s10, 0x400000
	s_addc_u32 s15, s11, 0
	global_store_short v213, v210, s[14:15] nt
	s_add_u32 s14, s10, 0x600000
	s_addc_u32 s15, s11, 0
	global_store_short v213, v193, s[14:15] nt
	s_add_u32 s10, s10, 0x20000
	s_addc_u32 s11, s11, 0
	s_add_u32 s12, s12, 0x2000
	s_addc_u32 s13, s13, 0
	global_load_dwordx4 v[160:163], v212, s[8:9] offset:0 nt
	global_load_dwordx4 v[164:167], v212, s[8:9] offset:1024 nt
	global_load_dwordx4 v[168:171], v212, s[8:9] offset:2048 nt
	global_load_dwordx4 v[172:175], v212, s[8:9] offset:3072 nt
	s_add_u32 s8, s8, 0x800000
	s_addc_u32 s9, s9, 0
	ds_write_b8 v240, v125 offset:512
	ds_write_b8 v240, v117 offset:513
	ds_write_b8 v240, v102 offset:514
	ds_write_b8 v240, v49 offset:515
	ds_write_b8 v240, v22 offset:516
	ds_write_b8 v240, v43 offset:517
	ds_write_b8 v240, v96 offset:518
	ds_write_b8 v240, v90 offset:519
	ds_write_b8 v240, v66 offset:520
	ds_write_b8 v240, v24 offset:521
	ds_write_b8 v240, v36 offset:522
	ds_write_b8 v240, v37 offset:523
	ds_write_b8 v240, v63 offset:524
	ds_write_b8 v240, v67 offset:525
	ds_write_b8 v240, v21 offset:526
	ds_write_b8 v240, v15 offset:527
	v_cndmask_b32_e64 v0, v128, v125, s[4:5]
	v_cndmask_b32_e64 v17, v125, v128, s[4:5]
	v_cndmask_b32_e64 v1, v129, v117, s[4:5]
	v_cndmask_b32_e64 v18, v117, v129, s[4:5]
	v_cndmask_b32_e64 v2, v130, v102, s[4:5]
	v_cndmask_b32_e64 v19, v102, v130, s[4:5]
	v_cndmask_b32_e64 v3, v131, v49, s[4:5]
	v_cndmask_b32_e64 v20, v49, v131, s[4:5]
	v_cndmask_b32_e64 v4, v132, v22, s[4:5]
	v_cndmask_b32_e64 v23, v22, v132, s[4:5]
	v_cndmask_b32_e64 v5, v133, v43, s[4:5]
	v_cndmask_b32_e64 v25, v43, v133, s[4:5]
	v_cndmask_b32_e64 v6, v134, v96, s[4:5]
	v_cndmask_b32_e64 v26, v96, v134, s[4:5]
	v_cndmask_b32_e64 v7, v135, v90, s[4:5]
	v_cndmask_b32_e64 v27, v90, v135, s[4:5]
	v_cndmask_b32_e64 v8, v136, v66, s[4:5]
	v_cndmask_b32_e64 v28, v66, v136, s[4:5]
	v_cndmask_b32_e64 v9, v137, v24, s[4:5]
	v_cndmask_b32_e64 v29, v24, v137, s[4:5]
	v_cndmask_b32_e64 v10, v138, v36, s[4:5]
	v_cndmask_b32_e64 v30, v36, v138, s[4:5]
	v_cndmask_b32_e64 v11, v139, v37, s[4:5]
	v_cndmask_b32_e64 v31, v37, v139, s[4:5]
	v_cndmask_b32_e64 v12, v140, v63, s[4:5]
	v_cndmask_b32_e64 v32, v63, v140, s[4:5]
	v_cndmask_b32_e64 v13, v141, v67, s[4:5]
	v_cndmask_b32_e64 v33, v67, v141, s[4:5]
	v_cndmask_b32_e64 v14, v142, v21, s[4:5]
	v_cndmask_b32_e64 v34, v21, v142, s[4:5]
	v_cndmask_b32_e64 v16, v143, v15, s[4:5]
	v_cndmask_b32_e64 v35, v15, v143, s[4:5]
	v_and_b32_e32 v0, s6, v0
	v_and_b32_e32 v17, s6, v17
	v_and_b32_e32 v1, s6, v1
	v_and_b32_e32 v18, s6, v18
	v_and_b32_e32 v2, s6, v2
	v_and_b32_e32 v19, s6, v19
	v_and_b32_e32 v3, s6, v3
	v_and_b32_e32 v20, s6, v20
	v_and_b32_e32 v4, s6, v4
	v_and_b32_e32 v23, s6, v23
	v_and_b32_e32 v5, s6, v5
	v_and_b32_e32 v25, s6, v25
	v_and_b32_e32 v6, s6, v6
	v_and_b32_e32 v26, s6, v26
	v_and_b32_e32 v7, s6, v7
	v_and_b32_e32 v27, s6, v27
	v_and_b32_e32 v8, s6, v8
	v_and_b32_e32 v28, s6, v28
	v_and_b32_e32 v9, s6, v9
	v_and_b32_e32 v29, s6, v29
	v_and_b32_e32 v10, s6, v10
	v_and_b32_e32 v30, s6, v30
	v_and_b32_e32 v11, s6, v11
	v_and_b32_e32 v31, s6, v31
	v_and_b32_e32 v12, s6, v12
	v_and_b32_e32 v32, s6, v32
	v_and_b32_e32 v13, s6, v13
	v_and_b32_e32 v33, s6, v33
	v_and_b32_e32 v14, s6, v14
	v_and_b32_e32 v34, s6, v34
	v_and_b32_e32 v16, s6, v16
	v_and_b32_e32 v35, s6, v35
	v_add_f32_e32 v38, v0, v18
	v_and_or_b32 v38, v38, s7, 0
	v_add_f32_e32 v39, v0, v19
	v_and_or_b32 v39, v39, s7, 2
	v_add_f32_e32 v40, v0, v20
	v_and_or_b32 v40, v40, s7, 4
	v_add_f32_e32 v41, v0, v23
	v_and_or_b32 v41, v41, s7, 6
	v_add_f32_e32 v42, v0, v25
	v_and_or_b32 v42, v42, s7, 8
	v_add_f32_e32 v44, v0, v26
	v_and_or_b32 v44, v44, s7, 10
	v_add_f32_e32 v45, v0, v27
	v_and_or_b32 v45, v45, s7, 12
	v_add_f32_e32 v46, v0, v28
	v_and_or_b32 v46, v46, s7, 14
	v_add_f32_e32 v47, v0, v29
	v_and_or_b32 v47, v47, s7, 16
	v_add_f32_e32 v48, v0, v30
	v_and_or_b32 v48, v48, s7, 18
	v_add_f32_e32 v50, v0, v31
	v_and_or_b32 v50, v50, s7, 20
	v_add_f32_e32 v51, v0, v32
	v_and_or_b32 v51, v51, s7, 22
	v_add_f32_e32 v52, v0, v33
	v_and_or_b32 v52, v52, s7, 24
	v_add_f32_e32 v53, v0, v34
	v_and_or_b32 v53, v53, s7, 26
	v_add_f32_e32 v54, v0, v35
	v_and_or_b32 v54, v54, s7, 28
	v_add_f32_e32 v55, v1, v19
	v_and_or_b32 v55, v55, s7, 30
	v_add_f32_e32 v56, v1, v20
	v_and_or_b32 v56, v56, s7, 32
	v_add_f32_e32 v57, v1, v23
	v_and_or_b32 v57, v57, s7, 34
	v_add_f32_e32 v58, v1, v25
	v_and_or_b32 v58, v58, s7, 36
	v_add_f32_e32 v59, v1, v26
	v_and_or_b32 v59, v59, s7, 38
	v_add_f32_e32 v60, v1, v27
	v_and_or_b32 v60, v60, s7, 40
	v_add_f32_e32 v61, v2, v20
	v_and_or_b32 v61, v61, s7, 42
	v_add_f32_e32 v62, v2, v23
	v_and_or_b32 v62, v62, s7, 44
	v_add_f32_e32 v64, v0, v17
	v_and_or_b32 v64, v64, s7, 46
	v_cndmask_b32_e64 v64, v64, v244, s[4:5]
	v_add_f32_e32 v65, v1, v18
	v_and_or_b32 v65, v65, s7, 48
	v_cndmask_b32_e64 v65, v65, v244, s[4:5]
	v_add_f32_e32 v68, v2, v19
	v_and_or_b32 v68, v68, s7, 50
	v_cndmask_b32_e64 v68, v68, v244, s[4:5]
	v_add_f32_e32 v69, v3, v20
	v_and_or_b32 v69, v69, s7, 52
	v_cndmask_b32_e64 v69, v69, v244, s[4:5]
	v_max_f32_e32 v70, v38, v53
	v_min_f32_e32 v53, v38, v53
	v_max_f32_e32 v71, v39, v52
	v_min_f32_e32 v52, v39, v52
	v_max_f32_e32 v72, v40, v55
	v_min_f32_e32 v55, v40, v55
	v_max_f32_e32 v73, v41, v54
	v_min_f32_e32 v54, v41, v54
	v_max_f32_e32 v74, v42, v47
	v_min_f32_e32 v47, v42, v47
	v_max_f32_e32 v75, v44, v45
	v_min_f32_e32 v45, v44, v45
	v_max_f32_e32 v76, v46, v51
	v_min_f32_e32 v51, v46, v51
	v_max_f32_e32 v77, v48, v50
	v_min_f32_e32 v50, v48, v50
	v_max_f32_e32 v78, v70, v75
	v_min_f32_e32 v75, v70, v75
	v_max_f32_e32 v79, v71, v76
	v_min_f32_e32 v76, v71, v76
	v_max_f32_e32 v80, v72, v77
	v_min_f32_e32 v77, v72, v77
	v_max_f32_e32 v81, v73, v74
	v_min_f32_e32 v74, v73, v74
	v_max_f32_e32 v82, v45, v53
	v_min_f32_e32 v53, v45, v53
	v_max_f32_e32 v83, v47, v54
	v_min_f32_e32 v54, v47, v54
	v_max_f32_e32 v84, v50, v55
	v_min_f32_e32 v55, v50, v55
	v_max_f32_e32 v85, v51, v52
	v_min_f32_e32 v52, v51, v52
	v_max_f32_e32 v86, v78, v79
	v_min_f32_e32 v79, v78, v79
	v_max_f32_e32 v87, v80, v81
	v_min_f32_e32 v81, v80, v81
	v_max_f32_e32 v88, v74, v75
	v_min_f32_e32 v75, v74, v75
	v_max_f32_e32 v89, v82, v83
	v_min_f32_e32 v83, v82, v83
	v_max_f32_e32 v91, v76, v77
	v_min_f32_e32 v77, v76, v77
	v_max_f32_e32 v92, v84, v85
	v_min_f32_e32 v85, v84, v85
	v_max_f32_e32 v93, v52, v53
	v_min_f32_e32 v53, v52, v53
	v_max_f32_e32 v94, v54, v55
	v_min_f32_e32 v55, v54, v55
	v_max_f32_e32 v95, v86, v87
	v_min_f32_e32 v87, v86, v87
	v_max_f32_e32 v97, v79, v81
	v_min_f32_e32 v81, v79, v81
	v_max_f32_e32 v98, v88, v92
	v_min_f32_e32 v92, v88, v92
	v_max_f32_e32 v99, v75, v85
	v_min_f32_e32 v85, v75, v85
	v_max_f32_e32 v100, v89, v91
	v_min_f32_e32 v91, v89, v91
	v_max_f32_e32 v101, v83, v77
	v_min_f32_e32 v77, v83, v77
	v_max_f32_e32 v103, v93, v94
	v_min_f32_e32 v94, v93, v94
	v_max_f32_e32 v104, v53, v55
	v_min_f32_e32 v55, v53, v55
	v_max_f32_e32 v105, v97, v87
	v_min_f32_e32 v87, v97, v87
	v_max_f32_e32 v106, v81, v103
	v_min_f32_e32 v103, v81, v103
	v_max_f32_e32 v107, v98, v100
	v_min_f32_e32 v100, v98, v100
	v_max_f32_e32 v108, v99, v91
	v_min_f32_e32 v91, v99, v91
	v_max_f32_e32 v109, v101, v92
	v_min_f32_e32 v92, v101, v92
	v_max_f32_e32 v110, v77, v85
	v_min_f32_e32 v85, v77, v85
	v_max_f32_e32 v111, v104, v94
	v_min_f32_e32 v94, v104, v94
	v_max_f32_e32 v112, v105, v107
	v_min_f32_e32 v107, v105, v107
	v_max_f32_e32 v113, v87, v100
	v_min_f32_e32 v100, v87, v100
	v_max_f32_e32 v114, v108, v109
	v_min_f32_e32 v109, v108, v109
	v_max_f32_e32 v115, v91, v92
	v_min_f32_e32 v92, v91, v92
	v_max_f32_e32 v116, v110, v111
	v_min_f32_e32 v111, v110, v111
	v_max_f32_e32 v118, v85, v94
	v_min_f32_e32 v94, v85, v94
	v_max_f32_e32 v119, v113, v107
	v_min_f32_e32 v107, v113, v107
	v_max_f32_e32 v120, v106, v100
	v_min_f32_e32 v100, v106, v100
	v_max_f32_e32 v121, v116, v103
	v_min_f32_e32 v103, v116, v103
	v_max_f32_e32 v122, v118, v111
	v_min_f32_e32 v111, v118, v111
	v_max_f32_e32 v123, v120, v114
	v_min_f32_e32 v114, v120, v114
	v_max_f32_e32 v124, v100, v109
	v_min_f32_e32 v109, v100, v109
	v_max_f32_e32 v126, v115, v121
	v_min_f32_e32 v121, v115, v121
	v_max_f32_e32 v127, v92, v103
	v_min_f32_e32 v103, v92, v103
	v_max_f32_e32 v144, v123, v107
	v_min_f32_e32 v107, v123, v107
	v_max_f32_e32 v145, v114, v124
	v_min_f32_e32 v124, v114, v124
	v_max_f32_e32 v146, v126, v109
	v_min_f32_e32 v109, v126, v109
	v_max_f32_e32 v147, v121, v127
	v_min_f32_e32 v127, v121, v127
	v_max_f32_e32 v148, v122, v103
	v_min_f32_e32 v103, v122, v103
	v_max_f32_e32 v149, v124, v146
	v_min_f32_e32 v146, v124, v146
	v_max_f32_e32 v150, v109, v147
	v_min_f32_e32 v147, v109, v147
	v_max_f32_e32 v151, v60, v65
	v_min_f32_e32 v65, v60, v65
	v_max_f32_e32 v249, v61, v62
	v_min_f32_e32 v62, v61, v62
	v_max_f32_e32 v250, v68, v69
	v_min_f32_e32 v69, v68, v69
	v_max_f32_e32 v251, v56, v249
	v_min_f32_e32 v249, v56, v249
	v_max_f32_e32 v252, v57, v64
	v_min_f32_e32 v64, v57, v64
	v_max_f32_e32 v253, v58, v250
	v_min_f32_e32 v250, v58, v250
	v_max_f32_e32 v254, v59, v151
	v_min_f32_e32 v151, v59, v151
	v_max_f32_e32 v255, v251, v252
	v_min_f32_e32 v252, v251, v252
	v_max_f32_e32 v128, v253, v254
	v_min_f32_e32 v254, v253, v254
	v_max_f32_e32 v129, v151, v249
	v_min_f32_e32 v249, v151, v249
	v_max_f32_e32 v130, v62, v65
	v_min_f32_e32 v65, v62, v65
	v_max_f32_e32 v131, v64, v250
	v_min_f32_e32 v250, v64, v250
	v_max_f32_e32 v132, v255, v128
	v_min_f32_e32 v128, v255, v128
	v_max_f32_e32 v133, v252, v254
	v_min_f32_e32 v254, v252, v254
	v_max_f32_e32 v134, v129, v69
	v_min_f32_e32 v69, v129, v69
	v_max_f32_e32 v135, v130, v131
	v_min_f32_e32 v131, v130, v131
	v_max_f32_e32 v136, v65, v250
	v_min_f32_e32 v250, v65, v250
	v_max_f32_e32 v137, v133, v128
	v_min_f32_e32 v128, v133, v128
	v_max_f32_e32 v138, v134, v135
	v_min_f32_e32 v135, v134, v135
	v_max_f32_e32 v139, v249, v131
	v_min_f32_e32 v131, v249, v131
	v_max_f32_e32 v140, v136, v69
	v_min_f32_e32 v69, v136, v69
	v_max_f32_e32 v141, v137, v138
	v_min_f32_e32 v138, v137, v138
	v_max_f32_e32 v142, v128, v135
	v_min_f32_e32 v135, v128, v135
	v_max_f32_e32 v143, v139, v140
	v_min_f32_e32 v140, v139, v140
	v_max_f32_e32 v125, v131, v69
	v_min_f32_e32 v69, v131, v69
	v_max_f32_e32 v117, v142, v138
	v_min_f32_e32 v138, v142, v138
	v_max_f32_e32 v102, v254, v135
	v_min_f32_e32 v135, v254, v135
	v_max_f32_e32 v49, v102, v143
	v_min_f32_e32 v143, v102, v143
	v_max_f32_e32 v22, v135, v140
	v_min_f32_e32 v140, v135, v140
	v_max_f32_e32 v43, v125, v250
	v_min_f32_e32 v250, v125, v250
	v_max_f32_e32 v96, v49, v138
	v_min_f32_e32 v138, v49, v138
	v_max_f32_e32 v90, v143, v22
	v_min_f32_e32 v22, v143, v22
	v_max_f32_e32 v66, v43, v140
	v_min_f32_e32 v140, v43, v140
	v_max_f32_e32 v24, v250, v69
	v_min_f32_e32 v69, v250, v69
	v_max_f32_e32 v36, v22, v66
	v_min_f32_e32 v66, v22, v66
	v_max_f32_e32 v37, v140, v24
	v_min_f32_e32 v24, v140, v24
	s_waitcnt vmcnt(0)
	v_pk_mul_f32 v[160:161], v[160:161], v[176:177]
	v_pk_mul_f32 v[162:163], v[162:163], v[178:179]
	v_pk_mul_f32 v[164:165], v[164:165], v[180:181]
	v_pk_mul_f32 v[166:167], v[166:167], v[182:183]
	v_pk_mul_f32 v[168:169], v[168:169], v[184:185]
	v_pk_mul_f32 v[170:171], v[170:171], v[186:187]
	v_pk_mul_f32 v[172:173], v[172:173], v[188:189]
	v_pk_mul_f32 v[174:175], v[174:175], v[190:191]
	v_max3_f32 v192, |v160|, |v161|, |v162|
	v_max3_f32 v192, |v163|, |v164|, v192
	v_max3_f32 v192, |v165|, |v166|, v192
	v_max3_f32 v192, |v167|, |v168|, v192
	v_max3_f32 v192, |v169|, |v170|, v192
	v_max3_f32 v192, |v171|, |v172|, v192
	v_max3_f32 v192, |v173|, |v174|, v192
	v_max_f32_e64 v192, |v175|, v192
	s_nop 1
	v_mov_b32_dpp v193, v192 quad_perm:[1,0,3,2] row_mask:0xf bank_mask:0xf bound_ctrl:1
	v_max_f32_e32 v192, v192, v193
	s_nop 1
	v_mov_b32_dpp v193, v192 quad_perm:[2,3,0,1] row_mask:0xf bank_mask:0xf bound_ctrl:1
	v_max_f32_e32 v192, v192, v193
	s_nop 1
	v_mov_b32_dpp v193, v192 row_half_mirror row_mask:0xf bank_mask:0xf bound_ctrl:1
	v_max_f32_e32 v192, v192, v193
	s_nop 1
	v_mov_b32_dpp v193, v192 row_mirror row_mask:0xf bank_mask:0xf bound_ctrl:1
	v_max_f32_e32 v192, v192, v193
	v_mov_b32_e32 v193, v192
	s_nop 1
	v_permlane16_swap_b32_e32 v192, v193
	s_nop 1
	v_max_f32_e32 v192, v192, v193
	v_mov_b32_e32 v193, v192
	s_nop 1
	v_permlane32_swap_b32_e32 v192, v193
	s_nop 1
	v_max_f32_e32 v192, v192, v193
	v_max_f32_e32 v192, 0xda24260, v192
	v_mul_f32_e32 v194, 0x3e2aaaab, v192
	global_store_dword v214, v194, s[12:13]
	v_div_scale_f32 v195, s[26:27], v194, v194, 1.0
	v_rcp_f32_e32 v196, v195
	v_div_scale_f32 v204, vcc, 1.0, v194, 1.0
	v_fma_f32 v205, -v195, v196, 1.0
	v_fmac_f32_e32 v196, v205, v196
	v_mul_f32_e32 v205, v204, v196
	v_fma_f32 v206, -v195, v205, v204
	v_fmac_f32_e32 v205, v206, v196
	v_fma_f32 v195, -v195, v205, v204
	s_nop 0
	v_div_fmas_f32 v195, v195, v196, v205
	v_div_fixup_f32 v207, v195, v194, 1.0
	v_mul_f32_e32 v160, v207, v160
	v_mul_f32_e32 v161, v207, v161
	v_mul_f32_e32 v162, v207, v162
	v_mul_f32_e32 v163, v207, v163
	v_mul_f32_e32 v164, v207, v164
	v_mul_f32_e32 v165, v207, v165
	v_mul_f32_e32 v166, v207, v166
	v_mul_f32_e32 v167, v207, v167
	v_mul_f32_e32 v168, v207, v168
	v_mul_f32_e32 v169, v207, v169
	v_mul_f32_e32 v170, v207, v170
	v_mul_f32_e32 v171, v207, v171
	v_mul_f32_e32 v172, v207, v172
	v_mul_f32_e32 v173, v207, v173
	v_mul_f32_e32 v174, v207, v174
	v_mul_f32_e32 v175, v207, v175
	v_mov_b32_e32 v208, 0
	v_mov_b32_e32 v209, 0
	v_mov_b32_e32 v210, 0
	v_mov_b32_e32 v193, 0
	v_cvt_scalef32_pk_fp4_f32 v208, v160, v161, 1.0
	v_cvt_scalef32_pk_fp4_f32 v209, v164, v165, 1.0
	v_cvt_scalef32_pk_fp4_f32 v210, v168, v169, 1.0
	v_cvt_scalef32_pk_fp4_f32 v193, v172, v173, 1.0
	v_cvt_scalef32_pk_fp4_f32 v208, v162, v163, 1.0 op_sel:[0,0,1,0]
	v_cvt_scalef32_pk_fp4_f32 v209, v166, v167, 1.0 op_sel:[0,0,1,0]
	v_cvt_scalef32_pk_fp4_f32 v210, v170, v171, 1.0 op_sel:[0,0,1,0]
	v_cvt_scalef32_pk_fp4_f32 v193, v174, v175, 1.0 op_sel:[0,0,1,0]
	global_store_short v213, v208, s[10:11] nt
	s_add_u32 s14, s10, 0x200000
	s_addc_u32 s15, s11, 0
	global_store_short v213, v209, s[14:15] nt
	s_add_u32 s14, s10, 0x400000
	s_addc_u32 s15, s11, 0
	global_store_short v213, v210, s[14:15] nt
	s_add_u32 s14, s10, 0x600000
	s_addc_u32 s15, s11, 0
	global_store_short v213, v193, s[14:15] nt
	s_add_u32 s10, s10, 0x20000
	s_addc_u32 s11, s11, 0
	s_add_u32 s12, s12, 0x2000
	s_addc_u32 s13, s13, 0
	global_load_dwordx4 v[160:163], v212, s[8:9] offset:0 nt
	global_load_dwordx4 v[164:167], v212, s[8:9] offset:1024 nt
	global_load_dwordx4 v[168:171], v212, s[8:9] offset:2048 nt
	global_load_dwordx4 v[172:175], v212, s[8:9] offset:3072 nt
	s_add_u32 s8, s8, 0x800000
	s_addc_u32 s9, s9, 0
	v_max_f32_e32 v145, v145, v69
	v_max_f32_e32 v149, v149, v24
	v_max_f32_e32 v146, v146, v37
	v_max_f32_e32 v150, v150, v66
	v_max_f32_e32 v147, v147, v36
	v_max_f32_e32 v127, v127, v90
	v_max_f32_e32 v148, v148, v138
	v_max_f32_e32 v103, v103, v96
	v_max_f32_e32 v111, v111, v117
	v_max_f32_e32 v94, v94, v141
	v_max_f32_e32 v55, v55, v132
	v_max_f32_e32 v63, v95, v150
	v_min_f32_e32 v150, v95, v150
	v_max_f32_e32 v67, v112, v147
	v_min_f32_e32 v147, v112, v147
	v_max_f32_e32 v21, v119, v127
	v_min_f32_e32 v127, v119, v127
	v_max_f32_e32 v15, v144, v148
	v_min_f32_e32 v148, v144, v148
	v_max_f32_e32 v0, v107, v103
	v_min_f32_e32 v103, v107, v103
	v_max_f32_e32 v1, v145, v111
	v_min_f32_e32 v111, v145, v111
	v_max_f32_e32 v2, v149, v94
	v_min_f32_e32 v94, v149, v94
	v_max_f32_e32 v3, v146, v55
	v_min_f32_e32 v55, v146, v55
	v_max_f32_e32 v4, v63, v0
	v_min_f32_e32 v0, v63, v0
	v_max_f32_e32 v5, v67, v1
	v_min_f32_e32 v1, v67, v1
	v_max_f32_e32 v6, v21, v2
	v_min_f32_e32 v2, v21, v2
	v_max_f32_e32 v7, v15, v3
	v_min_f32_e32 v3, v15, v3
	v_max_f32_e32 v8, v150, v103
	v_min_f32_e32 v103, v150, v103
	v_max_f32_e32 v9, v147, v111
	v_min_f32_e32 v111, v147, v111
	v_max_f32_e32 v10, v127, v94
	v_min_f32_e32 v94, v127, v94
	v_max_f32_e32 v11, v148, v55
	v_min_f32_e32 v55, v148, v55
	v_max_f32_e32 v12, v4, v6
	v_min_f32_e32 v6, v4, v6
	v_max_f32_e32 v13, v5, v7
	v_min_f32_e32 v7, v5, v7
	v_max_f32_e32 v14, v0, v2
	v_min_f32_e32 v2, v0, v2
	v_max_f32_e32 v16, v1, v3
	v_min_f32_e32 v3, v1, v3
	v_max_f32_e32 v17, v8, v10
	v_min_f32_e32 v10, v8, v10
	v_max_f32_e32 v18, v9, v11
	v_min_f32_e32 v11, v9, v11
	v_max_f32_e32 v19, v103, v94
	v_min_f32_e32 v94, v103, v94
	v_max_f32_e32 v20, v111, v55
	v_min_f32_e32 v55, v111, v55
	v_max_f32_e32 v23, v12, v13
	v_min_f32_e32 v13, v12, v13
	v_max_f32_e32 v25, v6, v7
	v_min_f32_e32 v7, v6, v7
	v_max_f32_e32 v26, v14, v16
	v_min_f32_e32 v16, v14, v16
	v_max_f32_e32 v27, v2, v3
	v_min_f32_e32 v3, v2, v3
	v_max_f32_e32 v28, v17, v18
	v_min_f32_e32 v18, v17, v18
	v_max_f32_e32 v29, v10, v11
	v_min_f32_e32 v11, v10, v11
	v_max_f32_e32 v30, v19, v20
	v_min_f32_e32 v20, v19, v20
	v_max_f32_e32 v31, v94, v55
	v_min_f32_e32 v55, v94, v55
	v_or_b32_e32 v23, v23, v245
	v_or_b32_e32 v13, v13, v245
	v_or_b32_e32 v25, v25, v245
	v_or_b32_e32 v7, v7, v245
	v_or_b32_e32 v26, v26, v245
	v_or_b32_e32 v16, v16, v245
	v_or_b32_e32 v27, v27, v245
	v_or_b32_e32 v3, v3, v245
	v_or_b32_e32 v28, v28, v245
	v_or_b32_e32 v18, v18, v245
	v_or_b32_e32 v29, v29, v245
	v_or_b32_e32 v11, v11, v245
	v_or_b32_e32 v30, v30, v245
	v_or_b32_e32 v20, v20, v245
	v_or_b32_e32 v31, v31, v245
	v_or_b32_e32 v55, v55, v245
	v_mov_b32_e32 v32, v23
	v_mov_b32_e32 v33, v13
	v_mov_b32_e32 v34, v25
	v_mov_b32_e32 v35, v7
	v_mov_b32_e32 v38, v26
	v_mov_b32_e32 v39, v16
	v_mov_b32_e32 v40, v27
	v_mov_b32_e32 v41, v3
	v_mov_b32_e32 v42, v28
	v_mov_b32_e32 v44, v18
	v_mov_b32_e32 v46, v29
	v_mov_b32_e32 v48, v11
	v_mov_b32_e32 v70, v30
	v_mov_b32_e32 v71, v20
	v_mov_b32_e32 v72, v31
	v_mov_b32_e32 v73, v55
	s_nop 1
	v_permlane32_swap_b32_e32 v23, v32
	v_permlane32_swap_b32_e32 v13, v33
	v_permlane32_swap_b32_e32 v25, v34
	v_permlane32_swap_b32_e32 v7, v35
	v_permlane32_swap_b32_e32 v26, v38
	v_permlane32_swap_b32_e32 v16, v39
	v_permlane32_swap_b32_e32 v27, v40
	v_permlane32_swap_b32_e32 v3, v41
	v_permlane32_swap_b32_e32 v28, v42
	v_permlane32_swap_b32_e32 v18, v44
	v_permlane32_swap_b32_e32 v29, v46
	v_permlane32_swap_b32_e32 v11, v48
	v_permlane32_swap_b32_e32 v30, v70
	v_permlane32_swap_b32_e32 v20, v71
	v_permlane32_swap_b32_e32 v31, v72
	v_permlane32_swap_b32_e32 v55, v73
	s_nop 1
	v_max_f32_e32 v23, v23, v73
	v_max_f32_e32 v13, v13, v72
	v_max_f32_e32 v25, v25, v71
	v_max_f32_e32 v7, v7, v70
	v_max_f32_e32 v26, v26, v48
	v_max_f32_e32 v16, v16, v46
	v_max_f32_e32 v27, v27, v44
	v_max_f32_e32 v3, v3, v42
	v_max_f32_e32 v28, v28, v41
	v_max_f32_e32 v18, v18, v40
	v_max_f32_e32 v29, v29, v39
	v_max_f32_e32 v11, v11, v38
	v_max_f32_e32 v30, v30, v35
	v_max_f32_e32 v20, v20, v34
	v_max_f32_e32 v31, v31, v33
	v_max_f32_e32 v55, v55, v32
	v_max_f32_e32 v45, v23, v28
	v_min_f32_e32 v28, v23, v28
	v_max_f32_e32 v47, v13, v18
	v_min_f32_e32 v18, v13, v18
	v_max_f32_e32 v50, v25, v29
	v_min_f32_e32 v29, v25, v29
	v_max_f32_e32 v51, v7, v11
	v_min_f32_e32 v11, v7, v11
	v_max_f32_e32 v78, v26, v30
	v_min_f32_e32 v30, v26, v30
	v_max_f32_e32 v80, v16, v20
	v_min_f32_e32 v20, v16, v20
	v_max_f32_e32 v74, v27, v31
	v_min_f32_e32 v31, v27, v31
	v_max_f32_e32 v82, v3, v55
	v_min_f32_e32 v55, v3, v55
	v_max_f32_e32 v76, v45, v78
	v_min_f32_e32 v78, v45, v78
	v_max_f32_e32 v84, v47, v80
	v_min_f32_e32 v80, v47, v80
	v_max_f32_e32 v52, v50, v74
	v_min_f32_e32 v74, v50, v74
	v_max_f32_e32 v54, v51, v82
	v_min_f32_e32 v82, v51, v82
	v_max_f32_e32 v86, v28, v30
	v_min_f32_e32 v30, v28, v30
	v_max_f32_e32 v79, v18, v20
	v_min_f32_e32 v20, v18, v20
	v_max_f32_e32 v88, v29, v31
	v_min_f32_e32 v31, v29, v31
	v_max_f32_e32 v75, v11, v55
	v_min_f32_e32 v55, v11, v55
	v_max_f32_e32 v89, v76, v52
	v_min_f32_e32 v52, v76, v52
	v_max_f32_e32 v83, v84, v54
	v_min_f32_e32 v54, v84, v54
	v_max_f32_e32 v93, v78, v74
	v_min_f32_e32 v74, v78, v74
	v_max_f32_e32 v53, v80, v82
	v_min_f32_e32 v82, v80, v82
	v_max_f32_e32 v97, v86, v88
	v_min_f32_e32 v88, v86, v88
	v_max_f32_e32 v81, v79, v75
	v_min_f32_e32 v75, v79, v75
	v_max_f32_e32 v98, v30, v31
	v_min_f32_e32 v31, v30, v31
	v_max_f32_e32 v99, v20, v55
	v_min_f32_e32 v55, v20, v55
	v_max_f32_e32 v101, v89, v83
	v_min_f32_e32 v83, v89, v83
	v_max_f32_e32 v77, v52, v54
	v_min_f32_e32 v54, v52, v54
	v_max_f32_e32 v104, v93, v53
	v_min_f32_e32 v53, v93, v53
	v_max_f32_e32 v105, v74, v82
	v_min_f32_e32 v82, v74, v82
	v_max_f32_e32 v87, v97, v81
	v_min_f32_e32 v81, v97, v81
	v_max_f32_e32 v108, v88, v75
	v_min_f32_e32 v75, v88, v75
	v_max_f32_e32 v91, v98, v99
	v_min_f32_e32 v99, v98, v99
	v_max_f32_e32 v110, v31, v55
	v_min_f32_e32 v55, v31, v55
	v_and_b32_e32 v85, s7, v101
	v_cndmask_b32_e64 v113, v101, v87, s[4:5]
	v_cndmask_b32_e64 v106, v83, v81, s[4:5]
	v_cndmask_b32_e64 v116, v77, v108, s[4:5]
	v_cndmask_b32_e64 v118, v54, v75, s[4:5]
	v_cndmask_b32_e64 v120, v104, v91, s[4:5]
	v_cndmask_b32_e64 v100, v53, v99, s[4:5]
	v_cndmask_b32_e64 v115, v105, v110, s[4:5]
	v_cndmask_b32_e64 v92, v82, v55, s[4:5]
	v_and_or_b32 v123, v113, 63, v246
	ds_read_u8 v123, v123
	v_and_or_b32 v114, v106, 63, v246
	ds_read_u8 v114, v114
	v_and_or_b32 v126, v116, 63, v246
	ds_read_u8 v126, v126
	v_and_or_b32 v121, v118, 63, v246
	ds_read_u8 v121, v121
	v_and_or_b32 v122, v120, 63, v246
	ds_read_u8 v122, v122
	v_and_or_b32 v124, v100, 63, v246
	ds_read_u8 v124, v124
	v_and_or_b32 v109, v115, 63, v246
	ds_read_u8 v109, v109
	v_and_or_b32 v60, v92, 63, v246
	ds_read_u8 v60, v60
	v_and_b32_e32 v113, s7, v113
	v_sub_f32_e32 v113, v113, v85
	v_mul_f32_e32 v113, 0x3fb8aa3b, v113
	v_exp_f32_e32 v113, v113
	v_and_b32_e32 v106, s7, v106
	v_sub_f32_e32 v106, v106, v85
	v_mul_f32_e32 v106, 0x3fb8aa3b, v106
	v_exp_f32_e32 v106, v106
	v_and_b32_e32 v116, s7, v116
	v_sub_f32_e32 v116, v116, v85
	v_mul_f32_e32 v116, 0x3fb8aa3b, v116
	v_exp_f32_e32 v116, v116
	v_and_b32_e32 v118, s7, v118
	v_sub_f32_e32 v118, v118, v85
	v_mul_f32_e32 v118, 0x3fb8aa3b, v118
	v_exp_f32_e32 v118, v118
	v_and_b32_e32 v120, s7, v120
	v_sub_f32_e32 v120, v120, v85
	v_mul_f32_e32 v120, 0x3fb8aa3b, v120
	v_exp_f32_e32 v120, v120
	v_and_b32_e32 v100, s7, v100
	v_sub_f32_e32 v100, v100, v85
	v_mul_f32_e32 v100, 0x3fb8aa3b, v100
	v_exp_f32_e32 v100, v100
	v_and_b32_e32 v115, s7, v115
	v_sub_f32_e32 v115, v115, v85
	v_mul_f32_e32 v115, 0x3fb8aa3b, v115
	v_exp_f32_e32 v115, v115
	v_and_b32_e32 v92, s7, v92
	v_sub_f32_e32 v92, v92, v85
	v_mul_f32_e32 v92, 0x3fb8aa3b, v92
	v_exp_f32_e32 v92, v92
	s_nop 0
	v_add_f32_e32 v85, v113, v106
	v_add_f32_e32 v85, v85, v116
	v_add_f32_e32 v85, v85, v118
	v_add_f32_e32 v85, v85, v120
	v_add_f32_e32 v85, v85, v100
	v_add_f32_e32 v85, v85, v115
	v_add_f32_e32 v85, v85, v92
	v_mov_b32_e32 v61, v85
	s_nop 1
	v_permlane32_swap_b32_e32 v85, v61
	s_nop 1
	v_add_f32_e32 v85, v85, v61
	s_waitcnt lgkmcnt(0)
	v_bfe_u32 v68, v123, 4, 4
	v_or_b32_e32 v68, v68, v240
	v_and_or_b32 v123, v123, 15, v240
	ds_read_u8 v68, v68
	ds_read_u8 v123, v123 offset:512
	v_bfe_u32 v56, v114, 4, 4
	v_or_b32_e32 v56, v56, v240
	v_and_or_b32 v114, v114, 15, v240
	ds_read_u8 v56, v56
	ds_read_u8 v114, v114 offset:512
	v_bfe_u32 v57, v126, 4, 4
	v_or_b32_e32 v57, v57, v240
	v_and_or_b32 v126, v126, 15, v240
	ds_read_u8 v57, v57
	ds_read_u8 v126, v126 offset:512
	v_bfe_u32 v58, v121, 4, 4
	v_or_b32_e32 v58, v58, v240
	v_and_or_b32 v121, v121, 15, v240
	ds_read_u8 v58, v58
	ds_read_u8 v121, v121 offset:512
	v_bfe_u32 v59, v122, 4, 4
	v_or_b32_e32 v59, v59, v240
	v_and_or_b32 v122, v122, 15, v240
	ds_read_u8 v59, v59
	ds_read_u8 v122, v122 offset:512
	v_bfe_u32 v251, v124, 4, 4
	v_or_b32_e32 v251, v251, v240
	v_and_or_b32 v124, v124, 15, v240
	ds_read_u8 v251, v251
	ds_read_u8 v124, v124 offset:512
	v_bfe_u32 v253, v109, 4, 4
	v_or_b32_e32 v253, v253, v240
	v_and_or_b32 v109, v109, 15, v240
	ds_read_u8 v253, v253
	ds_read_u8 v109, v109 offset:512
	v_bfe_u32 v151, v60, 4, 4
	v_or_b32_e32 v151, v151, v240
	v_and_or_b32 v60, v60, 15, v240
	ds_read_u8 v151, v151
	ds_read_u8 v60, v60 offset:512
	v_div_scale_f32 v134, s[26:27], v85, v85, v113
	v_rcp_f32_e32 v249, v134
	s_nop 0
	v_fma_f32 v136, -v134, v249, 1.0
	v_fmac_f32_e32 v249, v136, v249
	v_div_scale_f32 v136, vcc, v113, v85, v113
	v_mul_f32_e32 v137, v136, v249
	v_fma_f32 v62, -v134, v137, v136
	v_fmac_f32_e32 v137, v62, v249
	v_fma_f32 v136, -v134, v137, v136
	s_nop 0
	v_div_fmas_f32 v136, v136, v249, v137
	v_div_fixup_f32 v62, v136, v85, v113
	v_div_scale_f32 v134, s[26:27], v85, v85, v106
	v_rcp_f32_e32 v249, v134
	s_nop 0
	v_fma_f32 v136, -v134, v249, 1.0
	v_fmac_f32_e32 v249, v136, v249
	v_div_scale_f32 v136, vcc, v106, v85, v106
	v_mul_f32_e32 v137, v136, v249
	v_fma_f32 v64, -v134, v137, v136
	v_fmac_f32_e32 v137, v64, v249
	v_fma_f32 v136, -v134, v137, v136
	s_nop 0
	v_div_fmas_f32 v136, v136, v249, v137
	v_div_fixup_f32 v64, v136, v85, v106
	v_div_scale_f32 v134, s[26:27], v85, v85, v116
	v_rcp_f32_e32 v249, v134
	s_nop 0
	v_fma_f32 v136, -v134, v249, 1.0
	v_fmac_f32_e32 v249, v136, v249
	v_div_scale_f32 v136, vcc, v116, v85, v116
	v_mul_f32_e32 v137, v136, v249
	v_fma_f32 v255, -v134, v137, v136
	v_fmac_f32_e32 v137, v255, v249
	v_fma_f32 v136, -v134, v137, v136
	s_nop 0
	v_div_fmas_f32 v136, v136, v249, v137
	v_div_fixup_f32 v255, v136, v85, v116
	v_div_scale_f32 v134, s[26:27], v85, v85, v118
	v_rcp_f32_e32 v249, v134
	s_nop 0
	v_fma_f32 v136, -v134, v249, 1.0
	v_fmac_f32_e32 v249, v136, v249
	v_div_scale_f32 v136, vcc, v118, v85, v118
	v_mul_f32_e32 v137, v136, v249
	v_fma_f32 v252, -v134, v137, v136
	v_fmac_f32_e32 v137, v252, v249
	v_fma_f32 v136, -v134, v137, v136
	s_nop 0
	v_div_fmas_f32 v136, v136, v249, v137
	v_div_fixup_f32 v252, v136, v85, v118
	v_div_scale_f32 v134, s[26:27], v85, v85, v120
	v_rcp_f32_e32 v249, v134
	s_nop 0
	v_fma_f32 v136, -v134, v249, 1.0
	v_fmac_f32_e32 v249, v136, v249
	v_div_scale_f32 v136, vcc, v120, v85, v120
	v_mul_f32_e32 v137, v136, v249
	v_fma_f32 v129, -v134, v137, v136
	v_fmac_f32_e32 v137, v129, v249
	v_fma_f32 v136, -v134, v137, v136
	s_nop 0
	v_div_fmas_f32 v136, v136, v249, v137
	v_div_fixup_f32 v129, v136, v85, v120
	v_div_scale_f32 v134, s[26:27], v85, v85, v100
	v_rcp_f32_e32 v249, v134
	s_nop 0
	v_fma_f32 v136, -v134, v249, 1.0
	v_fmac_f32_e32 v249, v136, v249
	v_div_scale_f32 v136, vcc, v100, v85, v100
	v_mul_f32_e32 v137, v136, v249
	v_fma_f32 v130, -v134, v137, v136
	v_fmac_f32_e32 v137, v130, v249
	v_fma_f32 v136, -v134, v137, v136
	s_nop 0
	v_div_fmas_f32 v136, v136, v249, v137
	v_div_fixup_f32 v130, v136, v85, v100
	v_div_scale_f32 v134, s[26:27], v85, v85, v115
	v_rcp_f32_e32 v249, v134
	s_nop 0
	v_fma_f32 v136, -v134, v249, 1.0
	v_fmac_f32_e32 v249, v136, v249
	v_div_scale_f32 v136, vcc, v115, v85, v115
	v_mul_f32_e32 v137, v136, v249
	v_fma_f32 v65, -v134, v137, v136
	v_fmac_f32_e32 v137, v65, v249
	v_fma_f32 v136, -v134, v137, v136
	s_nop 0
	v_div_fmas_f32 v136, v136, v249, v137
	v_div_fixup_f32 v65, v136, v85, v115
	v_div_scale_f32 v134, s[26:27], v85, v85, v92
	v_rcp_f32_e32 v249, v134
	s_nop 0
	v_fma_f32 v136, -v134, v249, 1.0
	v_fmac_f32_e32 v249, v136, v249
	v_div_scale_f32 v136, vcc, v92, v85, v92
	v_mul_f32_e32 v137, v136, v249
	v_fma_f32 v133, -v134, v137, v136
	v_fmac_f32_e32 v137, v133, v249
	v_fma_f32 v136, -v134, v137, v136
	s_nop 0
	v_div_fmas_f32 v136, v136, v249, v137
	v_div_fixup_f32 v133, v136, v85, v92
	s_waitcnt lgkmcnt(0)
	v_and_b32_e32 v68, 0x7f, v68
	v_and_b32_e32 v123, 0x7f, v123
	v_lshl_or_b32 v68, v68, 7, v123
	v_xor_b32_e32 v68, 0x3fff, v68
	v_and_b32_e32 v56, 0x7f, v56
	v_and_b32_e32 v114, 0x7f, v114
	v_lshl_or_b32 v56, v56, 7, v114
	v_xor_b32_e32 v56, 0x3fff, v56
	v_and_b32_e32 v57, 0x7f, v57
	v_and_b32_e32 v126, 0x7f, v126
	v_lshl_or_b32 v57, v57, 7, v126
	v_xor_b32_e32 v57, 0x3fff, v57
	v_and_b32_e32 v58, 0x7f, v58
	v_and_b32_e32 v121, 0x7f, v121
	v_lshl_or_b32 v58, v58, 7, v121
	v_xor_b32_e32 v58, 0x3fff, v58
	v_and_b32_e32 v59, 0x7f, v59
	v_and_b32_e32 v122, 0x7f, v122
	v_lshl_or_b32 v59, v59, 7, v122
	v_xor_b32_e32 v59, 0x3fff, v59
	v_and_b32_e32 v251, 0x7f, v251
	v_and_b32_e32 v124, 0x7f, v124
	v_lshl_or_b32 v251, v251, 7, v124
	v_xor_b32_e32 v251, 0x3fff, v251
	v_and_b32_e32 v253, 0x7f, v253
	v_and_b32_e32 v109, 0x7f, v109
	v_lshl_or_b32 v253, v253, 7, v109
	v_xor_b32_e32 v253, 0x3fff, v253
	v_and_b32_e32 v151, 0x7f, v151
	v_and_b32_e32 v60, 0x7f, v60
	v_lshl_or_b32 v151, v151, 7, v60
	v_xor_b32_e32 v151, 0x3fff, v151
	s_waitcnt vmcnt(0)
	v_pk_mul_f32 v[160:161], v[160:161], v[176:177]
	v_pk_mul_f32 v[162:163], v[162:163], v[178:179]
	v_pk_mul_f32 v[164:165], v[164:165], v[180:181]
	v_pk_mul_f32 v[166:167], v[166:167], v[182:183]
	v_pk_mul_f32 v[168:169], v[168:169], v[184:185]
	v_pk_mul_f32 v[170:171], v[170:171], v[186:187]
	v_pk_mul_f32 v[172:173], v[172:173], v[188:189]
	v_pk_mul_f32 v[174:175], v[174:175], v[190:191]
	v_max3_f32 v192, |v160|, |v161|, |v162|
	v_max3_f32 v192, |v163|, |v164|, v192
	v_max3_f32 v192, |v165|, |v166|, v192
	v_max3_f32 v192, |v167|, |v168|, v192
	v_max3_f32 v192, |v169|, |v170|, v192
	v_max3_f32 v192, |v171|, |v172|, v192
	v_max3_f32 v192, |v173|, |v174|, v192
	v_max_f32_e64 v192, |v175|, v192
	s_nop 1
	v_mov_b32_dpp v193, v192 quad_perm:[1,0,3,2] row_mask:0xf bank_mask:0xf bound_ctrl:1
	v_max_f32_e32 v192, v192, v193
	s_nop 1
	v_mov_b32_dpp v193, v192 quad_perm:[2,3,0,1] row_mask:0xf bank_mask:0xf bound_ctrl:1
	v_max_f32_e32 v192, v192, v193
	s_nop 1
	v_mov_b32_dpp v193, v192 row_half_mirror row_mask:0xf bank_mask:0xf bound_ctrl:1
	v_max_f32_e32 v192, v192, v193
	s_nop 1
	v_mov_b32_dpp v193, v192 row_mirror row_mask:0xf bank_mask:0xf bound_ctrl:1
	v_max_f32_e32 v192, v192, v193
	v_mov_b32_e32 v193, v192
	s_nop 1
	v_permlane16_swap_b32_e32 v192, v193
	s_nop 1
	v_max_f32_e32 v192, v192, v193
	v_mov_b32_e32 v193, v192
	s_nop 1
	v_permlane32_swap_b32_e32 v192, v193
	s_nop 1
	v_max_f32_e32 v192, v192, v193
	v_max_f32_e32 v192, 0xda24260, v192
	v_mul_f32_e32 v194, 0x3e2aaaab, v192
	global_store_dword v214, v194, s[12:13]
	v_div_scale_f32 v195, s[26:27], v194, v194, 1.0
	v_rcp_f32_e32 v196, v195
	v_div_scale_f32 v204, vcc, 1.0, v194, 1.0
	v_fma_f32 v205, -v195, v196, 1.0
	v_fmac_f32_e32 v196, v205, v196
	v_mul_f32_e32 v205, v204, v196
	v_fma_f32 v206, -v195, v205, v204
	v_fmac_f32_e32 v205, v206, v196
	v_fma_f32 v195, -v195, v205, v204
	s_nop 0
	v_div_fmas_f32 v195, v195, v196, v205
	v_div_fixup_f32 v207, v195, v194, 1.0
	v_mul_f32_e32 v160, v207, v160
	v_mul_f32_e32 v161, v207, v161
	v_mul_f32_e32 v162, v207, v162
	v_mul_f32_e32 v163, v207, v163
	v_mul_f32_e32 v164, v207, v164
	v_mul_f32_e32 v165, v207, v165
	v_mul_f32_e32 v166, v207, v166
	v_mul_f32_e32 v167, v207, v167
	v_mul_f32_e32 v168, v207, v168
	v_mul_f32_e32 v169, v207, v169
	v_mul_f32_e32 v170, v207, v170
	v_mul_f32_e32 v171, v207, v171
	v_mul_f32_e32 v172, v207, v172
	v_mul_f32_e32 v173, v207, v173
	v_mul_f32_e32 v174, v207, v174
	v_mul_f32_e32 v175, v207, v175
	v_mov_b32_e32 v208, 0
	v_mov_b32_e32 v209, 0
	v_mov_b32_e32 v210, 0
	v_mov_b32_e32 v193, 0
	v_cvt_scalef32_pk_fp4_f32 v208, v160, v161, 1.0
	v_cvt_scalef32_pk_fp4_f32 v209, v164, v165, 1.0
	v_cvt_scalef32_pk_fp4_f32 v210, v168, v169, 1.0
	v_cvt_scalef32_pk_fp4_f32 v193, v172, v173, 1.0
	v_cvt_scalef32_pk_fp4_f32 v208, v162, v163, 1.0 op_sel:[0,0,1,0]
	v_cvt_scalef32_pk_fp4_f32 v209, v166, v167, 1.0 op_sel:[0,0,1,0]
	v_cvt_scalef32_pk_fp4_f32 v210, v170, v171, 1.0 op_sel:[0,0,1,0]
	v_cvt_scalef32_pk_fp4_f32 v193, v174, v175, 1.0 op_sel:[0,0,1,0]
	global_store_short v213, v208, s[10:11] nt
	s_add_u32 s14, s10, 0x200000
	s_addc_u32 s15, s11, 0
	global_store_short v213, v209, s[14:15] nt
	s_add_u32 s14, s10, 0x400000
	s_addc_u32 s15, s11, 0
	global_store_short v213, v210, s[14:15] nt
	s_add_u32 s14, s10, 0x600000
	s_addc_u32 s15, s11, 0
	global_store_short v213, v193, s[14:15] nt
	s_add_u32 s10, s10, 0x20000
	s_addc_u32 s11, s11, 0
	s_add_u32 s12, s12, 0x2000
	s_addc_u32 s13, s13, 0
	s_cmp_eq_u32 s22, 1
	s_cbranch_scc1 .Ltk1_noload7
	global_load_dwordx4 v[160:163], v212, s[8:9] offset:0 nt
	global_load_dwordx4 v[164:167], v212, s[8:9] offset:1024 nt
	global_load_dwordx4 v[168:171], v212, s[8:9] offset:2048 nt
	global_load_dwordx4 v[172:175], v212, s[8:9] offset:3072 nt
	s_add_u32 s8, s8, 0x800000
	s_addc_u32 s9, s9, 0
